# phase-2 stage 0: RWW tiles on ranks 0-31 and RWA tiles on ranks 32-63 in parallel (was both back to back on ranks 0-31); t0 items follow the RWW tile on ranks 0-16
# baseline (speedup 1.0000x reference)
; __global__ void __launch_bounds__(256, 2) fwd_megakernel(Params p) {
;     ...
;         const bool mine = (stage == 0) || (pr >= 0);
;         const int start = stage == 0 ? X.rank : pr, stride = stage == 0 ? X.cnt : PS, lo = stage * 32, hi = stage == 0 ? 32 : 128;
;         if (mine) {
;           for (int i = lo + start; i < hi; i += stride) gemm_tile<G_RWW>(p, b * 32 + (i >> 2), i & 3, 0, smem);
;           for (int i = lo + start; i < hi; i += stride) gemm_tile<G_RWA>(p, b * 32 + (i >> 2), i & 3, 0, smem);
;         }
;         if (stage == 0) {
;           for (int i = (X.rank + (X.cnt >> 1)) % X.cnt; i < 17; i += X.cnt) t0_item(p, b * 17 + i, smem);
.LBB0_203:
	s_cmp_eq_u32 s84, 32
	s_cbranch_scc0 .Lsplit_orig
	s_cmp_eq_u32 s77, 64
	s_cbranch_scc0 .Lsplit_orig
	s_cmp_lt_i32 s85, 32
	s_cbranch_scc1 .Lsplit_orig
	s_sub_i32 s8, s85, 32
	s_lshl_b32 s7, s8, 5
	s_lshl_b32 s6, s8, 7
	v_readlane_b32 s0, v252, 16
	s_lshl_b32 s2, s0, 12
	v_readlane_b32 s1, v252, 17
	s_branch .LBB0_343

; #define MFMA(a, b, c) __builtin_amdgcn_mfma_f32_32x32x16_f16(__builtin_bit_cast(h16x8, (a)), __builtin_bit_cast(h16x8, (b)), (c), 0, 0, 0)
; DI unsigned pack2(float a, float b) { f32x2 v = {a, b}; bfx2 r = __builtin_convertvector(v, bfx2); return __builtin_bit_cast(unsigned, r); }
; DI float lo_bf(unsigned u) { bfx2 h = __builtin_bit_cast(bfx2, u); return (float)h[0]; }
; DI float hi_bf(unsigned u) { bfx2 h = __builtin_bit_cast(bfx2, u); return (float)h[1]; }
; DI float sigmoidf_(float x) { return 1.f / (1.f + __expf(-x)); }
; template <int MODE> DI uint4 load_a(const Params& p, int tm, int kv, int row, int kt, int c) {
;     ...
;     for (int e = 0; e < 4; ++e) {
;       float c0 = lo_bf(cu[e]), c1 = hi_bf(cu[e]), p0 = lo_bf(pu[e]), p1 = hi_bf(pu[e]);
;       float z0 = c0 + (p0 - c0) * mm[2 * e], z1 = c1 + (p1 - c1) * mm[2 * e + 1];
;       if constexpr (MODE == G_RWG) { z0 = sigmoidf_(z0); z1 = sigmoidf_(z1); }
;       if constexpr (MODE == G_RWW) { z0 = tanhf(z0); z1 = tanhf(z1); }
;       o[e] = pack2(z0, z1);
;     }
; template <int MODE, bool BIG = false> DI void gemm_tile(const Params& p, int tm, int tn, int kv, char* smem) {
;     ...
;     for (int kt = 0; kt < KT; ++kt) {
;       __syncthreads();
; #pragma unroll
;       for (int i = 0; i < 4; ++i) {
;         const int id = tid + 256 * i;
;         *(uint4*)(As + (id >> 3) * 144 + (id & 7) * 16) = ra[i];
;         *(uint4*)(Bs + (id >> 3) * 144 + (id & 7) * 16) = rb[i];
;       }
;       __syncthreads();
;       if (kt + 1 < KT) {
; #pragma unroll
;         for (int i = 0; i < 4; ++i) { const int id = tid + 256 * i; ra[i] = load_a<MODE>(p, tma, kv, id >> 3, kt + 1, id & 7); rb[i] = load_b<MODE>(p, tn, kv, id >> 3, kt + 1, id & 7); }
;       }
; #pragma unroll
;       for (int s = 0; s < 4; ++s) {
;         bf16x8 af[2], bfr[2];
; #pragma unroll
;         for (int i = 0; i < 2; ++i) af[i] = *(const bf16x8*)(As + (wm * 64 + i * 32 + r) * 144 + s * 32 + hf * 16);
; #pragma unroll
;         for (int j = 0; j < 2; ++j) bfr[j] = *(const bf16x8*)(Bs + (wn * 64 + j * 32 + r) * 144 + s * 32 + hf * 16);
; #pragma unroll
;         for (int i = 0; i < 2; ++i)
; #pragma unroll
;           for (int j = 0; j < 2; ++j) acc[i][j] = MFMA(af[i], bfr[j], acc[i][j]);
;       }
.LBB0_205:
	s_or_b64 exec, exec, s[0:1]
	v_add_u32_e32 v56, s7, v84
	v_ashrrev_i32_e32 v57, 31, v56
	v_lshlrev_b64 v[56:57], 7, v[56:57]
	v_lshl_add_u64 v[38:39], v[38:39], 0, v[56:57]
	global_load_dwordx4 v[88:91], v[38:39], off
	s_brev_b32 s0, -2
	v_bfi_b32 v29, s0, v86, v55
	v_bfi_b32 v39, s0, v79, v49
	v_bfi_b32 v49, s0, v81, v51
	v_bfi_b32 v51, s0, v83, v53
	v_bfi_b32 v52, s0, v82, v52
	v_bfi_b32 v53, s0, v28, v5
	v_bfi_b32 v27, s0, v27, v3
	v_bfi_b32 v28, s0, v24, v2
	v_bfi_b32 v26, s0, v26, v13
	v_bfi_b32 v55, s0, v23, v12
	v_bfi_b32 v56, s0, v22, v11
	v_bfi_b32 v0, s0, v0, v10
	v_lshlrev_b32_e32 v57, 4, v66
	v_ashrrev_i32_e32 v82, 1, v66
	v_bfi_b32 v38, s0, v85, v54
	v_bfi_b32 v48, s0, v78, v48
	v_bfi_b32 v37, s0, v68, v37
	v_bfi_b32 v36, s0, v67, v36
	v_bfi_b32 v31, s0, v60, v31
	v_bfi_b32 v30, s0, v59, v30
	v_bfi_b32 v33, s0, v62, v33
	v_bfi_b32 v32, s0, v61, v32
	v_bfi_b32 v35, s0, v64, v35
	v_bfi_b32 v34, s0, v63, v34
	v_bfe_u32 v67, v66, 5, 1
	v_and_b32_e32 v83, 31, v66
	v_cvt_pk_f16_f32 v28, v28, v27
	v_cvt_pk_f16_f32 v27, v55, v26
	v_cvt_pk_f16_f32 v26, v0, v56
	v_and_b32_e32 v0, 0x70, v57
	v_and_b32_e32 v85, 0xffffffc0, v82
	v_bfi_b32 v50, s0, v80, v50
	v_bfi_b32 v47, s0, v77, v47
	v_bfi_b32 v46, s0, v76, v46
	v_bfi_b32 v41, s0, v70, v41
	v_bfi_b32 v40, s0, v69, v40
	v_bfi_b32 v43, s0, v72, v43
	v_bfi_b32 v42, s0, v71, v42
	v_bfi_b32 v45, s0, v74, v45
	v_bfi_b32 v44, s0, v73, v44
	v_bfi_b32 v54, s0, v25, v4
	v_cvt_pk_f16_f32 v5, v38, v29
	v_cvt_pk_f16_f32 v2, v48, v39
	v_cvt_pk_f16_f32 v25, v36, v37
	v_cvt_pk_f16_f32 v22, v30, v31
	v_cvt_pk_f16_f32 v23, v32, v33
	v_cvt_pk_f16_f32 v24, v34, v35
	v_lshlrev_b32_e32 v30, 4, v67
	v_mad_u64_u32 v[32:33], s[0:1], v58, s33, v[0:1]
	v_mad_u64_u32 v[34:35], s[0:1], v65, s33, v[0:1]
	v_mad_u64_u32 v[36:37], s[0:1], v75, s33, v[0:1]
	v_mad_u64_u32 v[38:39], s[0:1], v84, s33, v[0:1]
	v_or_b32_e32 v0, v85, v83
	v_cvt_pk_f16_f32 v3, v50, v49
	v_cvt_pk_f16_f32 v4, v52, v51
	v_mad_u64_u32 v[80:81], s[0:1], v0, s33, v[30:31]
	v_cvt_pk_f16_f32 v13, v46, v47
	v_cvt_pk_f16_f32 v10, v40, v41
	v_cvt_pk_f16_f32 v11, v42, v43
	v_cvt_pk_f16_f32 v12, v44, v45
	v_cvt_pk_f16_f32 v29, v54, v53
	s_barrier
	v_bfe_u32 v0, v66, 6, 1
	v_lshlrev_b32_e32 v66, 6, v66
	ds_write_b128 v32, v[22:25]
	ds_write_b128 v32, v[6:9] offset:18432
	ds_write_b128 v34, v[10:13]
	ds_write_b128 v34, v[14:17] offset:18432
	ds_write_b128 v36, v[2:5]
	ds_write_b128 v36, v[18:21] offset:18432
	ds_write_b128 v38, v[26:29]
	s_waitcnt vmcnt(0)
	ds_write_b128 v38, v[88:91] offset:18432
	s_waitcnt lgkmcnt(0)
	s_barrier
	ds_read_b128 v[2:5], v80
	ds_read_b128 v[22:25], v80 offset:4608
	v_lshl_or_b32 v6, v0, 6, v83
	v_mad_u32_u24 v81, v6, s33, v30
	ds_read_b128 v[6:9], v81 offset:18432
	ds_read_b128 v[18:21], v81 offset:23040
	s_waitcnt lgkmcnt(1)
	v_mfma_f32_32x32x16_f16 v[34:49], v[2:5], v[6:9], 0
	ds_read_b128 v[68:71], v80 offset:32
	ds_read_b128 v[72:75], v81 offset:18464
	ds_read_b128 v[76:79], v81 offset:23072
	v_lshlrev_b32_e32 v0, 8, v0
	v_lshl_or_b32 v67, v67, 2, v85
	v_lshl_or_b32 v0, v83, 2, v0
	s_mov_b32 s8, 0x3f2aaaab
	s_mov_b32 s9, 0x3f317218
	s_waitcnt lgkmcnt(3)
	v_mfma_f32_32x32x16_f16 v[50:65], v[2:5], v[18:21], 0
	s_mov_b32 s10, 0x33800000
	s_add_i32 s5, s5, s77
	s_add_i32 s4, s4, s87
	s_add_i32 s3, s3, s89
	s_cmp_ge_i32 s5, s84
	s_waitcnt lgkmcnt(1)
	v_mfma_f32_32x32x16_f16 v[34:49], v[68:71], v[72:75], v[34:49]
	s_waitcnt lgkmcnt(0)
	v_mfma_f32_32x32x16_f16 v[50:65], v[68:71], v[76:79], v[50:65]
	ds_read_b128 v[68:71], v80 offset:4640
	v_mfma_f32_32x32x16_f16 v[2:17], v[22:25], v[6:9], 0
	v_mfma_f32_32x32x16_f16 v[18:33], v[22:25], v[18:21], 0
	s_waitcnt lgkmcnt(0)
	v_mfma_f32_32x32x16_f16 v[2:17], v[68:71], v[72:75], v[2:17]
	v_mfma_f32_32x32x16_f16 v[18:33], v[68:71], v[76:79], v[18:33]
	ds_read_b128 v[68:71], v80 offset:64
	ds_read_b128 v[72:75], v81 offset:18496
	ds_read_b128 v[76:79], v81 offset:23104
	s_waitcnt lgkmcnt(1)
	v_mfma_f32_32x32x16_f16 v[34:49], v[68:71], v[72:75], v[34:49]
	s_waitcnt lgkmcnt(0)
	v_mfma_f32_32x32x16_f16 v[50:65], v[68:71], v[76:79], v[50:65]
	ds_read_b128 v[68:71], v80 offset:4672
	s_waitcnt lgkmcnt(0)
	v_mfma_f32_32x32x16_f16 v[2:17], v[68:71], v[72:75], v[2:17]
	v_mfma_f32_32x32x16_f16 v[18:33], v[68:71], v[76:79], v[18:33]
	ds_read_b128 v[68:71], v80 offset:96
	ds_read_b128 v[72:75], v81 offset:18528
	ds_read_b128 v[76:79], v81 offset:23136
	s_waitcnt lgkmcnt(1)
	v_mfma_f32_32x32x16_f16 v[34:49], v[68:71], v[72:75], v[34:49]
	s_waitcnt lgkmcnt(0)
	v_mfma_f32_32x32x16_f16 v[50:65], v[68:71], v[76:79], v[50:65]
	ds_read_b128 v[68:71], v80 offset:4704
	s_waitcnt lgkmcnt(0)
	s_barrier
; template <int MODE, bool BIG = false> DI void gemm_tile(const Params& p, int tm, int tn, int kv, char* smem) {
;     ...
; #pragma unroll 1
;   for (int hh = 0; hh < (BIG ? 2 : 1); ++hh) {
;   __syncthreads();
;   if (!BIG || wm == hh) {
; #pragma unroll
;     for (int i = 0; i < MT; ++i)
; #pragma unroll
;       for (int j = 0; j < 2; ++j)
; #pragma unroll
;         for (int e = 0; e < 16; ++e) {
;           const int row = (BIG ? 0 : wm * 64) + i * 32 + 8 * (e >> 2) + 4 * hf + (e & 3);
;           const int col = wn * 64 + j * 32 + r;
;           Cs[row * 132 + col] = acc[i][j][e];
;         }
;   }
;   __syncthreads();
;     ...
;   } else if constexpr (MODE == G_RWW) {
;     float4* W4 = (float4*)((float*)(p.ws + OFF_BUFA) + (size_t)m * 512 + col0);
;     const float4* w04 = (const float4*)(p.w0 + col0);
; #pragma unroll
;     for (int c4 = 0; c4 < 16; ++c4) {
;       float4 v = crow4[c4], ww = w04[c4];
;       float u[4] = {v.x + ww.x, v.y + ww.y, v.z + ww.z, v.w + ww.w};
; #pragma unroll
;       for (int e = 0; e < 4; ++e) {
;         const float z = -u[e];
;         const float sp = fmaxf(z, 0.f) + log1pf(__expf(-fabsf(z)));
;         u[e] = __expf(-__expf(-sp - 0.5f));
;       }
	v_mfma_f32_32x32x16_f16 v[2:17], v[68:71], v[72:75], v[2:17]
	v_and_b32_e32 v72, 64, v66
	v_or_b32_e32 v73, s7, v72
	s_movk_i32 s7, 0x210
	v_mad_u64_u32 v[66:67], s[0:1], v67, s7, v[0:1]
	v_add_u32_e32 v0, 0x400, v66
	s_nop 2
	ds_write2_b32 v66, v34, v50 offset1:32
	ds_write2_b32 v66, v35, v51 offset0:132 offset1:164
	ds_write2_b32 v0, v36, v52 offset0:8 offset1:40
	ds_write2_b32 v0, v37, v53 offset0:140 offset1:172
	v_add_u32_e32 v0, 0x1000, v66
	v_mfma_f32_32x32x16_f16 v[18:33], v[68:71], v[76:79], v[18:33]
	ds_write2_b32 v0, v38, v54 offset0:32 offset1:64
	ds_write2_b32 v0, v39, v55 offset0:164 offset1:196
	v_add_u32_e32 v0, 0x1400, v66
	ds_write2_b32 v0, v40, v56 offset0:40 offset1:72
	ds_write2_b32 v0, v41, v57 offset0:172 offset1:204
	v_add_u32_e32 v0, 0x2000, v66
	ds_write2_b32 v0, v42, v58 offset0:64 offset1:96
	ds_write2_b32 v0, v43, v59 offset0:196 offset1:228
	v_add_u32_e32 v0, 0x2400, v66
	ds_write2_b32 v0, v44, v60 offset0:72 offset1:104
	ds_write2_b32 v0, v45, v61 offset0:204 offset1:236
	v_add_u32_e32 v0, 0x3000, v66
	ds_write2_b32 v0, v46, v62 offset0:96 offset1:128
	v_add_u32_e32 v0, 0x3200, v66
	ds_write2_b32 v0, v47, v63 offset0:100 offset1:132
	v_add_u32_e32 v0, 0x3400, v66
	ds_write2_b32 v0, v48, v64 offset0:104 offset1:136
	v_add_u32_e32 v0, 0x3600, v66
	ds_write2_b32 v0, v49, v65 offset0:108 offset1:140
	v_add_u32_e32 v0, 0x4000, v66
	ds_write2_b32 v0, v2, v18 offset0:128 offset1:160
	v_add_u32_e32 v0, 0x4400, v66
	ds_write2_b32 v0, v3, v19 offset0:4 offset1:36
	ds_write2_b32 v0, v4, v20 offset0:136 offset1:168
	v_add_u32_e32 v0, 0x4800, v66
	ds_write2_b32 v0, v5, v21 offset0:12 offset1:44
	v_add_u32_e32 v0, 0x5000, v66
	ds_write2_b32 v0, v6, v22 offset0:160 offset1:192
	v_add_u32_e32 v0, 0x5400, v66
	ds_write2_b32 v0, v7, v23 offset0:36 offset1:68
	ds_write2_b32 v0, v8, v24 offset0:168 offset1:200
	v_add_u32_e32 v0, 0x5800, v66
	ds_write2_b32 v0, v9, v25 offset0:44 offset1:76
	v_add_u32_e32 v0, 0x6000, v66
	ds_write2_b32 v0, v10, v26 offset0:192 offset1:224
	v_add_u32_e32 v0, 0x6400, v66
	ds_write2_b32 v0, v11, v27 offset0:68 offset1:100
	ds_write2_b32 v0, v12, v28 offset0:200 offset1:232
	v_add_u32_e32 v0, 0x6800, v66
	ds_write2_b32 v0, v13, v29 offset0:76 offset1:108
	v_add_u32_e32 v0, 0x7200, v66
	ds_write2_b32 v0, v14, v30 offset0:96 offset1:128
	v_add_u32_e32 v0, 0x7400, v66
	ds_write2_b32 v0, v15, v31 offset0:100 offset1:132
	v_add_u32_e32 v0, 0x7600, v66
	ds_write2_b32 v0, v16, v32 offset0:104 offset1:136
	v_add_u32_e32 v0, 0x7800, v66
	ds_write2_b32 v0, v17, v33 offset0:108 offset1:140
	s_waitcnt lgkmcnt(0)
	v_and_b32_e32 v74, 0xffffffbf, v73
	v_and_b32_e32 v75, 31, v173
	v_lshlrev_b32_e32 v74, 2, v74
	v_lshl_add_u32 v74, v75, 4, v74
	global_load_dwordx4 v[76:79], v74, s[74:75]
	v_lshlrev_b32_e32 v0, 4, v75
	v_add_u32_e32 v0, 0x10800, v0
	s_waitcnt vmcnt(0)
	ds_write_b128 v0, v[76:79]
	s_waitcnt lgkmcnt(0)
	v_lshlrev_b32_e32 v74, 2, v72
	v_add_u32_e32 v74, 0x10800, v74
	v_lshlrev_b32_e32 v0, 2, v73
	v_mul_u32_u24_e32 v75, 0x210, v82
	v_lshl_add_u32 v75, v72, 2, v75
	s_waitcnt lgkmcnt(0)
	s_barrier
	ds_read_b128 v[4:7], v74
	v_mul_lo_u32 v2, v82, s7
	v_lshl_add_u32 v12, v72, 2, v2
	ds_read_b128 v[8:11], v12
	s_mov_b32 s7, 0xbfb8aa3b
	v_add_u32_e32 v2, s6, v82
	s_mov_b32 s6, 0x7f800000
	v_ashrrev_i32_e32 v3, 31, v2
	v_readlane_b32 s0, v253, 4
	v_lshlrev_b64 v[2:3], 11, v[2:3]
	v_readlane_b32 s1, v253, 5
	s_waitcnt lgkmcnt(0)
	v_add_f32_e32 v4, v8, v4
	v_mul_f32_e64 v8, |v4|, s7
	v_exp_f32_e32 v8, v8
	v_add_f32_e32 v9, v9, v5
	v_add_f32_e32 v6, v10, v6
	v_max_f32_e64 v10, -v4, 0
	v_add_f32_e32 v13, 1.0, v8
	v_add_f32_e32 v14, -1.0, v13
	v_frexp_mant_f32_e32 v15, v13
	v_cvt_f64_f32_e32 v[4:5], v13
	v_sub_f32_e32 v16, v14, v13
	v_cmp_gt_f32_e32 vcc, s8, v15
	v_frexp_exp_i32_f64_e32 v4, v[4:5]
	v_sub_f32_e32 v14, v8, v14
	v_add_f32_e32 v5, 1.0, v16
	v_subbrev_co_u32_e32 v4, vcc, 0, v4, vcc
	v_add_f32_e32 v5, v14, v5
	v_sub_u32_e32 v14, 0, v4
	v_ldexp_f32 v13, v13, v14
	v_ldexp_f32 v5, v5, v14
	v_add_f32_e32 v14, -1.0, v13
	v_add_f32_e32 v15, 1.0, v13
	v_add_f32_e32 v16, 1.0, v14
	v_add_f32_e32 v18, -1.0, v15
	v_sub_f32_e32 v16, v13, v16
	v_sub_f32_e32 v13, v13, v18
	v_add_f32_e32 v16, v5, v16
	v_add_f32_e32 v5, v5, v13
	v_add_f32_e32 v13, v15, v5
	v_rcp_f32_e32 v18, v13
	v_add_f32_e32 v17, v14, v16
	v_sub_f32_e32 v15, v13, v15
	v_sub_f32_e32 v14, v17, v14
	v_sub_f32_e32 v5, v5, v15
	v_mul_f32_e32 v15, v17, v18
	v_sub_f32_e32 v14, v16, v14
	v_mul_f32_e32 v16, v13, v15
	v_fma_f32 v19, v15, v13, -v16
	v_fmac_f32_e32 v19, v15, v5
	v_add_f32_e32 v20, v16, v19
	v_sub_f32_e32 v21, v17, v20
	v_sub_f32_e32 v17, v17, v21
	v_sub_f32_e32 v16, v20, v16
	v_sub_f32_e32 v17, v17, v20
	v_add_f32_e32 v14, v14, v17
	v_sub_f32_e32 v16, v16, v19
	v_add_f32_e32 v14, v16, v14
	v_add_f32_e32 v16, v21, v14
	v_mul_f32_e32 v17, v18, v16
	v_mul_f32_e32 v19, v13, v17
	v_fma_f32 v13, v17, v13, -v19
	v_fmac_f32_e32 v13, v17, v5
	v_sub_f32_e32 v5, v21, v16
	v_add_f32_e32 v5, v14, v5
	v_add_f32_e32 v14, v19, v13
	v_sub_f32_e32 v20, v16, v14
	v_sub_f32_e32 v16, v16, v20
	v_sub_f32_e32 v19, v14, v19
	v_sub_f32_e32 v14, v16, v14
	v_add_f32_e32 v5, v5, v14
	v_sub_f32_e32 v13, v19, v13
	v_cvt_f32_i32_e32 v4, v4
	v_add_f32_e32 v5, v13, v5
	v_add_f32_e32 v13, v15, v17
	v_add_f32_e32 v5, v20, v5
	v_sub_f32_e32 v14, v13, v15
	v_mul_f32_e32 v5, v18, v5
	v_sub_f32_e32 v14, v17, v14
	v_add_f32_e32 v5, v14, v5
	v_mul_f32_e32 v17, 0x3f317218, v4
	v_add_f32_e32 v14, v13, v5
	v_fma_f32 v18, v4, s9, -v17
	v_mul_f32_e32 v15, v14, v14
	v_fmac_f32_e32 v18, 0xb102e308, v4
	v_sub_f32_e32 v4, v14, v13
	v_fmamk_f32 v16, v15, 0x3e9b6dac, v231
	v_sub_f32_e32 v4, v5, v4
; template <int MODE, bool BIG = false> DI void gemm_tile(const Params& p, int tm, int tn, int kv, char* smem) {
;     ...
;   } else if constexpr (MODE == G_RWW) {
;     float4* W4 = (float4*)((float*)(p.ws + OFF_BUFA) + (size_t)m * 512 + col0);
;     const float4* w04 = (const float4*)(p.w0 + col0);
; #pragma unroll
;     for (int c4 = 0; c4 < 16; ++c4) {
;       float4 v = crow4[c4], ww = w04[c4];
;       float u[4] = {v.x + ww.x, v.y + ww.y, v.z + ww.z, v.w + ww.w};
; #pragma unroll
;       for (int e = 0; e < 4; ++e) {
;         const float z = -u[e];
;         const float sp = fmaxf(z, 0.f) + log1pf(__expf(-fabsf(z)));
;         u[e] = __expf(-__expf(-sp - 0.5f));
;       }
;       W4[c4] = make_float4(u[0], u[1], u[2], u[3]);
;     }
	v_add_f32_e32 v5, v17, v18
	v_fmaak_f32 v16, v15, v16, 0x3f2aaada
	v_sub_f32_e32 v13, v5, v17
	v_ldexp_f32 v17, v14, 1
	v_mul_f32_e32 v14, v14, v15
	v_mul_f32_e32 v14, v14, v16
	v_add_f32_e32 v15, v17, v14
	v_sub_f32_e32 v16, v15, v17
	v_ldexp_f32 v4, v4, 1
	v_sub_f32_e32 v14, v14, v16
	v_add_f32_e32 v4, v4, v14
	v_add_f32_e32 v14, v15, v4
	v_sub_f32_e32 v15, v14, v15
	v_sub_f32_e32 v4, v4, v15
	v_add_f32_e32 v15, v5, v14
	v_sub_f32_e32 v16, v15, v5
	v_sub_f32_e32 v17, v15, v16
	v_sub_f32_e32 v13, v18, v13
	v_sub_f32_e32 v5, v5, v17
	v_sub_f32_e32 v14, v14, v16
	v_add_f32_e32 v5, v14, v5
	v_add_f32_e32 v14, v13, v4
	v_sub_f32_e32 v16, v14, v13
	v_sub_f32_e32 v17, v14, v16
	v_sub_f32_e32 v13, v13, v17
	v_sub_f32_e32 v4, v4, v16
	v_add_f32_e32 v5, v14, v5
	v_add_f32_e32 v4, v4, v13
	v_add_f32_e32 v13, v15, v5
	v_sub_f32_e32 v14, v13, v15
	v_sub_f32_e32 v5, v5, v14
	v_add_f32_e32 v4, v4, v5
	v_add_f32_e32 v4, v13, v4
	v_cmp_neq_f32_e32 vcc, s6, v8
	v_mul_f32_e64 v5, |v9|, s7
	v_max_f32_e64 v9, -v9, 0
	v_cndmask_b32_e32 v4, v238, v4, vcc
	v_cmp_ngt_f32_e32 vcc, -1.0, v8
	v_lshl_add_u64 v[2:3], s[0:1], 0, v[2:3]
	s_nop 0
	v_cndmask_b32_e32 v4, v239, v4, vcc
	v_cmp_neq_f32_e32 vcc, -1.0, v8
	s_nop 1
	v_cndmask_b32_e32 v4, v240, v4, vcc
	v_cmp_lt_f32_e64 vcc, |v8|, s10
	s_nop 1
	v_cndmask_b32_e32 v4, v4, v8, vcc
	v_add_f32_e32 v4, v10, v4
	v_sub_f32_e32 v4, -0.5, v4
	v_mul_f32_e32 v4, 0x3fb8aa3b, v4
	v_exp_f32_e32 v8, v5
	v_exp_f32_e32 v4, v4
	v_add_f32_e32 v10, v11, v7
	v_add_f32_e32 v11, 1.0, v8
	v_mul_f32_e32 v7, 0xbfb8aa3b, v4
	v_add_f32_e32 v4, -1.0, v11
	v_sub_f32_e32 v5, v4, v11
	v_add_f32_e32 v5, 1.0, v5
	v_sub_f32_e32 v4, v8, v4
	v_add_f32_e32 v13, v4, v5
	v_frexp_mant_f32_e32 v4, v11
	v_cmp_gt_f32_e32 vcc, s8, v4
	v_cvt_f64_f32_e32 v[4:5], v11
	v_frexp_exp_i32_f64_e32 v4, v[4:5]
	v_subbrev_co_u32_e32 v4, vcc, 0, v4, vcc
	v_sub_u32_e32 v5, 0, v4
	v_ldexp_f32 v11, v11, v5
	v_ldexp_f32 v5, v13, v5
	v_add_f32_e32 v13, -1.0, v11
	v_add_f32_e32 v16, 1.0, v11
	v_add_f32_e32 v14, 1.0, v13
	v_add_f32_e32 v17, -1.0, v16
	v_sub_f32_e32 v14, v11, v14
	v_sub_f32_e32 v11, v11, v17
	v_add_f32_e32 v14, v5, v14
	v_add_f32_e32 v5, v5, v11
	v_add_f32_e32 v11, v16, v5
	v_rcp_f32_e32 v17, v11
	v_add_f32_e32 v15, v13, v14
	v_sub_f32_e32 v13, v15, v13
	v_sub_f32_e32 v13, v14, v13
	v_sub_f32_e32 v14, v11, v16
	v_sub_f32_e32 v5, v5, v14
	v_mul_f32_e32 v14, v15, v17
	v_mul_f32_e32 v16, v11, v14
	v_fma_f32 v18, v14, v11, -v16
	v_fmac_f32_e32 v18, v14, v5
	v_add_f32_e32 v19, v16, v18
	v_sub_f32_e32 v20, v15, v19
	v_sub_f32_e32 v15, v15, v20
	v_sub_f32_e32 v16, v19, v16
	v_sub_f32_e32 v15, v15, v19
	v_add_f32_e32 v13, v13, v15
	v_sub_f32_e32 v15, v16, v18
	v_add_f32_e32 v13, v15, v13
	v_add_f32_e32 v15, v20, v13
	v_mul_f32_e32 v16, v17, v15
	v_mul_f32_e32 v18, v11, v16
	v_fma_f32 v11, v16, v11, -v18
	v_fmac_f32_e32 v11, v16, v5
	v_sub_f32_e32 v5, v20, v15
	v_add_f32_e32 v5, v13, v5
	v_add_f32_e32 v13, v18, v11
	v_sub_f32_e32 v19, v15, v13
	v_sub_f32_e32 v15, v15, v19
	v_sub_f32_e32 v18, v13, v18
	v_sub_f32_e32 v13, v15, v13
	v_add_f32_e32 v5, v5, v13
	v_sub_f32_e32 v11, v18, v11
	v_cvt_f32_i32_e32 v4, v4
	v_add_f32_e32 v5, v11, v5
	v_add_f32_e32 v11, v14, v16
	v_add_f32_e32 v5, v19, v5
	v_sub_f32_e32 v13, v11, v14
	v_mul_f32_e32 v5, v17, v5
	v_sub_f32_e32 v13, v16, v13
	v_add_f32_e32 v5, v13, v5
	v_mul_f32_e32 v16, 0x3f317218, v4
	v_add_f32_e32 v13, v11, v5
	v_fma_f32 v17, v4, s9, -v16
	v_mul_f32_e32 v14, v13, v13
	v_fmac_f32_e32 v17, 0xb102e308, v4
	v_sub_f32_e32 v4, v13, v11
	v_fmamk_f32 v15, v14, 0x3e9b6dac, v231
	v_sub_f32_e32 v4, v5, v4
	v_add_f32_e32 v5, v16, v17
	v_fmaak_f32 v15, v14, v15, 0x3f2aaada
	v_sub_f32_e32 v11, v5, v16
	v_ldexp_f32 v16, v13, 1
	v_mul_f32_e32 v13, v13, v14
	v_mul_f32_e32 v13, v13, v15
	v_add_f32_e32 v14, v16, v13
	v_sub_f32_e32 v15, v14, v16
	v_ldexp_f32 v4, v4, 1
	v_sub_f32_e32 v13, v13, v15
	v_add_f32_e32 v4, v4, v13
	v_add_f32_e32 v13, v14, v4
	v_sub_f32_e32 v14, v13, v14
	v_sub_f32_e32 v4, v4, v14
	v_add_f32_e32 v14, v5, v13
	v_sub_f32_e32 v15, v14, v5
	v_sub_f32_e32 v16, v14, v15
	v_sub_f32_e32 v11, v17, v11
	v_sub_f32_e32 v5, v5, v16
	v_sub_f32_e32 v13, v13, v15
	v_add_f32_e32 v5, v13, v5
	v_add_f32_e32 v13, v11, v4
	v_sub_f32_e32 v15, v13, v11
	v_sub_f32_e32 v16, v13, v15
	v_sub_f32_e32 v11, v11, v16
	v_sub_f32_e32 v4, v4, v15
	v_add_f32_e32 v5, v13, v5
	v_add_f32_e32 v4, v4, v11
	v_add_f32_e32 v11, v14, v5
	v_sub_f32_e32 v13, v11, v14
	v_sub_f32_e32 v5, v5, v13
	v_add_f32_e32 v4, v4, v5
	v_add_f32_e32 v4, v11, v4
	v_cmp_neq_f32_e32 vcc, s6, v8
	s_nop 1
	v_cndmask_b32_e32 v4, v238, v4, vcc
	v_cmp_ngt_f32_e32 vcc, -1.0, v8
	s_nop 1
	v_cndmask_b32_e32 v4, v239, v4, vcc
	v_cmp_neq_f32_e32 vcc, -1.0, v8
	s_nop 1
	v_cndmask_b32_e32 v4, v240, v4, vcc
	v_cmp_lt_f32_e64 vcc, |v8|, s10
	s_nop 1
	v_cndmask_b32_e32 v4, v4, v8, vcc
	v_add_f32_e32 v4, v9, v4
	v_sub_f32_e32 v4, -0.5, v4
	v_mul_f32_e32 v4, 0x3fb8aa3b, v4
	v_exp_f32_e32 v5, v4
	v_mul_f32_e64 v4, |v6|, s7
	v_exp_f32_e32 v8, v4
	v_max_f32_e64 v9, -v6, 0
	v_exp_f32_e32 v4, v7
	v_mul_f32_e32 v5, 0xbfb8aa3b, v5
	v_add_f32_e32 v11, 1.0, v8
	v_add_f32_e32 v6, -1.0, v11
	v_sub_f32_e32 v7, v6, v11
	v_add_f32_e32 v7, 1.0, v7
	v_sub_f32_e32 v6, v8, v6
	v_add_f32_e32 v13, v6, v7
	v_frexp_mant_f32_e32 v6, v11
	v_cmp_gt_f32_e32 vcc, s8, v6
	v_cvt_f64_f32_e32 v[6:7], v11
	v_frexp_exp_i32_f64_e32 v6, v[6:7]
	v_subbrev_co_u32_e32 v6, vcc, 0, v6, vcc
	v_sub_u32_e32 v7, 0, v6
	v_ldexp_f32 v11, v11, v7
	v_ldexp_f32 v7, v13, v7
	v_add_f32_e32 v13, -1.0, v11
	v_add_f32_e32 v16, 1.0, v11
	v_add_f32_e32 v14, 1.0, v13
	v_add_f32_e32 v17, -1.0, v16
	v_sub_f32_e32 v14, v11, v14
	v_sub_f32_e32 v11, v11, v17
; template <int MODE, bool BIG = false> DI void gemm_tile(const Params& p, int tm, int tn, int kv, char* smem) {
;     ...
;   } else if constexpr (MODE == G_RWW) {
;     float4* W4 = (float4*)((float*)(p.ws + OFF_BUFA) + (size_t)m * 512 + col0);
;     const float4* w04 = (const float4*)(p.w0 + col0);
; #pragma unroll
;     for (int c4 = 0; c4 < 16; ++c4) {
;       float4 v = crow4[c4], ww = w04[c4];
;       float u[4] = {v.x + ww.x, v.y + ww.y, v.z + ww.z, v.w + ww.w};
; #pragma unroll
;       for (int e = 0; e < 4; ++e) {
;         const float z = -u[e];
;         const float sp = fmaxf(z, 0.f) + log1pf(__expf(-fabsf(z)));
;         u[e] = __expf(-__expf(-sp - 0.5f));
;       }
;       W4[c4] = make_float4(u[0], u[1], u[2], u[3]);
;     }
	v_add_f32_e32 v14, v7, v14
	v_add_f32_e32 v7, v7, v11
	v_add_f32_e32 v11, v16, v7
	v_rcp_f32_e32 v17, v11
	v_add_f32_e32 v15, v13, v14
	v_sub_f32_e32 v13, v15, v13
	v_sub_f32_e32 v13, v14, v13
	v_sub_f32_e32 v14, v11, v16
	v_sub_f32_e32 v7, v7, v14
	v_mul_f32_e32 v14, v15, v17
	v_mul_f32_e32 v16, v11, v14
	v_fma_f32 v18, v14, v11, -v16
	v_fmac_f32_e32 v18, v14, v7
	v_add_f32_e32 v19, v16, v18
	v_sub_f32_e32 v20, v15, v19
	v_sub_f32_e32 v15, v15, v20
	v_sub_f32_e32 v16, v19, v16
	v_sub_f32_e32 v15, v15, v19
	v_add_f32_e32 v13, v13, v15
	v_sub_f32_e32 v15, v16, v18
	v_add_f32_e32 v13, v15, v13
	v_add_f32_e32 v15, v20, v13
	v_mul_f32_e32 v16, v17, v15
	v_mul_f32_e32 v18, v11, v16
	v_fma_f32 v11, v16, v11, -v18
	v_fmac_f32_e32 v11, v16, v7
	v_sub_f32_e32 v7, v20, v15
	v_add_f32_e32 v7, v13, v7
	v_add_f32_e32 v13, v18, v11
	v_sub_f32_e32 v19, v15, v13
	v_sub_f32_e32 v15, v15, v19
	v_sub_f32_e32 v18, v13, v18
	v_sub_f32_e32 v13, v15, v13
	v_add_f32_e32 v7, v7, v13
	v_sub_f32_e32 v11, v18, v11
	v_cvt_f32_i32_e32 v6, v6
	v_add_f32_e32 v7, v11, v7
	v_add_f32_e32 v11, v14, v16
	v_add_f32_e32 v7, v19, v7
	v_sub_f32_e32 v13, v11, v14
	v_mul_f32_e32 v7, v17, v7
	v_sub_f32_e32 v13, v16, v13
	v_add_f32_e32 v7, v13, v7
	v_mul_f32_e32 v16, 0x3f317218, v6
	v_add_f32_e32 v13, v11, v7
	v_fma_f32 v17, v6, s9, -v16
	v_mul_f32_e32 v14, v13, v13
	v_fmac_f32_e32 v17, 0xb102e308, v6
	v_sub_f32_e32 v6, v13, v11
	v_fmamk_f32 v15, v14, 0x3e9b6dac, v231
	v_sub_f32_e32 v6, v7, v6
	v_add_f32_e32 v7, v16, v17
	v_fmaak_f32 v15, v14, v15, 0x3f2aaada
	v_sub_f32_e32 v11, v7, v16
	v_ldexp_f32 v16, v13, 1
	v_mul_f32_e32 v13, v13, v14
	v_mul_f32_e32 v13, v13, v15
	v_add_f32_e32 v14, v16, v13
	v_sub_f32_e32 v15, v14, v16
	v_ldexp_f32 v6, v6, 1
	v_sub_f32_e32 v13, v13, v15
	v_add_f32_e32 v6, v6, v13
	v_add_f32_e32 v13, v14, v6
	v_sub_f32_e32 v14, v13, v14
	v_sub_f32_e32 v6, v6, v14
	v_add_f32_e32 v14, v7, v13
	v_sub_f32_e32 v15, v14, v7
	v_sub_f32_e32 v16, v14, v15
	v_sub_f32_e32 v11, v17, v11
	v_sub_f32_e32 v7, v7, v16
	v_sub_f32_e32 v13, v13, v15
	v_add_f32_e32 v7, v13, v7
	v_add_f32_e32 v13, v11, v6
	v_sub_f32_e32 v15, v13, v11
	v_sub_f32_e32 v16, v13, v15
	v_sub_f32_e32 v11, v11, v16
	v_sub_f32_e32 v6, v6, v15
	v_add_f32_e32 v7, v13, v7
	v_add_f32_e32 v6, v6, v11
	v_add_f32_e32 v11, v14, v7
	v_sub_f32_e32 v13, v11, v14
	v_sub_f32_e32 v7, v7, v13
	v_add_f32_e32 v6, v6, v7
	v_add_f32_e32 v6, v11, v6
	v_cmp_neq_f32_e32 vcc, s6, v8
	v_mul_f32_e64 v7, |v10|, s7
	v_max_f32_e64 v10, -v10, 0
	v_cndmask_b32_e32 v6, v238, v6, vcc
	v_cmp_ngt_f32_e32 vcc, -1.0, v8
	v_exp_f32_e32 v5, v5
	s_nop 0
	v_cndmask_b32_e32 v6, v239, v6, vcc
	v_cmp_neq_f32_e32 vcc, -1.0, v8
	s_nop 1
	v_cndmask_b32_e32 v6, v240, v6, vcc
	v_cmp_lt_f32_e64 vcc, |v8|, s10
	s_nop 1
	v_cndmask_b32_e32 v6, v6, v8, vcc
	v_exp_f32_e32 v8, v7
	v_add_f32_e32 v6, v9, v6
	v_sub_f32_e32 v6, -0.5, v6
	v_mul_f32_e32 v6, 0x3fb8aa3b, v6
	v_add_f32_e32 v11, 1.0, v8
	v_exp_f32_e32 v9, v6
	v_add_f32_e32 v6, -1.0, v11
	v_sub_f32_e32 v7, v6, v11
	v_add_f32_e32 v7, 1.0, v7
	v_sub_f32_e32 v6, v8, v6
	v_add_f32_e32 v13, v6, v7
	v_frexp_mant_f32_e32 v6, v11
	v_cmp_gt_f32_e32 vcc, s8, v6
	v_cvt_f64_f32_e32 v[6:7], v11
	v_frexp_exp_i32_f64_e32 v6, v[6:7]
	v_subbrev_co_u32_e32 v6, vcc, 0, v6, vcc
	v_sub_u32_e32 v7, 0, v6
	v_ldexp_f32 v11, v11, v7
	v_ldexp_f32 v7, v13, v7
	v_add_f32_e32 v13, -1.0, v11
	v_add_f32_e32 v16, 1.0, v11
	v_add_f32_e32 v14, 1.0, v13
	v_add_f32_e32 v17, -1.0, v16
	v_sub_f32_e32 v14, v11, v14
	v_sub_f32_e32 v11, v11, v17
	v_add_f32_e32 v14, v7, v14
	v_add_f32_e32 v7, v7, v11
	v_add_f32_e32 v11, v16, v7
	v_rcp_f32_e32 v17, v11
	v_add_f32_e32 v15, v13, v14
	v_sub_f32_e32 v13, v15, v13
	v_sub_f32_e32 v13, v14, v13
	v_sub_f32_e32 v14, v11, v16
	v_sub_f32_e32 v7, v7, v14
	v_mul_f32_e32 v14, v15, v17
	v_mul_f32_e32 v16, v11, v14
	v_fma_f32 v18, v14, v11, -v16
	v_fmac_f32_e32 v18, v14, v7
	v_add_f32_e32 v19, v16, v18
	v_sub_f32_e32 v20, v15, v19
	v_sub_f32_e32 v15, v15, v20
	v_sub_f32_e32 v16, v19, v16
	v_sub_f32_e32 v15, v15, v19
	v_add_f32_e32 v13, v13, v15
	v_sub_f32_e32 v15, v16, v18
	v_add_f32_e32 v13, v15, v13
	v_add_f32_e32 v15, v20, v13
	v_mul_f32_e32 v16, v17, v15
	v_mul_f32_e32 v18, v11, v16
	v_fma_f32 v11, v16, v11, -v18
	v_fmac_f32_e32 v11, v16, v7
	v_sub_f32_e32 v7, v20, v15
	v_add_f32_e32 v7, v13, v7
	v_add_f32_e32 v13, v18, v11
	v_sub_f32_e32 v19, v15, v13
	v_sub_f32_e32 v15, v15, v19
	v_sub_f32_e32 v18, v13, v18
	v_sub_f32_e32 v13, v15, v13
	v_add_f32_e32 v7, v7, v13
	v_sub_f32_e32 v11, v18, v11
	v_cvt_f32_i32_e32 v6, v6
	v_add_f32_e32 v7, v11, v7
	v_add_f32_e32 v11, v14, v16
	v_add_f32_e32 v7, v19, v7
	v_sub_f32_e32 v13, v11, v14
	v_mul_f32_e32 v7, v17, v7
	v_sub_f32_e32 v13, v16, v13
	v_add_f32_e32 v7, v13, v7
	v_mul_f32_e32 v16, 0x3f317218, v6
	v_add_f32_e32 v13, v11, v7
	v_fma_f32 v17, v6, s9, -v16
	v_mul_f32_e32 v14, v13, v13
	v_fmac_f32_e32 v17, 0xb102e308, v6
	v_sub_f32_e32 v6, v13, v11
	v_fmamk_f32 v15, v14, 0x3e9b6dac, v231
	v_sub_f32_e32 v6, v7, v6
	v_add_f32_e32 v7, v16, v17
	v_fmaak_f32 v15, v14, v15, 0x3f2aaada
	v_sub_f32_e32 v11, v7, v16
	v_ldexp_f32 v16, v13, 1
	v_mul_f32_e32 v13, v13, v14
	v_mul_f32_e32 v13, v13, v15
	v_add_f32_e32 v14, v16, v13
	v_sub_f32_e32 v15, v14, v16
	v_ldexp_f32 v6, v6, 1
	v_sub_f32_e32 v13, v13, v15
	v_add_f32_e32 v6, v6, v13
	v_add_f32_e32 v13, v14, v6
	v_sub_f32_e32 v14, v13, v14
	v_sub_f32_e32 v6, v6, v14
	v_add_f32_e32 v14, v7, v13
	v_sub_f32_e32 v15, v14, v7
	v_sub_f32_e32 v16, v14, v15
	v_sub_f32_e32 v11, v17, v11
	v_sub_f32_e32 v7, v7, v16
	v_sub_f32_e32 v13, v13, v15
	v_add_f32_e32 v7, v13, v7
	v_add_f32_e32 v13, v11, v6
	v_sub_f32_e32 v15, v13, v11
	v_sub_f32_e32 v16, v13, v15
	v_sub_f32_e32 v11, v11, v16
	v_sub_f32_e32 v6, v6, v15
	v_add_f32_e32 v7, v13, v7
	v_add_f32_e32 v6, v6, v11
	v_add_f32_e32 v11, v14, v7
	v_sub_f32_e32 v13, v11, v14
	v_sub_f32_e32 v7, v7, v13
	v_add_f32_e32 v6, v6, v7
	v_add_f32_e32 v6, v11, v6
	v_cmp_neq_f32_e32 vcc, s6, v8
	s_nop 1
	v_cndmask_b32_e32 v6, v238, v6, vcc
	v_cmp_ngt_f32_e32 vcc, -1.0, v8
	s_nop 1
	v_cndmask_b32_e32 v6, v239, v6, vcc
	v_cmp_neq_f32_e32 vcc, -1.0, v8
	s_nop 1
	v_cndmask_b32_e32 v6, v240, v6, vcc
	v_cmp_lt_f32_e64 vcc, |v8|, s10
	s_nop 1
	v_cndmask_b32_e32 v6, v6, v8, vcc
	v_add_f32_e32 v6, v10, v6
	v_sub_f32_e32 v6, -0.5, v6
	v_mul_f32_e32 v6, 0x3fb8aa3b, v6
	v_exp_f32_e32 v7, v6
	v_mul_f32_e32 v6, 0xbfb8aa3b, v9
	v_exp_f32_e32 v6, v6
	v_lshl_add_u64 v[10:11], v[2:3], 0, v[0:1]
	v_mul_f32_e32 v7, 0xbfb8aa3b, v7
	v_exp_f32_e32 v7, v7
	ds_write_b128 v75, v[4:7]
	ds_read_b128 v[2:5], v74 offset:16
	ds_read_b128 v[6:9], v12 offset:16
	s_waitcnt lgkmcnt(0)
; template <int MODE, bool BIG = false> DI void gemm_tile(const Params& p, int tm, int tn, int kv, char* smem) {
;     ...
;   } else if constexpr (MODE == G_RWW) {
;     float4* W4 = (float4*)((float*)(p.ws + OFF_BUFA) + (size_t)m * 512 + col0);
;     const float4* w04 = (const float4*)(p.w0 + col0);
; #pragma unroll
;     for (int c4 = 0; c4 < 16; ++c4) {
;       float4 v = crow4[c4], ww = w04[c4];
;       float u[4] = {v.x + ww.x, v.y + ww.y, v.z + ww.z, v.w + ww.w};
; #pragma unroll
;       for (int e = 0; e < 4; ++e) {
;         const float z = -u[e];
;         const float sp = fmaxf(z, 0.f) + log1pf(__expf(-fabsf(z)));
;         u[e] = __expf(-__expf(-sp - 0.5f));
;       }
;       W4[c4] = make_float4(u[0], u[1], u[2], u[3]);
;     }
	v_add_f32_e32 v2, v6, v2
	v_mul_f32_e64 v6, |v2|, s7
	v_exp_f32_e32 v6, v6
	v_add_f32_e32 v4, v8, v4
	v_max_f32_e64 v8, -v2, 0
	v_add_f32_e32 v7, v7, v3
	v_add_f32_e32 v13, 1.0, v6
	v_add_f32_e32 v2, -1.0, v13
	v_sub_f32_e32 v3, v2, v13
	v_add_f32_e32 v3, 1.0, v3
	v_sub_f32_e32 v2, v6, v2
	v_add_f32_e32 v14, v2, v3
	v_frexp_mant_f32_e32 v2, v13
	v_cmp_gt_f32_e32 vcc, s8, v2
	v_cvt_f64_f32_e32 v[2:3], v13
	v_frexp_exp_i32_f64_e32 v2, v[2:3]
	v_subbrev_co_u32_e32 v2, vcc, 0, v2, vcc
	v_sub_u32_e32 v3, 0, v2
	v_ldexp_f32 v13, v13, v3
	v_ldexp_f32 v3, v14, v3
	v_add_f32_e32 v14, -1.0, v13
	v_add_f32_e32 v17, 1.0, v13
	v_add_f32_e32 v15, 1.0, v14
	v_add_f32_e32 v18, -1.0, v17
	v_sub_f32_e32 v15, v13, v15
	v_sub_f32_e32 v13, v13, v18
	v_add_f32_e32 v15, v3, v15
	v_add_f32_e32 v3, v3, v13
	v_add_f32_e32 v13, v17, v3
	v_rcp_f32_e32 v18, v13
	v_add_f32_e32 v16, v14, v15
	v_sub_f32_e32 v14, v16, v14
	v_sub_f32_e32 v14, v15, v14
	v_sub_f32_e32 v15, v13, v17
	v_sub_f32_e32 v3, v3, v15
	v_mul_f32_e32 v15, v16, v18
	v_mul_f32_e32 v17, v13, v15
	v_fma_f32 v19, v15, v13, -v17
	v_fmac_f32_e32 v19, v15, v3
	v_add_f32_e32 v20, v17, v19
	v_sub_f32_e32 v21, v16, v20
	v_sub_f32_e32 v16, v16, v21
	v_sub_f32_e32 v17, v20, v17
	v_sub_f32_e32 v16, v16, v20
	v_add_f32_e32 v14, v14, v16
	v_sub_f32_e32 v16, v17, v19
	v_add_f32_e32 v14, v16, v14
	v_add_f32_e32 v16, v21, v14
	v_mul_f32_e32 v17, v18, v16
	v_mul_f32_e32 v19, v13, v17
	v_fma_f32 v13, v17, v13, -v19
	v_fmac_f32_e32 v13, v17, v3
	v_sub_f32_e32 v3, v21, v16
	v_add_f32_e32 v3, v14, v3
	v_add_f32_e32 v14, v19, v13
	v_sub_f32_e32 v20, v16, v14
	v_sub_f32_e32 v16, v16, v20
	v_sub_f32_e32 v19, v14, v19
	v_sub_f32_e32 v14, v16, v14
	v_add_f32_e32 v3, v3, v14
	v_sub_f32_e32 v13, v19, v13
	v_cvt_f32_i32_e32 v2, v2
	v_add_f32_e32 v3, v13, v3
	v_add_f32_e32 v13, v15, v17
	v_add_f32_e32 v3, v20, v3
	v_sub_f32_e32 v14, v13, v15
	v_mul_f32_e32 v3, v18, v3
	v_sub_f32_e32 v14, v17, v14
	v_add_f32_e32 v3, v14, v3
	v_mul_f32_e32 v17, 0x3f317218, v2
	v_add_f32_e32 v14, v13, v3
	v_fma_f32 v18, v2, s9, -v17
	v_mul_f32_e32 v15, v14, v14
	v_fmac_f32_e32 v18, 0xb102e308, v2
	v_sub_f32_e32 v2, v14, v13
	v_fmamk_f32 v16, v15, 0x3e9b6dac, v231
	v_sub_f32_e32 v2, v3, v2
	v_add_f32_e32 v3, v17, v18
	v_fmaak_f32 v16, v15, v16, 0x3f2aaada
	v_sub_f32_e32 v13, v3, v17
	v_ldexp_f32 v17, v14, 1
	v_mul_f32_e32 v14, v14, v15
	v_mul_f32_e32 v14, v14, v16
	v_add_f32_e32 v15, v17, v14
	v_sub_f32_e32 v16, v15, v17
	v_ldexp_f32 v2, v2, 1
	v_sub_f32_e32 v14, v14, v16
	v_add_f32_e32 v2, v2, v14
	v_add_f32_e32 v14, v15, v2
	v_sub_f32_e32 v15, v14, v15
	v_sub_f32_e32 v2, v2, v15
	v_add_f32_e32 v15, v3, v14
	v_sub_f32_e32 v16, v15, v3
	v_sub_f32_e32 v17, v15, v16
	v_sub_f32_e32 v13, v18, v13
	v_sub_f32_e32 v3, v3, v17
	v_sub_f32_e32 v14, v14, v16
	v_add_f32_e32 v3, v14, v3
	v_add_f32_e32 v14, v13, v2
	v_sub_f32_e32 v16, v14, v13
	v_sub_f32_e32 v17, v14, v16
	v_sub_f32_e32 v13, v13, v17
	v_sub_f32_e32 v2, v2, v16
	v_add_f32_e32 v3, v14, v3
	v_add_f32_e32 v2, v2, v13
	v_add_f32_e32 v13, v15, v3
	v_sub_f32_e32 v14, v13, v15
	v_sub_f32_e32 v3, v3, v14
	v_add_f32_e32 v2, v2, v3
	v_add_f32_e32 v2, v13, v2
	v_cmp_neq_f32_e32 vcc, s6, v6
	v_mul_f32_e64 v3, |v7|, s7
	v_max_f32_e64 v7, -v7, 0
	v_cndmask_b32_e32 v2, v238, v2, vcc
	v_cmp_ngt_f32_e32 vcc, -1.0, v6
	s_nop 1
	v_cndmask_b32_e32 v2, v239, v2, vcc
	v_cmp_neq_f32_e32 vcc, -1.0, v6
	s_nop 1
	v_cndmask_b32_e32 v2, v240, v2, vcc
	v_cmp_lt_f32_e64 vcc, |v6|, s10
	s_nop 1
	v_cndmask_b32_e32 v2, v2, v6, vcc
	v_add_f32_e32 v2, v8, v2
	v_sub_f32_e32 v2, -0.5, v2
	v_mul_f32_e32 v2, 0x3fb8aa3b, v2
	v_exp_f32_e32 v6, v3
	v_exp_f32_e32 v2, v2
	v_add_f32_e32 v8, v9, v5
	v_add_f32_e32 v9, 1.0, v6
	v_mul_f32_e32 v5, 0xbfb8aa3b, v2
	v_add_f32_e32 v2, -1.0, v9
	v_sub_f32_e32 v3, v2, v9
	v_add_f32_e32 v3, 1.0, v3
	v_sub_f32_e32 v2, v6, v2
	v_add_f32_e32 v13, v2, v3
	v_frexp_mant_f32_e32 v2, v9
	v_cmp_gt_f32_e32 vcc, s8, v2
	v_cvt_f64_f32_e32 v[2:3], v9
	v_frexp_exp_i32_f64_e32 v2, v[2:3]
	v_subbrev_co_u32_e32 v2, vcc, 0, v2, vcc
	v_sub_u32_e32 v3, 0, v2
	v_ldexp_f32 v9, v9, v3
	v_ldexp_f32 v3, v13, v3
	v_add_f32_e32 v13, -1.0, v9
	v_add_f32_e32 v16, 1.0, v9
	v_add_f32_e32 v14, 1.0, v13
	v_add_f32_e32 v17, -1.0, v16
	v_sub_f32_e32 v14, v9, v14
	v_sub_f32_e32 v9, v9, v17
	v_add_f32_e32 v14, v3, v14
	v_add_f32_e32 v3, v3, v9
	v_add_f32_e32 v9, v16, v3
	v_rcp_f32_e32 v17, v9
	v_add_f32_e32 v15, v13, v14
	v_sub_f32_e32 v13, v15, v13
	v_sub_f32_e32 v13, v14, v13
	v_sub_f32_e32 v14, v9, v16
	v_sub_f32_e32 v3, v3, v14
	v_mul_f32_e32 v14, v15, v17
	v_mul_f32_e32 v16, v9, v14
	v_fma_f32 v18, v14, v9, -v16
	v_fmac_f32_e32 v18, v14, v3
	v_add_f32_e32 v19, v16, v18
	v_sub_f32_e32 v20, v15, v19
	v_sub_f32_e32 v15, v15, v20
	v_sub_f32_e32 v16, v19, v16
	v_sub_f32_e32 v15, v15, v19
	v_add_f32_e32 v13, v13, v15
	v_sub_f32_e32 v15, v16, v18
	v_add_f32_e32 v13, v15, v13
	v_add_f32_e32 v15, v20, v13
	v_mul_f32_e32 v16, v17, v15
	v_mul_f32_e32 v18, v9, v16
	v_fma_f32 v9, v16, v9, -v18
	v_fmac_f32_e32 v9, v16, v3
	v_sub_f32_e32 v3, v20, v15
	v_add_f32_e32 v3, v13, v3
	v_add_f32_e32 v13, v18, v9
	v_sub_f32_e32 v19, v15, v13
	v_sub_f32_e32 v15, v15, v19
	v_sub_f32_e32 v18, v13, v18
	v_sub_f32_e32 v13, v15, v13
	v_add_f32_e32 v3, v3, v13
	v_sub_f32_e32 v9, v18, v9
	v_cvt_f32_i32_e32 v2, v2
	v_add_f32_e32 v3, v9, v3
	v_add_f32_e32 v9, v14, v16
	v_add_f32_e32 v3, v19, v3
	v_sub_f32_e32 v13, v9, v14
	v_mul_f32_e32 v3, v17, v3
	v_sub_f32_e32 v13, v16, v13
	v_add_f32_e32 v3, v13, v3
	v_mul_f32_e32 v16, 0x3f317218, v2
	v_add_f32_e32 v13, v9, v3
	v_fma_f32 v17, v2, s9, -v16
	v_mul_f32_e32 v14, v13, v13
	v_fmac_f32_e32 v17, 0xb102e308, v2
; template <int MODE, bool BIG = false> DI void gemm_tile(const Params& p, int tm, int tn, int kv, char* smem) {
;     ...
;   } else if constexpr (MODE == G_RWW) {
;     float4* W4 = (float4*)((float*)(p.ws + OFF_BUFA) + (size_t)m * 512 + col0);
;     const float4* w04 = (const float4*)(p.w0 + col0);
; #pragma unroll
;     for (int c4 = 0; c4 < 16; ++c4) {
;       float4 v = crow4[c4], ww = w04[c4];
;       float u[4] = {v.x + ww.x, v.y + ww.y, v.z + ww.z, v.w + ww.w};
; #pragma unroll
;       for (int e = 0; e < 4; ++e) {
;         const float z = -u[e];
;         const float sp = fmaxf(z, 0.f) + log1pf(__expf(-fabsf(z)));
;         u[e] = __expf(-__expf(-sp - 0.5f));
;       }
;       W4[c4] = make_float4(u[0], u[1], u[2], u[3]);
;     }
	v_sub_f32_e32 v2, v13, v9
	v_fmamk_f32 v15, v14, 0x3e9b6dac, v231
	v_sub_f32_e32 v2, v3, v2
	v_add_f32_e32 v3, v16, v17
	v_fmaak_f32 v15, v14, v15, 0x3f2aaada
	v_sub_f32_e32 v9, v3, v16
	v_ldexp_f32 v16, v13, 1
	v_mul_f32_e32 v13, v13, v14
	v_mul_f32_e32 v13, v13, v15
	v_add_f32_e32 v14, v16, v13
	v_sub_f32_e32 v15, v14, v16
	v_ldexp_f32 v2, v2, 1
	v_sub_f32_e32 v13, v13, v15
	v_add_f32_e32 v2, v2, v13
	v_add_f32_e32 v13, v14, v2
	v_sub_f32_e32 v14, v13, v14
	v_sub_f32_e32 v2, v2, v14
	v_add_f32_e32 v14, v3, v13
	v_sub_f32_e32 v15, v14, v3
	v_sub_f32_e32 v16, v14, v15
	v_sub_f32_e32 v9, v17, v9
	v_sub_f32_e32 v3, v3, v16
	v_sub_f32_e32 v13, v13, v15
	v_add_f32_e32 v3, v13, v3
	v_add_f32_e32 v13, v9, v2
	v_sub_f32_e32 v15, v13, v9
	v_sub_f32_e32 v16, v13, v15
	v_sub_f32_e32 v9, v9, v16
	v_sub_f32_e32 v2, v2, v15
	v_add_f32_e32 v3, v13, v3
	v_add_f32_e32 v2, v2, v9
	v_add_f32_e32 v9, v14, v3
	v_sub_f32_e32 v13, v9, v14
	v_sub_f32_e32 v3, v3, v13
	v_add_f32_e32 v2, v2, v3
	v_add_f32_e32 v2, v9, v2
	v_cmp_neq_f32_e32 vcc, s6, v6
	s_nop 1
	v_cndmask_b32_e32 v2, v238, v2, vcc
	v_cmp_ngt_f32_e32 vcc, -1.0, v6
	s_nop 1
	v_cndmask_b32_e32 v2, v239, v2, vcc
	v_cmp_neq_f32_e32 vcc, -1.0, v6
	s_nop 1
	v_cndmask_b32_e32 v2, v240, v2, vcc
	v_cmp_lt_f32_e64 vcc, |v6|, s10
	s_nop 1
	v_cndmask_b32_e32 v2, v2, v6, vcc
	v_add_f32_e32 v2, v7, v2
	v_sub_f32_e32 v2, -0.5, v2
	v_mul_f32_e32 v2, 0x3fb8aa3b, v2
	v_exp_f32_e32 v3, v2
	v_mul_f32_e64 v2, |v4|, s7
	v_exp_f32_e32 v6, v2
	v_max_f32_e64 v7, -v4, 0
	v_exp_f32_e32 v2, v5
	v_mul_f32_e32 v3, 0xbfb8aa3b, v3
	v_add_f32_e32 v9, 1.0, v6
	v_add_f32_e32 v4, -1.0, v9
	v_sub_f32_e32 v5, v4, v9
	v_add_f32_e32 v5, 1.0, v5
	v_sub_f32_e32 v4, v6, v4
	v_add_f32_e32 v13, v4, v5
	v_frexp_mant_f32_e32 v4, v9
	v_cmp_gt_f32_e32 vcc, s8, v4
	v_cvt_f64_f32_e32 v[4:5], v9
	v_frexp_exp_i32_f64_e32 v4, v[4:5]
	v_subbrev_co_u32_e32 v4, vcc, 0, v4, vcc
	v_sub_u32_e32 v5, 0, v4
	v_ldexp_f32 v9, v9, v5
	v_ldexp_f32 v5, v13, v5
	v_add_f32_e32 v13, -1.0, v9
	v_add_f32_e32 v16, 1.0, v9
	v_add_f32_e32 v14, 1.0, v13
	v_add_f32_e32 v17, -1.0, v16
	v_sub_f32_e32 v14, v9, v14
	v_sub_f32_e32 v9, v9, v17
	v_add_f32_e32 v14, v5, v14
	v_add_f32_e32 v5, v5, v9
	v_add_f32_e32 v9, v16, v5
	v_rcp_f32_e32 v17, v9
	v_add_f32_e32 v15, v13, v14
	v_sub_f32_e32 v13, v15, v13
	v_sub_f32_e32 v13, v14, v13
	v_sub_f32_e32 v14, v9, v16
	v_sub_f32_e32 v5, v5, v14
	v_mul_f32_e32 v14, v15, v17
	v_mul_f32_e32 v16, v9, v14
	v_fma_f32 v18, v14, v9, -v16
	v_fmac_f32_e32 v18, v14, v5
	v_add_f32_e32 v19, v16, v18
	v_sub_f32_e32 v20, v15, v19
	v_sub_f32_e32 v15, v15, v20
	v_sub_f32_e32 v16, v19, v16
	v_sub_f32_e32 v15, v15, v19
	v_add_f32_e32 v13, v13, v15
	v_sub_f32_e32 v15, v16, v18
	v_add_f32_e32 v13, v15, v13
	v_add_f32_e32 v15, v20, v13
	v_mul_f32_e32 v16, v17, v15
	v_mul_f32_e32 v18, v9, v16
	v_fma_f32 v9, v16, v9, -v18
	v_fmac_f32_e32 v9, v16, v5
	v_sub_f32_e32 v5, v20, v15
	v_add_f32_e32 v5, v13, v5
	v_add_f32_e32 v13, v18, v9
	v_sub_f32_e32 v19, v15, v13
	v_sub_f32_e32 v15, v15, v19
	v_sub_f32_e32 v18, v13, v18
	v_sub_f32_e32 v13, v15, v13
	v_add_f32_e32 v5, v5, v13
	v_sub_f32_e32 v9, v18, v9
	v_cvt_f32_i32_e32 v4, v4
	v_add_f32_e32 v5, v9, v5
	v_add_f32_e32 v9, v14, v16
	v_add_f32_e32 v5, v19, v5
	v_sub_f32_e32 v13, v9, v14
	v_mul_f32_e32 v5, v17, v5
	v_sub_f32_e32 v13, v16, v13
	v_add_f32_e32 v5, v13, v5
	v_mul_f32_e32 v16, 0x3f317218, v4
	v_add_f32_e32 v13, v9, v5
	v_fma_f32 v17, v4, s9, -v16
	v_mul_f32_e32 v14, v13, v13
	v_fmac_f32_e32 v17, 0xb102e308, v4
	v_sub_f32_e32 v4, v13, v9
	v_fmamk_f32 v15, v14, 0x3e9b6dac, v231
	v_sub_f32_e32 v4, v5, v4
	v_add_f32_e32 v5, v16, v17
	v_fmaak_f32 v15, v14, v15, 0x3f2aaada
	v_sub_f32_e32 v9, v5, v16
	v_ldexp_f32 v16, v13, 1
	v_mul_f32_e32 v13, v13, v14
	v_mul_f32_e32 v13, v13, v15
	v_add_f32_e32 v14, v16, v13
	v_sub_f32_e32 v15, v14, v16
	v_ldexp_f32 v4, v4, 1
	v_sub_f32_e32 v13, v13, v15
	v_add_f32_e32 v4, v4, v13
	v_add_f32_e32 v13, v14, v4
	v_sub_f32_e32 v14, v13, v14
	v_sub_f32_e32 v4, v4, v14
	v_add_f32_e32 v14, v5, v13
	v_sub_f32_e32 v15, v14, v5
	v_sub_f32_e32 v16, v14, v15
	v_sub_f32_e32 v9, v17, v9
	v_sub_f32_e32 v5, v5, v16
	v_sub_f32_e32 v13, v13, v15
	v_add_f32_e32 v5, v13, v5
	v_add_f32_e32 v13, v9, v4
	v_sub_f32_e32 v15, v13, v9
	v_sub_f32_e32 v16, v13, v15
	v_sub_f32_e32 v9, v9, v16
	v_sub_f32_e32 v4, v4, v15
	v_add_f32_e32 v5, v13, v5
	v_add_f32_e32 v4, v4, v9
	v_add_f32_e32 v9, v14, v5
	v_sub_f32_e32 v13, v9, v14
	v_sub_f32_e32 v5, v5, v13
	v_add_f32_e32 v4, v4, v5
	v_add_f32_e32 v4, v9, v4
	v_cmp_neq_f32_e32 vcc, s6, v6
	v_mul_f32_e64 v5, |v8|, s7
	v_max_f32_e64 v8, -v8, 0
	v_cndmask_b32_e32 v4, v238, v4, vcc
	v_cmp_ngt_f32_e32 vcc, -1.0, v6
	v_exp_f32_e32 v3, v3
	s_nop 0
	v_cndmask_b32_e32 v4, v239, v4, vcc
	v_cmp_neq_f32_e32 vcc, -1.0, v6
	s_nop 1
	v_cndmask_b32_e32 v4, v240, v4, vcc
	v_cmp_lt_f32_e64 vcc, |v6|, s10
	s_nop 1
	v_cndmask_b32_e32 v4, v4, v6, vcc
	v_exp_f32_e32 v6, v5
	v_add_f32_e32 v4, v7, v4
	v_sub_f32_e32 v4, -0.5, v4
	v_mul_f32_e32 v4, 0x3fb8aa3b, v4
	v_add_f32_e32 v9, 1.0, v6
	v_exp_f32_e32 v7, v4
	v_add_f32_e32 v4, -1.0, v9
	v_sub_f32_e32 v5, v4, v9
	v_add_f32_e32 v5, 1.0, v5
	v_sub_f32_e32 v4, v6, v4
	v_add_f32_e32 v13, v4, v5
	v_frexp_mant_f32_e32 v4, v9
	v_cmp_gt_f32_e32 vcc, s8, v4
	v_cvt_f64_f32_e32 v[4:5], v9
	v_frexp_exp_i32_f64_e32 v4, v[4:5]
	v_subbrev_co_u32_e32 v4, vcc, 0, v4, vcc
	v_sub_u32_e32 v5, 0, v4
	v_ldexp_f32 v9, v9, v5
	v_ldexp_f32 v5, v13, v5
	v_add_f32_e32 v13, -1.0, v9
	v_add_f32_e32 v16, 1.0, v9
	v_add_f32_e32 v14, 1.0, v13
	v_add_f32_e32 v17, -1.0, v16
	v_sub_f32_e32 v14, v9, v14
	v_sub_f32_e32 v9, v9, v17
	v_add_f32_e32 v14, v5, v14
	v_add_f32_e32 v5, v5, v9
; template <int MODE, bool BIG = false> DI void gemm_tile(const Params& p, int tm, int tn, int kv, char* smem) {
;     ...
;   } else if constexpr (MODE == G_RWW) {
;     float4* W4 = (float4*)((float*)(p.ws + OFF_BUFA) + (size_t)m * 512 + col0);
;     const float4* w04 = (const float4*)(p.w0 + col0);
; #pragma unroll
;     for (int c4 = 0; c4 < 16; ++c4) {
;       float4 v = crow4[c4], ww = w04[c4];
;       float u[4] = {v.x + ww.x, v.y + ww.y, v.z + ww.z, v.w + ww.w};
; #pragma unroll
;       for (int e = 0; e < 4; ++e) {
;         const float z = -u[e];
;         const float sp = fmaxf(z, 0.f) + log1pf(__expf(-fabsf(z)));
;         u[e] = __expf(-__expf(-sp - 0.5f));
;       }
;       W4[c4] = make_float4(u[0], u[1], u[2], u[3]);
;     }
	v_add_f32_e32 v9, v16, v5
	v_rcp_f32_e32 v17, v9
	v_add_f32_e32 v15, v13, v14
	v_sub_f32_e32 v13, v15, v13
	v_sub_f32_e32 v13, v14, v13
	v_sub_f32_e32 v14, v9, v16
	v_sub_f32_e32 v5, v5, v14
	v_mul_f32_e32 v14, v15, v17
	v_mul_f32_e32 v16, v9, v14
	v_fma_f32 v18, v14, v9, -v16
	v_fmac_f32_e32 v18, v14, v5
	v_add_f32_e32 v19, v16, v18
	v_sub_f32_e32 v20, v15, v19
	v_sub_f32_e32 v15, v15, v20
	v_sub_f32_e32 v16, v19, v16
	v_sub_f32_e32 v15, v15, v19
	v_add_f32_e32 v13, v13, v15
	v_sub_f32_e32 v15, v16, v18
	v_add_f32_e32 v13, v15, v13
	v_add_f32_e32 v15, v20, v13
	v_mul_f32_e32 v16, v17, v15
	v_mul_f32_e32 v18, v9, v16
	v_fma_f32 v9, v16, v9, -v18
	v_fmac_f32_e32 v9, v16, v5
	v_sub_f32_e32 v5, v20, v15
	v_add_f32_e32 v5, v13, v5
	v_add_f32_e32 v13, v18, v9
	v_sub_f32_e32 v19, v15, v13
	v_sub_f32_e32 v15, v15, v19
	v_sub_f32_e32 v18, v13, v18
	v_sub_f32_e32 v13, v15, v13
	v_add_f32_e32 v5, v5, v13
	v_sub_f32_e32 v9, v18, v9
	v_cvt_f32_i32_e32 v4, v4
	v_add_f32_e32 v5, v9, v5
	v_add_f32_e32 v9, v14, v16
	v_add_f32_e32 v5, v19, v5
	v_sub_f32_e32 v13, v9, v14
	v_mul_f32_e32 v5, v17, v5
	v_sub_f32_e32 v13, v16, v13
	v_add_f32_e32 v5, v13, v5
	v_mul_f32_e32 v16, 0x3f317218, v4
	v_add_f32_e32 v13, v9, v5
	v_fma_f32 v17, v4, s9, -v16
	v_mul_f32_e32 v14, v13, v13
	v_fmac_f32_e32 v17, 0xb102e308, v4
	v_sub_f32_e32 v4, v13, v9
	v_fmamk_f32 v15, v14, 0x3e9b6dac, v231
	v_sub_f32_e32 v4, v5, v4
	v_add_f32_e32 v5, v16, v17
	v_fmaak_f32 v15, v14, v15, 0x3f2aaada
	v_sub_f32_e32 v9, v5, v16
	v_ldexp_f32 v16, v13, 1
	v_mul_f32_e32 v13, v13, v14
	v_mul_f32_e32 v13, v13, v15
	v_add_f32_e32 v14, v16, v13
	v_sub_f32_e32 v15, v14, v16
	v_ldexp_f32 v4, v4, 1
	v_sub_f32_e32 v13, v13, v15
	v_add_f32_e32 v4, v4, v13
	v_add_f32_e32 v13, v14, v4
	v_sub_f32_e32 v14, v13, v14
	v_sub_f32_e32 v4, v4, v14
	v_add_f32_e32 v14, v5, v13
	v_sub_f32_e32 v15, v14, v5
	v_sub_f32_e32 v16, v14, v15
	v_sub_f32_e32 v9, v17, v9
	v_sub_f32_e32 v5, v5, v16
	v_sub_f32_e32 v13, v13, v15
	v_add_f32_e32 v5, v13, v5
	v_add_f32_e32 v13, v9, v4
	v_sub_f32_e32 v15, v13, v9
	v_sub_f32_e32 v16, v13, v15
	v_sub_f32_e32 v9, v9, v16
	v_sub_f32_e32 v4, v4, v15
	v_add_f32_e32 v5, v13, v5
	v_add_f32_e32 v4, v4, v9
	v_add_f32_e32 v9, v14, v5
	v_sub_f32_e32 v13, v9, v14
	v_sub_f32_e32 v5, v5, v13
	v_add_f32_e32 v4, v4, v5
	v_add_f32_e32 v4, v9, v4
	v_cmp_neq_f32_e32 vcc, s6, v6
	s_nop 1
	v_cndmask_b32_e32 v4, v238, v4, vcc
	v_cmp_ngt_f32_e32 vcc, -1.0, v6
	s_nop 1
	v_cndmask_b32_e32 v4, v239, v4, vcc
	v_cmp_neq_f32_e32 vcc, -1.0, v6
	s_nop 1
	v_cndmask_b32_e32 v4, v240, v4, vcc
	v_cmp_lt_f32_e64 vcc, |v6|, s10
	s_nop 1
	v_cndmask_b32_e32 v4, v4, v6, vcc
	v_add_f32_e32 v4, v8, v4
	v_sub_f32_e32 v4, -0.5, v4
	v_mul_f32_e32 v4, 0x3fb8aa3b, v4
	v_exp_f32_e32 v5, v4
	v_mul_f32_e32 v4, 0xbfb8aa3b, v7
	v_exp_f32_e32 v4, v4
	ds_read_b128 v[6:9], v12 offset:32
	v_mul_f32_e32 v5, 0xbfb8aa3b, v5
	v_exp_f32_e32 v5, v5
	ds_write_b128 v75, v[2:5] offset:16
	ds_read_b128 v[2:5], v74 offset:32
	s_waitcnt lgkmcnt(0)
	v_add_f32_e32 v2, v6, v2
	v_mul_f32_e64 v6, |v2|, s7
	v_exp_f32_e32 v6, v6
	v_add_f32_e32 v4, v8, v4
	v_max_f32_e64 v8, -v2, 0
	v_add_f32_e32 v7, v7, v3
	v_add_f32_e32 v13, 1.0, v6
	v_add_f32_e32 v2, -1.0, v13
	v_sub_f32_e32 v3, v2, v13
	v_add_f32_e32 v3, 1.0, v3
	v_sub_f32_e32 v2, v6, v2
	v_add_f32_e32 v14, v2, v3
	v_frexp_mant_f32_e32 v2, v13
	v_cmp_gt_f32_e32 vcc, s8, v2
	v_cvt_f64_f32_e32 v[2:3], v13
	v_frexp_exp_i32_f64_e32 v2, v[2:3]
	v_subbrev_co_u32_e32 v2, vcc, 0, v2, vcc
	v_sub_u32_e32 v3, 0, v2
	v_ldexp_f32 v13, v13, v3
	v_ldexp_f32 v3, v14, v3
	v_add_f32_e32 v14, -1.0, v13
	v_add_f32_e32 v17, 1.0, v13
	v_add_f32_e32 v15, 1.0, v14
	v_add_f32_e32 v18, -1.0, v17
	v_sub_f32_e32 v15, v13, v15
	v_sub_f32_e32 v13, v13, v18
	v_add_f32_e32 v15, v3, v15
	v_add_f32_e32 v3, v3, v13
	v_add_f32_e32 v13, v17, v3
	v_rcp_f32_e32 v18, v13
	v_add_f32_e32 v16, v14, v15
	v_sub_f32_e32 v14, v16, v14
	v_sub_f32_e32 v14, v15, v14
	v_sub_f32_e32 v15, v13, v17
	v_sub_f32_e32 v3, v3, v15
	v_mul_f32_e32 v15, v16, v18
	v_mul_f32_e32 v17, v13, v15
	v_fma_f32 v19, v15, v13, -v17
	v_fmac_f32_e32 v19, v15, v3
	v_add_f32_e32 v20, v17, v19
	v_sub_f32_e32 v21, v16, v20
	v_sub_f32_e32 v16, v16, v21
	v_sub_f32_e32 v17, v20, v17
	v_sub_f32_e32 v16, v16, v20
	v_add_f32_e32 v14, v14, v16
	v_sub_f32_e32 v16, v17, v19
	v_add_f32_e32 v14, v16, v14
	v_add_f32_e32 v16, v21, v14
	v_mul_f32_e32 v17, v18, v16
	v_mul_f32_e32 v19, v13, v17
	v_fma_f32 v13, v17, v13, -v19
	v_fmac_f32_e32 v13, v17, v3
	v_sub_f32_e32 v3, v21, v16
	v_add_f32_e32 v3, v14, v3
	v_add_f32_e32 v14, v19, v13
	v_sub_f32_e32 v20, v16, v14
	v_sub_f32_e32 v16, v16, v20
	v_sub_f32_e32 v19, v14, v19
	v_sub_f32_e32 v14, v16, v14
	v_add_f32_e32 v3, v3, v14
	v_sub_f32_e32 v13, v19, v13
	v_cvt_f32_i32_e32 v2, v2
	v_add_f32_e32 v3, v13, v3
	v_add_f32_e32 v13, v15, v17
	v_add_f32_e32 v3, v20, v3
	v_sub_f32_e32 v14, v13, v15
	v_mul_f32_e32 v3, v18, v3
	v_sub_f32_e32 v14, v17, v14
	v_add_f32_e32 v3, v14, v3
	v_mul_f32_e32 v17, 0x3f317218, v2
	v_add_f32_e32 v14, v13, v3
	v_fma_f32 v18, v2, s9, -v17
	v_mul_f32_e32 v15, v14, v14
	v_fmac_f32_e32 v18, 0xb102e308, v2
	v_sub_f32_e32 v2, v14, v13
	v_fmamk_f32 v16, v15, 0x3e9b6dac, v231
	v_sub_f32_e32 v2, v3, v2
	v_add_f32_e32 v3, v17, v18
	v_fmaak_f32 v16, v15, v16, 0x3f2aaada
	v_sub_f32_e32 v13, v3, v17
	v_ldexp_f32 v17, v14, 1
	v_mul_f32_e32 v14, v14, v15
	v_mul_f32_e32 v14, v14, v16
	v_add_f32_e32 v15, v17, v14
	v_sub_f32_e32 v16, v15, v17
	v_ldexp_f32 v2, v2, 1
	v_sub_f32_e32 v14, v14, v16
	v_add_f32_e32 v2, v2, v14
	v_add_f32_e32 v14, v15, v2
	v_sub_f32_e32 v15, v14, v15
	v_sub_f32_e32 v2, v2, v15
	v_add_f32_e32 v15, v3, v14
; template <int MODE, bool BIG = false> DI void gemm_tile(const Params& p, int tm, int tn, int kv, char* smem) {
;     ...
;     for (int c4 = 0; c4 < 16; ++c4) {
;       float4 v = crow4[c4], ww = w04[c4];
;       float u[4] = {v.x + ww.x, v.y + ww.y, v.z + ww.z, v.w + ww.w};
; #pragma unroll
;       for (int e = 0; e < 4; ++e) {
;         const float z = -u[e];
;         const float sp = fmaxf(z, 0.f) + log1pf(__expf(-fabsf(z)));
;         u[e] = __expf(-__expf(-sp - 0.5f));
;       }
	v_sub_f32_e32 v16, v15, v3
	v_sub_f32_e32 v17, v15, v16
	v_sub_f32_e32 v13, v18, v13
	v_sub_f32_e32 v3, v3, v17
	v_sub_f32_e32 v14, v14, v16
	v_add_f32_e32 v3, v14, v3
	v_add_f32_e32 v14, v13, v2
	v_sub_f32_e32 v16, v14, v13
	v_sub_f32_e32 v17, v14, v16
	v_sub_f32_e32 v13, v13, v17
	v_sub_f32_e32 v2, v2, v16
	v_add_f32_e32 v3, v14, v3
	v_add_f32_e32 v2, v2, v13
	v_add_f32_e32 v13, v15, v3
	v_sub_f32_e32 v14, v13, v15
	v_sub_f32_e32 v3, v3, v14
	v_add_f32_e32 v2, v2, v3
	v_add_f32_e32 v2, v13, v2
	v_cmp_neq_f32_e32 vcc, s6, v6
	v_mul_f32_e64 v3, |v7|, s7
	v_max_f32_e64 v7, -v7, 0
	v_cndmask_b32_e32 v2, v238, v2, vcc
	v_cmp_ngt_f32_e32 vcc, -1.0, v6
	s_nop 1
	v_cndmask_b32_e32 v2, v239, v2, vcc
	v_cmp_neq_f32_e32 vcc, -1.0, v6
	s_nop 1
	v_cndmask_b32_e32 v2, v240, v2, vcc
	v_cmp_lt_f32_e64 vcc, |v6|, s10
	s_nop 1
	v_cndmask_b32_e32 v2, v2, v6, vcc
	v_add_f32_e32 v2, v8, v2
	v_sub_f32_e32 v2, -0.5, v2
	v_mul_f32_e32 v2, 0x3fb8aa3b, v2
	v_exp_f32_e32 v6, v3
	v_exp_f32_e32 v2, v2
	v_add_f32_e32 v8, v9, v5
	v_add_f32_e32 v9, 1.0, v6
	v_mul_f32_e32 v5, 0xbfb8aa3b, v2
	v_add_f32_e32 v2, -1.0, v9
	v_sub_f32_e32 v3, v2, v9
	v_add_f32_e32 v3, 1.0, v3
	v_sub_f32_e32 v2, v6, v2
	v_add_f32_e32 v13, v2, v3
	v_frexp_mant_f32_e32 v2, v9
	v_cmp_gt_f32_e32 vcc, s8, v2
	v_cvt_f64_f32_e32 v[2:3], v9
	v_frexp_exp_i32_f64_e32 v2, v[2:3]
	v_subbrev_co_u32_e32 v2, vcc, 0, v2, vcc
	v_sub_u32_e32 v3, 0, v2
	v_ldexp_f32 v9, v9, v3
	v_ldexp_f32 v3, v13, v3
	v_add_f32_e32 v13, -1.0, v9
	v_add_f32_e32 v16, 1.0, v9
	v_add_f32_e32 v14, 1.0, v13
	v_add_f32_e32 v17, -1.0, v16
	v_sub_f32_e32 v14, v9, v14
	v_sub_f32_e32 v9, v9, v17
	v_add_f32_e32 v14, v3, v14
	v_add_f32_e32 v3, v3, v9
	v_add_f32_e32 v9, v16, v3
	v_rcp_f32_e32 v17, v9
	v_add_f32_e32 v15, v13, v14
	v_sub_f32_e32 v13, v15, v13
	v_sub_f32_e32 v13, v14, v13
	v_sub_f32_e32 v14, v9, v16
	v_sub_f32_e32 v3, v3, v14
	v_mul_f32_e32 v14, v15, v17
	v_mul_f32_e32 v16, v9, v14
	v_fma_f32 v18, v14, v9, -v16
	v_fmac_f32_e32 v18, v14, v3
	v_add_f32_e32 v19, v16, v18
	v_sub_f32_e32 v20, v15, v19
	v_sub_f32_e32 v15, v15, v20
	v_sub_f32_e32 v16, v19, v16
	v_sub_f32_e32 v15, v15, v19
	v_add_f32_e32 v13, v13, v15
	v_sub_f32_e32 v15, v16, v18
	v_add_f32_e32 v13, v15, v13
	v_add_f32_e32 v15, v20, v13
	v_mul_f32_e32 v16, v17, v15
	v_mul_f32_e32 v18, v9, v16
	v_fma_f32 v9, v16, v9, -v18
	v_fmac_f32_e32 v9, v16, v3
	v_sub_f32_e32 v3, v20, v15
	v_add_f32_e32 v3, v13, v3
	v_add_f32_e32 v13, v18, v9
	v_sub_f32_e32 v19, v15, v13
	v_sub_f32_e32 v15, v15, v19
	v_sub_f32_e32 v18, v13, v18
	v_sub_f32_e32 v13, v15, v13
	v_add_f32_e32 v3, v3, v13
	v_sub_f32_e32 v9, v18, v9
	v_cvt_f32_i32_e32 v2, v2
	v_add_f32_e32 v3, v9, v3
	v_add_f32_e32 v9, v14, v16
	v_add_f32_e32 v3, v19, v3
	v_sub_f32_e32 v13, v9, v14
	v_mul_f32_e32 v3, v17, v3
	v_sub_f32_e32 v13, v16, v13
	v_add_f32_e32 v3, v13, v3
	v_mul_f32_e32 v16, 0x3f317218, v2
	v_add_f32_e32 v13, v9, v3
	v_fma_f32 v17, v2, s9, -v16
	v_mul_f32_e32 v14, v13, v13
	v_fmac_f32_e32 v17, 0xb102e308, v2
	v_sub_f32_e32 v2, v13, v9
	v_fmamk_f32 v15, v14, 0x3e9b6dac, v231
	v_sub_f32_e32 v2, v3, v2
	v_add_f32_e32 v3, v16, v17
	v_fmaak_f32 v15, v14, v15, 0x3f2aaada
	v_sub_f32_e32 v9, v3, v16
	v_ldexp_f32 v16, v13, 1
	v_mul_f32_e32 v13, v13, v14
	v_mul_f32_e32 v13, v13, v15
	v_add_f32_e32 v14, v16, v13
	v_sub_f32_e32 v15, v14, v16
	v_ldexp_f32 v2, v2, 1
	v_sub_f32_e32 v13, v13, v15
	v_add_f32_e32 v2, v2, v13
	v_add_f32_e32 v13, v14, v2
	v_sub_f32_e32 v14, v13, v14
	v_sub_f32_e32 v2, v2, v14
	v_add_f32_e32 v14, v3, v13
	v_sub_f32_e32 v15, v14, v3
	v_sub_f32_e32 v16, v14, v15
	v_sub_f32_e32 v9, v17, v9
	v_sub_f32_e32 v3, v3, v16
	v_sub_f32_e32 v13, v13, v15
	v_add_f32_e32 v3, v13, v3
	v_add_f32_e32 v13, v9, v2
	v_sub_f32_e32 v15, v13, v9
	v_sub_f32_e32 v16, v13, v15
	v_sub_f32_e32 v9, v9, v16
	v_sub_f32_e32 v2, v2, v15
	v_add_f32_e32 v3, v13, v3
	v_add_f32_e32 v2, v2, v9
	v_add_f32_e32 v9, v14, v3
	v_sub_f32_e32 v13, v9, v14
	v_sub_f32_e32 v3, v3, v13
	v_add_f32_e32 v2, v2, v3
	v_add_f32_e32 v2, v9, v2
	v_cmp_neq_f32_e32 vcc, s6, v6
	s_nop 1
	v_cndmask_b32_e32 v2, v238, v2, vcc
	v_cmp_ngt_f32_e32 vcc, -1.0, v6
	s_nop 1
	v_cndmask_b32_e32 v2, v239, v2, vcc
	v_cmp_neq_f32_e32 vcc, -1.0, v6
	s_nop 1
	v_cndmask_b32_e32 v2, v240, v2, vcc
	v_cmp_lt_f32_e64 vcc, |v6|, s10
	s_nop 1
	v_cndmask_b32_e32 v2, v2, v6, vcc
	v_add_f32_e32 v2, v7, v2
	v_sub_f32_e32 v2, -0.5, v2
	v_mul_f32_e32 v2, 0x3fb8aa3b, v2
	v_exp_f32_e32 v3, v2
	v_mul_f32_e64 v2, |v4|, s7
	v_exp_f32_e32 v6, v2
	v_max_f32_e64 v7, -v4, 0
	v_exp_f32_e32 v2, v5
	v_mul_f32_e32 v3, 0xbfb8aa3b, v3
	v_add_f32_e32 v9, 1.0, v6
	v_add_f32_e32 v4, -1.0, v9
	v_sub_f32_e32 v5, v4, v9
	v_add_f32_e32 v5, 1.0, v5
	v_sub_f32_e32 v4, v6, v4
	v_add_f32_e32 v13, v4, v5
	v_frexp_mant_f32_e32 v4, v9
	v_cmp_gt_f32_e32 vcc, s8, v4
	v_cvt_f64_f32_e32 v[4:5], v9
	v_frexp_exp_i32_f64_e32 v4, v[4:5]
	v_subbrev_co_u32_e32 v4, vcc, 0, v4, vcc
	v_sub_u32_e32 v5, 0, v4
	v_ldexp_f32 v9, v9, v5
	v_ldexp_f32 v5, v13, v5
	v_add_f32_e32 v13, -1.0, v9
	v_add_f32_e32 v16, 1.0, v9
	v_add_f32_e32 v14, 1.0, v13
	v_add_f32_e32 v17, -1.0, v16
	v_sub_f32_e32 v14, v9, v14
	v_sub_f32_e32 v9, v9, v17
	v_add_f32_e32 v14, v5, v14
	v_add_f32_e32 v5, v5, v9
	v_add_f32_e32 v9, v16, v5
	v_rcp_f32_e32 v17, v9
	v_add_f32_e32 v15, v13, v14
	v_sub_f32_e32 v13, v15, v13
	v_sub_f32_e32 v13, v14, v13
	v_sub_f32_e32 v14, v9, v16
	v_sub_f32_e32 v5, v5, v14
	v_mul_f32_e32 v14, v15, v17
	v_mul_f32_e32 v16, v9, v14
	v_fma_f32 v18, v14, v9, -v16
	v_fmac_f32_e32 v18, v14, v5
	v_add_f32_e32 v19, v16, v18
	v_sub_f32_e32 v20, v15, v19
	v_sub_f32_e32 v15, v15, v20
	v_sub_f32_e32 v16, v19, v16
	v_sub_f32_e32 v15, v15, v19
; template <int MODE, bool BIG = false> DI void gemm_tile(const Params& p, int tm, int tn, int kv, char* smem) {
;     ...
;     for (int c4 = 0; c4 < 16; ++c4) {
;       float4 v = crow4[c4], ww = w04[c4];
;       float u[4] = {v.x + ww.x, v.y + ww.y, v.z + ww.z, v.w + ww.w};
; #pragma unroll
;       for (int e = 0; e < 4; ++e) {
;         const float z = -u[e];
;         const float sp = fmaxf(z, 0.f) + log1pf(__expf(-fabsf(z)));
;         u[e] = __expf(-__expf(-sp - 0.5f));
;       }
;       W4[c4] = make_float4(u[0], u[1], u[2], u[3]);
	v_add_f32_e32 v13, v13, v15
	v_sub_f32_e32 v15, v16, v18
	v_add_f32_e32 v13, v15, v13
	v_add_f32_e32 v15, v20, v13
	v_mul_f32_e32 v16, v17, v15
	v_mul_f32_e32 v18, v9, v16
	v_fma_f32 v9, v16, v9, -v18
	v_fmac_f32_e32 v9, v16, v5
	v_sub_f32_e32 v5, v20, v15
	v_add_f32_e32 v5, v13, v5
	v_add_f32_e32 v13, v18, v9
	v_sub_f32_e32 v19, v15, v13
	v_sub_f32_e32 v15, v15, v19
	v_sub_f32_e32 v18, v13, v18
	v_sub_f32_e32 v13, v15, v13
	v_add_f32_e32 v5, v5, v13
	v_sub_f32_e32 v9, v18, v9
	v_cvt_f32_i32_e32 v4, v4
	v_add_f32_e32 v5, v9, v5
	v_add_f32_e32 v9, v14, v16
	v_add_f32_e32 v5, v19, v5
	v_sub_f32_e32 v13, v9, v14
	v_mul_f32_e32 v5, v17, v5
	v_sub_f32_e32 v13, v16, v13
	v_add_f32_e32 v5, v13, v5
	v_mul_f32_e32 v16, 0x3f317218, v4
	v_add_f32_e32 v13, v9, v5
	v_fma_f32 v17, v4, s9, -v16
	v_mul_f32_e32 v14, v13, v13
	v_fmac_f32_e32 v17, 0xb102e308, v4
	v_sub_f32_e32 v4, v13, v9
	v_fmamk_f32 v15, v14, 0x3e9b6dac, v231
	v_sub_f32_e32 v4, v5, v4
	v_add_f32_e32 v5, v16, v17
	v_fmaak_f32 v15, v14, v15, 0x3f2aaada
	v_sub_f32_e32 v9, v5, v16
	v_ldexp_f32 v16, v13, 1
	v_mul_f32_e32 v13, v13, v14
	v_mul_f32_e32 v13, v13, v15
	v_add_f32_e32 v14, v16, v13
	v_sub_f32_e32 v15, v14, v16
	v_ldexp_f32 v4, v4, 1
	v_sub_f32_e32 v13, v13, v15
	v_add_f32_e32 v4, v4, v13
	v_add_f32_e32 v13, v14, v4
	v_sub_f32_e32 v14, v13, v14
	v_sub_f32_e32 v4, v4, v14
	v_add_f32_e32 v14, v5, v13
	v_sub_f32_e32 v15, v14, v5
	v_sub_f32_e32 v16, v14, v15
	v_sub_f32_e32 v9, v17, v9
	v_sub_f32_e32 v5, v5, v16
	v_sub_f32_e32 v13, v13, v15
	v_add_f32_e32 v5, v13, v5
	v_add_f32_e32 v13, v9, v4
	v_sub_f32_e32 v15, v13, v9
	v_sub_f32_e32 v16, v13, v15
	v_sub_f32_e32 v9, v9, v16
	v_sub_f32_e32 v4, v4, v15
	v_add_f32_e32 v5, v13, v5
	v_add_f32_e32 v4, v4, v9
	v_add_f32_e32 v9, v14, v5
	v_sub_f32_e32 v13, v9, v14
	v_sub_f32_e32 v5, v5, v13
	v_add_f32_e32 v4, v4, v5
	v_add_f32_e32 v4, v9, v4
	v_cmp_neq_f32_e32 vcc, s6, v6
	v_mul_f32_e64 v5, |v8|, s7
	v_max_f32_e64 v8, -v8, 0
	v_cndmask_b32_e32 v4, v238, v4, vcc
	v_cmp_ngt_f32_e32 vcc, -1.0, v6
	v_exp_f32_e32 v3, v3
	s_nop 0
	v_cndmask_b32_e32 v4, v239, v4, vcc
	v_cmp_neq_f32_e32 vcc, -1.0, v6
	s_nop 1
	v_cndmask_b32_e32 v4, v240, v4, vcc
	v_cmp_lt_f32_e64 vcc, |v6|, s10
	s_nop 1
	v_cndmask_b32_e32 v4, v4, v6, vcc
	v_exp_f32_e32 v6, v5
	v_add_f32_e32 v4, v7, v4
	v_sub_f32_e32 v4, -0.5, v4
	v_mul_f32_e32 v4, 0x3fb8aa3b, v4
	v_add_f32_e32 v9, 1.0, v6
	v_exp_f32_e32 v7, v4
	v_add_f32_e32 v4, -1.0, v9
	v_sub_f32_e32 v5, v4, v9
	v_add_f32_e32 v5, 1.0, v5
	v_sub_f32_e32 v4, v6, v4
	v_add_f32_e32 v13, v4, v5
	v_frexp_mant_f32_e32 v4, v9
	v_cmp_gt_f32_e32 vcc, s8, v4
	v_cvt_f64_f32_e32 v[4:5], v9
	v_frexp_exp_i32_f64_e32 v4, v[4:5]
	v_subbrev_co_u32_e32 v4, vcc, 0, v4, vcc
	v_sub_u32_e32 v5, 0, v4
	v_ldexp_f32 v9, v9, v5
	v_ldexp_f32 v5, v13, v5
	v_add_f32_e32 v13, -1.0, v9
	v_add_f32_e32 v16, 1.0, v9
	v_add_f32_e32 v14, 1.0, v13
	v_add_f32_e32 v17, -1.0, v16
	v_sub_f32_e32 v14, v9, v14
	v_sub_f32_e32 v9, v9, v17
	v_add_f32_e32 v14, v5, v14
	v_add_f32_e32 v5, v5, v9
	v_add_f32_e32 v9, v16, v5
	v_rcp_f32_e32 v17, v9
	v_add_f32_e32 v15, v13, v14
	v_sub_f32_e32 v13, v15, v13
	v_sub_f32_e32 v13, v14, v13
	v_sub_f32_e32 v14, v9, v16
	v_sub_f32_e32 v5, v5, v14
	v_mul_f32_e32 v14, v15, v17
	v_mul_f32_e32 v16, v9, v14
	v_fma_f32 v18, v14, v9, -v16
	v_fmac_f32_e32 v18, v14, v5
	v_add_f32_e32 v19, v16, v18
	v_sub_f32_e32 v20, v15, v19
	v_sub_f32_e32 v15, v15, v20
	v_sub_f32_e32 v16, v19, v16
	v_sub_f32_e32 v15, v15, v19
	v_add_f32_e32 v13, v13, v15
	v_sub_f32_e32 v15, v16, v18
	v_add_f32_e32 v13, v15, v13
	v_add_f32_e32 v15, v20, v13
	v_mul_f32_e32 v16, v17, v15
	v_mul_f32_e32 v18, v9, v16
	v_fma_f32 v9, v16, v9, -v18
	v_fmac_f32_e32 v9, v16, v5
	v_sub_f32_e32 v5, v20, v15
	v_add_f32_e32 v5, v13, v5
	v_add_f32_e32 v13, v18, v9
	v_sub_f32_e32 v19, v15, v13
	v_sub_f32_e32 v15, v15, v19
	v_sub_f32_e32 v18, v13, v18
	v_sub_f32_e32 v13, v15, v13
	v_add_f32_e32 v5, v5, v13
	v_sub_f32_e32 v9, v18, v9
	v_cvt_f32_i32_e32 v4, v4
	v_add_f32_e32 v5, v9, v5
	v_add_f32_e32 v9, v14, v16
	v_add_f32_e32 v5, v19, v5
	v_sub_f32_e32 v13, v9, v14
	v_mul_f32_e32 v5, v17, v5
	v_sub_f32_e32 v13, v16, v13
	v_add_f32_e32 v5, v13, v5
	v_mul_f32_e32 v16, 0x3f317218, v4
	v_add_f32_e32 v13, v9, v5
	v_fma_f32 v17, v4, s9, -v16
	v_mul_f32_e32 v14, v13, v13
	v_fmac_f32_e32 v17, 0xb102e308, v4
	v_sub_f32_e32 v4, v13, v9
	v_fmamk_f32 v15, v14, 0x3e9b6dac, v231
	v_sub_f32_e32 v4, v5, v4
	v_add_f32_e32 v5, v16, v17
	v_fmaak_f32 v15, v14, v15, 0x3f2aaada
	v_sub_f32_e32 v9, v5, v16
	v_ldexp_f32 v16, v13, 1
	v_mul_f32_e32 v13, v13, v14
	v_mul_f32_e32 v13, v13, v15
	v_add_f32_e32 v14, v16, v13
	v_sub_f32_e32 v15, v14, v16
	v_ldexp_f32 v4, v4, 1
	v_sub_f32_e32 v13, v13, v15
	v_add_f32_e32 v4, v4, v13
	v_add_f32_e32 v13, v14, v4
	v_sub_f32_e32 v14, v13, v14
	v_sub_f32_e32 v4, v4, v14
	v_add_f32_e32 v14, v5, v13
	v_sub_f32_e32 v15, v14, v5
	v_sub_f32_e32 v16, v14, v15
	v_sub_f32_e32 v9, v17, v9
	v_sub_f32_e32 v5, v5, v16
	v_sub_f32_e32 v13, v13, v15
	v_add_f32_e32 v5, v13, v5
	v_add_f32_e32 v13, v9, v4
	v_sub_f32_e32 v15, v13, v9
	v_sub_f32_e32 v16, v13, v15
	v_sub_f32_e32 v9, v9, v16
	v_sub_f32_e32 v4, v4, v15
	v_add_f32_e32 v5, v13, v5
	v_add_f32_e32 v4, v4, v9
	v_add_f32_e32 v9, v14, v5
	v_sub_f32_e32 v13, v9, v14
	v_sub_f32_e32 v5, v5, v13
	v_add_f32_e32 v4, v4, v5
	v_add_f32_e32 v4, v9, v4
	v_cmp_neq_f32_e32 vcc, s6, v6
	s_nop 1
	v_cndmask_b32_e32 v4, v238, v4, vcc
	v_cmp_ngt_f32_e32 vcc, -1.0, v6
	s_nop 1
	v_cndmask_b32_e32 v4, v239, v4, vcc
	v_cmp_neq_f32_e32 vcc, -1.0, v6
	s_nop 1
	v_cndmask_b32_e32 v4, v240, v4, vcc
	v_cmp_lt_f32_e64 vcc, |v6|, s10
	s_nop 1
	v_cndmask_b32_e32 v4, v4, v6, vcc
	v_add_f32_e32 v4, v8, v4
	v_sub_f32_e32 v4, -0.5, v4
	v_mul_f32_e32 v4, 0x3fb8aa3b, v4
	v_exp_f32_e32 v5, v4
	v_mul_f32_e32 v4, 0xbfb8aa3b, v7
	v_exp_f32_e32 v4, v4
	ds_read_b128 v[6:9], v12 offset:48
	v_mul_f32_e32 v5, 0xbfb8aa3b, v5
	v_exp_f32_e32 v5, v5
	ds_write_b128 v75, v[2:5] offset:32
	ds_read_b128 v[2:5], v74 offset:48
	s_waitcnt lgkmcnt(0)
; template <int MODE, bool BIG = false> DI void gemm_tile(const Params& p, int tm, int tn, int kv, char* smem) {
;     ...
;       float4 v = crow4[c4], ww = w04[c4];
;       float u[4] = {v.x + ww.x, v.y + ww.y, v.z + ww.z, v.w + ww.w};
; #pragma unroll
;       for (int e = 0; e < 4; ++e) {
;         const float z = -u[e];
;         const float sp = fmaxf(z, 0.f) + log1pf(__expf(-fabsf(z)));
;         u[e] = __expf(-__expf(-sp - 0.5f));
;       }
	v_add_f32_e32 v2, v6, v2
	v_mul_f32_e64 v6, |v2|, s7
	v_exp_f32_e32 v6, v6
	v_add_f32_e32 v4, v8, v4
	v_max_f32_e64 v8, -v2, 0
	v_add_f32_e32 v7, v7, v3
	v_add_f32_e32 v13, 1.0, v6
	v_add_f32_e32 v2, -1.0, v13
	v_sub_f32_e32 v3, v2, v13
	v_add_f32_e32 v3, 1.0, v3
	v_sub_f32_e32 v2, v6, v2
	v_add_f32_e32 v14, v2, v3
	v_frexp_mant_f32_e32 v2, v13
	v_cmp_gt_f32_e32 vcc, s8, v2
	v_cvt_f64_f32_e32 v[2:3], v13
	v_frexp_exp_i32_f64_e32 v2, v[2:3]
	v_subbrev_co_u32_e32 v2, vcc, 0, v2, vcc
	v_sub_u32_e32 v3, 0, v2
	v_ldexp_f32 v13, v13, v3
	v_ldexp_f32 v3, v14, v3
	v_add_f32_e32 v14, -1.0, v13
	v_add_f32_e32 v17, 1.0, v13
	v_add_f32_e32 v15, 1.0, v14
	v_add_f32_e32 v18, -1.0, v17
	v_sub_f32_e32 v15, v13, v15
	v_sub_f32_e32 v13, v13, v18
	v_add_f32_e32 v15, v3, v15
	v_add_f32_e32 v3, v3, v13
	v_add_f32_e32 v13, v17, v3
	v_rcp_f32_e32 v18, v13
	v_add_f32_e32 v16, v14, v15
	v_sub_f32_e32 v14, v16, v14
	v_sub_f32_e32 v14, v15, v14
	v_sub_f32_e32 v15, v13, v17
	v_sub_f32_e32 v3, v3, v15
	v_mul_f32_e32 v15, v16, v18
	v_mul_f32_e32 v17, v13, v15
	v_fma_f32 v19, v15, v13, -v17
	v_fmac_f32_e32 v19, v15, v3
	v_add_f32_e32 v20, v17, v19
	v_sub_f32_e32 v21, v16, v20
	v_sub_f32_e32 v16, v16, v21
	v_sub_f32_e32 v17, v20, v17
	v_sub_f32_e32 v16, v16, v20
	v_add_f32_e32 v14, v14, v16
	v_sub_f32_e32 v16, v17, v19
	v_add_f32_e32 v14, v16, v14
	v_add_f32_e32 v16, v21, v14
	v_mul_f32_e32 v17, v18, v16
	v_mul_f32_e32 v19, v13, v17
	v_fma_f32 v13, v17, v13, -v19
	v_fmac_f32_e32 v13, v17, v3
	v_sub_f32_e32 v3, v21, v16
	v_add_f32_e32 v3, v14, v3
	v_add_f32_e32 v14, v19, v13
	v_sub_f32_e32 v20, v16, v14
	v_sub_f32_e32 v16, v16, v20
	v_sub_f32_e32 v19, v14, v19
	v_sub_f32_e32 v14, v16, v14
	v_add_f32_e32 v3, v3, v14
	v_sub_f32_e32 v13, v19, v13
	v_cvt_f32_i32_e32 v2, v2
	v_add_f32_e32 v3, v13, v3
	v_add_f32_e32 v13, v15, v17
	v_add_f32_e32 v3, v20, v3
	v_sub_f32_e32 v14, v13, v15
	v_mul_f32_e32 v3, v18, v3
	v_sub_f32_e32 v14, v17, v14
	v_add_f32_e32 v3, v14, v3
	v_mul_f32_e32 v17, 0x3f317218, v2
	v_add_f32_e32 v14, v13, v3
	v_fma_f32 v18, v2, s9, -v17
	v_mul_f32_e32 v15, v14, v14
	v_fmac_f32_e32 v18, 0xb102e308, v2
	v_sub_f32_e32 v2, v14, v13
	v_fmamk_f32 v16, v15, 0x3e9b6dac, v231
	v_sub_f32_e32 v2, v3, v2
	v_add_f32_e32 v3, v17, v18
	v_fmaak_f32 v16, v15, v16, 0x3f2aaada
	v_sub_f32_e32 v13, v3, v17
	v_ldexp_f32 v17, v14, 1
	v_mul_f32_e32 v14, v14, v15
	v_mul_f32_e32 v14, v14, v16
	v_add_f32_e32 v15, v17, v14
	v_sub_f32_e32 v16, v15, v17
	v_ldexp_f32 v2, v2, 1
	v_sub_f32_e32 v14, v14, v16
	v_add_f32_e32 v2, v2, v14
	v_add_f32_e32 v14, v15, v2
	v_sub_f32_e32 v15, v14, v15
	v_sub_f32_e32 v2, v2, v15
	v_add_f32_e32 v15, v3, v14
	v_sub_f32_e32 v16, v15, v3
	v_sub_f32_e32 v17, v15, v16
	v_sub_f32_e32 v13, v18, v13
	v_sub_f32_e32 v3, v3, v17
	v_sub_f32_e32 v14, v14, v16
	v_add_f32_e32 v3, v14, v3
	v_add_f32_e32 v14, v13, v2
	v_sub_f32_e32 v16, v14, v13
	v_sub_f32_e32 v17, v14, v16
	v_sub_f32_e32 v13, v13, v17
	v_sub_f32_e32 v2, v2, v16
	v_add_f32_e32 v3, v14, v3
	v_add_f32_e32 v2, v2, v13
	v_add_f32_e32 v13, v15, v3
	v_sub_f32_e32 v14, v13, v15
	v_sub_f32_e32 v3, v3, v14
	v_add_f32_e32 v2, v2, v3
	v_add_f32_e32 v2, v13, v2
	v_cmp_neq_f32_e32 vcc, s6, v6
	v_mul_f32_e64 v3, |v7|, s7
	v_max_f32_e64 v7, -v7, 0
	v_cndmask_b32_e32 v2, v238, v2, vcc
	v_cmp_ngt_f32_e32 vcc, -1.0, v6
	s_nop 1
	v_cndmask_b32_e32 v2, v239, v2, vcc
	v_cmp_neq_f32_e32 vcc, -1.0, v6
	s_nop 1
	v_cndmask_b32_e32 v2, v240, v2, vcc
	v_cmp_lt_f32_e64 vcc, |v6|, s10
	s_nop 1
	v_cndmask_b32_e32 v2, v2, v6, vcc
	v_add_f32_e32 v2, v8, v2
	v_sub_f32_e32 v2, -0.5, v2
	v_mul_f32_e32 v2, 0x3fb8aa3b, v2
	v_exp_f32_e32 v6, v3
	v_exp_f32_e32 v2, v2
	v_add_f32_e32 v8, v9, v5
	v_add_f32_e32 v9, 1.0, v6
	v_mul_f32_e32 v5, 0xbfb8aa3b, v2
	v_add_f32_e32 v2, -1.0, v9
	v_sub_f32_e32 v3, v2, v9
	v_add_f32_e32 v3, 1.0, v3
	v_sub_f32_e32 v2, v6, v2
	v_add_f32_e32 v13, v2, v3
	v_frexp_mant_f32_e32 v2, v9
	v_cmp_gt_f32_e32 vcc, s8, v2
	v_cvt_f64_f32_e32 v[2:3], v9
	v_frexp_exp_i32_f64_e32 v2, v[2:3]
	v_subbrev_co_u32_e32 v2, vcc, 0, v2, vcc
	v_sub_u32_e32 v3, 0, v2
	v_ldexp_f32 v9, v9, v3
	v_ldexp_f32 v3, v13, v3
	v_add_f32_e32 v13, -1.0, v9
	v_add_f32_e32 v16, 1.0, v9
	v_add_f32_e32 v14, 1.0, v13
	v_add_f32_e32 v17, -1.0, v16
	v_sub_f32_e32 v14, v9, v14
	v_sub_f32_e32 v9, v9, v17
	v_add_f32_e32 v14, v3, v14
	v_add_f32_e32 v3, v3, v9
	v_add_f32_e32 v9, v16, v3
	v_rcp_f32_e32 v17, v9
	v_add_f32_e32 v15, v13, v14
	v_sub_f32_e32 v13, v15, v13
	v_sub_f32_e32 v13, v14, v13
	v_sub_f32_e32 v14, v9, v16
	v_sub_f32_e32 v3, v3, v14
	v_mul_f32_e32 v14, v15, v17
	v_mul_f32_e32 v16, v9, v14
	v_fma_f32 v18, v14, v9, -v16
	v_fmac_f32_e32 v18, v14, v3
	v_add_f32_e32 v19, v16, v18
	v_sub_f32_e32 v20, v15, v19
	v_sub_f32_e32 v15, v15, v20
	v_sub_f32_e32 v16, v19, v16
	v_sub_f32_e32 v15, v15, v19
	v_add_f32_e32 v13, v13, v15
	v_sub_f32_e32 v15, v16, v18
	v_add_f32_e32 v13, v15, v13
	v_add_f32_e32 v15, v20, v13
	v_mul_f32_e32 v16, v17, v15
	v_mul_f32_e32 v18, v9, v16
	v_fma_f32 v9, v16, v9, -v18
	v_fmac_f32_e32 v9, v16, v3
	v_sub_f32_e32 v3, v20, v15
	v_add_f32_e32 v3, v13, v3
	v_add_f32_e32 v13, v18, v9
	v_sub_f32_e32 v19, v15, v13
	v_sub_f32_e32 v15, v15, v19
	v_sub_f32_e32 v18, v13, v18
	v_sub_f32_e32 v13, v15, v13
	v_add_f32_e32 v3, v3, v13
	v_sub_f32_e32 v9, v18, v9
	v_cvt_f32_i32_e32 v2, v2
	v_add_f32_e32 v3, v9, v3
	v_add_f32_e32 v9, v14, v16
	v_add_f32_e32 v3, v19, v3
	v_sub_f32_e32 v13, v9, v14
	v_mul_f32_e32 v3, v17, v3
	v_sub_f32_e32 v13, v16, v13
	v_add_f32_e32 v3, v13, v3
	v_mul_f32_e32 v16, 0x3f317218, v2
	v_add_f32_e32 v13, v9, v3
	v_fma_f32 v17, v2, s9, -v16
	v_mul_f32_e32 v14, v13, v13
	v_fmac_f32_e32 v17, 0xb102e308, v2
; template <int MODE, bool BIG = false> DI void gemm_tile(const Params& p, int tm, int tn, int kv, char* smem) {
;     ...
;       for (int e = 0; e < 4; ++e) {
;         const float z = -u[e];
;         const float sp = fmaxf(z, 0.f) + log1pf(__expf(-fabsf(z)));
;         u[e] = __expf(-__expf(-sp - 0.5f));
;       }
	v_sub_f32_e32 v2, v13, v9
	v_fmamk_f32 v15, v14, 0x3e9b6dac, v231
	v_sub_f32_e32 v2, v3, v2
	v_add_f32_e32 v3, v16, v17
	v_fmaak_f32 v15, v14, v15, 0x3f2aaada
	v_sub_f32_e32 v9, v3, v16
	v_ldexp_f32 v16, v13, 1
	v_mul_f32_e32 v13, v13, v14
	v_mul_f32_e32 v13, v13, v15
	v_add_f32_e32 v14, v16, v13
	v_sub_f32_e32 v15, v14, v16
	v_ldexp_f32 v2, v2, 1
	v_sub_f32_e32 v13, v13, v15
	v_add_f32_e32 v2, v2, v13
	v_add_f32_e32 v13, v14, v2
	v_sub_f32_e32 v14, v13, v14
	v_sub_f32_e32 v2, v2, v14
	v_add_f32_e32 v14, v3, v13
	v_sub_f32_e32 v15, v14, v3
	v_sub_f32_e32 v16, v14, v15
	v_sub_f32_e32 v9, v17, v9
	v_sub_f32_e32 v3, v3, v16
	v_sub_f32_e32 v13, v13, v15
	v_add_f32_e32 v3, v13, v3
	v_add_f32_e32 v13, v9, v2
	v_sub_f32_e32 v15, v13, v9
	v_sub_f32_e32 v16, v13, v15
	v_sub_f32_e32 v9, v9, v16
	v_sub_f32_e32 v2, v2, v15
	v_add_f32_e32 v3, v13, v3
	v_add_f32_e32 v2, v2, v9
	v_add_f32_e32 v9, v14, v3
	v_sub_f32_e32 v13, v9, v14
	v_sub_f32_e32 v3, v3, v13
	v_add_f32_e32 v2, v2, v3
	v_add_f32_e32 v2, v9, v2
	v_cmp_neq_f32_e32 vcc, s6, v6
	s_nop 1
	v_cndmask_b32_e32 v2, v238, v2, vcc
	v_cmp_ngt_f32_e32 vcc, -1.0, v6
	s_nop 1
	v_cndmask_b32_e32 v2, v239, v2, vcc
	v_cmp_neq_f32_e32 vcc, -1.0, v6
	s_nop 1
	v_cndmask_b32_e32 v2, v240, v2, vcc
	v_cmp_lt_f32_e64 vcc, |v6|, s10
	s_nop 1
	v_cndmask_b32_e32 v2, v2, v6, vcc
	v_add_f32_e32 v2, v7, v2
	v_sub_f32_e32 v2, -0.5, v2
	v_mul_f32_e32 v2, 0x3fb8aa3b, v2
	v_exp_f32_e32 v3, v2
	v_mul_f32_e64 v2, |v4|, s7
	v_exp_f32_e32 v6, v2
	v_max_f32_e64 v7, -v4, 0
	v_exp_f32_e32 v2, v5
	v_mul_f32_e32 v3, 0xbfb8aa3b, v3
	v_add_f32_e32 v9, 1.0, v6
	v_add_f32_e32 v4, -1.0, v9
	v_sub_f32_e32 v5, v4, v9
	v_add_f32_e32 v5, 1.0, v5
	v_sub_f32_e32 v4, v6, v4
	v_add_f32_e32 v13, v4, v5
	v_frexp_mant_f32_e32 v4, v9
	v_cmp_gt_f32_e32 vcc, s8, v4
	v_cvt_f64_f32_e32 v[4:5], v9
	v_frexp_exp_i32_f64_e32 v4, v[4:5]
	v_subbrev_co_u32_e32 v4, vcc, 0, v4, vcc
	v_sub_u32_e32 v5, 0, v4
	v_ldexp_f32 v9, v9, v5
	v_ldexp_f32 v5, v13, v5
	v_add_f32_e32 v13, -1.0, v9
	v_add_f32_e32 v16, 1.0, v9
	v_add_f32_e32 v14, 1.0, v13
	v_add_f32_e32 v17, -1.0, v16
	v_sub_f32_e32 v14, v9, v14
	v_sub_f32_e32 v9, v9, v17
	v_add_f32_e32 v14, v5, v14
	v_add_f32_e32 v5, v5, v9
	v_add_f32_e32 v9, v16, v5
	v_rcp_f32_e32 v17, v9
	v_add_f32_e32 v15, v13, v14
	v_sub_f32_e32 v13, v15, v13
	v_sub_f32_e32 v13, v14, v13
	v_sub_f32_e32 v14, v9, v16
	v_sub_f32_e32 v5, v5, v14
	v_mul_f32_e32 v14, v15, v17
	v_mul_f32_e32 v16, v9, v14
	v_fma_f32 v18, v14, v9, -v16
	v_fmac_f32_e32 v18, v14, v5
	v_add_f32_e32 v19, v16, v18
	v_sub_f32_e32 v20, v15, v19
	v_sub_f32_e32 v15, v15, v20
	v_sub_f32_e32 v16, v19, v16
	v_sub_f32_e32 v15, v15, v19
	v_add_f32_e32 v13, v13, v15
	v_sub_f32_e32 v15, v16, v18
	v_add_f32_e32 v13, v15, v13
	v_add_f32_e32 v15, v20, v13
	v_mul_f32_e32 v16, v17, v15
	v_mul_f32_e32 v18, v9, v16
	v_fma_f32 v9, v16, v9, -v18
	v_fmac_f32_e32 v9, v16, v5
	v_sub_f32_e32 v5, v20, v15
	v_add_f32_e32 v5, v13, v5
	v_add_f32_e32 v13, v18, v9
	v_sub_f32_e32 v19, v15, v13
	v_sub_f32_e32 v15, v15, v19
	v_sub_f32_e32 v18, v13, v18
	v_sub_f32_e32 v13, v15, v13
	v_add_f32_e32 v5, v5, v13
	v_sub_f32_e32 v9, v18, v9
	v_cvt_f32_i32_e32 v4, v4
	v_add_f32_e32 v5, v9, v5
	v_add_f32_e32 v9, v14, v16
	v_add_f32_e32 v5, v19, v5
	v_sub_f32_e32 v13, v9, v14
	v_mul_f32_e32 v5, v17, v5
	v_sub_f32_e32 v13, v16, v13
	v_add_f32_e32 v5, v13, v5
	v_mul_f32_e32 v16, 0x3f317218, v4
	v_add_f32_e32 v13, v9, v5
	v_fma_f32 v17, v4, s9, -v16
	v_mul_f32_e32 v14, v13, v13
	v_fmac_f32_e32 v17, 0xb102e308, v4
	v_sub_f32_e32 v4, v13, v9
	v_fmamk_f32 v15, v14, 0x3e9b6dac, v231
	v_sub_f32_e32 v4, v5, v4
	v_add_f32_e32 v5, v16, v17
	v_fmaak_f32 v15, v14, v15, 0x3f2aaada
	v_sub_f32_e32 v9, v5, v16
	v_ldexp_f32 v16, v13, 1
	v_mul_f32_e32 v13, v13, v14
	v_mul_f32_e32 v13, v13, v15
	v_add_f32_e32 v14, v16, v13
	v_sub_f32_e32 v15, v14, v16
	v_ldexp_f32 v4, v4, 1
	v_sub_f32_e32 v13, v13, v15
	v_add_f32_e32 v4, v4, v13
	v_add_f32_e32 v13, v14, v4
	v_sub_f32_e32 v14, v13, v14
	v_sub_f32_e32 v4, v4, v14
	v_add_f32_e32 v14, v5, v13
	v_sub_f32_e32 v15, v14, v5
	v_sub_f32_e32 v16, v14, v15
	v_sub_f32_e32 v9, v17, v9
	v_sub_f32_e32 v5, v5, v16
	v_sub_f32_e32 v13, v13, v15
	v_add_f32_e32 v5, v13, v5
	v_add_f32_e32 v13, v9, v4
	v_sub_f32_e32 v15, v13, v9
	v_sub_f32_e32 v16, v13, v15
	v_sub_f32_e32 v9, v9, v16
	v_sub_f32_e32 v4, v4, v15
	v_add_f32_e32 v5, v13, v5
	v_add_f32_e32 v4, v4, v9
	v_add_f32_e32 v9, v14, v5
	v_sub_f32_e32 v13, v9, v14
	v_sub_f32_e32 v5, v5, v13
	v_add_f32_e32 v4, v4, v5
	v_add_f32_e32 v4, v9, v4
	v_cmp_neq_f32_e32 vcc, s6, v6
	v_mul_f32_e64 v5, |v8|, s7
	v_max_f32_e64 v8, -v8, 0
	v_cndmask_b32_e32 v4, v238, v4, vcc
	v_cmp_ngt_f32_e32 vcc, -1.0, v6
	v_exp_f32_e32 v3, v3
	s_nop 0
	v_cndmask_b32_e32 v4, v239, v4, vcc
	v_cmp_neq_f32_e32 vcc, -1.0, v6
	s_nop 1
	v_cndmask_b32_e32 v4, v240, v4, vcc
	v_cmp_lt_f32_e64 vcc, |v6|, s10
	s_nop 1
	v_cndmask_b32_e32 v4, v4, v6, vcc
	v_exp_f32_e32 v6, v5
	v_add_f32_e32 v4, v7, v4
	v_sub_f32_e32 v4, -0.5, v4
	v_mul_f32_e32 v4, 0x3fb8aa3b, v4
	v_add_f32_e32 v9, 1.0, v6
	v_exp_f32_e32 v7, v4
	v_add_f32_e32 v4, -1.0, v9
	v_sub_f32_e32 v5, v4, v9
	v_add_f32_e32 v5, 1.0, v5
	v_sub_f32_e32 v4, v6, v4
	v_add_f32_e32 v13, v4, v5
	v_frexp_mant_f32_e32 v4, v9
	v_cmp_gt_f32_e32 vcc, s8, v4
	v_cvt_f64_f32_e32 v[4:5], v9
	v_frexp_exp_i32_f64_e32 v4, v[4:5]
	v_subbrev_co_u32_e32 v4, vcc, 0, v4, vcc
	v_sub_u32_e32 v5, 0, v4
	v_ldexp_f32 v9, v9, v5
	v_ldexp_f32 v5, v13, v5
	v_add_f32_e32 v13, -1.0, v9
	v_add_f32_e32 v16, 1.0, v9
	v_add_f32_e32 v14, 1.0, v13
	v_add_f32_e32 v17, -1.0, v16
	v_sub_f32_e32 v14, v9, v14
	v_sub_f32_e32 v9, v9, v17
	v_add_f32_e32 v14, v5, v14
	v_add_f32_e32 v5, v5, v9
; template <int MODE, bool BIG = false> DI void gemm_tile(const Params& p, int tm, int tn, int kv, char* smem) {
;     ...
;     for (int c4 = 0; c4 < 16; ++c4) {
;       float4 v = crow4[c4], ww = w04[c4];
;       float u[4] = {v.x + ww.x, v.y + ww.y, v.z + ww.z, v.w + ww.w};
; #pragma unroll
;       for (int e = 0; e < 4; ++e) {
;         const float z = -u[e];
;         const float sp = fmaxf(z, 0.f) + log1pf(__expf(-fabsf(z)));
;         u[e] = __expf(-__expf(-sp - 0.5f));
;       }
;       W4[c4] = make_float4(u[0], u[1], u[2], u[3]);
	v_add_f32_e32 v9, v16, v5
	v_rcp_f32_e32 v17, v9
	v_add_f32_e32 v15, v13, v14
	v_sub_f32_e32 v13, v15, v13
	v_sub_f32_e32 v13, v14, v13
	v_sub_f32_e32 v14, v9, v16
	v_sub_f32_e32 v5, v5, v14
	v_mul_f32_e32 v14, v15, v17
	v_mul_f32_e32 v16, v9, v14
	v_fma_f32 v18, v14, v9, -v16
	v_fmac_f32_e32 v18, v14, v5
	v_add_f32_e32 v19, v16, v18
	v_sub_f32_e32 v20, v15, v19
	v_sub_f32_e32 v15, v15, v20
	v_sub_f32_e32 v16, v19, v16
	v_sub_f32_e32 v15, v15, v19
	v_add_f32_e32 v13, v13, v15
	v_sub_f32_e32 v15, v16, v18
	v_add_f32_e32 v13, v15, v13
	v_add_f32_e32 v15, v20, v13
	v_mul_f32_e32 v16, v17, v15
	v_mul_f32_e32 v18, v9, v16
	v_fma_f32 v9, v16, v9, -v18
	v_fmac_f32_e32 v9, v16, v5
	v_sub_f32_e32 v5, v20, v15
	v_add_f32_e32 v5, v13, v5
	v_add_f32_e32 v13, v18, v9
	v_sub_f32_e32 v19, v15, v13
	v_sub_f32_e32 v15, v15, v19
	v_sub_f32_e32 v18, v13, v18
	v_sub_f32_e32 v13, v15, v13
	v_add_f32_e32 v5, v5, v13
	v_sub_f32_e32 v9, v18, v9
	v_cvt_f32_i32_e32 v4, v4
	v_add_f32_e32 v5, v9, v5
	v_add_f32_e32 v9, v14, v16
	v_add_f32_e32 v5, v19, v5
	v_sub_f32_e32 v13, v9, v14
	v_mul_f32_e32 v5, v17, v5
	v_sub_f32_e32 v13, v16, v13
	v_add_f32_e32 v5, v13, v5
	v_mul_f32_e32 v16, 0x3f317218, v4
	v_add_f32_e32 v13, v9, v5
	v_fma_f32 v17, v4, s9, -v16
	v_mul_f32_e32 v14, v13, v13
	v_fmac_f32_e32 v17, 0xb102e308, v4
	v_sub_f32_e32 v4, v13, v9
	v_fmamk_f32 v15, v14, 0x3e9b6dac, v231
	v_sub_f32_e32 v4, v5, v4
	v_add_f32_e32 v5, v16, v17
	v_fmaak_f32 v15, v14, v15, 0x3f2aaada
	v_sub_f32_e32 v9, v5, v16
	v_ldexp_f32 v16, v13, 1
	v_mul_f32_e32 v13, v13, v14
	v_mul_f32_e32 v13, v13, v15
	v_add_f32_e32 v14, v16, v13
	v_sub_f32_e32 v15, v14, v16
	v_ldexp_f32 v4, v4, 1
	v_sub_f32_e32 v13, v13, v15
	v_add_f32_e32 v4, v4, v13
	v_add_f32_e32 v13, v14, v4
	v_sub_f32_e32 v14, v13, v14
	v_sub_f32_e32 v4, v4, v14
	v_add_f32_e32 v14, v5, v13
	v_sub_f32_e32 v15, v14, v5
	v_sub_f32_e32 v16, v14, v15
	v_sub_f32_e32 v9, v17, v9
	v_sub_f32_e32 v5, v5, v16
	v_sub_f32_e32 v13, v13, v15
	v_add_f32_e32 v5, v13, v5
	v_add_f32_e32 v13, v9, v4
	v_sub_f32_e32 v15, v13, v9
	v_sub_f32_e32 v16, v13, v15
	v_sub_f32_e32 v9, v9, v16
	v_sub_f32_e32 v4, v4, v15
	v_add_f32_e32 v5, v13, v5
	v_add_f32_e32 v4, v4, v9
	v_add_f32_e32 v9, v14, v5
	v_sub_f32_e32 v13, v9, v14
	v_sub_f32_e32 v5, v5, v13
	v_add_f32_e32 v4, v4, v5
	v_add_f32_e32 v4, v9, v4
	v_cmp_neq_f32_e32 vcc, s6, v6
	s_nop 1
	v_cndmask_b32_e32 v4, v238, v4, vcc
	v_cmp_ngt_f32_e32 vcc, -1.0, v6
	s_nop 1
	v_cndmask_b32_e32 v4, v239, v4, vcc
	v_cmp_neq_f32_e32 vcc, -1.0, v6
	s_nop 1
	v_cndmask_b32_e32 v4, v240, v4, vcc
	v_cmp_lt_f32_e64 vcc, |v6|, s10
	s_nop 1
	v_cndmask_b32_e32 v4, v4, v6, vcc
	v_add_f32_e32 v4, v8, v4
	v_sub_f32_e32 v4, -0.5, v4
	v_mul_f32_e32 v4, 0x3fb8aa3b, v4
	v_exp_f32_e32 v5, v4
	v_mul_f32_e32 v4, 0xbfb8aa3b, v7
	v_exp_f32_e32 v4, v4
	ds_read_b128 v[6:9], v12 offset:64
	v_mul_f32_e32 v5, 0xbfb8aa3b, v5
	v_exp_f32_e32 v5, v5
	ds_write_b128 v75, v[2:5] offset:48
	ds_read_b128 v[2:5], v74 offset:64
	s_waitcnt lgkmcnt(0)
	v_add_f32_e32 v2, v6, v2
	v_mul_f32_e64 v6, |v2|, s7
	v_exp_f32_e32 v6, v6
	v_add_f32_e32 v4, v8, v4
	v_max_f32_e64 v8, -v2, 0
	v_add_f32_e32 v7, v7, v3
	v_add_f32_e32 v13, 1.0, v6
	v_add_f32_e32 v2, -1.0, v13
	v_sub_f32_e32 v3, v2, v13
	v_add_f32_e32 v3, 1.0, v3
	v_sub_f32_e32 v2, v6, v2
	v_add_f32_e32 v14, v2, v3
	v_frexp_mant_f32_e32 v2, v13
	v_cmp_gt_f32_e32 vcc, s8, v2
	v_cvt_f64_f32_e32 v[2:3], v13
	v_frexp_exp_i32_f64_e32 v2, v[2:3]
	v_subbrev_co_u32_e32 v2, vcc, 0, v2, vcc
	v_sub_u32_e32 v3, 0, v2
	v_ldexp_f32 v13, v13, v3
	v_ldexp_f32 v3, v14, v3
	v_add_f32_e32 v14, -1.0, v13
	v_add_f32_e32 v17, 1.0, v13
	v_add_f32_e32 v15, 1.0, v14
	v_add_f32_e32 v18, -1.0, v17
	v_sub_f32_e32 v15, v13, v15
	v_sub_f32_e32 v13, v13, v18
	v_add_f32_e32 v15, v3, v15
	v_add_f32_e32 v3, v3, v13
	v_add_f32_e32 v13, v17, v3
	v_rcp_f32_e32 v18, v13
	v_add_f32_e32 v16, v14, v15
	v_sub_f32_e32 v14, v16, v14
	v_sub_f32_e32 v14, v15, v14
	v_sub_f32_e32 v15, v13, v17
	v_sub_f32_e32 v3, v3, v15
	v_mul_f32_e32 v15, v16, v18
	v_mul_f32_e32 v17, v13, v15
	v_fma_f32 v19, v15, v13, -v17
	v_fmac_f32_e32 v19, v15, v3
	v_add_f32_e32 v20, v17, v19
	v_sub_f32_e32 v21, v16, v20
	v_sub_f32_e32 v16, v16, v21
	v_sub_f32_e32 v17, v20, v17
	v_sub_f32_e32 v16, v16, v20
	v_add_f32_e32 v14, v14, v16
	v_sub_f32_e32 v16, v17, v19
	v_add_f32_e32 v14, v16, v14
	v_add_f32_e32 v16, v21, v14
	v_mul_f32_e32 v17, v18, v16
	v_mul_f32_e32 v19, v13, v17
	v_fma_f32 v13, v17, v13, -v19
	v_fmac_f32_e32 v13, v17, v3
	v_sub_f32_e32 v3, v21, v16
	v_add_f32_e32 v3, v14, v3
	v_add_f32_e32 v14, v19, v13
	v_sub_f32_e32 v20, v16, v14
	v_sub_f32_e32 v16, v16, v20
	v_sub_f32_e32 v19, v14, v19
	v_sub_f32_e32 v14, v16, v14
	v_add_f32_e32 v3, v3, v14
	v_sub_f32_e32 v13, v19, v13
	v_cvt_f32_i32_e32 v2, v2
	v_add_f32_e32 v3, v13, v3
	v_add_f32_e32 v13, v15, v17
	v_add_f32_e32 v3, v20, v3
	v_sub_f32_e32 v14, v13, v15
	v_mul_f32_e32 v3, v18, v3
	v_sub_f32_e32 v14, v17, v14
	v_add_f32_e32 v3, v14, v3
	v_mul_f32_e32 v17, 0x3f317218, v2
	v_add_f32_e32 v14, v13, v3
	v_fma_f32 v18, v2, s9, -v17
	v_mul_f32_e32 v15, v14, v14
	v_fmac_f32_e32 v18, 0xb102e308, v2
	v_sub_f32_e32 v2, v14, v13
	v_fmamk_f32 v16, v15, 0x3e9b6dac, v231
	v_sub_f32_e32 v2, v3, v2
	v_add_f32_e32 v3, v17, v18
	v_fmaak_f32 v16, v15, v16, 0x3f2aaada
	v_sub_f32_e32 v13, v3, v17
	v_ldexp_f32 v17, v14, 1
	v_mul_f32_e32 v14, v14, v15
	v_mul_f32_e32 v14, v14, v16
	v_add_f32_e32 v15, v17, v14
	v_sub_f32_e32 v16, v15, v17
	v_ldexp_f32 v2, v2, 1
	v_sub_f32_e32 v14, v14, v16
	v_add_f32_e32 v2, v2, v14
	v_add_f32_e32 v14, v15, v2
	v_sub_f32_e32 v15, v14, v15
	v_sub_f32_e32 v2, v2, v15
	v_add_f32_e32 v15, v3, v14
; template <int MODE, bool BIG = false> DI void gemm_tile(const Params& p, int tm, int tn, int kv, char* smem) {
;     ...
;       for (int e = 0; e < 4; ++e) {
;         const float z = -u[e];
;         const float sp = fmaxf(z, 0.f) + log1pf(__expf(-fabsf(z)));
;         u[e] = __expf(-__expf(-sp - 0.5f));
;       }
	v_sub_f32_e32 v16, v15, v3
	v_sub_f32_e32 v17, v15, v16
	v_sub_f32_e32 v13, v18, v13
	v_sub_f32_e32 v3, v3, v17
	v_sub_f32_e32 v14, v14, v16
	v_add_f32_e32 v3, v14, v3
	v_add_f32_e32 v14, v13, v2
	v_sub_f32_e32 v16, v14, v13
	v_sub_f32_e32 v17, v14, v16
	v_sub_f32_e32 v13, v13, v17
	v_sub_f32_e32 v2, v2, v16
	v_add_f32_e32 v3, v14, v3
	v_add_f32_e32 v2, v2, v13
	v_add_f32_e32 v13, v15, v3
	v_sub_f32_e32 v14, v13, v15
	v_sub_f32_e32 v3, v3, v14
	v_add_f32_e32 v2, v2, v3
	v_add_f32_e32 v2, v13, v2
	v_cmp_neq_f32_e32 vcc, s6, v6
	v_mul_f32_e64 v3, |v7|, s7
	v_max_f32_e64 v7, -v7, 0
	v_cndmask_b32_e32 v2, v238, v2, vcc
	v_cmp_ngt_f32_e32 vcc, -1.0, v6
	s_nop 1
	v_cndmask_b32_e32 v2, v239, v2, vcc
	v_cmp_neq_f32_e32 vcc, -1.0, v6
	s_nop 1
	v_cndmask_b32_e32 v2, v240, v2, vcc
	v_cmp_lt_f32_e64 vcc, |v6|, s10
	s_nop 1
	v_cndmask_b32_e32 v2, v2, v6, vcc
	v_add_f32_e32 v2, v8, v2
	v_sub_f32_e32 v2, -0.5, v2
	v_mul_f32_e32 v2, 0x3fb8aa3b, v2
	v_exp_f32_e32 v6, v3
	v_exp_f32_e32 v2, v2
	v_add_f32_e32 v8, v9, v5
	v_add_f32_e32 v9, 1.0, v6
	v_mul_f32_e32 v5, 0xbfb8aa3b, v2
	v_add_f32_e32 v2, -1.0, v9
	v_sub_f32_e32 v3, v2, v9
	v_add_f32_e32 v3, 1.0, v3
	v_sub_f32_e32 v2, v6, v2
	v_add_f32_e32 v13, v2, v3
	v_frexp_mant_f32_e32 v2, v9
	v_cmp_gt_f32_e32 vcc, s8, v2
	v_cvt_f64_f32_e32 v[2:3], v9
	v_frexp_exp_i32_f64_e32 v2, v[2:3]
	v_subbrev_co_u32_e32 v2, vcc, 0, v2, vcc
	v_sub_u32_e32 v3, 0, v2
	v_ldexp_f32 v9, v9, v3
	v_ldexp_f32 v3, v13, v3
	v_add_f32_e32 v13, -1.0, v9
	v_add_f32_e32 v16, 1.0, v9
	v_add_f32_e32 v14, 1.0, v13
	v_add_f32_e32 v17, -1.0, v16
	v_sub_f32_e32 v14, v9, v14
	v_sub_f32_e32 v9, v9, v17
	v_add_f32_e32 v14, v3, v14
	v_add_f32_e32 v3, v3, v9
	v_add_f32_e32 v9, v16, v3
	v_rcp_f32_e32 v17, v9
	v_add_f32_e32 v15, v13, v14
	v_sub_f32_e32 v13, v15, v13
	v_sub_f32_e32 v13, v14, v13
	v_sub_f32_e32 v14, v9, v16
	v_sub_f32_e32 v3, v3, v14
	v_mul_f32_e32 v14, v15, v17
	v_mul_f32_e32 v16, v9, v14
	v_fma_f32 v18, v14, v9, -v16
	v_fmac_f32_e32 v18, v14, v3
	v_add_f32_e32 v19, v16, v18
	v_sub_f32_e32 v20, v15, v19
	v_sub_f32_e32 v15, v15, v20
	v_sub_f32_e32 v16, v19, v16
	v_sub_f32_e32 v15, v15, v19
	v_add_f32_e32 v13, v13, v15
	v_sub_f32_e32 v15, v16, v18
	v_add_f32_e32 v13, v15, v13
	v_add_f32_e32 v15, v20, v13
	v_mul_f32_e32 v16, v17, v15
	v_mul_f32_e32 v18, v9, v16
	v_fma_f32 v9, v16, v9, -v18
	v_fmac_f32_e32 v9, v16, v3
	v_sub_f32_e32 v3, v20, v15
	v_add_f32_e32 v3, v13, v3
	v_add_f32_e32 v13, v18, v9
	v_sub_f32_e32 v19, v15, v13
	v_sub_f32_e32 v15, v15, v19
	v_sub_f32_e32 v18, v13, v18
	v_sub_f32_e32 v13, v15, v13
	v_add_f32_e32 v3, v3, v13
	v_sub_f32_e32 v9, v18, v9
	v_cvt_f32_i32_e32 v2, v2
	v_add_f32_e32 v3, v9, v3
	v_add_f32_e32 v9, v14, v16
	v_add_f32_e32 v3, v19, v3
	v_sub_f32_e32 v13, v9, v14
	v_mul_f32_e32 v3, v17, v3
	v_sub_f32_e32 v13, v16, v13
	v_add_f32_e32 v3, v13, v3
	v_mul_f32_e32 v16, 0x3f317218, v2
	v_add_f32_e32 v13, v9, v3
	v_fma_f32 v17, v2, s9, -v16
	v_mul_f32_e32 v14, v13, v13
	v_fmac_f32_e32 v17, 0xb102e308, v2
	v_sub_f32_e32 v2, v13, v9
	v_fmamk_f32 v15, v14, 0x3e9b6dac, v231
	v_sub_f32_e32 v2, v3, v2
	v_add_f32_e32 v3, v16, v17
	v_fmaak_f32 v15, v14, v15, 0x3f2aaada
	v_sub_f32_e32 v9, v3, v16
	v_ldexp_f32 v16, v13, 1
	v_mul_f32_e32 v13, v13, v14
	v_mul_f32_e32 v13, v13, v15
	v_add_f32_e32 v14, v16, v13
	v_sub_f32_e32 v15, v14, v16
	v_ldexp_f32 v2, v2, 1
	v_sub_f32_e32 v13, v13, v15
	v_add_f32_e32 v2, v2, v13
	v_add_f32_e32 v13, v14, v2
	v_sub_f32_e32 v14, v13, v14
	v_sub_f32_e32 v2, v2, v14
	v_add_f32_e32 v14, v3, v13
	v_sub_f32_e32 v15, v14, v3
	v_sub_f32_e32 v16, v14, v15
	v_sub_f32_e32 v9, v17, v9
	v_sub_f32_e32 v3, v3, v16
	v_sub_f32_e32 v13, v13, v15
	v_add_f32_e32 v3, v13, v3
	v_add_f32_e32 v13, v9, v2
	v_sub_f32_e32 v15, v13, v9
	v_sub_f32_e32 v16, v13, v15
	v_sub_f32_e32 v9, v9, v16
	v_sub_f32_e32 v2, v2, v15
	v_add_f32_e32 v3, v13, v3
	v_add_f32_e32 v2, v2, v9
	v_add_f32_e32 v9, v14, v3
	v_sub_f32_e32 v13, v9, v14
	v_sub_f32_e32 v3, v3, v13
	v_add_f32_e32 v2, v2, v3
	v_add_f32_e32 v2, v9, v2
	v_cmp_neq_f32_e32 vcc, s6, v6
	s_nop 1
	v_cndmask_b32_e32 v2, v238, v2, vcc
	v_cmp_ngt_f32_e32 vcc, -1.0, v6
	s_nop 1
	v_cndmask_b32_e32 v2, v239, v2, vcc
	v_cmp_neq_f32_e32 vcc, -1.0, v6
	s_nop 1
	v_cndmask_b32_e32 v2, v240, v2, vcc
	v_cmp_lt_f32_e64 vcc, |v6|, s10
	s_nop 1
	v_cndmask_b32_e32 v2, v2, v6, vcc
	v_add_f32_e32 v2, v7, v2
	v_sub_f32_e32 v2, -0.5, v2
	v_mul_f32_e32 v2, 0x3fb8aa3b, v2
	v_exp_f32_e32 v3, v2
	v_mul_f32_e64 v2, |v4|, s7
	v_exp_f32_e32 v6, v2
	v_max_f32_e64 v7, -v4, 0
	v_exp_f32_e32 v2, v5
	v_mul_f32_e32 v3, 0xbfb8aa3b, v3
	v_add_f32_e32 v9, 1.0, v6
	v_add_f32_e32 v4, -1.0, v9
	v_sub_f32_e32 v5, v4, v9
	v_add_f32_e32 v5, 1.0, v5
	v_sub_f32_e32 v4, v6, v4
	v_add_f32_e32 v13, v4, v5
	v_frexp_mant_f32_e32 v4, v9
	v_cmp_gt_f32_e32 vcc, s8, v4
	v_cvt_f64_f32_e32 v[4:5], v9
	v_frexp_exp_i32_f64_e32 v4, v[4:5]
	v_subbrev_co_u32_e32 v4, vcc, 0, v4, vcc
	v_sub_u32_e32 v5, 0, v4
	v_ldexp_f32 v9, v9, v5
	v_ldexp_f32 v5, v13, v5
	v_add_f32_e32 v13, -1.0, v9
	v_add_f32_e32 v16, 1.0, v9
	v_add_f32_e32 v14, 1.0, v13
	v_add_f32_e32 v17, -1.0, v16
	v_sub_f32_e32 v14, v9, v14
	v_sub_f32_e32 v9, v9, v17
	v_add_f32_e32 v14, v5, v14
	v_add_f32_e32 v5, v5, v9
	v_add_f32_e32 v9, v16, v5
	v_rcp_f32_e32 v17, v9
	v_add_f32_e32 v15, v13, v14
	v_sub_f32_e32 v13, v15, v13
	v_sub_f32_e32 v13, v14, v13
	v_sub_f32_e32 v14, v9, v16
	v_sub_f32_e32 v5, v5, v14
	v_mul_f32_e32 v14, v15, v17
	v_mul_f32_e32 v16, v9, v14
	v_fma_f32 v18, v14, v9, -v16
	v_fmac_f32_e32 v18, v14, v5
	v_add_f32_e32 v19, v16, v18
	v_sub_f32_e32 v20, v15, v19
	v_sub_f32_e32 v15, v15, v20
	v_sub_f32_e32 v16, v19, v16
	v_sub_f32_e32 v15, v15, v19
; template <int MODE, bool BIG = false> DI void gemm_tile(const Params& p, int tm, int tn, int kv, char* smem) {
;     ...
;     for (int c4 = 0; c4 < 16; ++c4) {
;       float4 v = crow4[c4], ww = w04[c4];
;       float u[4] = {v.x + ww.x, v.y + ww.y, v.z + ww.z, v.w + ww.w};
; #pragma unroll
;       for (int e = 0; e < 4; ++e) {
;         const float z = -u[e];
;         const float sp = fmaxf(z, 0.f) + log1pf(__expf(-fabsf(z)));
;         u[e] = __expf(-__expf(-sp - 0.5f));
;       }
;       W4[c4] = make_float4(u[0], u[1], u[2], u[3]);
	v_add_f32_e32 v13, v13, v15
	v_sub_f32_e32 v15, v16, v18
	v_add_f32_e32 v13, v15, v13
	v_add_f32_e32 v15, v20, v13
	v_mul_f32_e32 v16, v17, v15
	v_mul_f32_e32 v18, v9, v16
	v_fma_f32 v9, v16, v9, -v18
	v_fmac_f32_e32 v9, v16, v5
	v_sub_f32_e32 v5, v20, v15
	v_add_f32_e32 v5, v13, v5
	v_add_f32_e32 v13, v18, v9
	v_sub_f32_e32 v19, v15, v13
	v_sub_f32_e32 v15, v15, v19
	v_sub_f32_e32 v18, v13, v18
	v_sub_f32_e32 v13, v15, v13
	v_add_f32_e32 v5, v5, v13
	v_sub_f32_e32 v9, v18, v9
	v_cvt_f32_i32_e32 v4, v4
	v_add_f32_e32 v5, v9, v5
	v_add_f32_e32 v9, v14, v16
	v_add_f32_e32 v5, v19, v5
	v_sub_f32_e32 v13, v9, v14
	v_mul_f32_e32 v5, v17, v5
	v_sub_f32_e32 v13, v16, v13
	v_add_f32_e32 v5, v13, v5
	v_mul_f32_e32 v16, 0x3f317218, v4
	v_add_f32_e32 v13, v9, v5
	v_fma_f32 v17, v4, s9, -v16
	v_mul_f32_e32 v14, v13, v13
	v_fmac_f32_e32 v17, 0xb102e308, v4
	v_sub_f32_e32 v4, v13, v9
	v_fmamk_f32 v15, v14, 0x3e9b6dac, v231
	v_sub_f32_e32 v4, v5, v4
	v_add_f32_e32 v5, v16, v17
	v_fmaak_f32 v15, v14, v15, 0x3f2aaada
	v_sub_f32_e32 v9, v5, v16
	v_ldexp_f32 v16, v13, 1
	v_mul_f32_e32 v13, v13, v14
	v_mul_f32_e32 v13, v13, v15
	v_add_f32_e32 v14, v16, v13
	v_sub_f32_e32 v15, v14, v16
	v_ldexp_f32 v4, v4, 1
	v_sub_f32_e32 v13, v13, v15
	v_add_f32_e32 v4, v4, v13
	v_add_f32_e32 v13, v14, v4
	v_sub_f32_e32 v14, v13, v14
	v_sub_f32_e32 v4, v4, v14
	v_add_f32_e32 v14, v5, v13
	v_sub_f32_e32 v15, v14, v5
	v_sub_f32_e32 v16, v14, v15
	v_sub_f32_e32 v9, v17, v9
	v_sub_f32_e32 v5, v5, v16
	v_sub_f32_e32 v13, v13, v15
	v_add_f32_e32 v5, v13, v5
	v_add_f32_e32 v13, v9, v4
	v_sub_f32_e32 v15, v13, v9
	v_sub_f32_e32 v16, v13, v15
	v_sub_f32_e32 v9, v9, v16
	v_sub_f32_e32 v4, v4, v15
	v_add_f32_e32 v5, v13, v5
	v_add_f32_e32 v4, v4, v9
	v_add_f32_e32 v9, v14, v5
	v_sub_f32_e32 v13, v9, v14
	v_sub_f32_e32 v5, v5, v13
	v_add_f32_e32 v4, v4, v5
	v_add_f32_e32 v4, v9, v4
	v_cmp_neq_f32_e32 vcc, s6, v6
	v_mul_f32_e64 v5, |v8|, s7
	v_max_f32_e64 v8, -v8, 0
	v_cndmask_b32_e32 v4, v238, v4, vcc
	v_cmp_ngt_f32_e32 vcc, -1.0, v6
	v_exp_f32_e32 v3, v3
	s_nop 0
	v_cndmask_b32_e32 v4, v239, v4, vcc
	v_cmp_neq_f32_e32 vcc, -1.0, v6
	s_nop 1
	v_cndmask_b32_e32 v4, v240, v4, vcc
	v_cmp_lt_f32_e64 vcc, |v6|, s10
	s_nop 1
	v_cndmask_b32_e32 v4, v4, v6, vcc
	v_exp_f32_e32 v6, v5
	v_add_f32_e32 v4, v7, v4
	v_sub_f32_e32 v4, -0.5, v4
	v_mul_f32_e32 v4, 0x3fb8aa3b, v4
	v_add_f32_e32 v9, 1.0, v6
	v_exp_f32_e32 v7, v4
	v_add_f32_e32 v4, -1.0, v9
	v_sub_f32_e32 v5, v4, v9
	v_add_f32_e32 v5, 1.0, v5
	v_sub_f32_e32 v4, v6, v4
	v_add_f32_e32 v13, v4, v5
	v_frexp_mant_f32_e32 v4, v9
	v_cmp_gt_f32_e32 vcc, s8, v4
	v_cvt_f64_f32_e32 v[4:5], v9
	v_frexp_exp_i32_f64_e32 v4, v[4:5]
	v_subbrev_co_u32_e32 v4, vcc, 0, v4, vcc
	v_sub_u32_e32 v5, 0, v4
	v_ldexp_f32 v9, v9, v5
	v_ldexp_f32 v5, v13, v5
	v_add_f32_e32 v13, -1.0, v9
	v_add_f32_e32 v16, 1.0, v9
	v_add_f32_e32 v14, 1.0, v13
	v_add_f32_e32 v17, -1.0, v16
	v_sub_f32_e32 v14, v9, v14
	v_sub_f32_e32 v9, v9, v17
	v_add_f32_e32 v14, v5, v14
	v_add_f32_e32 v5, v5, v9
	v_add_f32_e32 v9, v16, v5
	v_rcp_f32_e32 v17, v9
	v_add_f32_e32 v15, v13, v14
	v_sub_f32_e32 v13, v15, v13
	v_sub_f32_e32 v13, v14, v13
	v_sub_f32_e32 v14, v9, v16
	v_sub_f32_e32 v5, v5, v14
	v_mul_f32_e32 v14, v15, v17
	v_mul_f32_e32 v16, v9, v14
	v_fma_f32 v18, v14, v9, -v16
	v_fmac_f32_e32 v18, v14, v5
	v_add_f32_e32 v19, v16, v18
	v_sub_f32_e32 v20, v15, v19
	v_sub_f32_e32 v15, v15, v20
	v_sub_f32_e32 v16, v19, v16
	v_sub_f32_e32 v15, v15, v19
	v_add_f32_e32 v13, v13, v15
	v_sub_f32_e32 v15, v16, v18
	v_add_f32_e32 v13, v15, v13
	v_add_f32_e32 v15, v20, v13
	v_mul_f32_e32 v16, v17, v15
	v_mul_f32_e32 v18, v9, v16
	v_fma_f32 v9, v16, v9, -v18
	v_fmac_f32_e32 v9, v16, v5
	v_sub_f32_e32 v5, v20, v15
	v_add_f32_e32 v5, v13, v5
	v_add_f32_e32 v13, v18, v9
	v_sub_f32_e32 v19, v15, v13
	v_sub_f32_e32 v15, v15, v19
	v_sub_f32_e32 v18, v13, v18
	v_sub_f32_e32 v13, v15, v13
	v_add_f32_e32 v5, v5, v13
	v_sub_f32_e32 v9, v18, v9
	v_cvt_f32_i32_e32 v4, v4
	v_add_f32_e32 v5, v9, v5
	v_add_f32_e32 v9, v14, v16
	v_add_f32_e32 v5, v19, v5
	v_sub_f32_e32 v13, v9, v14
	v_mul_f32_e32 v5, v17, v5
	v_sub_f32_e32 v13, v16, v13
	v_add_f32_e32 v5, v13, v5
	v_mul_f32_e32 v16, 0x3f317218, v4
	v_add_f32_e32 v13, v9, v5
	v_fma_f32 v17, v4, s9, -v16
	v_mul_f32_e32 v14, v13, v13
	v_fmac_f32_e32 v17, 0xb102e308, v4
	v_sub_f32_e32 v4, v13, v9
	v_fmamk_f32 v15, v14, 0x3e9b6dac, v231
	v_sub_f32_e32 v4, v5, v4
	v_add_f32_e32 v5, v16, v17
	v_fmaak_f32 v15, v14, v15, 0x3f2aaada
	v_sub_f32_e32 v9, v5, v16
	v_ldexp_f32 v16, v13, 1
	v_mul_f32_e32 v13, v13, v14
	v_mul_f32_e32 v13, v13, v15
	v_add_f32_e32 v14, v16, v13
	v_sub_f32_e32 v15, v14, v16
	v_ldexp_f32 v4, v4, 1
	v_sub_f32_e32 v13, v13, v15
	v_add_f32_e32 v4, v4, v13
	v_add_f32_e32 v13, v14, v4
	v_sub_f32_e32 v14, v13, v14
	v_sub_f32_e32 v4, v4, v14
	v_add_f32_e32 v14, v5, v13
	v_sub_f32_e32 v15, v14, v5
	v_sub_f32_e32 v16, v14, v15
	v_sub_f32_e32 v9, v17, v9
	v_sub_f32_e32 v5, v5, v16
	v_sub_f32_e32 v13, v13, v15
	v_add_f32_e32 v5, v13, v5
	v_add_f32_e32 v13, v9, v4
	v_sub_f32_e32 v15, v13, v9
	v_sub_f32_e32 v16, v13, v15
	v_sub_f32_e32 v9, v9, v16
	v_sub_f32_e32 v4, v4, v15
	v_add_f32_e32 v5, v13, v5
	v_add_f32_e32 v4, v4, v9
	v_add_f32_e32 v9, v14, v5
	v_sub_f32_e32 v13, v9, v14
	v_sub_f32_e32 v5, v5, v13
	v_add_f32_e32 v4, v4, v5
	v_add_f32_e32 v4, v9, v4
	v_cmp_neq_f32_e32 vcc, s6, v6
	s_nop 1
	v_cndmask_b32_e32 v4, v238, v4, vcc
	v_cmp_ngt_f32_e32 vcc, -1.0, v6
	s_nop 1
	v_cndmask_b32_e32 v4, v239, v4, vcc
	v_cmp_neq_f32_e32 vcc, -1.0, v6
	s_nop 1
	v_cndmask_b32_e32 v4, v240, v4, vcc
	v_cmp_lt_f32_e64 vcc, |v6|, s10
	s_nop 1
	v_cndmask_b32_e32 v4, v4, v6, vcc
	v_add_f32_e32 v4, v8, v4
	v_sub_f32_e32 v4, -0.5, v4
	v_mul_f32_e32 v4, 0x3fb8aa3b, v4
	v_exp_f32_e32 v5, v4
	v_mul_f32_e32 v4, 0xbfb8aa3b, v7
	v_exp_f32_e32 v4, v4
	ds_read_b128 v[6:9], v12 offset:80
	v_mul_f32_e32 v5, 0xbfb8aa3b, v5
	v_exp_f32_e32 v5, v5
	ds_write_b128 v75, v[2:5] offset:64
	ds_read_b128 v[2:5], v74 offset:80
	s_waitcnt lgkmcnt(0)
; template <int MODE, bool BIG = false> DI void gemm_tile(const Params& p, int tm, int tn, int kv, char* smem) {
;     ...
;       float4 v = crow4[c4], ww = w04[c4];
;       float u[4] = {v.x + ww.x, v.y + ww.y, v.z + ww.z, v.w + ww.w};
; #pragma unroll
;       for (int e = 0; e < 4; ++e) {
;         const float z = -u[e];
;         const float sp = fmaxf(z, 0.f) + log1pf(__expf(-fabsf(z)));
;         u[e] = __expf(-__expf(-sp - 0.5f));
;       }
	v_add_f32_e32 v2, v6, v2
	v_mul_f32_e64 v6, |v2|, s7
	v_exp_f32_e32 v6, v6
	v_add_f32_e32 v4, v8, v4
	v_max_f32_e64 v8, -v2, 0
	v_add_f32_e32 v7, v7, v3
	v_add_f32_e32 v13, 1.0, v6
	v_add_f32_e32 v2, -1.0, v13
	v_sub_f32_e32 v3, v2, v13
	v_add_f32_e32 v3, 1.0, v3
	v_sub_f32_e32 v2, v6, v2
	v_add_f32_e32 v14, v2, v3
	v_frexp_mant_f32_e32 v2, v13
	v_cmp_gt_f32_e32 vcc, s8, v2
	v_cvt_f64_f32_e32 v[2:3], v13
	v_frexp_exp_i32_f64_e32 v2, v[2:3]
	v_subbrev_co_u32_e32 v2, vcc, 0, v2, vcc
	v_sub_u32_e32 v3, 0, v2
	v_ldexp_f32 v13, v13, v3
	v_ldexp_f32 v3, v14, v3
	v_add_f32_e32 v14, -1.0, v13
	v_add_f32_e32 v17, 1.0, v13
	v_add_f32_e32 v15, 1.0, v14
	v_add_f32_e32 v18, -1.0, v17
	v_sub_f32_e32 v15, v13, v15
	v_sub_f32_e32 v13, v13, v18
	v_add_f32_e32 v15, v3, v15
	v_add_f32_e32 v3, v3, v13
	v_add_f32_e32 v13, v17, v3
	v_rcp_f32_e32 v18, v13
	v_add_f32_e32 v16, v14, v15
	v_sub_f32_e32 v14, v16, v14
	v_sub_f32_e32 v14, v15, v14
	v_sub_f32_e32 v15, v13, v17
	v_sub_f32_e32 v3, v3, v15
	v_mul_f32_e32 v15, v16, v18
	v_mul_f32_e32 v17, v13, v15
	v_fma_f32 v19, v15, v13, -v17
	v_fmac_f32_e32 v19, v15, v3
	v_add_f32_e32 v20, v17, v19
	v_sub_f32_e32 v21, v16, v20
	v_sub_f32_e32 v16, v16, v21
	v_sub_f32_e32 v17, v20, v17
	v_sub_f32_e32 v16, v16, v20
	v_add_f32_e32 v14, v14, v16
	v_sub_f32_e32 v16, v17, v19
	v_add_f32_e32 v14, v16, v14
	v_add_f32_e32 v16, v21, v14
	v_mul_f32_e32 v17, v18, v16
	v_mul_f32_e32 v19, v13, v17
	v_fma_f32 v13, v17, v13, -v19
	v_fmac_f32_e32 v13, v17, v3
	v_sub_f32_e32 v3, v21, v16
	v_add_f32_e32 v3, v14, v3
	v_add_f32_e32 v14, v19, v13
	v_sub_f32_e32 v20, v16, v14
	v_sub_f32_e32 v16, v16, v20
	v_sub_f32_e32 v19, v14, v19
	v_sub_f32_e32 v14, v16, v14
	v_add_f32_e32 v3, v3, v14
	v_sub_f32_e32 v13, v19, v13
	v_cvt_f32_i32_e32 v2, v2
	v_add_f32_e32 v3, v13, v3
	v_add_f32_e32 v13, v15, v17
	v_add_f32_e32 v3, v20, v3
	v_sub_f32_e32 v14, v13, v15
	v_mul_f32_e32 v3, v18, v3
	v_sub_f32_e32 v14, v17, v14
	v_add_f32_e32 v3, v14, v3
	v_mul_f32_e32 v17, 0x3f317218, v2
	v_add_f32_e32 v14, v13, v3
	v_fma_f32 v18, v2, s9, -v17
	v_mul_f32_e32 v15, v14, v14
	v_fmac_f32_e32 v18, 0xb102e308, v2
	v_sub_f32_e32 v2, v14, v13
	v_fmamk_f32 v16, v15, 0x3e9b6dac, v231
	v_sub_f32_e32 v2, v3, v2
	v_add_f32_e32 v3, v17, v18
	v_fmaak_f32 v16, v15, v16, 0x3f2aaada
	v_sub_f32_e32 v13, v3, v17
	v_ldexp_f32 v17, v14, 1
	v_mul_f32_e32 v14, v14, v15
	v_mul_f32_e32 v14, v14, v16
	v_add_f32_e32 v15, v17, v14
	v_sub_f32_e32 v16, v15, v17
	v_ldexp_f32 v2, v2, 1
	v_sub_f32_e32 v14, v14, v16
	v_add_f32_e32 v2, v2, v14
	v_add_f32_e32 v14, v15, v2
	v_sub_f32_e32 v15, v14, v15
	v_sub_f32_e32 v2, v2, v15
	v_add_f32_e32 v15, v3, v14
	v_sub_f32_e32 v16, v15, v3
	v_sub_f32_e32 v17, v15, v16
	v_sub_f32_e32 v13, v18, v13
	v_sub_f32_e32 v3, v3, v17
	v_sub_f32_e32 v14, v14, v16
	v_add_f32_e32 v3, v14, v3
	v_add_f32_e32 v14, v13, v2
	v_sub_f32_e32 v16, v14, v13
	v_sub_f32_e32 v17, v14, v16
	v_sub_f32_e32 v13, v13, v17
	v_sub_f32_e32 v2, v2, v16
	v_add_f32_e32 v3, v14, v3
	v_add_f32_e32 v2, v2, v13
	v_add_f32_e32 v13, v15, v3
	v_sub_f32_e32 v14, v13, v15
	v_sub_f32_e32 v3, v3, v14
	v_add_f32_e32 v2, v2, v3
	v_add_f32_e32 v2, v13, v2
	v_cmp_neq_f32_e32 vcc, s6, v6
	v_mul_f32_e64 v3, |v7|, s7
	v_max_f32_e64 v7, -v7, 0
	v_cndmask_b32_e32 v2, v238, v2, vcc
	v_cmp_ngt_f32_e32 vcc, -1.0, v6
	s_nop 1
	v_cndmask_b32_e32 v2, v239, v2, vcc
	v_cmp_neq_f32_e32 vcc, -1.0, v6
	s_nop 1
	v_cndmask_b32_e32 v2, v240, v2, vcc
	v_cmp_lt_f32_e64 vcc, |v6|, s10
	s_nop 1
	v_cndmask_b32_e32 v2, v2, v6, vcc
	v_add_f32_e32 v2, v8, v2
	v_sub_f32_e32 v2, -0.5, v2
	v_mul_f32_e32 v2, 0x3fb8aa3b, v2
	v_exp_f32_e32 v6, v3
	v_exp_f32_e32 v2, v2
	v_add_f32_e32 v8, v9, v5
	v_add_f32_e32 v9, 1.0, v6
	v_mul_f32_e32 v5, 0xbfb8aa3b, v2
	v_add_f32_e32 v2, -1.0, v9
	v_sub_f32_e32 v3, v2, v9
	v_add_f32_e32 v3, 1.0, v3
	v_sub_f32_e32 v2, v6, v2
	v_add_f32_e32 v13, v2, v3
	v_frexp_mant_f32_e32 v2, v9
	v_cmp_gt_f32_e32 vcc, s8, v2
	v_cvt_f64_f32_e32 v[2:3], v9
	v_frexp_exp_i32_f64_e32 v2, v[2:3]
	v_subbrev_co_u32_e32 v2, vcc, 0, v2, vcc
	v_sub_u32_e32 v3, 0, v2
	v_ldexp_f32 v9, v9, v3
	v_ldexp_f32 v3, v13, v3
	v_add_f32_e32 v13, -1.0, v9
	v_add_f32_e32 v16, 1.0, v9
	v_add_f32_e32 v14, 1.0, v13
	v_add_f32_e32 v17, -1.0, v16
	v_sub_f32_e32 v14, v9, v14
	v_sub_f32_e32 v9, v9, v17
	v_add_f32_e32 v14, v3, v14
	v_add_f32_e32 v3, v3, v9
	v_add_f32_e32 v9, v16, v3
	v_rcp_f32_e32 v17, v9
	v_add_f32_e32 v15, v13, v14
	v_sub_f32_e32 v13, v15, v13
	v_sub_f32_e32 v13, v14, v13
	v_sub_f32_e32 v14, v9, v16
	v_sub_f32_e32 v3, v3, v14
	v_mul_f32_e32 v14, v15, v17
	v_mul_f32_e32 v16, v9, v14
	v_fma_f32 v18, v14, v9, -v16
	v_fmac_f32_e32 v18, v14, v3
	v_add_f32_e32 v19, v16, v18
	v_sub_f32_e32 v20, v15, v19
	v_sub_f32_e32 v15, v15, v20
	v_sub_f32_e32 v16, v19, v16
	v_sub_f32_e32 v15, v15, v19
	v_add_f32_e32 v13, v13, v15
	v_sub_f32_e32 v15, v16, v18
	v_add_f32_e32 v13, v15, v13
	v_add_f32_e32 v15, v20, v13
	v_mul_f32_e32 v16, v17, v15
	v_mul_f32_e32 v18, v9, v16
	v_fma_f32 v9, v16, v9, -v18
	v_fmac_f32_e32 v9, v16, v3
	v_sub_f32_e32 v3, v20, v15
	v_add_f32_e32 v3, v13, v3
	v_add_f32_e32 v13, v18, v9
	v_sub_f32_e32 v19, v15, v13
	v_sub_f32_e32 v15, v15, v19
	v_sub_f32_e32 v18, v13, v18
	v_sub_f32_e32 v13, v15, v13
	v_add_f32_e32 v3, v3, v13
	v_sub_f32_e32 v9, v18, v9
	v_cvt_f32_i32_e32 v2, v2
	v_add_f32_e32 v3, v9, v3
	v_add_f32_e32 v9, v14, v16
	v_add_f32_e32 v3, v19, v3
	v_sub_f32_e32 v13, v9, v14
	v_mul_f32_e32 v3, v17, v3
	v_sub_f32_e32 v13, v16, v13
	v_add_f32_e32 v3, v13, v3
	v_mul_f32_e32 v16, 0x3f317218, v2
	v_add_f32_e32 v13, v9, v3
	v_fma_f32 v17, v2, s9, -v16
	v_mul_f32_e32 v14, v13, v13
	v_fmac_f32_e32 v17, 0xb102e308, v2
; template <int MODE, bool BIG = false> DI void gemm_tile(const Params& p, int tm, int tn, int kv, char* smem) {
;     ...
;       for (int e = 0; e < 4; ++e) {
;         const float z = -u[e];
;         const float sp = fmaxf(z, 0.f) + log1pf(__expf(-fabsf(z)));
;         u[e] = __expf(-__expf(-sp - 0.5f));
;       }
	v_sub_f32_e32 v2, v13, v9
	v_fmamk_f32 v15, v14, 0x3e9b6dac, v231
	v_sub_f32_e32 v2, v3, v2
	v_add_f32_e32 v3, v16, v17
	v_fmaak_f32 v15, v14, v15, 0x3f2aaada
	v_sub_f32_e32 v9, v3, v16
	v_ldexp_f32 v16, v13, 1
	v_mul_f32_e32 v13, v13, v14
	v_mul_f32_e32 v13, v13, v15
	v_add_f32_e32 v14, v16, v13
	v_sub_f32_e32 v15, v14, v16
	v_ldexp_f32 v2, v2, 1
	v_sub_f32_e32 v13, v13, v15
	v_add_f32_e32 v2, v2, v13
	v_add_f32_e32 v13, v14, v2
	v_sub_f32_e32 v14, v13, v14
	v_sub_f32_e32 v2, v2, v14
	v_add_f32_e32 v14, v3, v13
	v_sub_f32_e32 v15, v14, v3
	v_sub_f32_e32 v16, v14, v15
	v_sub_f32_e32 v9, v17, v9
	v_sub_f32_e32 v3, v3, v16
	v_sub_f32_e32 v13, v13, v15
	v_add_f32_e32 v3, v13, v3
	v_add_f32_e32 v13, v9, v2
	v_sub_f32_e32 v15, v13, v9
	v_sub_f32_e32 v16, v13, v15
	v_sub_f32_e32 v9, v9, v16
	v_sub_f32_e32 v2, v2, v15
	v_add_f32_e32 v3, v13, v3
	v_add_f32_e32 v2, v2, v9
	v_add_f32_e32 v9, v14, v3
	v_sub_f32_e32 v13, v9, v14
	v_sub_f32_e32 v3, v3, v13
	v_add_f32_e32 v2, v2, v3
	v_add_f32_e32 v2, v9, v2
	v_cmp_neq_f32_e32 vcc, s6, v6
	s_nop 1
	v_cndmask_b32_e32 v2, v238, v2, vcc
	v_cmp_ngt_f32_e32 vcc, -1.0, v6
	s_nop 1
	v_cndmask_b32_e32 v2, v239, v2, vcc
	v_cmp_neq_f32_e32 vcc, -1.0, v6
	s_nop 1
	v_cndmask_b32_e32 v2, v240, v2, vcc
	v_cmp_lt_f32_e64 vcc, |v6|, s10
	s_nop 1
	v_cndmask_b32_e32 v2, v2, v6, vcc
	v_add_f32_e32 v2, v7, v2
	v_sub_f32_e32 v2, -0.5, v2
	v_mul_f32_e32 v2, 0x3fb8aa3b, v2
	v_exp_f32_e32 v3, v2
	v_mul_f32_e64 v2, |v4|, s7
	v_exp_f32_e32 v6, v2
	v_max_f32_e64 v7, -v4, 0
	v_exp_f32_e32 v2, v5
	v_mul_f32_e32 v3, 0xbfb8aa3b, v3
	v_add_f32_e32 v9, 1.0, v6
	v_add_f32_e32 v4, -1.0, v9
	v_sub_f32_e32 v5, v4, v9
	v_add_f32_e32 v5, 1.0, v5
	v_sub_f32_e32 v4, v6, v4
	v_add_f32_e32 v13, v4, v5
	v_frexp_mant_f32_e32 v4, v9
	v_cmp_gt_f32_e32 vcc, s8, v4
	v_cvt_f64_f32_e32 v[4:5], v9
	v_frexp_exp_i32_f64_e32 v4, v[4:5]
	v_subbrev_co_u32_e32 v4, vcc, 0, v4, vcc
	v_sub_u32_e32 v5, 0, v4
	v_ldexp_f32 v9, v9, v5
	v_ldexp_f32 v5, v13, v5
	v_add_f32_e32 v13, -1.0, v9
	v_add_f32_e32 v16, 1.0, v9
	v_add_f32_e32 v14, 1.0, v13
	v_add_f32_e32 v17, -1.0, v16
	v_sub_f32_e32 v14, v9, v14
	v_sub_f32_e32 v9, v9, v17
	v_add_f32_e32 v14, v5, v14
	v_add_f32_e32 v5, v5, v9
	v_add_f32_e32 v9, v16, v5
	v_rcp_f32_e32 v17, v9
	v_add_f32_e32 v15, v13, v14
	v_sub_f32_e32 v13, v15, v13
	v_sub_f32_e32 v13, v14, v13
	v_sub_f32_e32 v14, v9, v16
	v_sub_f32_e32 v5, v5, v14
	v_mul_f32_e32 v14, v15, v17
	v_mul_f32_e32 v16, v9, v14
	v_fma_f32 v18, v14, v9, -v16
	v_fmac_f32_e32 v18, v14, v5
	v_add_f32_e32 v19, v16, v18
	v_sub_f32_e32 v20, v15, v19
	v_sub_f32_e32 v15, v15, v20
	v_sub_f32_e32 v16, v19, v16
	v_sub_f32_e32 v15, v15, v19
	v_add_f32_e32 v13, v13, v15
	v_sub_f32_e32 v15, v16, v18
	v_add_f32_e32 v13, v15, v13
	v_add_f32_e32 v15, v20, v13
	v_mul_f32_e32 v16, v17, v15
	v_mul_f32_e32 v18, v9, v16
	v_fma_f32 v9, v16, v9, -v18
	v_fmac_f32_e32 v9, v16, v5
	v_sub_f32_e32 v5, v20, v15
	v_add_f32_e32 v5, v13, v5
	v_add_f32_e32 v13, v18, v9
	v_sub_f32_e32 v19, v15, v13
	v_sub_f32_e32 v15, v15, v19
	v_sub_f32_e32 v18, v13, v18
	v_sub_f32_e32 v13, v15, v13
	v_add_f32_e32 v5, v5, v13
	v_sub_f32_e32 v9, v18, v9
	v_cvt_f32_i32_e32 v4, v4
	v_add_f32_e32 v5, v9, v5
	v_add_f32_e32 v9, v14, v16
	v_add_f32_e32 v5, v19, v5
	v_sub_f32_e32 v13, v9, v14
	v_mul_f32_e32 v5, v17, v5
	v_sub_f32_e32 v13, v16, v13
	v_add_f32_e32 v5, v13, v5
	v_mul_f32_e32 v16, 0x3f317218, v4
	v_add_f32_e32 v13, v9, v5
	v_fma_f32 v17, v4, s9, -v16
	v_mul_f32_e32 v14, v13, v13
	v_fmac_f32_e32 v17, 0xb102e308, v4
	v_sub_f32_e32 v4, v13, v9
	v_fmamk_f32 v15, v14, 0x3e9b6dac, v231
	v_sub_f32_e32 v4, v5, v4
	v_add_f32_e32 v5, v16, v17
	v_fmaak_f32 v15, v14, v15, 0x3f2aaada
	v_sub_f32_e32 v9, v5, v16
	v_ldexp_f32 v16, v13, 1
	v_mul_f32_e32 v13, v13, v14
	v_mul_f32_e32 v13, v13, v15
	v_add_f32_e32 v14, v16, v13
	v_sub_f32_e32 v15, v14, v16
	v_ldexp_f32 v4, v4, 1
	v_sub_f32_e32 v13, v13, v15
	v_add_f32_e32 v4, v4, v13
	v_add_f32_e32 v13, v14, v4
	v_sub_f32_e32 v14, v13, v14
	v_sub_f32_e32 v4, v4, v14
	v_add_f32_e32 v14, v5, v13
	v_sub_f32_e32 v15, v14, v5
	v_sub_f32_e32 v16, v14, v15
	v_sub_f32_e32 v9, v17, v9
	v_sub_f32_e32 v5, v5, v16
	v_sub_f32_e32 v13, v13, v15
	v_add_f32_e32 v5, v13, v5
	v_add_f32_e32 v13, v9, v4
	v_sub_f32_e32 v15, v13, v9
	v_sub_f32_e32 v16, v13, v15
	v_sub_f32_e32 v9, v9, v16
	v_sub_f32_e32 v4, v4, v15
	v_add_f32_e32 v5, v13, v5
	v_add_f32_e32 v4, v4, v9
	v_add_f32_e32 v9, v14, v5
	v_sub_f32_e32 v13, v9, v14
	v_sub_f32_e32 v5, v5, v13
	v_add_f32_e32 v4, v4, v5
	v_add_f32_e32 v4, v9, v4
	v_cmp_neq_f32_e32 vcc, s6, v6
	v_mul_f32_e64 v5, |v8|, s7
	v_max_f32_e64 v8, -v8, 0
	v_cndmask_b32_e32 v4, v238, v4, vcc
	v_cmp_ngt_f32_e32 vcc, -1.0, v6
	v_exp_f32_e32 v3, v3
	s_nop 0
	v_cndmask_b32_e32 v4, v239, v4, vcc
	v_cmp_neq_f32_e32 vcc, -1.0, v6
	s_nop 1
	v_cndmask_b32_e32 v4, v240, v4, vcc
	v_cmp_lt_f32_e64 vcc, |v6|, s10
	s_nop 1
	v_cndmask_b32_e32 v4, v4, v6, vcc
	v_exp_f32_e32 v6, v5
	v_add_f32_e32 v4, v7, v4
	v_sub_f32_e32 v4, -0.5, v4
	v_mul_f32_e32 v4, 0x3fb8aa3b, v4
	v_add_f32_e32 v9, 1.0, v6
	v_exp_f32_e32 v7, v4
	v_add_f32_e32 v4, -1.0, v9
	v_sub_f32_e32 v5, v4, v9
	v_add_f32_e32 v5, 1.0, v5
	v_sub_f32_e32 v4, v6, v4
	v_add_f32_e32 v13, v4, v5
	v_frexp_mant_f32_e32 v4, v9
	v_cmp_gt_f32_e32 vcc, s8, v4
	v_cvt_f64_f32_e32 v[4:5], v9
	v_frexp_exp_i32_f64_e32 v4, v[4:5]
	v_subbrev_co_u32_e32 v4, vcc, 0, v4, vcc
	v_sub_u32_e32 v5, 0, v4
	v_ldexp_f32 v9, v9, v5
	v_ldexp_f32 v5, v13, v5
	v_add_f32_e32 v13, -1.0, v9
	v_add_f32_e32 v16, 1.0, v9
	v_add_f32_e32 v14, 1.0, v13
	v_add_f32_e32 v17, -1.0, v16
	v_sub_f32_e32 v14, v9, v14
	v_sub_f32_e32 v9, v9, v17
	v_add_f32_e32 v14, v5, v14
	v_add_f32_e32 v5, v5, v9
; template <int MODE, bool BIG = false> DI void gemm_tile(const Params& p, int tm, int tn, int kv, char* smem) {
;     ...
;     for (int c4 = 0; c4 < 16; ++c4) {
;       float4 v = crow4[c4], ww = w04[c4];
;       float u[4] = {v.x + ww.x, v.y + ww.y, v.z + ww.z, v.w + ww.w};
; #pragma unroll
;       for (int e = 0; e < 4; ++e) {
;         const float z = -u[e];
;         const float sp = fmaxf(z, 0.f) + log1pf(__expf(-fabsf(z)));
;         u[e] = __expf(-__expf(-sp - 0.5f));
;       }
;       W4[c4] = make_float4(u[0], u[1], u[2], u[3]);
	v_add_f32_e32 v9, v16, v5
	v_rcp_f32_e32 v17, v9
	v_add_f32_e32 v15, v13, v14
	v_sub_f32_e32 v13, v15, v13
	v_sub_f32_e32 v13, v14, v13
	v_sub_f32_e32 v14, v9, v16
	v_sub_f32_e32 v5, v5, v14
	v_mul_f32_e32 v14, v15, v17
	v_mul_f32_e32 v16, v9, v14
	v_fma_f32 v18, v14, v9, -v16
	v_fmac_f32_e32 v18, v14, v5
	v_add_f32_e32 v19, v16, v18
	v_sub_f32_e32 v20, v15, v19
	v_sub_f32_e32 v15, v15, v20
	v_sub_f32_e32 v16, v19, v16
	v_sub_f32_e32 v15, v15, v19
	v_add_f32_e32 v13, v13, v15
	v_sub_f32_e32 v15, v16, v18
	v_add_f32_e32 v13, v15, v13
	v_add_f32_e32 v15, v20, v13
	v_mul_f32_e32 v16, v17, v15
	v_mul_f32_e32 v18, v9, v16
	v_fma_f32 v9, v16, v9, -v18
	v_fmac_f32_e32 v9, v16, v5
	v_sub_f32_e32 v5, v20, v15
	v_add_f32_e32 v5, v13, v5
	v_add_f32_e32 v13, v18, v9
	v_sub_f32_e32 v19, v15, v13
	v_sub_f32_e32 v15, v15, v19
	v_sub_f32_e32 v18, v13, v18
	v_sub_f32_e32 v13, v15, v13
	v_add_f32_e32 v5, v5, v13
	v_sub_f32_e32 v9, v18, v9
	v_cvt_f32_i32_e32 v4, v4
	v_add_f32_e32 v5, v9, v5
	v_add_f32_e32 v9, v14, v16
	v_add_f32_e32 v5, v19, v5
	v_sub_f32_e32 v13, v9, v14
	v_mul_f32_e32 v5, v17, v5
	v_sub_f32_e32 v13, v16, v13
	v_add_f32_e32 v5, v13, v5
	v_mul_f32_e32 v16, 0x3f317218, v4
	v_add_f32_e32 v13, v9, v5
	v_fma_f32 v17, v4, s9, -v16
	v_mul_f32_e32 v14, v13, v13
	v_fmac_f32_e32 v17, 0xb102e308, v4
	v_sub_f32_e32 v4, v13, v9
	v_fmamk_f32 v15, v14, 0x3e9b6dac, v231
	v_sub_f32_e32 v4, v5, v4
	v_add_f32_e32 v5, v16, v17
	v_fmaak_f32 v15, v14, v15, 0x3f2aaada
	v_sub_f32_e32 v9, v5, v16
	v_ldexp_f32 v16, v13, 1
	v_mul_f32_e32 v13, v13, v14
	v_mul_f32_e32 v13, v13, v15
	v_add_f32_e32 v14, v16, v13
	v_sub_f32_e32 v15, v14, v16
	v_ldexp_f32 v4, v4, 1
	v_sub_f32_e32 v13, v13, v15
	v_add_f32_e32 v4, v4, v13
	v_add_f32_e32 v13, v14, v4
	v_sub_f32_e32 v14, v13, v14
	v_sub_f32_e32 v4, v4, v14
	v_add_f32_e32 v14, v5, v13
	v_sub_f32_e32 v15, v14, v5
	v_sub_f32_e32 v16, v14, v15
	v_sub_f32_e32 v9, v17, v9
	v_sub_f32_e32 v5, v5, v16
	v_sub_f32_e32 v13, v13, v15
	v_add_f32_e32 v5, v13, v5
	v_add_f32_e32 v13, v9, v4
	v_sub_f32_e32 v15, v13, v9
	v_sub_f32_e32 v16, v13, v15
	v_sub_f32_e32 v9, v9, v16
	v_sub_f32_e32 v4, v4, v15
	v_add_f32_e32 v5, v13, v5
	v_add_f32_e32 v4, v4, v9
	v_add_f32_e32 v9, v14, v5
	v_sub_f32_e32 v13, v9, v14
	v_sub_f32_e32 v5, v5, v13
	v_add_f32_e32 v4, v4, v5
	v_add_f32_e32 v4, v9, v4
	v_cmp_neq_f32_e32 vcc, s6, v6
	s_nop 1
	v_cndmask_b32_e32 v4, v238, v4, vcc
	v_cmp_ngt_f32_e32 vcc, -1.0, v6
	s_nop 1
	v_cndmask_b32_e32 v4, v239, v4, vcc
	v_cmp_neq_f32_e32 vcc, -1.0, v6
	s_nop 1
	v_cndmask_b32_e32 v4, v240, v4, vcc
	v_cmp_lt_f32_e64 vcc, |v6|, s10
	s_nop 1
	v_cndmask_b32_e32 v4, v4, v6, vcc
	v_add_f32_e32 v4, v8, v4
	v_sub_f32_e32 v4, -0.5, v4
	v_mul_f32_e32 v4, 0x3fb8aa3b, v4
	v_exp_f32_e32 v5, v4
	v_mul_f32_e32 v4, 0xbfb8aa3b, v7
	v_exp_f32_e32 v4, v4
	ds_read_b128 v[6:9], v12 offset:96
	v_mul_f32_e32 v5, 0xbfb8aa3b, v5
	v_exp_f32_e32 v5, v5
	ds_write_b128 v75, v[2:5] offset:80
	ds_read_b128 v[2:5], v74 offset:96
	s_waitcnt lgkmcnt(0)
	v_add_f32_e32 v2, v6, v2
	v_mul_f32_e64 v6, |v2|, s7
	v_exp_f32_e32 v6, v6
	v_add_f32_e32 v4, v8, v4
	v_max_f32_e64 v8, -v2, 0
	v_add_f32_e32 v7, v7, v3
	v_add_f32_e32 v13, 1.0, v6
	v_add_f32_e32 v2, -1.0, v13
	v_sub_f32_e32 v3, v2, v13
	v_add_f32_e32 v3, 1.0, v3
	v_sub_f32_e32 v2, v6, v2
	v_add_f32_e32 v14, v2, v3
	v_frexp_mant_f32_e32 v2, v13
	v_cmp_gt_f32_e32 vcc, s8, v2
	v_cvt_f64_f32_e32 v[2:3], v13
	v_frexp_exp_i32_f64_e32 v2, v[2:3]
	v_subbrev_co_u32_e32 v2, vcc, 0, v2, vcc
	v_sub_u32_e32 v3, 0, v2
	v_ldexp_f32 v13, v13, v3
	v_ldexp_f32 v3, v14, v3
	v_add_f32_e32 v14, -1.0, v13
	v_add_f32_e32 v17, 1.0, v13
	v_add_f32_e32 v15, 1.0, v14
	v_add_f32_e32 v18, -1.0, v17
	v_sub_f32_e32 v15, v13, v15
	v_sub_f32_e32 v13, v13, v18
	v_add_f32_e32 v15, v3, v15
	v_add_f32_e32 v3, v3, v13
	v_add_f32_e32 v13, v17, v3
	v_rcp_f32_e32 v18, v13
	v_add_f32_e32 v16, v14, v15
	v_sub_f32_e32 v14, v16, v14
	v_sub_f32_e32 v14, v15, v14
	v_sub_f32_e32 v15, v13, v17
	v_sub_f32_e32 v3, v3, v15
	v_mul_f32_e32 v15, v16, v18
	v_mul_f32_e32 v17, v13, v15
	v_fma_f32 v19, v15, v13, -v17
	v_fmac_f32_e32 v19, v15, v3
	v_add_f32_e32 v20, v17, v19
	v_sub_f32_e32 v21, v16, v20
	v_sub_f32_e32 v16, v16, v21
	v_sub_f32_e32 v17, v20, v17
	v_sub_f32_e32 v16, v16, v20
	v_add_f32_e32 v14, v14, v16
	v_sub_f32_e32 v16, v17, v19
	v_add_f32_e32 v14, v16, v14
	v_add_f32_e32 v16, v21, v14
	v_mul_f32_e32 v17, v18, v16
	v_mul_f32_e32 v19, v13, v17
	v_fma_f32 v13, v17, v13, -v19
	v_fmac_f32_e32 v13, v17, v3
	v_sub_f32_e32 v3, v21, v16
	v_add_f32_e32 v3, v14, v3
	v_add_f32_e32 v14, v19, v13
	v_sub_f32_e32 v20, v16, v14
	v_sub_f32_e32 v16, v16, v20
	v_sub_f32_e32 v19, v14, v19
	v_sub_f32_e32 v14, v16, v14
	v_add_f32_e32 v3, v3, v14
	v_sub_f32_e32 v13, v19, v13
	v_cvt_f32_i32_e32 v2, v2
	v_add_f32_e32 v3, v13, v3
	v_add_f32_e32 v13, v15, v17
	v_add_f32_e32 v3, v20, v3
	v_sub_f32_e32 v14, v13, v15
	v_mul_f32_e32 v3, v18, v3
	v_sub_f32_e32 v14, v17, v14
	v_add_f32_e32 v3, v14, v3
	v_mul_f32_e32 v17, 0x3f317218, v2
	v_add_f32_e32 v14, v13, v3
	v_fma_f32 v18, v2, s9, -v17
	v_mul_f32_e32 v15, v14, v14
	v_fmac_f32_e32 v18, 0xb102e308, v2
	v_sub_f32_e32 v2, v14, v13
	v_fmamk_f32 v16, v15, 0x3e9b6dac, v231
	v_sub_f32_e32 v2, v3, v2
	v_add_f32_e32 v3, v17, v18
	v_fmaak_f32 v16, v15, v16, 0x3f2aaada
	v_sub_f32_e32 v13, v3, v17
	v_ldexp_f32 v17, v14, 1
	v_mul_f32_e32 v14, v14, v15
	v_mul_f32_e32 v14, v14, v16
	v_add_f32_e32 v15, v17, v14
	v_sub_f32_e32 v16, v15, v17
	v_ldexp_f32 v2, v2, 1
	v_sub_f32_e32 v14, v14, v16
	v_add_f32_e32 v2, v2, v14
	v_add_f32_e32 v14, v15, v2
	v_sub_f32_e32 v15, v14, v15
	v_sub_f32_e32 v2, v2, v15
	v_add_f32_e32 v15, v3, v14
; template <int MODE, bool BIG = false> DI void gemm_tile(const Params& p, int tm, int tn, int kv, char* smem) {
;     ...
;       for (int e = 0; e < 4; ++e) {
;         const float z = -u[e];
;         const float sp = fmaxf(z, 0.f) + log1pf(__expf(-fabsf(z)));
;         u[e] = __expf(-__expf(-sp - 0.5f));
;       }
	v_sub_f32_e32 v16, v15, v3
	v_sub_f32_e32 v17, v15, v16
	v_sub_f32_e32 v13, v18, v13
	v_sub_f32_e32 v3, v3, v17
	v_sub_f32_e32 v14, v14, v16
	v_add_f32_e32 v3, v14, v3
	v_add_f32_e32 v14, v13, v2
	v_sub_f32_e32 v16, v14, v13
	v_sub_f32_e32 v17, v14, v16
	v_sub_f32_e32 v13, v13, v17
	v_sub_f32_e32 v2, v2, v16
	v_add_f32_e32 v3, v14, v3
	v_add_f32_e32 v2, v2, v13
	v_add_f32_e32 v13, v15, v3
	v_sub_f32_e32 v14, v13, v15
	v_sub_f32_e32 v3, v3, v14
	v_add_f32_e32 v2, v2, v3
	v_add_f32_e32 v2, v13, v2
	v_cmp_neq_f32_e32 vcc, s6, v6
	v_mul_f32_e64 v3, |v7|, s7
	v_max_f32_e64 v7, -v7, 0
	v_cndmask_b32_e32 v2, v238, v2, vcc
	v_cmp_ngt_f32_e32 vcc, -1.0, v6
	s_nop 1
	v_cndmask_b32_e32 v2, v239, v2, vcc
	v_cmp_neq_f32_e32 vcc, -1.0, v6
	s_nop 1
	v_cndmask_b32_e32 v2, v240, v2, vcc
	v_cmp_lt_f32_e64 vcc, |v6|, s10
	s_nop 1
	v_cndmask_b32_e32 v2, v2, v6, vcc
	v_add_f32_e32 v2, v8, v2
	v_sub_f32_e32 v2, -0.5, v2
	v_mul_f32_e32 v2, 0x3fb8aa3b, v2
	v_exp_f32_e32 v6, v3
	v_exp_f32_e32 v2, v2
	v_add_f32_e32 v8, v9, v5
	v_add_f32_e32 v9, 1.0, v6
	v_mul_f32_e32 v5, 0xbfb8aa3b, v2
	v_add_f32_e32 v2, -1.0, v9
	v_sub_f32_e32 v3, v2, v9
	v_add_f32_e32 v3, 1.0, v3
	v_sub_f32_e32 v2, v6, v2
	v_add_f32_e32 v13, v2, v3
	v_frexp_mant_f32_e32 v2, v9
	v_cmp_gt_f32_e32 vcc, s8, v2
	v_cvt_f64_f32_e32 v[2:3], v9
	v_frexp_exp_i32_f64_e32 v2, v[2:3]
	v_subbrev_co_u32_e32 v2, vcc, 0, v2, vcc
	v_sub_u32_e32 v3, 0, v2
	v_ldexp_f32 v9, v9, v3
	v_ldexp_f32 v3, v13, v3
	v_add_f32_e32 v13, -1.0, v9
	v_add_f32_e32 v16, 1.0, v9
	v_add_f32_e32 v14, 1.0, v13
	v_add_f32_e32 v17, -1.0, v16
	v_sub_f32_e32 v14, v9, v14
	v_sub_f32_e32 v9, v9, v17
	v_add_f32_e32 v14, v3, v14
	v_add_f32_e32 v3, v3, v9
	v_add_f32_e32 v9, v16, v3
	v_rcp_f32_e32 v17, v9
	v_add_f32_e32 v15, v13, v14
	v_sub_f32_e32 v13, v15, v13
	v_sub_f32_e32 v13, v14, v13
	v_sub_f32_e32 v14, v9, v16
	v_sub_f32_e32 v3, v3, v14
	v_mul_f32_e32 v14, v15, v17
	v_mul_f32_e32 v16, v9, v14
	v_fma_f32 v18, v14, v9, -v16
	v_fmac_f32_e32 v18, v14, v3
	v_add_f32_e32 v19, v16, v18
	v_sub_f32_e32 v20, v15, v19
	v_sub_f32_e32 v15, v15, v20
	v_sub_f32_e32 v16, v19, v16
	v_sub_f32_e32 v15, v15, v19
	v_add_f32_e32 v13, v13, v15
	v_sub_f32_e32 v15, v16, v18
	v_add_f32_e32 v13, v15, v13
	v_add_f32_e32 v15, v20, v13
	v_mul_f32_e32 v16, v17, v15
	v_mul_f32_e32 v18, v9, v16
	v_fma_f32 v9, v16, v9, -v18
	v_fmac_f32_e32 v9, v16, v3
	v_sub_f32_e32 v3, v20, v15
	v_add_f32_e32 v3, v13, v3
	v_add_f32_e32 v13, v18, v9
	v_sub_f32_e32 v19, v15, v13
	v_sub_f32_e32 v15, v15, v19
	v_sub_f32_e32 v18, v13, v18
	v_sub_f32_e32 v13, v15, v13
	v_add_f32_e32 v3, v3, v13
	v_sub_f32_e32 v9, v18, v9
	v_cvt_f32_i32_e32 v2, v2
	v_add_f32_e32 v3, v9, v3
	v_add_f32_e32 v9, v14, v16
	v_add_f32_e32 v3, v19, v3
	v_sub_f32_e32 v13, v9, v14
	v_mul_f32_e32 v3, v17, v3
	v_sub_f32_e32 v13, v16, v13
	v_add_f32_e32 v3, v13, v3
	v_mul_f32_e32 v16, 0x3f317218, v2
	v_add_f32_e32 v13, v9, v3
	v_fma_f32 v17, v2, s9, -v16
	v_mul_f32_e32 v14, v13, v13
	v_fmac_f32_e32 v17, 0xb102e308, v2
	v_sub_f32_e32 v2, v13, v9
	v_fmamk_f32 v15, v14, 0x3e9b6dac, v231
	v_sub_f32_e32 v2, v3, v2
	v_add_f32_e32 v3, v16, v17
	v_fmaak_f32 v15, v14, v15, 0x3f2aaada
	v_sub_f32_e32 v9, v3, v16
	v_ldexp_f32 v16, v13, 1
	v_mul_f32_e32 v13, v13, v14
	v_mul_f32_e32 v13, v13, v15
	v_add_f32_e32 v14, v16, v13
	v_sub_f32_e32 v15, v14, v16
	v_ldexp_f32 v2, v2, 1
	v_sub_f32_e32 v13, v13, v15
	v_add_f32_e32 v2, v2, v13
	v_add_f32_e32 v13, v14, v2
	v_sub_f32_e32 v14, v13, v14
	v_sub_f32_e32 v2, v2, v14
	v_add_f32_e32 v14, v3, v13
	v_sub_f32_e32 v15, v14, v3
	v_sub_f32_e32 v16, v14, v15
	v_sub_f32_e32 v9, v17, v9
	v_sub_f32_e32 v3, v3, v16
	v_sub_f32_e32 v13, v13, v15
	v_add_f32_e32 v3, v13, v3
	v_add_f32_e32 v13, v9, v2
	v_sub_f32_e32 v15, v13, v9
	v_sub_f32_e32 v16, v13, v15
	v_sub_f32_e32 v9, v9, v16
	v_sub_f32_e32 v2, v2, v15
	v_add_f32_e32 v3, v13, v3
	v_add_f32_e32 v2, v2, v9
	v_add_f32_e32 v9, v14, v3
	v_sub_f32_e32 v13, v9, v14
	v_sub_f32_e32 v3, v3, v13
	v_add_f32_e32 v2, v2, v3
	v_add_f32_e32 v2, v9, v2
	v_cmp_neq_f32_e32 vcc, s6, v6
	s_nop 1
	v_cndmask_b32_e32 v2, v238, v2, vcc
	v_cmp_ngt_f32_e32 vcc, -1.0, v6
	s_nop 1
	v_cndmask_b32_e32 v2, v239, v2, vcc
	v_cmp_neq_f32_e32 vcc, -1.0, v6
	s_nop 1
	v_cndmask_b32_e32 v2, v240, v2, vcc
	v_cmp_lt_f32_e64 vcc, |v6|, s10
	s_nop 1
	v_cndmask_b32_e32 v2, v2, v6, vcc
	v_add_f32_e32 v2, v7, v2
	v_sub_f32_e32 v2, -0.5, v2
	v_mul_f32_e32 v2, 0x3fb8aa3b, v2
	v_exp_f32_e32 v3, v2
	v_mul_f32_e64 v2, |v4|, s7
	v_exp_f32_e32 v6, v2
	v_max_f32_e64 v7, -v4, 0
	v_exp_f32_e32 v2, v5
	v_mul_f32_e32 v3, 0xbfb8aa3b, v3
	v_add_f32_e32 v9, 1.0, v6
	v_add_f32_e32 v4, -1.0, v9
	v_sub_f32_e32 v5, v4, v9
	v_add_f32_e32 v5, 1.0, v5
	v_sub_f32_e32 v4, v6, v4
	v_add_f32_e32 v13, v4, v5
	v_frexp_mant_f32_e32 v4, v9
	v_cmp_gt_f32_e32 vcc, s8, v4
	v_cvt_f64_f32_e32 v[4:5], v9
	v_frexp_exp_i32_f64_e32 v4, v[4:5]
	v_subbrev_co_u32_e32 v4, vcc, 0, v4, vcc
	v_sub_u32_e32 v5, 0, v4
	v_ldexp_f32 v9, v9, v5
	v_ldexp_f32 v5, v13, v5
	v_add_f32_e32 v13, -1.0, v9
	v_add_f32_e32 v16, 1.0, v9
	v_add_f32_e32 v14, 1.0, v13
	v_add_f32_e32 v17, -1.0, v16
	v_sub_f32_e32 v14, v9, v14
	v_sub_f32_e32 v9, v9, v17
	v_add_f32_e32 v14, v5, v14
	v_add_f32_e32 v5, v5, v9
	v_add_f32_e32 v9, v16, v5
	v_rcp_f32_e32 v17, v9
	v_add_f32_e32 v15, v13, v14
	v_sub_f32_e32 v13, v15, v13
	v_sub_f32_e32 v13, v14, v13
	v_sub_f32_e32 v14, v9, v16
	v_sub_f32_e32 v5, v5, v14
	v_mul_f32_e32 v14, v15, v17
	v_mul_f32_e32 v16, v9, v14
	v_fma_f32 v18, v14, v9, -v16
	v_fmac_f32_e32 v18, v14, v5
	v_add_f32_e32 v19, v16, v18
	v_sub_f32_e32 v20, v15, v19
	v_sub_f32_e32 v15, v15, v20
	v_sub_f32_e32 v16, v19, v16
	v_sub_f32_e32 v15, v15, v19
; template <int MODE, bool BIG = false> DI void gemm_tile(const Params& p, int tm, int tn, int kv, char* smem) {
;     ...
;     for (int c4 = 0; c4 < 16; ++c4) {
;       float4 v = crow4[c4], ww = w04[c4];
;       float u[4] = {v.x + ww.x, v.y + ww.y, v.z + ww.z, v.w + ww.w};
; #pragma unroll
;       for (int e = 0; e < 4; ++e) {
;         const float z = -u[e];
;         const float sp = fmaxf(z, 0.f) + log1pf(__expf(-fabsf(z)));
;         u[e] = __expf(-__expf(-sp - 0.5f));
;       }
;       W4[c4] = make_float4(u[0], u[1], u[2], u[3]);
	v_add_f32_e32 v13, v13, v15
	v_sub_f32_e32 v15, v16, v18
	v_add_f32_e32 v13, v15, v13
	v_add_f32_e32 v15, v20, v13
	v_mul_f32_e32 v16, v17, v15
	v_mul_f32_e32 v18, v9, v16
	v_fma_f32 v9, v16, v9, -v18
	v_fmac_f32_e32 v9, v16, v5
	v_sub_f32_e32 v5, v20, v15
	v_add_f32_e32 v5, v13, v5
	v_add_f32_e32 v13, v18, v9
	v_sub_f32_e32 v19, v15, v13
	v_sub_f32_e32 v15, v15, v19
	v_sub_f32_e32 v18, v13, v18
	v_sub_f32_e32 v13, v15, v13
	v_add_f32_e32 v5, v5, v13
	v_sub_f32_e32 v9, v18, v9
	v_cvt_f32_i32_e32 v4, v4
	v_add_f32_e32 v5, v9, v5
	v_add_f32_e32 v9, v14, v16
	v_add_f32_e32 v5, v19, v5
	v_sub_f32_e32 v13, v9, v14
	v_mul_f32_e32 v5, v17, v5
	v_sub_f32_e32 v13, v16, v13
	v_add_f32_e32 v5, v13, v5
	v_mul_f32_e32 v16, 0x3f317218, v4
	v_add_f32_e32 v13, v9, v5
	v_fma_f32 v17, v4, s9, -v16
	v_mul_f32_e32 v14, v13, v13
	v_fmac_f32_e32 v17, 0xb102e308, v4
	v_sub_f32_e32 v4, v13, v9
	v_fmamk_f32 v15, v14, 0x3e9b6dac, v231
	v_sub_f32_e32 v4, v5, v4
	v_add_f32_e32 v5, v16, v17
	v_fmaak_f32 v15, v14, v15, 0x3f2aaada
	v_sub_f32_e32 v9, v5, v16
	v_ldexp_f32 v16, v13, 1
	v_mul_f32_e32 v13, v13, v14
	v_mul_f32_e32 v13, v13, v15
	v_add_f32_e32 v14, v16, v13
	v_sub_f32_e32 v15, v14, v16
	v_ldexp_f32 v4, v4, 1
	v_sub_f32_e32 v13, v13, v15
	v_add_f32_e32 v4, v4, v13
	v_add_f32_e32 v13, v14, v4
	v_sub_f32_e32 v14, v13, v14
	v_sub_f32_e32 v4, v4, v14
	v_add_f32_e32 v14, v5, v13
	v_sub_f32_e32 v15, v14, v5
	v_sub_f32_e32 v16, v14, v15
	v_sub_f32_e32 v9, v17, v9
	v_sub_f32_e32 v5, v5, v16
	v_sub_f32_e32 v13, v13, v15
	v_add_f32_e32 v5, v13, v5
	v_add_f32_e32 v13, v9, v4
	v_sub_f32_e32 v15, v13, v9
	v_sub_f32_e32 v16, v13, v15
	v_sub_f32_e32 v9, v9, v16
	v_sub_f32_e32 v4, v4, v15
	v_add_f32_e32 v5, v13, v5
	v_add_f32_e32 v4, v4, v9
	v_add_f32_e32 v9, v14, v5
	v_sub_f32_e32 v13, v9, v14
	v_sub_f32_e32 v5, v5, v13
	v_add_f32_e32 v4, v4, v5
	v_add_f32_e32 v4, v9, v4
	v_cmp_neq_f32_e32 vcc, s6, v6
	v_mul_f32_e64 v5, |v8|, s7
	v_max_f32_e64 v8, -v8, 0
	v_cndmask_b32_e32 v4, v238, v4, vcc
	v_cmp_ngt_f32_e32 vcc, -1.0, v6
	v_exp_f32_e32 v3, v3
	s_nop 0
	v_cndmask_b32_e32 v4, v239, v4, vcc
	v_cmp_neq_f32_e32 vcc, -1.0, v6
	s_nop 1
	v_cndmask_b32_e32 v4, v240, v4, vcc
	v_cmp_lt_f32_e64 vcc, |v6|, s10
	s_nop 1
	v_cndmask_b32_e32 v4, v4, v6, vcc
	v_exp_f32_e32 v6, v5
	v_add_f32_e32 v4, v7, v4
	v_sub_f32_e32 v4, -0.5, v4
	v_mul_f32_e32 v4, 0x3fb8aa3b, v4
	v_add_f32_e32 v9, 1.0, v6
	v_exp_f32_e32 v7, v4
	v_add_f32_e32 v4, -1.0, v9
	v_sub_f32_e32 v5, v4, v9
	v_add_f32_e32 v5, 1.0, v5
	v_sub_f32_e32 v4, v6, v4
	v_add_f32_e32 v13, v4, v5
	v_frexp_mant_f32_e32 v4, v9
	v_cmp_gt_f32_e32 vcc, s8, v4
	v_cvt_f64_f32_e32 v[4:5], v9
	v_frexp_exp_i32_f64_e32 v4, v[4:5]
	v_subbrev_co_u32_e32 v4, vcc, 0, v4, vcc
	v_sub_u32_e32 v5, 0, v4
	v_ldexp_f32 v9, v9, v5
	v_ldexp_f32 v5, v13, v5
	v_add_f32_e32 v13, -1.0, v9
	v_add_f32_e32 v16, 1.0, v9
	v_add_f32_e32 v14, 1.0, v13
	v_add_f32_e32 v17, -1.0, v16
	v_sub_f32_e32 v14, v9, v14
	v_sub_f32_e32 v9, v9, v17
	v_add_f32_e32 v14, v5, v14
	v_add_f32_e32 v5, v5, v9
	v_add_f32_e32 v9, v16, v5
	v_rcp_f32_e32 v17, v9
	v_add_f32_e32 v15, v13, v14
	v_sub_f32_e32 v13, v15, v13
	v_sub_f32_e32 v13, v14, v13
	v_sub_f32_e32 v14, v9, v16
	v_sub_f32_e32 v5, v5, v14
	v_mul_f32_e32 v14, v15, v17
	v_mul_f32_e32 v16, v9, v14
	v_fma_f32 v18, v14, v9, -v16
	v_fmac_f32_e32 v18, v14, v5
	v_add_f32_e32 v19, v16, v18
	v_sub_f32_e32 v20, v15, v19
	v_sub_f32_e32 v15, v15, v20
	v_sub_f32_e32 v16, v19, v16
	v_sub_f32_e32 v15, v15, v19
	v_add_f32_e32 v13, v13, v15
	v_sub_f32_e32 v15, v16, v18
	v_add_f32_e32 v13, v15, v13
	v_add_f32_e32 v15, v20, v13
	v_mul_f32_e32 v16, v17, v15
	v_mul_f32_e32 v18, v9, v16
	v_fma_f32 v9, v16, v9, -v18
	v_fmac_f32_e32 v9, v16, v5
	v_sub_f32_e32 v5, v20, v15
	v_add_f32_e32 v5, v13, v5
	v_add_f32_e32 v13, v18, v9
	v_sub_f32_e32 v19, v15, v13
	v_sub_f32_e32 v15, v15, v19
	v_sub_f32_e32 v18, v13, v18
	v_sub_f32_e32 v13, v15, v13
	v_add_f32_e32 v5, v5, v13
	v_sub_f32_e32 v9, v18, v9
	v_cvt_f32_i32_e32 v4, v4
	v_add_f32_e32 v5, v9, v5
	v_add_f32_e32 v9, v14, v16
	v_add_f32_e32 v5, v19, v5
	v_sub_f32_e32 v13, v9, v14
	v_mul_f32_e32 v5, v17, v5
	v_sub_f32_e32 v13, v16, v13
	v_add_f32_e32 v5, v13, v5
	v_mul_f32_e32 v16, 0x3f317218, v4
	v_add_f32_e32 v13, v9, v5
	v_fma_f32 v17, v4, s9, -v16
	v_mul_f32_e32 v14, v13, v13
	v_fmac_f32_e32 v17, 0xb102e308, v4
	v_sub_f32_e32 v4, v13, v9
	v_fmamk_f32 v15, v14, 0x3e9b6dac, v231
	v_sub_f32_e32 v4, v5, v4
	v_add_f32_e32 v5, v16, v17
	v_fmaak_f32 v15, v14, v15, 0x3f2aaada
	v_sub_f32_e32 v9, v5, v16
	v_ldexp_f32 v16, v13, 1
	v_mul_f32_e32 v13, v13, v14
	v_mul_f32_e32 v13, v13, v15
	v_add_f32_e32 v14, v16, v13
	v_sub_f32_e32 v15, v14, v16
	v_ldexp_f32 v4, v4, 1
	v_sub_f32_e32 v13, v13, v15
	v_add_f32_e32 v4, v4, v13
	v_add_f32_e32 v13, v14, v4
	v_sub_f32_e32 v14, v13, v14
	v_sub_f32_e32 v4, v4, v14
	v_add_f32_e32 v14, v5, v13
	v_sub_f32_e32 v15, v14, v5
	v_sub_f32_e32 v16, v14, v15
	v_sub_f32_e32 v9, v17, v9
	v_sub_f32_e32 v5, v5, v16
	v_sub_f32_e32 v13, v13, v15
	v_add_f32_e32 v5, v13, v5
	v_add_f32_e32 v13, v9, v4
	v_sub_f32_e32 v15, v13, v9
	v_sub_f32_e32 v16, v13, v15
	v_sub_f32_e32 v9, v9, v16
	v_sub_f32_e32 v4, v4, v15
	v_add_f32_e32 v5, v13, v5
	v_add_f32_e32 v4, v4, v9
	v_add_f32_e32 v9, v14, v5
	v_sub_f32_e32 v13, v9, v14
	v_sub_f32_e32 v5, v5, v13
	v_add_f32_e32 v4, v4, v5
	v_add_f32_e32 v4, v9, v4
	v_cmp_neq_f32_e32 vcc, s6, v6
	s_nop 1
	v_cndmask_b32_e32 v4, v238, v4, vcc
	v_cmp_ngt_f32_e32 vcc, -1.0, v6
	s_nop 1
	v_cndmask_b32_e32 v4, v239, v4, vcc
	v_cmp_neq_f32_e32 vcc, -1.0, v6
	s_nop 1
	v_cndmask_b32_e32 v4, v240, v4, vcc
	v_cmp_lt_f32_e64 vcc, |v6|, s10
	s_nop 1
	v_cndmask_b32_e32 v4, v4, v6, vcc
	v_add_f32_e32 v4, v8, v4
	v_sub_f32_e32 v4, -0.5, v4
	v_mul_f32_e32 v4, 0x3fb8aa3b, v4
	v_exp_f32_e32 v5, v4
	v_mul_f32_e32 v4, 0xbfb8aa3b, v7
	v_exp_f32_e32 v4, v4
	ds_read_b128 v[6:9], v12 offset:112
	v_mul_f32_e32 v5, 0xbfb8aa3b, v5
	v_exp_f32_e32 v5, v5
	ds_write_b128 v75, v[2:5] offset:96
	ds_read_b128 v[2:5], v74 offset:112
	s_waitcnt lgkmcnt(0)
; template <int MODE, bool BIG = false> DI void gemm_tile(const Params& p, int tm, int tn, int kv, char* smem) {
;     ...
;       float4 v = crow4[c4], ww = w04[c4];
;       float u[4] = {v.x + ww.x, v.y + ww.y, v.z + ww.z, v.w + ww.w};
; #pragma unroll
;       for (int e = 0; e < 4; ++e) {
;         const float z = -u[e];
;         const float sp = fmaxf(z, 0.f) + log1pf(__expf(-fabsf(z)));
;         u[e] = __expf(-__expf(-sp - 0.5f));
;       }
	v_add_f32_e32 v2, v6, v2
	v_mul_f32_e64 v6, |v2|, s7
	v_exp_f32_e32 v6, v6
	v_add_f32_e32 v4, v8, v4
	v_max_f32_e64 v8, -v2, 0
	v_add_f32_e32 v7, v7, v3
	v_add_f32_e32 v13, 1.0, v6
	v_add_f32_e32 v2, -1.0, v13
	v_sub_f32_e32 v3, v2, v13
	v_add_f32_e32 v3, 1.0, v3
	v_sub_f32_e32 v2, v6, v2
	v_add_f32_e32 v14, v2, v3
	v_frexp_mant_f32_e32 v2, v13
	v_cmp_gt_f32_e32 vcc, s8, v2
	v_cvt_f64_f32_e32 v[2:3], v13
	v_frexp_exp_i32_f64_e32 v2, v[2:3]
	v_subbrev_co_u32_e32 v2, vcc, 0, v2, vcc
	v_sub_u32_e32 v3, 0, v2
	v_ldexp_f32 v13, v13, v3
	v_ldexp_f32 v3, v14, v3
	v_add_f32_e32 v14, -1.0, v13
	v_add_f32_e32 v17, 1.0, v13
	v_add_f32_e32 v15, 1.0, v14
	v_add_f32_e32 v18, -1.0, v17
	v_sub_f32_e32 v15, v13, v15
	v_sub_f32_e32 v13, v13, v18
	v_add_f32_e32 v15, v3, v15
	v_add_f32_e32 v3, v3, v13
	v_add_f32_e32 v13, v17, v3
	v_rcp_f32_e32 v18, v13
	v_add_f32_e32 v16, v14, v15
	v_sub_f32_e32 v14, v16, v14
	v_sub_f32_e32 v14, v15, v14
	v_sub_f32_e32 v15, v13, v17
	v_sub_f32_e32 v3, v3, v15
	v_mul_f32_e32 v15, v16, v18
	v_mul_f32_e32 v17, v13, v15
	v_fma_f32 v19, v15, v13, -v17
	v_fmac_f32_e32 v19, v15, v3
	v_add_f32_e32 v20, v17, v19
	v_sub_f32_e32 v21, v16, v20
	v_sub_f32_e32 v16, v16, v21
	v_sub_f32_e32 v17, v20, v17
	v_sub_f32_e32 v16, v16, v20
	v_add_f32_e32 v14, v14, v16
	v_sub_f32_e32 v16, v17, v19
	v_add_f32_e32 v14, v16, v14
	v_add_f32_e32 v16, v21, v14
	v_mul_f32_e32 v17, v18, v16
	v_mul_f32_e32 v19, v13, v17
	v_fma_f32 v13, v17, v13, -v19
	v_fmac_f32_e32 v13, v17, v3
	v_sub_f32_e32 v3, v21, v16
	v_add_f32_e32 v3, v14, v3
	v_add_f32_e32 v14, v19, v13
	v_sub_f32_e32 v20, v16, v14
	v_sub_f32_e32 v16, v16, v20
	v_sub_f32_e32 v19, v14, v19
	v_sub_f32_e32 v14, v16, v14
	v_add_f32_e32 v3, v3, v14
	v_sub_f32_e32 v13, v19, v13
	v_cvt_f32_i32_e32 v2, v2
	v_add_f32_e32 v3, v13, v3
	v_add_f32_e32 v13, v15, v17
	v_add_f32_e32 v3, v20, v3
	v_sub_f32_e32 v14, v13, v15
	v_mul_f32_e32 v3, v18, v3
	v_sub_f32_e32 v14, v17, v14
	v_add_f32_e32 v3, v14, v3
	v_mul_f32_e32 v17, 0x3f317218, v2
	v_add_f32_e32 v14, v13, v3
	v_fma_f32 v18, v2, s9, -v17
	v_mul_f32_e32 v15, v14, v14
	v_fmac_f32_e32 v18, 0xb102e308, v2
	v_sub_f32_e32 v2, v14, v13
	v_fmamk_f32 v16, v15, 0x3e9b6dac, v231
	v_sub_f32_e32 v2, v3, v2
	v_add_f32_e32 v3, v17, v18
	v_fmaak_f32 v16, v15, v16, 0x3f2aaada
	v_sub_f32_e32 v13, v3, v17
	v_ldexp_f32 v17, v14, 1
	v_mul_f32_e32 v14, v14, v15
	v_mul_f32_e32 v14, v14, v16
	v_add_f32_e32 v15, v17, v14
	v_sub_f32_e32 v16, v15, v17
	v_ldexp_f32 v2, v2, 1
	v_sub_f32_e32 v14, v14, v16
	v_add_f32_e32 v2, v2, v14
	v_add_f32_e32 v14, v15, v2
	v_sub_f32_e32 v15, v14, v15
	v_sub_f32_e32 v2, v2, v15
	v_add_f32_e32 v15, v3, v14
	v_sub_f32_e32 v16, v15, v3
	v_sub_f32_e32 v17, v15, v16
	v_sub_f32_e32 v13, v18, v13
	v_sub_f32_e32 v3, v3, v17
	v_sub_f32_e32 v14, v14, v16
	v_add_f32_e32 v3, v14, v3
	v_add_f32_e32 v14, v13, v2
	v_sub_f32_e32 v16, v14, v13
	v_sub_f32_e32 v17, v14, v16
	v_sub_f32_e32 v13, v13, v17
	v_sub_f32_e32 v2, v2, v16
	v_add_f32_e32 v3, v14, v3
	v_add_f32_e32 v2, v2, v13
	v_add_f32_e32 v13, v15, v3
	v_sub_f32_e32 v14, v13, v15
	v_sub_f32_e32 v3, v3, v14
	v_add_f32_e32 v2, v2, v3
	v_add_f32_e32 v2, v13, v2
	v_cmp_neq_f32_e32 vcc, s6, v6
	v_mul_f32_e64 v3, |v7|, s7
	v_max_f32_e64 v7, -v7, 0
	v_cndmask_b32_e32 v2, v238, v2, vcc
	v_cmp_ngt_f32_e32 vcc, -1.0, v6
	s_nop 1
	v_cndmask_b32_e32 v2, v239, v2, vcc
	v_cmp_neq_f32_e32 vcc, -1.0, v6
	s_nop 1
	v_cndmask_b32_e32 v2, v240, v2, vcc
	v_cmp_lt_f32_e64 vcc, |v6|, s10
	s_nop 1
	v_cndmask_b32_e32 v2, v2, v6, vcc
	v_add_f32_e32 v2, v8, v2
	v_sub_f32_e32 v2, -0.5, v2
	v_mul_f32_e32 v2, 0x3fb8aa3b, v2
	v_exp_f32_e32 v6, v3
	v_exp_f32_e32 v2, v2
	v_add_f32_e32 v8, v9, v5
	v_add_f32_e32 v9, 1.0, v6
	v_mul_f32_e32 v5, 0xbfb8aa3b, v2
	v_add_f32_e32 v2, -1.0, v9
	v_sub_f32_e32 v3, v2, v9
	v_add_f32_e32 v3, 1.0, v3
	v_sub_f32_e32 v2, v6, v2
	v_add_f32_e32 v13, v2, v3
	v_frexp_mant_f32_e32 v2, v9
	v_cmp_gt_f32_e32 vcc, s8, v2
	v_cvt_f64_f32_e32 v[2:3], v9
	v_frexp_exp_i32_f64_e32 v2, v[2:3]
	v_subbrev_co_u32_e32 v2, vcc, 0, v2, vcc
	v_sub_u32_e32 v3, 0, v2
	v_ldexp_f32 v9, v9, v3
	v_ldexp_f32 v3, v13, v3
	v_add_f32_e32 v13, -1.0, v9
	v_add_f32_e32 v16, 1.0, v9
	v_add_f32_e32 v14, 1.0, v13
	v_add_f32_e32 v17, -1.0, v16
	v_sub_f32_e32 v14, v9, v14
	v_sub_f32_e32 v9, v9, v17
	v_add_f32_e32 v14, v3, v14
	v_add_f32_e32 v3, v3, v9
	v_add_f32_e32 v9, v16, v3
	v_rcp_f32_e32 v17, v9
	v_add_f32_e32 v15, v13, v14
	v_sub_f32_e32 v13, v15, v13
	v_sub_f32_e32 v13, v14, v13
	v_sub_f32_e32 v14, v9, v16
	v_sub_f32_e32 v3, v3, v14
	v_mul_f32_e32 v14, v15, v17
	v_mul_f32_e32 v16, v9, v14
	v_fma_f32 v18, v14, v9, -v16
	v_fmac_f32_e32 v18, v14, v3
	v_add_f32_e32 v19, v16, v18
	v_sub_f32_e32 v20, v15, v19
	v_sub_f32_e32 v15, v15, v20
	v_sub_f32_e32 v16, v19, v16
	v_sub_f32_e32 v15, v15, v19
	v_add_f32_e32 v13, v13, v15
	v_sub_f32_e32 v15, v16, v18
	v_add_f32_e32 v13, v15, v13
	v_add_f32_e32 v15, v20, v13
	v_mul_f32_e32 v16, v17, v15
	v_mul_f32_e32 v18, v9, v16
	v_fma_f32 v9, v16, v9, -v18
	v_fmac_f32_e32 v9, v16, v3
	v_sub_f32_e32 v3, v20, v15
	v_add_f32_e32 v3, v13, v3
	v_add_f32_e32 v13, v18, v9
	v_sub_f32_e32 v19, v15, v13
	v_sub_f32_e32 v15, v15, v19
	v_sub_f32_e32 v18, v13, v18
	v_sub_f32_e32 v13, v15, v13
	v_add_f32_e32 v3, v3, v13
	v_sub_f32_e32 v9, v18, v9
	v_cvt_f32_i32_e32 v2, v2
	v_add_f32_e32 v3, v9, v3
	v_add_f32_e32 v9, v14, v16
	v_add_f32_e32 v3, v19, v3
	v_sub_f32_e32 v13, v9, v14
	v_mul_f32_e32 v3, v17, v3
	v_sub_f32_e32 v13, v16, v13
	v_add_f32_e32 v3, v13, v3
	v_mul_f32_e32 v16, 0x3f317218, v2
	v_add_f32_e32 v13, v9, v3
	v_fma_f32 v17, v2, s9, -v16
	v_mul_f32_e32 v14, v13, v13
	v_fmac_f32_e32 v17, 0xb102e308, v2
; template <int MODE, bool BIG = false> DI void gemm_tile(const Params& p, int tm, int tn, int kv, char* smem) {
;     ...
;       for (int e = 0; e < 4; ++e) {
;         const float z = -u[e];
;         const float sp = fmaxf(z, 0.f) + log1pf(__expf(-fabsf(z)));
;         u[e] = __expf(-__expf(-sp - 0.5f));
;       }
	v_sub_f32_e32 v2, v13, v9
	v_fmamk_f32 v15, v14, 0x3e9b6dac, v231
	v_sub_f32_e32 v2, v3, v2
	v_add_f32_e32 v3, v16, v17
	v_fmaak_f32 v15, v14, v15, 0x3f2aaada
	v_sub_f32_e32 v9, v3, v16
	v_ldexp_f32 v16, v13, 1
	v_mul_f32_e32 v13, v13, v14
	v_mul_f32_e32 v13, v13, v15
	v_add_f32_e32 v14, v16, v13
	v_sub_f32_e32 v15, v14, v16
	v_ldexp_f32 v2, v2, 1
	v_sub_f32_e32 v13, v13, v15
	v_add_f32_e32 v2, v2, v13
	v_add_f32_e32 v13, v14, v2
	v_sub_f32_e32 v14, v13, v14
	v_sub_f32_e32 v2, v2, v14
	v_add_f32_e32 v14, v3, v13
	v_sub_f32_e32 v15, v14, v3
	v_sub_f32_e32 v16, v14, v15
	v_sub_f32_e32 v9, v17, v9
	v_sub_f32_e32 v3, v3, v16
	v_sub_f32_e32 v13, v13, v15
	v_add_f32_e32 v3, v13, v3
	v_add_f32_e32 v13, v9, v2
	v_sub_f32_e32 v15, v13, v9
	v_sub_f32_e32 v16, v13, v15
	v_sub_f32_e32 v9, v9, v16
	v_sub_f32_e32 v2, v2, v15
	v_add_f32_e32 v3, v13, v3
	v_add_f32_e32 v2, v2, v9
	v_add_f32_e32 v9, v14, v3
	v_sub_f32_e32 v13, v9, v14
	v_sub_f32_e32 v3, v3, v13
	v_add_f32_e32 v2, v2, v3
	v_add_f32_e32 v2, v9, v2
	v_cmp_neq_f32_e32 vcc, s6, v6
	s_nop 1
	v_cndmask_b32_e32 v2, v238, v2, vcc
	v_cmp_ngt_f32_e32 vcc, -1.0, v6
	s_nop 1
	v_cndmask_b32_e32 v2, v239, v2, vcc
	v_cmp_neq_f32_e32 vcc, -1.0, v6
	s_nop 1
	v_cndmask_b32_e32 v2, v240, v2, vcc
	v_cmp_lt_f32_e64 vcc, |v6|, s10
	s_nop 1
	v_cndmask_b32_e32 v2, v2, v6, vcc
	v_add_f32_e32 v2, v7, v2
	v_sub_f32_e32 v2, -0.5, v2
	v_mul_f32_e32 v2, 0x3fb8aa3b, v2
	v_exp_f32_e32 v3, v2
	v_mul_f32_e64 v2, |v4|, s7
	v_exp_f32_e32 v6, v2
	v_max_f32_e64 v7, -v4, 0
	v_exp_f32_e32 v2, v5
	v_mul_f32_e32 v3, 0xbfb8aa3b, v3
	v_add_f32_e32 v9, 1.0, v6
	v_add_f32_e32 v4, -1.0, v9
	v_sub_f32_e32 v5, v4, v9
	v_add_f32_e32 v5, 1.0, v5
	v_sub_f32_e32 v4, v6, v4
	v_add_f32_e32 v13, v4, v5
	v_frexp_mant_f32_e32 v4, v9
	v_cmp_gt_f32_e32 vcc, s8, v4
	v_cvt_f64_f32_e32 v[4:5], v9
	v_frexp_exp_i32_f64_e32 v4, v[4:5]
	v_subbrev_co_u32_e32 v4, vcc, 0, v4, vcc
	v_sub_u32_e32 v5, 0, v4
	v_ldexp_f32 v9, v9, v5
	v_ldexp_f32 v5, v13, v5
	v_add_f32_e32 v13, -1.0, v9
	v_add_f32_e32 v16, 1.0, v9
	v_add_f32_e32 v14, 1.0, v13
	v_add_f32_e32 v17, -1.0, v16
	v_sub_f32_e32 v14, v9, v14
	v_sub_f32_e32 v9, v9, v17
	v_add_f32_e32 v14, v5, v14
	v_add_f32_e32 v5, v5, v9
	v_add_f32_e32 v9, v16, v5
	v_rcp_f32_e32 v17, v9
	v_add_f32_e32 v15, v13, v14
	v_sub_f32_e32 v13, v15, v13
	v_sub_f32_e32 v13, v14, v13
	v_sub_f32_e32 v14, v9, v16
	v_sub_f32_e32 v5, v5, v14
	v_mul_f32_e32 v14, v15, v17
	v_mul_f32_e32 v16, v9, v14
	v_fma_f32 v18, v14, v9, -v16
	v_fmac_f32_e32 v18, v14, v5
	v_add_f32_e32 v19, v16, v18
	v_sub_f32_e32 v20, v15, v19
	v_sub_f32_e32 v15, v15, v20
	v_sub_f32_e32 v16, v19, v16
	v_sub_f32_e32 v15, v15, v19
	v_add_f32_e32 v13, v13, v15
	v_sub_f32_e32 v15, v16, v18
	v_add_f32_e32 v13, v15, v13
	v_add_f32_e32 v15, v20, v13
	v_mul_f32_e32 v16, v17, v15
	v_mul_f32_e32 v18, v9, v16
	v_fma_f32 v9, v16, v9, -v18
	v_fmac_f32_e32 v9, v16, v5
	v_sub_f32_e32 v5, v20, v15
	v_add_f32_e32 v5, v13, v5
	v_add_f32_e32 v13, v18, v9
	v_sub_f32_e32 v19, v15, v13
	v_sub_f32_e32 v15, v15, v19
	v_sub_f32_e32 v18, v13, v18
	v_sub_f32_e32 v13, v15, v13
	v_add_f32_e32 v5, v5, v13
	v_sub_f32_e32 v9, v18, v9
	v_cvt_f32_i32_e32 v4, v4
	v_add_f32_e32 v5, v9, v5
	v_add_f32_e32 v9, v14, v16
	v_add_f32_e32 v5, v19, v5
	v_sub_f32_e32 v13, v9, v14
	v_mul_f32_e32 v5, v17, v5
	v_sub_f32_e32 v13, v16, v13
	v_add_f32_e32 v5, v13, v5
	v_mul_f32_e32 v16, 0x3f317218, v4
	v_add_f32_e32 v13, v9, v5
	v_fma_f32 v17, v4, s9, -v16
	v_mul_f32_e32 v14, v13, v13
	v_fmac_f32_e32 v17, 0xb102e308, v4
	v_sub_f32_e32 v4, v13, v9
	v_fmamk_f32 v15, v14, 0x3e9b6dac, v231
	v_sub_f32_e32 v4, v5, v4
	v_add_f32_e32 v5, v16, v17
	v_fmaak_f32 v15, v14, v15, 0x3f2aaada
	v_sub_f32_e32 v9, v5, v16
	v_ldexp_f32 v16, v13, 1
	v_mul_f32_e32 v13, v13, v14
	v_mul_f32_e32 v13, v13, v15
	v_add_f32_e32 v14, v16, v13
	v_sub_f32_e32 v15, v14, v16
	v_ldexp_f32 v4, v4, 1
	v_sub_f32_e32 v13, v13, v15
	v_add_f32_e32 v4, v4, v13
	v_add_f32_e32 v13, v14, v4
	v_sub_f32_e32 v14, v13, v14
	v_sub_f32_e32 v4, v4, v14
	v_add_f32_e32 v14, v5, v13
	v_sub_f32_e32 v15, v14, v5
	v_sub_f32_e32 v16, v14, v15
	v_sub_f32_e32 v9, v17, v9
	v_sub_f32_e32 v5, v5, v16
	v_sub_f32_e32 v13, v13, v15
	v_add_f32_e32 v5, v13, v5
	v_add_f32_e32 v13, v9, v4
	v_sub_f32_e32 v15, v13, v9
	v_sub_f32_e32 v16, v13, v15
	v_sub_f32_e32 v9, v9, v16
	v_sub_f32_e32 v4, v4, v15
	v_add_f32_e32 v5, v13, v5
	v_add_f32_e32 v4, v4, v9
	v_add_f32_e32 v9, v14, v5
	v_sub_f32_e32 v13, v9, v14
	v_sub_f32_e32 v5, v5, v13
	v_add_f32_e32 v4, v4, v5
	v_add_f32_e32 v4, v9, v4
	v_cmp_neq_f32_e32 vcc, s6, v6
	v_mul_f32_e64 v5, |v8|, s7
	v_max_f32_e64 v8, -v8, 0
	v_cndmask_b32_e32 v4, v238, v4, vcc
	v_cmp_ngt_f32_e32 vcc, -1.0, v6
	v_exp_f32_e32 v3, v3
	s_nop 0
	v_cndmask_b32_e32 v4, v239, v4, vcc
	v_cmp_neq_f32_e32 vcc, -1.0, v6
	s_nop 1
	v_cndmask_b32_e32 v4, v240, v4, vcc
	v_cmp_lt_f32_e64 vcc, |v6|, s10
	s_nop 1
	v_cndmask_b32_e32 v4, v4, v6, vcc
	v_exp_f32_e32 v6, v5
	v_add_f32_e32 v4, v7, v4
	v_sub_f32_e32 v4, -0.5, v4
	v_mul_f32_e32 v4, 0x3fb8aa3b, v4
	v_add_f32_e32 v9, 1.0, v6
	v_exp_f32_e32 v7, v4
	v_add_f32_e32 v4, -1.0, v9
	v_sub_f32_e32 v5, v4, v9
	v_add_f32_e32 v5, 1.0, v5
	v_sub_f32_e32 v4, v6, v4
	v_add_f32_e32 v13, v4, v5
	v_frexp_mant_f32_e32 v4, v9
	v_cmp_gt_f32_e32 vcc, s8, v4
	v_cvt_f64_f32_e32 v[4:5], v9
	v_frexp_exp_i32_f64_e32 v4, v[4:5]
	v_subbrev_co_u32_e32 v4, vcc, 0, v4, vcc
	v_sub_u32_e32 v5, 0, v4
	v_ldexp_f32 v9, v9, v5
	v_ldexp_f32 v5, v13, v5
	v_add_f32_e32 v13, -1.0, v9
	v_add_f32_e32 v16, 1.0, v9
	v_add_f32_e32 v14, 1.0, v13
	v_add_f32_e32 v17, -1.0, v16
	v_sub_f32_e32 v14, v9, v14
	v_sub_f32_e32 v9, v9, v17
	v_add_f32_e32 v14, v5, v14
	v_add_f32_e32 v5, v5, v9
; template <int MODE, bool BIG = false> DI void gemm_tile(const Params& p, int tm, int tn, int kv, char* smem) {
;     ...
;     for (int c4 = 0; c4 < 16; ++c4) {
;       float4 v = crow4[c4], ww = w04[c4];
;       float u[4] = {v.x + ww.x, v.y + ww.y, v.z + ww.z, v.w + ww.w};
; #pragma unroll
;       for (int e = 0; e < 4; ++e) {
;         const float z = -u[e];
;         const float sp = fmaxf(z, 0.f) + log1pf(__expf(-fabsf(z)));
;         u[e] = __expf(-__expf(-sp - 0.5f));
;       }
;       W4[c4] = make_float4(u[0], u[1], u[2], u[3]);
	v_add_f32_e32 v9, v16, v5
	v_rcp_f32_e32 v17, v9
	v_add_f32_e32 v15, v13, v14
	v_sub_f32_e32 v13, v15, v13
	v_sub_f32_e32 v13, v14, v13
	v_sub_f32_e32 v14, v9, v16
	v_sub_f32_e32 v5, v5, v14
	v_mul_f32_e32 v14, v15, v17
	v_mul_f32_e32 v16, v9, v14
	v_fma_f32 v18, v14, v9, -v16
	v_fmac_f32_e32 v18, v14, v5
	v_add_f32_e32 v19, v16, v18
	v_sub_f32_e32 v20, v15, v19
	v_sub_f32_e32 v15, v15, v20
	v_sub_f32_e32 v16, v19, v16
	v_sub_f32_e32 v15, v15, v19
	v_add_f32_e32 v13, v13, v15
	v_sub_f32_e32 v15, v16, v18
	v_add_f32_e32 v13, v15, v13
	v_add_f32_e32 v15, v20, v13
	v_mul_f32_e32 v16, v17, v15
	v_mul_f32_e32 v18, v9, v16
	v_fma_f32 v9, v16, v9, -v18
	v_fmac_f32_e32 v9, v16, v5
	v_sub_f32_e32 v5, v20, v15
	v_add_f32_e32 v5, v13, v5
	v_add_f32_e32 v13, v18, v9
	v_sub_f32_e32 v19, v15, v13
	v_sub_f32_e32 v15, v15, v19
	v_sub_f32_e32 v18, v13, v18
	v_sub_f32_e32 v13, v15, v13
	v_add_f32_e32 v5, v5, v13
	v_sub_f32_e32 v9, v18, v9
	v_cvt_f32_i32_e32 v4, v4
	v_add_f32_e32 v5, v9, v5
	v_add_f32_e32 v9, v14, v16
	v_add_f32_e32 v5, v19, v5
	v_sub_f32_e32 v13, v9, v14
	v_mul_f32_e32 v5, v17, v5
	v_sub_f32_e32 v13, v16, v13
	v_add_f32_e32 v5, v13, v5
	v_mul_f32_e32 v16, 0x3f317218, v4
	v_add_f32_e32 v13, v9, v5
	v_fma_f32 v17, v4, s9, -v16
	v_mul_f32_e32 v14, v13, v13
	v_fmac_f32_e32 v17, 0xb102e308, v4
	v_sub_f32_e32 v4, v13, v9
	v_fmamk_f32 v15, v14, 0x3e9b6dac, v231
	v_sub_f32_e32 v4, v5, v4
	v_add_f32_e32 v5, v16, v17
	v_fmaak_f32 v15, v14, v15, 0x3f2aaada
	v_sub_f32_e32 v9, v5, v16
	v_ldexp_f32 v16, v13, 1
	v_mul_f32_e32 v13, v13, v14
	v_mul_f32_e32 v13, v13, v15
	v_add_f32_e32 v14, v16, v13
	v_sub_f32_e32 v15, v14, v16
	v_ldexp_f32 v4, v4, 1
	v_sub_f32_e32 v13, v13, v15
	v_add_f32_e32 v4, v4, v13
	v_add_f32_e32 v13, v14, v4
	v_sub_f32_e32 v14, v13, v14
	v_sub_f32_e32 v4, v4, v14
	v_add_f32_e32 v14, v5, v13
	v_sub_f32_e32 v15, v14, v5
	v_sub_f32_e32 v16, v14, v15
	v_sub_f32_e32 v9, v17, v9
	v_sub_f32_e32 v5, v5, v16
	v_sub_f32_e32 v13, v13, v15
	v_add_f32_e32 v5, v13, v5
	v_add_f32_e32 v13, v9, v4
	v_sub_f32_e32 v15, v13, v9
	v_sub_f32_e32 v16, v13, v15
	v_sub_f32_e32 v9, v9, v16
	v_sub_f32_e32 v4, v4, v15
	v_add_f32_e32 v5, v13, v5
	v_add_f32_e32 v4, v4, v9
	v_add_f32_e32 v9, v14, v5
	v_sub_f32_e32 v13, v9, v14
	v_sub_f32_e32 v5, v5, v13
	v_add_f32_e32 v4, v4, v5
	v_add_f32_e32 v4, v9, v4
	v_cmp_neq_f32_e32 vcc, s6, v6
	s_nop 1
	v_cndmask_b32_e32 v4, v238, v4, vcc
	v_cmp_ngt_f32_e32 vcc, -1.0, v6
	s_nop 1
	v_cndmask_b32_e32 v4, v239, v4, vcc
	v_cmp_neq_f32_e32 vcc, -1.0, v6
	s_nop 1
	v_cndmask_b32_e32 v4, v240, v4, vcc
	v_cmp_lt_f32_e64 vcc, |v6|, s10
	s_nop 1
	v_cndmask_b32_e32 v4, v4, v6, vcc
	v_add_f32_e32 v4, v8, v4
	v_sub_f32_e32 v4, -0.5, v4
	v_mul_f32_e32 v4, 0x3fb8aa3b, v4
	v_exp_f32_e32 v5, v4
	v_mul_f32_e32 v4, 0xbfb8aa3b, v7
	v_exp_f32_e32 v4, v4
	ds_read_b128 v[6:9], v12 offset:128
	v_mul_f32_e32 v5, 0xbfb8aa3b, v5
	v_exp_f32_e32 v5, v5
	ds_write_b128 v75, v[2:5] offset:112
	ds_read_b128 v[2:5], v74 offset:128
	s_waitcnt lgkmcnt(0)
	v_add_f32_e32 v2, v6, v2
	v_mul_f32_e64 v6, |v2|, s7
	v_exp_f32_e32 v6, v6
	v_add_f32_e32 v4, v8, v4
	v_max_f32_e64 v8, -v2, 0
	v_add_f32_e32 v7, v7, v3
	v_add_f32_e32 v13, 1.0, v6
	v_add_f32_e32 v2, -1.0, v13
	v_sub_f32_e32 v3, v2, v13
	v_add_f32_e32 v3, 1.0, v3
	v_sub_f32_e32 v2, v6, v2
	v_add_f32_e32 v14, v2, v3
	v_frexp_mant_f32_e32 v2, v13
	v_cmp_gt_f32_e32 vcc, s8, v2
	v_cvt_f64_f32_e32 v[2:3], v13
	v_frexp_exp_i32_f64_e32 v2, v[2:3]
	v_subbrev_co_u32_e32 v2, vcc, 0, v2, vcc
	v_sub_u32_e32 v3, 0, v2
	v_ldexp_f32 v13, v13, v3
	v_ldexp_f32 v3, v14, v3
	v_add_f32_e32 v14, -1.0, v13
	v_add_f32_e32 v17, 1.0, v13
	v_add_f32_e32 v15, 1.0, v14
	v_add_f32_e32 v18, -1.0, v17
	v_sub_f32_e32 v15, v13, v15
	v_sub_f32_e32 v13, v13, v18
	v_add_f32_e32 v15, v3, v15
	v_add_f32_e32 v3, v3, v13
	v_add_f32_e32 v13, v17, v3
	v_rcp_f32_e32 v18, v13
	v_add_f32_e32 v16, v14, v15
	v_sub_f32_e32 v14, v16, v14
	v_sub_f32_e32 v14, v15, v14
	v_sub_f32_e32 v15, v13, v17
	v_sub_f32_e32 v3, v3, v15
	v_mul_f32_e32 v15, v16, v18
	v_mul_f32_e32 v17, v13, v15
	v_fma_f32 v19, v15, v13, -v17
	v_fmac_f32_e32 v19, v15, v3
	v_add_f32_e32 v20, v17, v19
	v_sub_f32_e32 v21, v16, v20
	v_sub_f32_e32 v16, v16, v21
	v_sub_f32_e32 v17, v20, v17
	v_sub_f32_e32 v16, v16, v20
	v_add_f32_e32 v14, v14, v16
	v_sub_f32_e32 v16, v17, v19
	v_add_f32_e32 v14, v16, v14
	v_add_f32_e32 v16, v21, v14
	v_mul_f32_e32 v17, v18, v16
	v_mul_f32_e32 v19, v13, v17
	v_fma_f32 v13, v17, v13, -v19
	v_fmac_f32_e32 v13, v17, v3
	v_sub_f32_e32 v3, v21, v16
	v_add_f32_e32 v3, v14, v3
	v_add_f32_e32 v14, v19, v13
	v_sub_f32_e32 v20, v16, v14
	v_sub_f32_e32 v16, v16, v20
	v_sub_f32_e32 v19, v14, v19
	v_sub_f32_e32 v14, v16, v14
	v_add_f32_e32 v3, v3, v14
	v_sub_f32_e32 v13, v19, v13
	v_cvt_f32_i32_e32 v2, v2
	v_add_f32_e32 v3, v13, v3
	v_add_f32_e32 v13, v15, v17
	v_add_f32_e32 v3, v20, v3
	v_sub_f32_e32 v14, v13, v15
	v_mul_f32_e32 v3, v18, v3
	v_sub_f32_e32 v14, v17, v14
	v_add_f32_e32 v3, v14, v3
	v_mul_f32_e32 v17, 0x3f317218, v2
	v_add_f32_e32 v14, v13, v3
	v_fma_f32 v18, v2, s9, -v17
	v_mul_f32_e32 v15, v14, v14
	v_fmac_f32_e32 v18, 0xb102e308, v2
	v_sub_f32_e32 v2, v14, v13
	v_fmamk_f32 v16, v15, 0x3e9b6dac, v231
	v_sub_f32_e32 v2, v3, v2
	v_add_f32_e32 v3, v17, v18
	v_fmaak_f32 v16, v15, v16, 0x3f2aaada
	v_sub_f32_e32 v13, v3, v17
	v_ldexp_f32 v17, v14, 1
	v_mul_f32_e32 v14, v14, v15
	v_mul_f32_e32 v14, v14, v16
	v_add_f32_e32 v15, v17, v14
	v_sub_f32_e32 v16, v15, v17
	v_ldexp_f32 v2, v2, 1
	v_sub_f32_e32 v14, v14, v16
	v_add_f32_e32 v2, v2, v14
	v_add_f32_e32 v14, v15, v2
	v_sub_f32_e32 v15, v14, v15
	v_sub_f32_e32 v2, v2, v15
	v_add_f32_e32 v15, v3, v14
; template <int MODE, bool BIG = false> DI void gemm_tile(const Params& p, int tm, int tn, int kv, char* smem) {
;     ...
;       for (int e = 0; e < 4; ++e) {
;         const float z = -u[e];
;         const float sp = fmaxf(z, 0.f) + log1pf(__expf(-fabsf(z)));
;         u[e] = __expf(-__expf(-sp - 0.5f));
;       }
	v_sub_f32_e32 v16, v15, v3
	v_sub_f32_e32 v17, v15, v16
	v_sub_f32_e32 v13, v18, v13
	v_sub_f32_e32 v3, v3, v17
	v_sub_f32_e32 v14, v14, v16
	v_add_f32_e32 v3, v14, v3
	v_add_f32_e32 v14, v13, v2
	v_sub_f32_e32 v16, v14, v13
	v_sub_f32_e32 v17, v14, v16
	v_sub_f32_e32 v13, v13, v17
	v_sub_f32_e32 v2, v2, v16
	v_add_f32_e32 v3, v14, v3
	v_add_f32_e32 v2, v2, v13
	v_add_f32_e32 v13, v15, v3
	v_sub_f32_e32 v14, v13, v15
	v_sub_f32_e32 v3, v3, v14
	v_add_f32_e32 v2, v2, v3
	v_add_f32_e32 v2, v13, v2
	v_cmp_neq_f32_e32 vcc, s6, v6
	v_mul_f32_e64 v3, |v7|, s7
	v_max_f32_e64 v7, -v7, 0
	v_cndmask_b32_e32 v2, v238, v2, vcc
	v_cmp_ngt_f32_e32 vcc, -1.0, v6
	s_nop 1
	v_cndmask_b32_e32 v2, v239, v2, vcc
	v_cmp_neq_f32_e32 vcc, -1.0, v6
	s_nop 1
	v_cndmask_b32_e32 v2, v240, v2, vcc
	v_cmp_lt_f32_e64 vcc, |v6|, s10
	s_nop 1
	v_cndmask_b32_e32 v2, v2, v6, vcc
	v_add_f32_e32 v2, v8, v2
	v_sub_f32_e32 v2, -0.5, v2
	v_mul_f32_e32 v2, 0x3fb8aa3b, v2
	v_exp_f32_e32 v6, v3
	v_exp_f32_e32 v2, v2
	v_add_f32_e32 v8, v9, v5
	v_add_f32_e32 v9, 1.0, v6
	v_mul_f32_e32 v5, 0xbfb8aa3b, v2
	v_add_f32_e32 v2, -1.0, v9
	v_sub_f32_e32 v3, v2, v9
	v_add_f32_e32 v3, 1.0, v3
	v_sub_f32_e32 v2, v6, v2
	v_add_f32_e32 v13, v2, v3
	v_frexp_mant_f32_e32 v2, v9
	v_cmp_gt_f32_e32 vcc, s8, v2
	v_cvt_f64_f32_e32 v[2:3], v9
	v_frexp_exp_i32_f64_e32 v2, v[2:3]
	v_subbrev_co_u32_e32 v2, vcc, 0, v2, vcc
	v_sub_u32_e32 v3, 0, v2
	v_ldexp_f32 v9, v9, v3
	v_ldexp_f32 v3, v13, v3
	v_add_f32_e32 v13, -1.0, v9
	v_add_f32_e32 v16, 1.0, v9
	v_add_f32_e32 v14, 1.0, v13
	v_add_f32_e32 v17, -1.0, v16
	v_sub_f32_e32 v14, v9, v14
	v_sub_f32_e32 v9, v9, v17
	v_add_f32_e32 v14, v3, v14
	v_add_f32_e32 v3, v3, v9
	v_add_f32_e32 v9, v16, v3
	v_rcp_f32_e32 v17, v9
	v_add_f32_e32 v15, v13, v14
	v_sub_f32_e32 v13, v15, v13
	v_sub_f32_e32 v13, v14, v13
	v_sub_f32_e32 v14, v9, v16
	v_sub_f32_e32 v3, v3, v14
	v_mul_f32_e32 v14, v15, v17
	v_mul_f32_e32 v16, v9, v14
	v_fma_f32 v18, v14, v9, -v16
	v_fmac_f32_e32 v18, v14, v3
	v_add_f32_e32 v19, v16, v18
	v_sub_f32_e32 v20, v15, v19
	v_sub_f32_e32 v15, v15, v20
	v_sub_f32_e32 v16, v19, v16
	v_sub_f32_e32 v15, v15, v19
	v_add_f32_e32 v13, v13, v15
	v_sub_f32_e32 v15, v16, v18
	v_add_f32_e32 v13, v15, v13
	v_add_f32_e32 v15, v20, v13
	v_mul_f32_e32 v16, v17, v15
	v_mul_f32_e32 v18, v9, v16
	v_fma_f32 v9, v16, v9, -v18
	v_fmac_f32_e32 v9, v16, v3
	v_sub_f32_e32 v3, v20, v15
	v_add_f32_e32 v3, v13, v3
	v_add_f32_e32 v13, v18, v9
	v_sub_f32_e32 v19, v15, v13
	v_sub_f32_e32 v15, v15, v19
	v_sub_f32_e32 v18, v13, v18
	v_sub_f32_e32 v13, v15, v13
	v_add_f32_e32 v3, v3, v13
	v_sub_f32_e32 v9, v18, v9
	v_cvt_f32_i32_e32 v2, v2
	v_add_f32_e32 v3, v9, v3
	v_add_f32_e32 v9, v14, v16
	v_add_f32_e32 v3, v19, v3
	v_sub_f32_e32 v13, v9, v14
	v_mul_f32_e32 v3, v17, v3
	v_sub_f32_e32 v13, v16, v13
	v_add_f32_e32 v3, v13, v3
	v_mul_f32_e32 v16, 0x3f317218, v2
	v_add_f32_e32 v13, v9, v3
	v_fma_f32 v17, v2, s9, -v16
	v_mul_f32_e32 v14, v13, v13
	v_fmac_f32_e32 v17, 0xb102e308, v2
	v_sub_f32_e32 v2, v13, v9
	v_fmamk_f32 v15, v14, 0x3e9b6dac, v231
	v_sub_f32_e32 v2, v3, v2
	v_add_f32_e32 v3, v16, v17
	v_fmaak_f32 v15, v14, v15, 0x3f2aaada
	v_sub_f32_e32 v9, v3, v16
	v_ldexp_f32 v16, v13, 1
	v_mul_f32_e32 v13, v13, v14
	v_mul_f32_e32 v13, v13, v15
	v_add_f32_e32 v14, v16, v13
	v_sub_f32_e32 v15, v14, v16
	v_ldexp_f32 v2, v2, 1
	v_sub_f32_e32 v13, v13, v15
	v_add_f32_e32 v2, v2, v13
	v_add_f32_e32 v13, v14, v2
	v_sub_f32_e32 v14, v13, v14
	v_sub_f32_e32 v2, v2, v14
	v_add_f32_e32 v14, v3, v13
	v_sub_f32_e32 v15, v14, v3
	v_sub_f32_e32 v16, v14, v15
	v_sub_f32_e32 v9, v17, v9
	v_sub_f32_e32 v3, v3, v16
	v_sub_f32_e32 v13, v13, v15
	v_add_f32_e32 v3, v13, v3
	v_add_f32_e32 v13, v9, v2
	v_sub_f32_e32 v15, v13, v9
	v_sub_f32_e32 v16, v13, v15
	v_sub_f32_e32 v9, v9, v16
	v_sub_f32_e32 v2, v2, v15
	v_add_f32_e32 v3, v13, v3
	v_add_f32_e32 v2, v2, v9
	v_add_f32_e32 v9, v14, v3
	v_sub_f32_e32 v13, v9, v14
	v_sub_f32_e32 v3, v3, v13
	v_add_f32_e32 v2, v2, v3
	v_add_f32_e32 v2, v9, v2
	v_cmp_neq_f32_e32 vcc, s6, v6
	s_nop 1
	v_cndmask_b32_e32 v2, v238, v2, vcc
	v_cmp_ngt_f32_e32 vcc, -1.0, v6
	s_nop 1
	v_cndmask_b32_e32 v2, v239, v2, vcc
	v_cmp_neq_f32_e32 vcc, -1.0, v6
	s_nop 1
	v_cndmask_b32_e32 v2, v240, v2, vcc
	v_cmp_lt_f32_e64 vcc, |v6|, s10
	s_nop 1
	v_cndmask_b32_e32 v2, v2, v6, vcc
	v_add_f32_e32 v2, v7, v2
	v_sub_f32_e32 v2, -0.5, v2
	v_mul_f32_e32 v2, 0x3fb8aa3b, v2
	v_exp_f32_e32 v3, v2
	v_mul_f32_e64 v2, |v4|, s7
	v_exp_f32_e32 v6, v2
	v_max_f32_e64 v7, -v4, 0
	v_exp_f32_e32 v2, v5
	v_mul_f32_e32 v3, 0xbfb8aa3b, v3
	v_add_f32_e32 v9, 1.0, v6
	v_add_f32_e32 v4, -1.0, v9
	v_sub_f32_e32 v5, v4, v9
	v_add_f32_e32 v5, 1.0, v5
	v_sub_f32_e32 v4, v6, v4
	v_add_f32_e32 v13, v4, v5
	v_frexp_mant_f32_e32 v4, v9
	v_cmp_gt_f32_e32 vcc, s8, v4
	v_cvt_f64_f32_e32 v[4:5], v9
	v_frexp_exp_i32_f64_e32 v4, v[4:5]
	v_subbrev_co_u32_e32 v4, vcc, 0, v4, vcc
	v_sub_u32_e32 v5, 0, v4
	v_ldexp_f32 v9, v9, v5
	v_ldexp_f32 v5, v13, v5
	v_add_f32_e32 v13, -1.0, v9
	v_add_f32_e32 v16, 1.0, v9
	v_add_f32_e32 v14, 1.0, v13
	v_add_f32_e32 v17, -1.0, v16
	v_sub_f32_e32 v14, v9, v14
	v_sub_f32_e32 v9, v9, v17
	v_add_f32_e32 v14, v5, v14
	v_add_f32_e32 v5, v5, v9
	v_add_f32_e32 v9, v16, v5
	v_rcp_f32_e32 v17, v9
	v_add_f32_e32 v15, v13, v14
	v_sub_f32_e32 v13, v15, v13
	v_sub_f32_e32 v13, v14, v13
	v_sub_f32_e32 v14, v9, v16
	v_sub_f32_e32 v5, v5, v14
	v_mul_f32_e32 v14, v15, v17
	v_mul_f32_e32 v16, v9, v14
	v_fma_f32 v18, v14, v9, -v16
	v_fmac_f32_e32 v18, v14, v5
	v_add_f32_e32 v19, v16, v18
	v_sub_f32_e32 v20, v15, v19
	v_sub_f32_e32 v15, v15, v20
	v_sub_f32_e32 v16, v19, v16
	v_sub_f32_e32 v15, v15, v19
; template <int MODE, bool BIG = false> DI void gemm_tile(const Params& p, int tm, int tn, int kv, char* smem) {
;     ...
;     for (int c4 = 0; c4 < 16; ++c4) {
;       float4 v = crow4[c4], ww = w04[c4];
;       float u[4] = {v.x + ww.x, v.y + ww.y, v.z + ww.z, v.w + ww.w};
; #pragma unroll
;       for (int e = 0; e < 4; ++e) {
;         const float z = -u[e];
;         const float sp = fmaxf(z, 0.f) + log1pf(__expf(-fabsf(z)));
;         u[e] = __expf(-__expf(-sp - 0.5f));
;       }
;       W4[c4] = make_float4(u[0], u[1], u[2], u[3]);
	v_add_f32_e32 v13, v13, v15
	v_sub_f32_e32 v15, v16, v18
	v_add_f32_e32 v13, v15, v13
	v_add_f32_e32 v15, v20, v13
	v_mul_f32_e32 v16, v17, v15
	v_mul_f32_e32 v18, v9, v16
	v_fma_f32 v9, v16, v9, -v18
	v_fmac_f32_e32 v9, v16, v5
	v_sub_f32_e32 v5, v20, v15
	v_add_f32_e32 v5, v13, v5
	v_add_f32_e32 v13, v18, v9
	v_sub_f32_e32 v19, v15, v13
	v_sub_f32_e32 v15, v15, v19
	v_sub_f32_e32 v18, v13, v18
	v_sub_f32_e32 v13, v15, v13
	v_add_f32_e32 v5, v5, v13
	v_sub_f32_e32 v9, v18, v9
	v_cvt_f32_i32_e32 v4, v4
	v_add_f32_e32 v5, v9, v5
	v_add_f32_e32 v9, v14, v16
	v_add_f32_e32 v5, v19, v5
	v_sub_f32_e32 v13, v9, v14
	v_mul_f32_e32 v5, v17, v5
	v_sub_f32_e32 v13, v16, v13
	v_add_f32_e32 v5, v13, v5
	v_mul_f32_e32 v16, 0x3f317218, v4
	v_add_f32_e32 v13, v9, v5
	v_fma_f32 v17, v4, s9, -v16
	v_mul_f32_e32 v14, v13, v13
	v_fmac_f32_e32 v17, 0xb102e308, v4
	v_sub_f32_e32 v4, v13, v9
	v_fmamk_f32 v15, v14, 0x3e9b6dac, v231
	v_sub_f32_e32 v4, v5, v4
	v_add_f32_e32 v5, v16, v17
	v_fmaak_f32 v15, v14, v15, 0x3f2aaada
	v_sub_f32_e32 v9, v5, v16
	v_ldexp_f32 v16, v13, 1
	v_mul_f32_e32 v13, v13, v14
	v_mul_f32_e32 v13, v13, v15
	v_add_f32_e32 v14, v16, v13
	v_sub_f32_e32 v15, v14, v16
	v_ldexp_f32 v4, v4, 1
	v_sub_f32_e32 v13, v13, v15
	v_add_f32_e32 v4, v4, v13
	v_add_f32_e32 v13, v14, v4
	v_sub_f32_e32 v14, v13, v14
	v_sub_f32_e32 v4, v4, v14
	v_add_f32_e32 v14, v5, v13
	v_sub_f32_e32 v15, v14, v5
	v_sub_f32_e32 v16, v14, v15
	v_sub_f32_e32 v9, v17, v9
	v_sub_f32_e32 v5, v5, v16
	v_sub_f32_e32 v13, v13, v15
	v_add_f32_e32 v5, v13, v5
	v_add_f32_e32 v13, v9, v4
	v_sub_f32_e32 v15, v13, v9
	v_sub_f32_e32 v16, v13, v15
	v_sub_f32_e32 v9, v9, v16
	v_sub_f32_e32 v4, v4, v15
	v_add_f32_e32 v5, v13, v5
	v_add_f32_e32 v4, v4, v9
	v_add_f32_e32 v9, v14, v5
	v_sub_f32_e32 v13, v9, v14
	v_sub_f32_e32 v5, v5, v13
	v_add_f32_e32 v4, v4, v5
	v_add_f32_e32 v4, v9, v4
	v_cmp_neq_f32_e32 vcc, s6, v6
	v_mul_f32_e64 v5, |v8|, s7
	v_max_f32_e64 v8, -v8, 0
	v_cndmask_b32_e32 v4, v238, v4, vcc
	v_cmp_ngt_f32_e32 vcc, -1.0, v6
	v_exp_f32_e32 v3, v3
	s_nop 0
	v_cndmask_b32_e32 v4, v239, v4, vcc
	v_cmp_neq_f32_e32 vcc, -1.0, v6
	s_nop 1
	v_cndmask_b32_e32 v4, v240, v4, vcc
	v_cmp_lt_f32_e64 vcc, |v6|, s10
	s_nop 1
	v_cndmask_b32_e32 v4, v4, v6, vcc
	v_exp_f32_e32 v6, v5
	v_add_f32_e32 v4, v7, v4
	v_sub_f32_e32 v4, -0.5, v4
	v_mul_f32_e32 v4, 0x3fb8aa3b, v4
	v_add_f32_e32 v9, 1.0, v6
	v_exp_f32_e32 v7, v4
	v_add_f32_e32 v4, -1.0, v9
	v_sub_f32_e32 v5, v4, v9
	v_add_f32_e32 v5, 1.0, v5
	v_sub_f32_e32 v4, v6, v4
	v_add_f32_e32 v13, v4, v5
	v_frexp_mant_f32_e32 v4, v9
	v_cmp_gt_f32_e32 vcc, s8, v4
	v_cvt_f64_f32_e32 v[4:5], v9
	v_frexp_exp_i32_f64_e32 v4, v[4:5]
	v_subbrev_co_u32_e32 v4, vcc, 0, v4, vcc
	v_sub_u32_e32 v5, 0, v4
	v_ldexp_f32 v9, v9, v5
	v_ldexp_f32 v5, v13, v5
	v_add_f32_e32 v13, -1.0, v9
	v_add_f32_e32 v16, 1.0, v9
	v_add_f32_e32 v14, 1.0, v13
	v_add_f32_e32 v17, -1.0, v16
	v_sub_f32_e32 v14, v9, v14
	v_sub_f32_e32 v9, v9, v17
	v_add_f32_e32 v14, v5, v14
	v_add_f32_e32 v5, v5, v9
	v_add_f32_e32 v9, v16, v5
	v_rcp_f32_e32 v17, v9
	v_add_f32_e32 v15, v13, v14
	v_sub_f32_e32 v13, v15, v13
	v_sub_f32_e32 v13, v14, v13
	v_sub_f32_e32 v14, v9, v16
	v_sub_f32_e32 v5, v5, v14
	v_mul_f32_e32 v14, v15, v17
	v_mul_f32_e32 v16, v9, v14
	v_fma_f32 v18, v14, v9, -v16
	v_fmac_f32_e32 v18, v14, v5
	v_add_f32_e32 v19, v16, v18
	v_sub_f32_e32 v20, v15, v19
	v_sub_f32_e32 v15, v15, v20
	v_sub_f32_e32 v16, v19, v16
	v_sub_f32_e32 v15, v15, v19
	v_add_f32_e32 v13, v13, v15
	v_sub_f32_e32 v15, v16, v18
	v_add_f32_e32 v13, v15, v13
	v_add_f32_e32 v15, v20, v13
	v_mul_f32_e32 v16, v17, v15
	v_mul_f32_e32 v18, v9, v16
	v_fma_f32 v9, v16, v9, -v18
	v_fmac_f32_e32 v9, v16, v5
	v_sub_f32_e32 v5, v20, v15
	v_add_f32_e32 v5, v13, v5
	v_add_f32_e32 v13, v18, v9
	v_sub_f32_e32 v19, v15, v13
	v_sub_f32_e32 v15, v15, v19
	v_sub_f32_e32 v18, v13, v18
	v_sub_f32_e32 v13, v15, v13
	v_add_f32_e32 v5, v5, v13
	v_sub_f32_e32 v9, v18, v9
	v_cvt_f32_i32_e32 v4, v4
	v_add_f32_e32 v5, v9, v5
	v_add_f32_e32 v9, v14, v16
	v_add_f32_e32 v5, v19, v5
	v_sub_f32_e32 v13, v9, v14
	v_mul_f32_e32 v5, v17, v5
	v_sub_f32_e32 v13, v16, v13
	v_add_f32_e32 v5, v13, v5
	v_mul_f32_e32 v16, 0x3f317218, v4
	v_add_f32_e32 v13, v9, v5
	v_fma_f32 v17, v4, s9, -v16
	v_mul_f32_e32 v14, v13, v13
	v_fmac_f32_e32 v17, 0xb102e308, v4
	v_sub_f32_e32 v4, v13, v9
	v_fmamk_f32 v15, v14, 0x3e9b6dac, v231
	v_sub_f32_e32 v4, v5, v4
	v_add_f32_e32 v5, v16, v17
	v_fmaak_f32 v15, v14, v15, 0x3f2aaada
	v_sub_f32_e32 v9, v5, v16
	v_ldexp_f32 v16, v13, 1
	v_mul_f32_e32 v13, v13, v14
	v_mul_f32_e32 v13, v13, v15
	v_add_f32_e32 v14, v16, v13
	v_sub_f32_e32 v15, v14, v16
	v_ldexp_f32 v4, v4, 1
	v_sub_f32_e32 v13, v13, v15
	v_add_f32_e32 v4, v4, v13
	v_add_f32_e32 v13, v14, v4
	v_sub_f32_e32 v14, v13, v14
	v_sub_f32_e32 v4, v4, v14
	v_add_f32_e32 v14, v5, v13
	v_sub_f32_e32 v15, v14, v5
	v_sub_f32_e32 v16, v14, v15
	v_sub_f32_e32 v9, v17, v9
	v_sub_f32_e32 v5, v5, v16
	v_sub_f32_e32 v13, v13, v15
	v_add_f32_e32 v5, v13, v5
	v_add_f32_e32 v13, v9, v4
	v_sub_f32_e32 v15, v13, v9
	v_sub_f32_e32 v16, v13, v15
	v_sub_f32_e32 v9, v9, v16
	v_sub_f32_e32 v4, v4, v15
	v_add_f32_e32 v5, v13, v5
	v_add_f32_e32 v4, v4, v9
	v_add_f32_e32 v9, v14, v5
	v_sub_f32_e32 v13, v9, v14
	v_sub_f32_e32 v5, v5, v13
	v_add_f32_e32 v4, v4, v5
	v_add_f32_e32 v4, v9, v4
	v_cmp_neq_f32_e32 vcc, s6, v6
	s_nop 1
	v_cndmask_b32_e32 v4, v238, v4, vcc
	v_cmp_ngt_f32_e32 vcc, -1.0, v6
	s_nop 1
	v_cndmask_b32_e32 v4, v239, v4, vcc
	v_cmp_neq_f32_e32 vcc, -1.0, v6
	s_nop 1
	v_cndmask_b32_e32 v4, v240, v4, vcc
	v_cmp_lt_f32_e64 vcc, |v6|, s10
	s_nop 1
	v_cndmask_b32_e32 v4, v4, v6, vcc
	v_add_f32_e32 v4, v8, v4
	v_sub_f32_e32 v4, -0.5, v4
	v_mul_f32_e32 v4, 0x3fb8aa3b, v4
	v_exp_f32_e32 v5, v4
	v_mul_f32_e32 v4, 0xbfb8aa3b, v7
	v_exp_f32_e32 v4, v4
	ds_read_b128 v[6:9], v12 offset:144
	v_mul_f32_e32 v5, 0xbfb8aa3b, v5
	v_exp_f32_e32 v5, v5
	ds_write_b128 v75, v[2:5] offset:128
	ds_read_b128 v[2:5], v74 offset:144
	s_waitcnt lgkmcnt(0)
; template <int MODE, bool BIG = false> DI void gemm_tile(const Params& p, int tm, int tn, int kv, char* smem) {
;     ...
;       float4 v = crow4[c4], ww = w04[c4];
;       float u[4] = {v.x + ww.x, v.y + ww.y, v.z + ww.z, v.w + ww.w};
; #pragma unroll
;       for (int e = 0; e < 4; ++e) {
;         const float z = -u[e];
;         const float sp = fmaxf(z, 0.f) + log1pf(__expf(-fabsf(z)));
;         u[e] = __expf(-__expf(-sp - 0.5f));
;       }
	v_add_f32_e32 v2, v6, v2
	v_mul_f32_e64 v6, |v2|, s7
	v_exp_f32_e32 v6, v6
	v_add_f32_e32 v4, v8, v4
	v_max_f32_e64 v8, -v2, 0
	v_add_f32_e32 v7, v7, v3
	v_add_f32_e32 v13, 1.0, v6
	v_add_f32_e32 v2, -1.0, v13
	v_sub_f32_e32 v3, v2, v13
	v_add_f32_e32 v3, 1.0, v3
	v_sub_f32_e32 v2, v6, v2
	v_add_f32_e32 v14, v2, v3
	v_frexp_mant_f32_e32 v2, v13
	v_cmp_gt_f32_e32 vcc, s8, v2
	v_cvt_f64_f32_e32 v[2:3], v13
	v_frexp_exp_i32_f64_e32 v2, v[2:3]
	v_subbrev_co_u32_e32 v2, vcc, 0, v2, vcc
	v_sub_u32_e32 v3, 0, v2
	v_ldexp_f32 v13, v13, v3
	v_ldexp_f32 v3, v14, v3
	v_add_f32_e32 v14, -1.0, v13
	v_add_f32_e32 v17, 1.0, v13
	v_add_f32_e32 v15, 1.0, v14
	v_add_f32_e32 v18, -1.0, v17
	v_sub_f32_e32 v15, v13, v15
	v_sub_f32_e32 v13, v13, v18
	v_add_f32_e32 v15, v3, v15
	v_add_f32_e32 v3, v3, v13
	v_add_f32_e32 v13, v17, v3
	v_rcp_f32_e32 v18, v13
	v_add_f32_e32 v16, v14, v15
	v_sub_f32_e32 v14, v16, v14
	v_sub_f32_e32 v14, v15, v14
	v_sub_f32_e32 v15, v13, v17
	v_sub_f32_e32 v3, v3, v15
	v_mul_f32_e32 v15, v16, v18
	v_mul_f32_e32 v17, v13, v15
	v_fma_f32 v19, v15, v13, -v17
	v_fmac_f32_e32 v19, v15, v3
	v_add_f32_e32 v20, v17, v19
	v_sub_f32_e32 v21, v16, v20
	v_sub_f32_e32 v16, v16, v21
	v_sub_f32_e32 v17, v20, v17
	v_sub_f32_e32 v16, v16, v20
	v_add_f32_e32 v14, v14, v16
	v_sub_f32_e32 v16, v17, v19
	v_add_f32_e32 v14, v16, v14
	v_add_f32_e32 v16, v21, v14
	v_mul_f32_e32 v17, v18, v16
	v_mul_f32_e32 v19, v13, v17
	v_fma_f32 v13, v17, v13, -v19
	v_fmac_f32_e32 v13, v17, v3
	v_sub_f32_e32 v3, v21, v16
	v_add_f32_e32 v3, v14, v3
	v_add_f32_e32 v14, v19, v13
	v_sub_f32_e32 v20, v16, v14
	v_sub_f32_e32 v16, v16, v20
	v_sub_f32_e32 v19, v14, v19
	v_sub_f32_e32 v14, v16, v14
	v_add_f32_e32 v3, v3, v14
	v_sub_f32_e32 v13, v19, v13
	v_cvt_f32_i32_e32 v2, v2
	v_add_f32_e32 v3, v13, v3
	v_add_f32_e32 v13, v15, v17
	v_add_f32_e32 v3, v20, v3
	v_sub_f32_e32 v14, v13, v15
	v_mul_f32_e32 v3, v18, v3
	v_sub_f32_e32 v14, v17, v14
	v_add_f32_e32 v3, v14, v3
	v_mul_f32_e32 v17, 0x3f317218, v2
	v_add_f32_e32 v14, v13, v3
	v_fma_f32 v18, v2, s9, -v17
	v_mul_f32_e32 v15, v14, v14
	v_fmac_f32_e32 v18, 0xb102e308, v2
	v_sub_f32_e32 v2, v14, v13
	v_fmamk_f32 v16, v15, 0x3e9b6dac, v231
	v_sub_f32_e32 v2, v3, v2
	v_add_f32_e32 v3, v17, v18
	v_fmaak_f32 v16, v15, v16, 0x3f2aaada
	v_sub_f32_e32 v13, v3, v17
	v_ldexp_f32 v17, v14, 1
	v_mul_f32_e32 v14, v14, v15
	v_mul_f32_e32 v14, v14, v16
	v_add_f32_e32 v15, v17, v14
	v_sub_f32_e32 v16, v15, v17
	v_ldexp_f32 v2, v2, 1
	v_sub_f32_e32 v14, v14, v16
	v_add_f32_e32 v2, v2, v14
	v_add_f32_e32 v14, v15, v2
	v_sub_f32_e32 v15, v14, v15
	v_sub_f32_e32 v2, v2, v15
	v_add_f32_e32 v15, v3, v14
	v_sub_f32_e32 v16, v15, v3
	v_sub_f32_e32 v17, v15, v16
	v_sub_f32_e32 v13, v18, v13
	v_sub_f32_e32 v3, v3, v17
	v_sub_f32_e32 v14, v14, v16
	v_add_f32_e32 v3, v14, v3
	v_add_f32_e32 v14, v13, v2
	v_sub_f32_e32 v16, v14, v13
	v_sub_f32_e32 v17, v14, v16
	v_sub_f32_e32 v13, v13, v17
	v_sub_f32_e32 v2, v2, v16
	v_add_f32_e32 v3, v14, v3
	v_add_f32_e32 v2, v2, v13
	v_add_f32_e32 v13, v15, v3
	v_sub_f32_e32 v14, v13, v15
	v_sub_f32_e32 v3, v3, v14
	v_add_f32_e32 v2, v2, v3
	v_add_f32_e32 v2, v13, v2
	v_cmp_neq_f32_e32 vcc, s6, v6
	v_mul_f32_e64 v3, |v7|, s7
	v_max_f32_e64 v7, -v7, 0
	v_cndmask_b32_e32 v2, v238, v2, vcc
	v_cmp_ngt_f32_e32 vcc, -1.0, v6
	s_nop 1
	v_cndmask_b32_e32 v2, v239, v2, vcc
	v_cmp_neq_f32_e32 vcc, -1.0, v6
	s_nop 1
	v_cndmask_b32_e32 v2, v240, v2, vcc
	v_cmp_lt_f32_e64 vcc, |v6|, s10
	s_nop 1
	v_cndmask_b32_e32 v2, v2, v6, vcc
	v_add_f32_e32 v2, v8, v2
	v_sub_f32_e32 v2, -0.5, v2
	v_mul_f32_e32 v2, 0x3fb8aa3b, v2
	v_exp_f32_e32 v6, v3
	v_exp_f32_e32 v2, v2
	v_add_f32_e32 v8, v9, v5
	v_add_f32_e32 v9, 1.0, v6
	v_mul_f32_e32 v5, 0xbfb8aa3b, v2
	v_add_f32_e32 v2, -1.0, v9
	v_sub_f32_e32 v3, v2, v9
	v_add_f32_e32 v3, 1.0, v3
	v_sub_f32_e32 v2, v6, v2
	v_add_f32_e32 v13, v2, v3
	v_frexp_mant_f32_e32 v2, v9
	v_cmp_gt_f32_e32 vcc, s8, v2
	v_cvt_f64_f32_e32 v[2:3], v9
	v_frexp_exp_i32_f64_e32 v2, v[2:3]
	v_subbrev_co_u32_e32 v2, vcc, 0, v2, vcc
	v_sub_u32_e32 v3, 0, v2
	v_ldexp_f32 v9, v9, v3
	v_ldexp_f32 v3, v13, v3
	v_add_f32_e32 v13, -1.0, v9
	v_add_f32_e32 v16, 1.0, v9
	v_add_f32_e32 v14, 1.0, v13
	v_add_f32_e32 v17, -1.0, v16
	v_sub_f32_e32 v14, v9, v14
	v_sub_f32_e32 v9, v9, v17
	v_add_f32_e32 v14, v3, v14
	v_add_f32_e32 v3, v3, v9
	v_add_f32_e32 v9, v16, v3
	v_rcp_f32_e32 v17, v9
	v_add_f32_e32 v15, v13, v14
	v_sub_f32_e32 v13, v15, v13
	v_sub_f32_e32 v13, v14, v13
	v_sub_f32_e32 v14, v9, v16
	v_sub_f32_e32 v3, v3, v14
	v_mul_f32_e32 v14, v15, v17
	v_mul_f32_e32 v16, v9, v14
	v_fma_f32 v18, v14, v9, -v16
	v_fmac_f32_e32 v18, v14, v3
	v_add_f32_e32 v19, v16, v18
	v_sub_f32_e32 v20, v15, v19
	v_sub_f32_e32 v15, v15, v20
	v_sub_f32_e32 v16, v19, v16
	v_sub_f32_e32 v15, v15, v19
	v_add_f32_e32 v13, v13, v15
	v_sub_f32_e32 v15, v16, v18
	v_add_f32_e32 v13, v15, v13
	v_add_f32_e32 v15, v20, v13
	v_mul_f32_e32 v16, v17, v15
	v_mul_f32_e32 v18, v9, v16
	v_fma_f32 v9, v16, v9, -v18
	v_fmac_f32_e32 v9, v16, v3
	v_sub_f32_e32 v3, v20, v15
	v_add_f32_e32 v3, v13, v3
	v_add_f32_e32 v13, v18, v9
	v_sub_f32_e32 v19, v15, v13
	v_sub_f32_e32 v15, v15, v19
	v_sub_f32_e32 v18, v13, v18
	v_sub_f32_e32 v13, v15, v13
	v_add_f32_e32 v3, v3, v13
	v_sub_f32_e32 v9, v18, v9
	v_cvt_f32_i32_e32 v2, v2
	v_add_f32_e32 v3, v9, v3
	v_add_f32_e32 v9, v14, v16
	v_add_f32_e32 v3, v19, v3
	v_sub_f32_e32 v13, v9, v14
	v_mul_f32_e32 v3, v17, v3
	v_sub_f32_e32 v13, v16, v13
	v_add_f32_e32 v3, v13, v3
	v_mul_f32_e32 v16, 0x3f317218, v2
	v_add_f32_e32 v13, v9, v3
	v_fma_f32 v17, v2, s9, -v16
	v_mul_f32_e32 v14, v13, v13
	v_fmac_f32_e32 v17, 0xb102e308, v2
; template <int MODE, bool BIG = false> DI void gemm_tile(const Params& p, int tm, int tn, int kv, char* smem) {
;     ...
;       for (int e = 0; e < 4; ++e) {
;         const float z = -u[e];
;         const float sp = fmaxf(z, 0.f) + log1pf(__expf(-fabsf(z)));
;         u[e] = __expf(-__expf(-sp - 0.5f));
;       }
	v_sub_f32_e32 v2, v13, v9
	v_fmamk_f32 v15, v14, 0x3e9b6dac, v231
	v_sub_f32_e32 v2, v3, v2
	v_add_f32_e32 v3, v16, v17
	v_fmaak_f32 v15, v14, v15, 0x3f2aaada
	v_sub_f32_e32 v9, v3, v16
	v_ldexp_f32 v16, v13, 1
	v_mul_f32_e32 v13, v13, v14
	v_mul_f32_e32 v13, v13, v15
	v_add_f32_e32 v14, v16, v13
	v_sub_f32_e32 v15, v14, v16
	v_ldexp_f32 v2, v2, 1
	v_sub_f32_e32 v13, v13, v15
	v_add_f32_e32 v2, v2, v13
	v_add_f32_e32 v13, v14, v2
	v_sub_f32_e32 v14, v13, v14
	v_sub_f32_e32 v2, v2, v14
	v_add_f32_e32 v14, v3, v13
	v_sub_f32_e32 v15, v14, v3
	v_sub_f32_e32 v16, v14, v15
	v_sub_f32_e32 v9, v17, v9
	v_sub_f32_e32 v3, v3, v16
	v_sub_f32_e32 v13, v13, v15
	v_add_f32_e32 v3, v13, v3
	v_add_f32_e32 v13, v9, v2
	v_sub_f32_e32 v15, v13, v9
	v_sub_f32_e32 v16, v13, v15
	v_sub_f32_e32 v9, v9, v16
	v_sub_f32_e32 v2, v2, v15
	v_add_f32_e32 v3, v13, v3
	v_add_f32_e32 v2, v2, v9
	v_add_f32_e32 v9, v14, v3
	v_sub_f32_e32 v13, v9, v14
	v_sub_f32_e32 v3, v3, v13
	v_add_f32_e32 v2, v2, v3
	v_add_f32_e32 v2, v9, v2
	v_cmp_neq_f32_e32 vcc, s6, v6
	s_nop 1
	v_cndmask_b32_e32 v2, v238, v2, vcc
	v_cmp_ngt_f32_e32 vcc, -1.0, v6
	s_nop 1
	v_cndmask_b32_e32 v2, v239, v2, vcc
	v_cmp_neq_f32_e32 vcc, -1.0, v6
	s_nop 1
	v_cndmask_b32_e32 v2, v240, v2, vcc
	v_cmp_lt_f32_e64 vcc, |v6|, s10
	s_nop 1
	v_cndmask_b32_e32 v2, v2, v6, vcc
	v_add_f32_e32 v2, v7, v2
	v_sub_f32_e32 v2, -0.5, v2
	v_mul_f32_e32 v2, 0x3fb8aa3b, v2
	v_exp_f32_e32 v3, v2
	v_mul_f32_e64 v2, |v4|, s7
	v_exp_f32_e32 v6, v2
	v_max_f32_e64 v7, -v4, 0
	v_exp_f32_e32 v2, v5
	v_mul_f32_e32 v3, 0xbfb8aa3b, v3
	v_add_f32_e32 v9, 1.0, v6
	v_add_f32_e32 v4, -1.0, v9
	v_sub_f32_e32 v5, v4, v9
	v_add_f32_e32 v5, 1.0, v5
	v_sub_f32_e32 v4, v6, v4
	v_add_f32_e32 v13, v4, v5
	v_frexp_mant_f32_e32 v4, v9
	v_cmp_gt_f32_e32 vcc, s8, v4
	v_cvt_f64_f32_e32 v[4:5], v9
	v_frexp_exp_i32_f64_e32 v4, v[4:5]
	v_subbrev_co_u32_e32 v4, vcc, 0, v4, vcc
	v_sub_u32_e32 v5, 0, v4
	v_ldexp_f32 v9, v9, v5
	v_ldexp_f32 v5, v13, v5
	v_add_f32_e32 v13, -1.0, v9
	v_add_f32_e32 v16, 1.0, v9
	v_add_f32_e32 v14, 1.0, v13
	v_add_f32_e32 v17, -1.0, v16
	v_sub_f32_e32 v14, v9, v14
	v_sub_f32_e32 v9, v9, v17
	v_add_f32_e32 v14, v5, v14
	v_add_f32_e32 v5, v5, v9
	v_add_f32_e32 v9, v16, v5
	v_rcp_f32_e32 v17, v9
	v_add_f32_e32 v15, v13, v14
	v_sub_f32_e32 v13, v15, v13
	v_sub_f32_e32 v13, v14, v13
	v_sub_f32_e32 v14, v9, v16
	v_sub_f32_e32 v5, v5, v14
	v_mul_f32_e32 v14, v15, v17
	v_mul_f32_e32 v16, v9, v14
	v_fma_f32 v18, v14, v9, -v16
	v_fmac_f32_e32 v18, v14, v5
	v_add_f32_e32 v19, v16, v18
	v_sub_f32_e32 v20, v15, v19
	v_sub_f32_e32 v15, v15, v20
	v_sub_f32_e32 v16, v19, v16
	v_sub_f32_e32 v15, v15, v19
	v_add_f32_e32 v13, v13, v15
	v_sub_f32_e32 v15, v16, v18
	v_add_f32_e32 v13, v15, v13
	v_add_f32_e32 v15, v20, v13
	v_mul_f32_e32 v16, v17, v15
	v_mul_f32_e32 v18, v9, v16
	v_fma_f32 v9, v16, v9, -v18
	v_fmac_f32_e32 v9, v16, v5
	v_sub_f32_e32 v5, v20, v15
	v_add_f32_e32 v5, v13, v5
	v_add_f32_e32 v13, v18, v9
	v_sub_f32_e32 v19, v15, v13
	v_sub_f32_e32 v15, v15, v19
	v_sub_f32_e32 v18, v13, v18
	v_sub_f32_e32 v13, v15, v13
	v_add_f32_e32 v5, v5, v13
	v_sub_f32_e32 v9, v18, v9
	v_cvt_f32_i32_e32 v4, v4
	v_add_f32_e32 v5, v9, v5
	v_add_f32_e32 v9, v14, v16
	v_add_f32_e32 v5, v19, v5
	v_sub_f32_e32 v13, v9, v14
	v_mul_f32_e32 v5, v17, v5
	v_sub_f32_e32 v13, v16, v13
	v_add_f32_e32 v5, v13, v5
	v_mul_f32_e32 v16, 0x3f317218, v4
	v_add_f32_e32 v13, v9, v5
	v_fma_f32 v17, v4, s9, -v16
	v_mul_f32_e32 v14, v13, v13
	v_fmac_f32_e32 v17, 0xb102e308, v4
	v_sub_f32_e32 v4, v13, v9
	v_fmamk_f32 v15, v14, 0x3e9b6dac, v231
	v_sub_f32_e32 v4, v5, v4
	v_add_f32_e32 v5, v16, v17
	v_fmaak_f32 v15, v14, v15, 0x3f2aaada
	v_sub_f32_e32 v9, v5, v16
	v_ldexp_f32 v16, v13, 1
	v_mul_f32_e32 v13, v13, v14
	v_mul_f32_e32 v13, v13, v15
	v_add_f32_e32 v14, v16, v13
	v_sub_f32_e32 v15, v14, v16
	v_ldexp_f32 v4, v4, 1
	v_sub_f32_e32 v13, v13, v15
	v_add_f32_e32 v4, v4, v13
	v_add_f32_e32 v13, v14, v4
	v_sub_f32_e32 v14, v13, v14
	v_sub_f32_e32 v4, v4, v14
	v_add_f32_e32 v14, v5, v13
	v_sub_f32_e32 v15, v14, v5
	v_sub_f32_e32 v16, v14, v15
	v_sub_f32_e32 v9, v17, v9
	v_sub_f32_e32 v5, v5, v16
	v_sub_f32_e32 v13, v13, v15
	v_add_f32_e32 v5, v13, v5
	v_add_f32_e32 v13, v9, v4
	v_sub_f32_e32 v15, v13, v9
	v_sub_f32_e32 v16, v13, v15
	v_sub_f32_e32 v9, v9, v16
	v_sub_f32_e32 v4, v4, v15
	v_add_f32_e32 v5, v13, v5
	v_add_f32_e32 v4, v4, v9
	v_add_f32_e32 v9, v14, v5
	v_sub_f32_e32 v13, v9, v14
	v_sub_f32_e32 v5, v5, v13
	v_add_f32_e32 v4, v4, v5
	v_add_f32_e32 v4, v9, v4
	v_cmp_neq_f32_e32 vcc, s6, v6
	v_mul_f32_e64 v5, |v8|, s7
	v_max_f32_e64 v8, -v8, 0
	v_cndmask_b32_e32 v4, v238, v4, vcc
	v_cmp_ngt_f32_e32 vcc, -1.0, v6
	v_exp_f32_e32 v3, v3
	s_nop 0
	v_cndmask_b32_e32 v4, v239, v4, vcc
	v_cmp_neq_f32_e32 vcc, -1.0, v6
	s_nop 1
	v_cndmask_b32_e32 v4, v240, v4, vcc
	v_cmp_lt_f32_e64 vcc, |v6|, s10
	s_nop 1
	v_cndmask_b32_e32 v4, v4, v6, vcc
	v_exp_f32_e32 v6, v5
	v_add_f32_e32 v4, v7, v4
	v_sub_f32_e32 v4, -0.5, v4
	v_mul_f32_e32 v4, 0x3fb8aa3b, v4
	v_add_f32_e32 v9, 1.0, v6
	v_exp_f32_e32 v7, v4
	v_add_f32_e32 v4, -1.0, v9
	v_sub_f32_e32 v5, v4, v9
	v_add_f32_e32 v5, 1.0, v5
	v_sub_f32_e32 v4, v6, v4
	v_add_f32_e32 v13, v4, v5
	v_frexp_mant_f32_e32 v4, v9
	v_cmp_gt_f32_e32 vcc, s8, v4
	v_cvt_f64_f32_e32 v[4:5], v9
	v_frexp_exp_i32_f64_e32 v4, v[4:5]
	v_subbrev_co_u32_e32 v4, vcc, 0, v4, vcc
	v_sub_u32_e32 v5, 0, v4
	v_ldexp_f32 v9, v9, v5
	v_ldexp_f32 v5, v13, v5
	v_add_f32_e32 v13, -1.0, v9
	v_add_f32_e32 v16, 1.0, v9
	v_add_f32_e32 v14, 1.0, v13
	v_add_f32_e32 v17, -1.0, v16
	v_sub_f32_e32 v14, v9, v14
	v_sub_f32_e32 v9, v9, v17
	v_add_f32_e32 v14, v5, v14
	v_add_f32_e32 v5, v5, v9
; template <int MODE, bool BIG = false> DI void gemm_tile(const Params& p, int tm, int tn, int kv, char* smem) {
;     ...
;     for (int c4 = 0; c4 < 16; ++c4) {
;       float4 v = crow4[c4], ww = w04[c4];
;       float u[4] = {v.x + ww.x, v.y + ww.y, v.z + ww.z, v.w + ww.w};
; #pragma unroll
;       for (int e = 0; e < 4; ++e) {
;         const float z = -u[e];
;         const float sp = fmaxf(z, 0.f) + log1pf(__expf(-fabsf(z)));
;         u[e] = __expf(-__expf(-sp - 0.5f));
;       }
;       W4[c4] = make_float4(u[0], u[1], u[2], u[3]);
	v_add_f32_e32 v9, v16, v5
	v_rcp_f32_e32 v17, v9
	v_add_f32_e32 v15, v13, v14
	v_sub_f32_e32 v13, v15, v13
	v_sub_f32_e32 v13, v14, v13
	v_sub_f32_e32 v14, v9, v16
	v_sub_f32_e32 v5, v5, v14
	v_mul_f32_e32 v14, v15, v17
	v_mul_f32_e32 v16, v9, v14
	v_fma_f32 v18, v14, v9, -v16
	v_fmac_f32_e32 v18, v14, v5
	v_add_f32_e32 v19, v16, v18
	v_sub_f32_e32 v20, v15, v19
	v_sub_f32_e32 v15, v15, v20
	v_sub_f32_e32 v16, v19, v16
	v_sub_f32_e32 v15, v15, v19
	v_add_f32_e32 v13, v13, v15
	v_sub_f32_e32 v15, v16, v18
	v_add_f32_e32 v13, v15, v13
	v_add_f32_e32 v15, v20, v13
	v_mul_f32_e32 v16, v17, v15
	v_mul_f32_e32 v18, v9, v16
	v_fma_f32 v9, v16, v9, -v18
	v_fmac_f32_e32 v9, v16, v5
	v_sub_f32_e32 v5, v20, v15
	v_add_f32_e32 v5, v13, v5
	v_add_f32_e32 v13, v18, v9
	v_sub_f32_e32 v19, v15, v13
	v_sub_f32_e32 v15, v15, v19
	v_sub_f32_e32 v18, v13, v18
	v_sub_f32_e32 v13, v15, v13
	v_add_f32_e32 v5, v5, v13
	v_sub_f32_e32 v9, v18, v9
	v_cvt_f32_i32_e32 v4, v4
	v_add_f32_e32 v5, v9, v5
	v_add_f32_e32 v9, v14, v16
	v_add_f32_e32 v5, v19, v5
	v_sub_f32_e32 v13, v9, v14
	v_mul_f32_e32 v5, v17, v5
	v_sub_f32_e32 v13, v16, v13
	v_add_f32_e32 v5, v13, v5
	v_mul_f32_e32 v16, 0x3f317218, v4
	v_add_f32_e32 v13, v9, v5
	v_fma_f32 v17, v4, s9, -v16
	v_mul_f32_e32 v14, v13, v13
	v_fmac_f32_e32 v17, 0xb102e308, v4
	v_sub_f32_e32 v4, v13, v9
	v_fmamk_f32 v15, v14, 0x3e9b6dac, v231
	v_sub_f32_e32 v4, v5, v4
	v_add_f32_e32 v5, v16, v17
	v_fmaak_f32 v15, v14, v15, 0x3f2aaada
	v_sub_f32_e32 v9, v5, v16
	v_ldexp_f32 v16, v13, 1
	v_mul_f32_e32 v13, v13, v14
	v_mul_f32_e32 v13, v13, v15
	v_add_f32_e32 v14, v16, v13
	v_sub_f32_e32 v15, v14, v16
	v_ldexp_f32 v4, v4, 1
	v_sub_f32_e32 v13, v13, v15
	v_add_f32_e32 v4, v4, v13
	v_add_f32_e32 v13, v14, v4
	v_sub_f32_e32 v14, v13, v14
	v_sub_f32_e32 v4, v4, v14
	v_add_f32_e32 v14, v5, v13
	v_sub_f32_e32 v15, v14, v5
	v_sub_f32_e32 v16, v14, v15
	v_sub_f32_e32 v9, v17, v9
	v_sub_f32_e32 v5, v5, v16
	v_sub_f32_e32 v13, v13, v15
	v_add_f32_e32 v5, v13, v5
	v_add_f32_e32 v13, v9, v4
	v_sub_f32_e32 v15, v13, v9
	v_sub_f32_e32 v16, v13, v15
	v_sub_f32_e32 v9, v9, v16
	v_sub_f32_e32 v4, v4, v15
	v_add_f32_e32 v5, v13, v5
	v_add_f32_e32 v4, v4, v9
	v_add_f32_e32 v9, v14, v5
	v_sub_f32_e32 v13, v9, v14
	v_sub_f32_e32 v5, v5, v13
	v_add_f32_e32 v4, v4, v5
	v_add_f32_e32 v4, v9, v4
	v_cmp_neq_f32_e32 vcc, s6, v6
	s_nop 1
	v_cndmask_b32_e32 v4, v238, v4, vcc
	v_cmp_ngt_f32_e32 vcc, -1.0, v6
	s_nop 1
	v_cndmask_b32_e32 v4, v239, v4, vcc
	v_cmp_neq_f32_e32 vcc, -1.0, v6
	s_nop 1
	v_cndmask_b32_e32 v4, v240, v4, vcc
	v_cmp_lt_f32_e64 vcc, |v6|, s10
	s_nop 1
	v_cndmask_b32_e32 v4, v4, v6, vcc
	v_add_f32_e32 v4, v8, v4
	v_sub_f32_e32 v4, -0.5, v4
	v_mul_f32_e32 v4, 0x3fb8aa3b, v4
	v_exp_f32_e32 v5, v4
	v_mul_f32_e32 v4, 0xbfb8aa3b, v7
	v_exp_f32_e32 v4, v4
	ds_read_b128 v[6:9], v12 offset:160
	v_mul_f32_e32 v5, 0xbfb8aa3b, v5
	v_exp_f32_e32 v5, v5
	ds_write_b128 v75, v[2:5] offset:144
	ds_read_b128 v[2:5], v74 offset:160
	s_waitcnt lgkmcnt(0)
	v_add_f32_e32 v2, v6, v2
	v_mul_f32_e64 v6, |v2|, s7
	v_exp_f32_e32 v6, v6
	v_add_f32_e32 v4, v8, v4
	v_max_f32_e64 v8, -v2, 0
	v_add_f32_e32 v7, v7, v3
	v_add_f32_e32 v13, 1.0, v6
	v_add_f32_e32 v2, -1.0, v13
	v_sub_f32_e32 v3, v2, v13
	v_add_f32_e32 v3, 1.0, v3
	v_sub_f32_e32 v2, v6, v2
	v_add_f32_e32 v14, v2, v3
	v_frexp_mant_f32_e32 v2, v13
	v_cmp_gt_f32_e32 vcc, s8, v2
	v_cvt_f64_f32_e32 v[2:3], v13
	v_frexp_exp_i32_f64_e32 v2, v[2:3]
	v_subbrev_co_u32_e32 v2, vcc, 0, v2, vcc
	v_sub_u32_e32 v3, 0, v2
	v_ldexp_f32 v13, v13, v3
	v_ldexp_f32 v3, v14, v3
	v_add_f32_e32 v14, -1.0, v13
	v_add_f32_e32 v17, 1.0, v13
	v_add_f32_e32 v15, 1.0, v14
	v_add_f32_e32 v18, -1.0, v17
	v_sub_f32_e32 v15, v13, v15
	v_sub_f32_e32 v13, v13, v18
	v_add_f32_e32 v15, v3, v15
	v_add_f32_e32 v3, v3, v13
	v_add_f32_e32 v13, v17, v3
	v_rcp_f32_e32 v18, v13
	v_add_f32_e32 v16, v14, v15
	v_sub_f32_e32 v14, v16, v14
	v_sub_f32_e32 v14, v15, v14
	v_sub_f32_e32 v15, v13, v17
	v_sub_f32_e32 v3, v3, v15
	v_mul_f32_e32 v15, v16, v18
	v_mul_f32_e32 v17, v13, v15
	v_fma_f32 v19, v15, v13, -v17
	v_fmac_f32_e32 v19, v15, v3
	v_add_f32_e32 v20, v17, v19
	v_sub_f32_e32 v21, v16, v20
	v_sub_f32_e32 v16, v16, v21
	v_sub_f32_e32 v17, v20, v17
	v_sub_f32_e32 v16, v16, v20
	v_add_f32_e32 v14, v14, v16
	v_sub_f32_e32 v16, v17, v19
	v_add_f32_e32 v14, v16, v14
	v_add_f32_e32 v16, v21, v14
	v_mul_f32_e32 v17, v18, v16
	v_mul_f32_e32 v19, v13, v17
	v_fma_f32 v13, v17, v13, -v19
	v_fmac_f32_e32 v13, v17, v3
	v_sub_f32_e32 v3, v21, v16
	v_add_f32_e32 v3, v14, v3
	v_add_f32_e32 v14, v19, v13
	v_sub_f32_e32 v20, v16, v14
	v_sub_f32_e32 v16, v16, v20
	v_sub_f32_e32 v19, v14, v19
	v_sub_f32_e32 v14, v16, v14
	v_add_f32_e32 v3, v3, v14
	v_sub_f32_e32 v13, v19, v13
	v_cvt_f32_i32_e32 v2, v2
	v_add_f32_e32 v3, v13, v3
	v_add_f32_e32 v13, v15, v17
	v_add_f32_e32 v3, v20, v3
	v_sub_f32_e32 v14, v13, v15
	v_mul_f32_e32 v3, v18, v3
	v_sub_f32_e32 v14, v17, v14
	v_add_f32_e32 v3, v14, v3
	v_mul_f32_e32 v17, 0x3f317218, v2
	v_add_f32_e32 v14, v13, v3
	v_fma_f32 v18, v2, s9, -v17
	v_mul_f32_e32 v15, v14, v14
	v_fmac_f32_e32 v18, 0xb102e308, v2
	v_sub_f32_e32 v2, v14, v13
	v_fmamk_f32 v16, v15, 0x3e9b6dac, v231
	v_sub_f32_e32 v2, v3, v2
	v_add_f32_e32 v3, v17, v18
	v_fmaak_f32 v16, v15, v16, 0x3f2aaada
	v_sub_f32_e32 v13, v3, v17
	v_ldexp_f32 v17, v14, 1
	v_mul_f32_e32 v14, v14, v15
	v_mul_f32_e32 v14, v14, v16
	v_add_f32_e32 v15, v17, v14
	v_sub_f32_e32 v16, v15, v17
	v_ldexp_f32 v2, v2, 1
	v_sub_f32_e32 v14, v14, v16
	v_add_f32_e32 v2, v2, v14
	v_add_f32_e32 v14, v15, v2
	v_sub_f32_e32 v15, v14, v15
	v_sub_f32_e32 v2, v2, v15
	v_add_f32_e32 v15, v3, v14
; template <int MODE, bool BIG = false> DI void gemm_tile(const Params& p, int tm, int tn, int kv, char* smem) {
;     ...
;       for (int e = 0; e < 4; ++e) {
;         const float z = -u[e];
;         const float sp = fmaxf(z, 0.f) + log1pf(__expf(-fabsf(z)));
;         u[e] = __expf(-__expf(-sp - 0.5f));
;       }
	v_sub_f32_e32 v16, v15, v3
	v_sub_f32_e32 v17, v15, v16
	v_sub_f32_e32 v13, v18, v13
	v_sub_f32_e32 v3, v3, v17
	v_sub_f32_e32 v14, v14, v16
	v_add_f32_e32 v3, v14, v3
	v_add_f32_e32 v14, v13, v2
	v_sub_f32_e32 v16, v14, v13
	v_sub_f32_e32 v17, v14, v16
	v_sub_f32_e32 v13, v13, v17
	v_sub_f32_e32 v2, v2, v16
	v_add_f32_e32 v3, v14, v3
	v_add_f32_e32 v2, v2, v13
	v_add_f32_e32 v13, v15, v3
	v_sub_f32_e32 v14, v13, v15
	v_sub_f32_e32 v3, v3, v14
	v_add_f32_e32 v2, v2, v3
	v_add_f32_e32 v2, v13, v2
	v_cmp_neq_f32_e32 vcc, s6, v6
	v_mul_f32_e64 v3, |v7|, s7
	v_max_f32_e64 v7, -v7, 0
	v_cndmask_b32_e32 v2, v238, v2, vcc
	v_cmp_ngt_f32_e32 vcc, -1.0, v6
	s_nop 1
	v_cndmask_b32_e32 v2, v239, v2, vcc
	v_cmp_neq_f32_e32 vcc, -1.0, v6
	s_nop 1
	v_cndmask_b32_e32 v2, v240, v2, vcc
	v_cmp_lt_f32_e64 vcc, |v6|, s10
	s_nop 1
	v_cndmask_b32_e32 v2, v2, v6, vcc
	v_add_f32_e32 v2, v8, v2
	v_sub_f32_e32 v2, -0.5, v2
	v_mul_f32_e32 v2, 0x3fb8aa3b, v2
	v_exp_f32_e32 v6, v3
	v_exp_f32_e32 v2, v2
	v_add_f32_e32 v8, v9, v5
	v_add_f32_e32 v9, 1.0, v6
	v_mul_f32_e32 v5, 0xbfb8aa3b, v2
	v_add_f32_e32 v2, -1.0, v9
	v_sub_f32_e32 v3, v2, v9
	v_add_f32_e32 v3, 1.0, v3
	v_sub_f32_e32 v2, v6, v2
	v_add_f32_e32 v13, v2, v3
	v_frexp_mant_f32_e32 v2, v9
	v_cmp_gt_f32_e32 vcc, s8, v2
	v_cvt_f64_f32_e32 v[2:3], v9
	v_frexp_exp_i32_f64_e32 v2, v[2:3]
	v_subbrev_co_u32_e32 v2, vcc, 0, v2, vcc
	v_sub_u32_e32 v3, 0, v2
	v_ldexp_f32 v9, v9, v3
	v_ldexp_f32 v3, v13, v3
	v_add_f32_e32 v13, -1.0, v9
	v_add_f32_e32 v16, 1.0, v9
	v_add_f32_e32 v14, 1.0, v13
	v_add_f32_e32 v17, -1.0, v16
	v_sub_f32_e32 v14, v9, v14
	v_sub_f32_e32 v9, v9, v17
	v_add_f32_e32 v14, v3, v14
	v_add_f32_e32 v3, v3, v9
	v_add_f32_e32 v9, v16, v3
	v_rcp_f32_e32 v17, v9
	v_add_f32_e32 v15, v13, v14
	v_sub_f32_e32 v13, v15, v13
	v_sub_f32_e32 v13, v14, v13
	v_sub_f32_e32 v14, v9, v16
	v_sub_f32_e32 v3, v3, v14
	v_mul_f32_e32 v14, v15, v17
	v_mul_f32_e32 v16, v9, v14
	v_fma_f32 v18, v14, v9, -v16
	v_fmac_f32_e32 v18, v14, v3
	v_add_f32_e32 v19, v16, v18
	v_sub_f32_e32 v20, v15, v19
	v_sub_f32_e32 v15, v15, v20
	v_sub_f32_e32 v16, v19, v16
	v_sub_f32_e32 v15, v15, v19
	v_add_f32_e32 v13, v13, v15
	v_sub_f32_e32 v15, v16, v18
	v_add_f32_e32 v13, v15, v13
	v_add_f32_e32 v15, v20, v13
	v_mul_f32_e32 v16, v17, v15
	v_mul_f32_e32 v18, v9, v16
	v_fma_f32 v9, v16, v9, -v18
	v_fmac_f32_e32 v9, v16, v3
	v_sub_f32_e32 v3, v20, v15
	v_add_f32_e32 v3, v13, v3
	v_add_f32_e32 v13, v18, v9
	v_sub_f32_e32 v19, v15, v13
	v_sub_f32_e32 v15, v15, v19
	v_sub_f32_e32 v18, v13, v18
	v_sub_f32_e32 v13, v15, v13
	v_add_f32_e32 v3, v3, v13
	v_sub_f32_e32 v9, v18, v9
	v_cvt_f32_i32_e32 v2, v2
	v_add_f32_e32 v3, v9, v3
	v_add_f32_e32 v9, v14, v16
	v_add_f32_e32 v3, v19, v3
	v_sub_f32_e32 v13, v9, v14
	v_mul_f32_e32 v3, v17, v3
	v_sub_f32_e32 v13, v16, v13
	v_add_f32_e32 v3, v13, v3
	v_mul_f32_e32 v16, 0x3f317218, v2
	v_add_f32_e32 v13, v9, v3
	v_fma_f32 v17, v2, s9, -v16
	v_mul_f32_e32 v14, v13, v13
	v_fmac_f32_e32 v17, 0xb102e308, v2
	v_sub_f32_e32 v2, v13, v9
	v_fmamk_f32 v15, v14, 0x3e9b6dac, v231
	v_sub_f32_e32 v2, v3, v2
	v_add_f32_e32 v3, v16, v17
	v_fmaak_f32 v15, v14, v15, 0x3f2aaada
	v_sub_f32_e32 v9, v3, v16
	v_ldexp_f32 v16, v13, 1
	v_mul_f32_e32 v13, v13, v14
	v_mul_f32_e32 v13, v13, v15
	v_add_f32_e32 v14, v16, v13
	v_sub_f32_e32 v15, v14, v16
	v_ldexp_f32 v2, v2, 1
	v_sub_f32_e32 v13, v13, v15
	v_add_f32_e32 v2, v2, v13
	v_add_f32_e32 v13, v14, v2
	v_sub_f32_e32 v14, v13, v14
	v_sub_f32_e32 v2, v2, v14
	v_add_f32_e32 v14, v3, v13
	v_sub_f32_e32 v15, v14, v3
	v_sub_f32_e32 v16, v14, v15
	v_sub_f32_e32 v9, v17, v9
	v_sub_f32_e32 v3, v3, v16
	v_sub_f32_e32 v13, v13, v15
	v_add_f32_e32 v3, v13, v3
	v_add_f32_e32 v13, v9, v2
	v_sub_f32_e32 v15, v13, v9
	v_sub_f32_e32 v16, v13, v15
	v_sub_f32_e32 v9, v9, v16
	v_sub_f32_e32 v2, v2, v15
	v_add_f32_e32 v3, v13, v3
	v_add_f32_e32 v2, v2, v9
	v_add_f32_e32 v9, v14, v3
	v_sub_f32_e32 v13, v9, v14
	v_sub_f32_e32 v3, v3, v13
	v_add_f32_e32 v2, v2, v3
	v_add_f32_e32 v2, v9, v2
	v_cmp_neq_f32_e32 vcc, s6, v6
	s_nop 1
	v_cndmask_b32_e32 v2, v238, v2, vcc
	v_cmp_ngt_f32_e32 vcc, -1.0, v6
	s_nop 1
	v_cndmask_b32_e32 v2, v239, v2, vcc
	v_cmp_neq_f32_e32 vcc, -1.0, v6
	s_nop 1
	v_cndmask_b32_e32 v2, v240, v2, vcc
	v_cmp_lt_f32_e64 vcc, |v6|, s10
	s_nop 1
	v_cndmask_b32_e32 v2, v2, v6, vcc
	v_add_f32_e32 v2, v7, v2
	v_sub_f32_e32 v2, -0.5, v2
	v_mul_f32_e32 v2, 0x3fb8aa3b, v2
	v_exp_f32_e32 v3, v2
	v_mul_f32_e64 v2, |v4|, s7
	v_exp_f32_e32 v6, v2
	v_max_f32_e64 v7, -v4, 0
	v_exp_f32_e32 v2, v5
	v_mul_f32_e32 v3, 0xbfb8aa3b, v3
	v_add_f32_e32 v9, 1.0, v6
	v_add_f32_e32 v4, -1.0, v9
	v_sub_f32_e32 v5, v4, v9
	v_add_f32_e32 v5, 1.0, v5
	v_sub_f32_e32 v4, v6, v4
	v_add_f32_e32 v13, v4, v5
	v_frexp_mant_f32_e32 v4, v9
	v_cmp_gt_f32_e32 vcc, s8, v4
	v_cvt_f64_f32_e32 v[4:5], v9
	v_frexp_exp_i32_f64_e32 v4, v[4:5]
	v_subbrev_co_u32_e32 v4, vcc, 0, v4, vcc
	v_sub_u32_e32 v5, 0, v4
	v_ldexp_f32 v9, v9, v5
	v_ldexp_f32 v5, v13, v5
	v_add_f32_e32 v13, -1.0, v9
	v_add_f32_e32 v16, 1.0, v9
	v_add_f32_e32 v14, 1.0, v13
	v_add_f32_e32 v17, -1.0, v16
	v_sub_f32_e32 v14, v9, v14
	v_sub_f32_e32 v9, v9, v17
	v_add_f32_e32 v14, v5, v14
	v_add_f32_e32 v5, v5, v9
	v_add_f32_e32 v9, v16, v5
	v_rcp_f32_e32 v17, v9
	v_add_f32_e32 v15, v13, v14
	v_sub_f32_e32 v13, v15, v13
	v_sub_f32_e32 v13, v14, v13
	v_sub_f32_e32 v14, v9, v16
	v_sub_f32_e32 v5, v5, v14
	v_mul_f32_e32 v14, v15, v17
	v_mul_f32_e32 v16, v9, v14
	v_fma_f32 v18, v14, v9, -v16
	v_fmac_f32_e32 v18, v14, v5
	v_add_f32_e32 v19, v16, v18
	v_sub_f32_e32 v20, v15, v19
	v_sub_f32_e32 v15, v15, v20
	v_sub_f32_e32 v16, v19, v16
	v_sub_f32_e32 v15, v15, v19
; template <int MODE, bool BIG = false> DI void gemm_tile(const Params& p, int tm, int tn, int kv, char* smem) {
;     ...
;     for (int c4 = 0; c4 < 16; ++c4) {
;       float4 v = crow4[c4], ww = w04[c4];
;       float u[4] = {v.x + ww.x, v.y + ww.y, v.z + ww.z, v.w + ww.w};
; #pragma unroll
;       for (int e = 0; e < 4; ++e) {
;         const float z = -u[e];
;         const float sp = fmaxf(z, 0.f) + log1pf(__expf(-fabsf(z)));
;         u[e] = __expf(-__expf(-sp - 0.5f));
;       }
;       W4[c4] = make_float4(u[0], u[1], u[2], u[3]);
	v_add_f32_e32 v13, v13, v15
	v_sub_f32_e32 v15, v16, v18
	v_add_f32_e32 v13, v15, v13
	v_add_f32_e32 v15, v20, v13
	v_mul_f32_e32 v16, v17, v15
	v_mul_f32_e32 v18, v9, v16
	v_fma_f32 v9, v16, v9, -v18
	v_fmac_f32_e32 v9, v16, v5
	v_sub_f32_e32 v5, v20, v15
	v_add_f32_e32 v5, v13, v5
	v_add_f32_e32 v13, v18, v9
	v_sub_f32_e32 v19, v15, v13
	v_sub_f32_e32 v15, v15, v19
	v_sub_f32_e32 v18, v13, v18
	v_sub_f32_e32 v13, v15, v13
	v_add_f32_e32 v5, v5, v13
	v_sub_f32_e32 v9, v18, v9
	v_cvt_f32_i32_e32 v4, v4
	v_add_f32_e32 v5, v9, v5
	v_add_f32_e32 v9, v14, v16
	v_add_f32_e32 v5, v19, v5
	v_sub_f32_e32 v13, v9, v14
	v_mul_f32_e32 v5, v17, v5
	v_sub_f32_e32 v13, v16, v13
	v_add_f32_e32 v5, v13, v5
	v_mul_f32_e32 v16, 0x3f317218, v4
	v_add_f32_e32 v13, v9, v5
	v_fma_f32 v17, v4, s9, -v16
	v_mul_f32_e32 v14, v13, v13
	v_fmac_f32_e32 v17, 0xb102e308, v4
	v_sub_f32_e32 v4, v13, v9
	v_fmamk_f32 v15, v14, 0x3e9b6dac, v231
	v_sub_f32_e32 v4, v5, v4
	v_add_f32_e32 v5, v16, v17
	v_fmaak_f32 v15, v14, v15, 0x3f2aaada
	v_sub_f32_e32 v9, v5, v16
	v_ldexp_f32 v16, v13, 1
	v_mul_f32_e32 v13, v13, v14
	v_mul_f32_e32 v13, v13, v15
	v_add_f32_e32 v14, v16, v13
	v_sub_f32_e32 v15, v14, v16
	v_ldexp_f32 v4, v4, 1
	v_sub_f32_e32 v13, v13, v15
	v_add_f32_e32 v4, v4, v13
	v_add_f32_e32 v13, v14, v4
	v_sub_f32_e32 v14, v13, v14
	v_sub_f32_e32 v4, v4, v14
	v_add_f32_e32 v14, v5, v13
	v_sub_f32_e32 v15, v14, v5
	v_sub_f32_e32 v16, v14, v15
	v_sub_f32_e32 v9, v17, v9
	v_sub_f32_e32 v5, v5, v16
	v_sub_f32_e32 v13, v13, v15
	v_add_f32_e32 v5, v13, v5
	v_add_f32_e32 v13, v9, v4
	v_sub_f32_e32 v15, v13, v9
	v_sub_f32_e32 v16, v13, v15
	v_sub_f32_e32 v9, v9, v16
	v_sub_f32_e32 v4, v4, v15
	v_add_f32_e32 v5, v13, v5
	v_add_f32_e32 v4, v4, v9
	v_add_f32_e32 v9, v14, v5
	v_sub_f32_e32 v13, v9, v14
	v_sub_f32_e32 v5, v5, v13
	v_add_f32_e32 v4, v4, v5
	v_add_f32_e32 v4, v9, v4
	v_cmp_neq_f32_e32 vcc, s6, v6
	v_mul_f32_e64 v5, |v8|, s7
	v_max_f32_e64 v8, -v8, 0
	v_cndmask_b32_e32 v4, v238, v4, vcc
	v_cmp_ngt_f32_e32 vcc, -1.0, v6
	v_exp_f32_e32 v3, v3
	s_nop 0
	v_cndmask_b32_e32 v4, v239, v4, vcc
	v_cmp_neq_f32_e32 vcc, -1.0, v6
	s_nop 1
	v_cndmask_b32_e32 v4, v240, v4, vcc
	v_cmp_lt_f32_e64 vcc, |v6|, s10
	s_nop 1
	v_cndmask_b32_e32 v4, v4, v6, vcc
	v_exp_f32_e32 v6, v5
	v_add_f32_e32 v4, v7, v4
	v_sub_f32_e32 v4, -0.5, v4
	v_mul_f32_e32 v4, 0x3fb8aa3b, v4
	v_add_f32_e32 v9, 1.0, v6
	v_exp_f32_e32 v7, v4
	v_add_f32_e32 v4, -1.0, v9
	v_sub_f32_e32 v5, v4, v9
	v_add_f32_e32 v5, 1.0, v5
	v_sub_f32_e32 v4, v6, v4
	v_add_f32_e32 v13, v4, v5
	v_frexp_mant_f32_e32 v4, v9
	v_cmp_gt_f32_e32 vcc, s8, v4
	v_cvt_f64_f32_e32 v[4:5], v9
	v_frexp_exp_i32_f64_e32 v4, v[4:5]
	v_subbrev_co_u32_e32 v4, vcc, 0, v4, vcc
	v_sub_u32_e32 v5, 0, v4
	v_ldexp_f32 v9, v9, v5
	v_ldexp_f32 v5, v13, v5
	v_add_f32_e32 v13, -1.0, v9
	v_add_f32_e32 v16, 1.0, v9
	v_add_f32_e32 v14, 1.0, v13
	v_add_f32_e32 v17, -1.0, v16
	v_sub_f32_e32 v14, v9, v14
	v_sub_f32_e32 v9, v9, v17
	v_add_f32_e32 v14, v5, v14
	v_add_f32_e32 v5, v5, v9
	v_add_f32_e32 v9, v16, v5
	v_rcp_f32_e32 v17, v9
	v_add_f32_e32 v15, v13, v14
	v_sub_f32_e32 v13, v15, v13
	v_sub_f32_e32 v13, v14, v13
	v_sub_f32_e32 v14, v9, v16
	v_sub_f32_e32 v5, v5, v14
	v_mul_f32_e32 v14, v15, v17
	v_mul_f32_e32 v16, v9, v14
	v_fma_f32 v18, v14, v9, -v16
	v_fmac_f32_e32 v18, v14, v5
	v_add_f32_e32 v19, v16, v18
	v_sub_f32_e32 v20, v15, v19
	v_sub_f32_e32 v15, v15, v20
	v_sub_f32_e32 v16, v19, v16
	v_sub_f32_e32 v15, v15, v19
	v_add_f32_e32 v13, v13, v15
	v_sub_f32_e32 v15, v16, v18
	v_add_f32_e32 v13, v15, v13
	v_add_f32_e32 v15, v20, v13
	v_mul_f32_e32 v16, v17, v15
	v_mul_f32_e32 v18, v9, v16
	v_fma_f32 v9, v16, v9, -v18
	v_fmac_f32_e32 v9, v16, v5
	v_sub_f32_e32 v5, v20, v15
	v_add_f32_e32 v5, v13, v5
	v_add_f32_e32 v13, v18, v9
	v_sub_f32_e32 v19, v15, v13
	v_sub_f32_e32 v15, v15, v19
	v_sub_f32_e32 v18, v13, v18
	v_sub_f32_e32 v13, v15, v13
	v_add_f32_e32 v5, v5, v13
	v_sub_f32_e32 v9, v18, v9
	v_cvt_f32_i32_e32 v4, v4
	v_add_f32_e32 v5, v9, v5
	v_add_f32_e32 v9, v14, v16
	v_add_f32_e32 v5, v19, v5
	v_sub_f32_e32 v13, v9, v14
	v_mul_f32_e32 v5, v17, v5
	v_sub_f32_e32 v13, v16, v13
	v_add_f32_e32 v5, v13, v5
	v_mul_f32_e32 v16, 0x3f317218, v4
	v_add_f32_e32 v13, v9, v5
	v_fma_f32 v17, v4, s9, -v16
	v_mul_f32_e32 v14, v13, v13
	v_fmac_f32_e32 v17, 0xb102e308, v4
	v_sub_f32_e32 v4, v13, v9
	v_fmamk_f32 v15, v14, 0x3e9b6dac, v231
	v_sub_f32_e32 v4, v5, v4
	v_add_f32_e32 v5, v16, v17
	v_fmaak_f32 v15, v14, v15, 0x3f2aaada
	v_sub_f32_e32 v9, v5, v16
	v_ldexp_f32 v16, v13, 1
	v_mul_f32_e32 v13, v13, v14
	v_mul_f32_e32 v13, v13, v15
	v_add_f32_e32 v14, v16, v13
	v_sub_f32_e32 v15, v14, v16
	v_ldexp_f32 v4, v4, 1
	v_sub_f32_e32 v13, v13, v15
	v_add_f32_e32 v4, v4, v13
	v_add_f32_e32 v13, v14, v4
	v_sub_f32_e32 v14, v13, v14
	v_sub_f32_e32 v4, v4, v14
	v_add_f32_e32 v14, v5, v13
	v_sub_f32_e32 v15, v14, v5
	v_sub_f32_e32 v16, v14, v15
	v_sub_f32_e32 v9, v17, v9
	v_sub_f32_e32 v5, v5, v16
	v_sub_f32_e32 v13, v13, v15
	v_add_f32_e32 v5, v13, v5
	v_add_f32_e32 v13, v9, v4
	v_sub_f32_e32 v15, v13, v9
	v_sub_f32_e32 v16, v13, v15
	v_sub_f32_e32 v9, v9, v16
	v_sub_f32_e32 v4, v4, v15
	v_add_f32_e32 v5, v13, v5
	v_add_f32_e32 v4, v4, v9
	v_add_f32_e32 v9, v14, v5
	v_sub_f32_e32 v13, v9, v14
	v_sub_f32_e32 v5, v5, v13
	v_add_f32_e32 v4, v4, v5
	v_add_f32_e32 v4, v9, v4
	v_cmp_neq_f32_e32 vcc, s6, v6
	s_nop 1
	v_cndmask_b32_e32 v4, v238, v4, vcc
	v_cmp_ngt_f32_e32 vcc, -1.0, v6
	s_nop 1
	v_cndmask_b32_e32 v4, v239, v4, vcc
	v_cmp_neq_f32_e32 vcc, -1.0, v6
	s_nop 1
	v_cndmask_b32_e32 v4, v240, v4, vcc
	v_cmp_lt_f32_e64 vcc, |v6|, s10
	s_nop 1
	v_cndmask_b32_e32 v4, v4, v6, vcc
	v_add_f32_e32 v4, v8, v4
	v_sub_f32_e32 v4, -0.5, v4
	v_mul_f32_e32 v4, 0x3fb8aa3b, v4
	v_exp_f32_e32 v5, v4
	v_mul_f32_e32 v4, 0xbfb8aa3b, v7
	v_exp_f32_e32 v4, v4
	ds_read_b128 v[6:9], v12 offset:176
	v_mul_f32_e32 v5, 0xbfb8aa3b, v5
	v_exp_f32_e32 v5, v5
	ds_write_b128 v75, v[2:5] offset:160
	ds_read_b128 v[2:5], v74 offset:176
	s_waitcnt lgkmcnt(0)
; template <int MODE, bool BIG = false> DI void gemm_tile(const Params& p, int tm, int tn, int kv, char* smem) {
;     ...
;     for (int c4 = 0; c4 < 16; ++c4) {
;       float4 v = crow4[c4], ww = w04[c4];
;       float u[4] = {v.x + ww.x, v.y + ww.y, v.z + ww.z, v.w + ww.w};
; #pragma unroll
;       for (int e = 0; e < 4; ++e) {
;         const float z = -u[e];
;         const float sp = fmaxf(z, 0.f) + log1pf(__expf(-fabsf(z)));
;         u[e] = __expf(-__expf(-sp - 0.5f));
;       }
;       W4[c4] = make_float4(u[0], u[1], u[2], u[3]);
	v_add_f32_e32 v2, v6, v2
	v_mul_f32_e64 v6, |v2|, s7
	v_exp_f32_e32 v6, v6
	v_add_f32_e32 v4, v8, v4
	v_max_f32_e64 v8, -v2, 0
	v_add_f32_e32 v7, v7, v3
	v_add_f32_e32 v13, 1.0, v6
	v_add_f32_e32 v2, -1.0, v13
	v_sub_f32_e32 v3, v2, v13
	v_add_f32_e32 v3, 1.0, v3
	v_sub_f32_e32 v2, v6, v2
	v_add_f32_e32 v14, v2, v3
	v_frexp_mant_f32_e32 v2, v13
	v_cmp_gt_f32_e32 vcc, s8, v2
	v_cvt_f64_f32_e32 v[2:3], v13
	v_frexp_exp_i32_f64_e32 v2, v[2:3]
	v_subbrev_co_u32_e32 v2, vcc, 0, v2, vcc
	v_sub_u32_e32 v3, 0, v2
	v_ldexp_f32 v13, v13, v3
	v_ldexp_f32 v3, v14, v3
	v_add_f32_e32 v14, -1.0, v13
	v_add_f32_e32 v17, 1.0, v13
	v_add_f32_e32 v15, 1.0, v14
	v_add_f32_e32 v18, -1.0, v17
	v_sub_f32_e32 v15, v13, v15
	v_sub_f32_e32 v13, v13, v18
	v_add_f32_e32 v15, v3, v15
	v_add_f32_e32 v3, v3, v13
	v_add_f32_e32 v13, v17, v3
	v_rcp_f32_e32 v18, v13
	v_add_f32_e32 v16, v14, v15
	v_sub_f32_e32 v14, v16, v14
	v_sub_f32_e32 v14, v15, v14
	v_sub_f32_e32 v15, v13, v17
	v_sub_f32_e32 v3, v3, v15
	v_mul_f32_e32 v15, v16, v18
	v_mul_f32_e32 v17, v13, v15
	v_fma_f32 v19, v15, v13, -v17
	v_fmac_f32_e32 v19, v15, v3
	v_add_f32_e32 v20, v17, v19
	v_sub_f32_e32 v21, v16, v20
	v_sub_f32_e32 v16, v16, v21
	v_sub_f32_e32 v17, v20, v17
	v_sub_f32_e32 v16, v16, v20
	v_add_f32_e32 v14, v14, v16
	v_sub_f32_e32 v16, v17, v19
	v_add_f32_e32 v14, v16, v14
	v_add_f32_e32 v16, v21, v14
	v_mul_f32_e32 v17, v18, v16
	v_mul_f32_e32 v19, v13, v17
	v_fma_f32 v13, v17, v13, -v19
	v_fmac_f32_e32 v13, v17, v3
	v_sub_f32_e32 v3, v21, v16
	v_add_f32_e32 v3, v14, v3
	v_add_f32_e32 v14, v19, v13
	v_sub_f32_e32 v20, v16, v14
	v_sub_f32_e32 v16, v16, v20
	v_sub_f32_e32 v19, v14, v19
	v_sub_f32_e32 v14, v16, v14
	v_add_f32_e32 v3, v3, v14
	v_sub_f32_e32 v13, v19, v13
	v_cvt_f32_i32_e32 v2, v2
	v_add_f32_e32 v3, v13, v3
	v_add_f32_e32 v13, v15, v17
	v_add_f32_e32 v3, v20, v3
	v_sub_f32_e32 v14, v13, v15
	v_mul_f32_e32 v3, v18, v3
	v_sub_f32_e32 v14, v17, v14
	v_add_f32_e32 v3, v14, v3
	v_mul_f32_e32 v17, 0x3f317218, v2
	v_add_f32_e32 v14, v13, v3
	v_fma_f32 v18, v2, s9, -v17
	v_mul_f32_e32 v15, v14, v14
	v_fmac_f32_e32 v18, 0xb102e308, v2
	v_sub_f32_e32 v2, v14, v13
	v_fmamk_f32 v16, v15, 0x3e9b6dac, v231
	v_sub_f32_e32 v2, v3, v2
	v_add_f32_e32 v3, v17, v18
	v_fmaak_f32 v16, v15, v16, 0x3f2aaada
	v_sub_f32_e32 v13, v3, v17
	v_ldexp_f32 v17, v14, 1
	v_mul_f32_e32 v14, v14, v15
	v_mul_f32_e32 v14, v14, v16
	v_add_f32_e32 v15, v17, v14
	v_sub_f32_e32 v16, v15, v17
	v_ldexp_f32 v2, v2, 1
	v_sub_f32_e32 v14, v14, v16
	v_add_f32_e32 v2, v2, v14
	v_add_f32_e32 v14, v15, v2
	v_sub_f32_e32 v15, v14, v15
	v_sub_f32_e32 v2, v2, v15
	v_add_f32_e32 v15, v3, v14
	v_sub_f32_e32 v16, v15, v3
	v_sub_f32_e32 v17, v15, v16
	v_sub_f32_e32 v13, v18, v13
	v_sub_f32_e32 v3, v3, v17
	v_sub_f32_e32 v14, v14, v16
	v_add_f32_e32 v3, v14, v3
	v_add_f32_e32 v14, v13, v2
	v_sub_f32_e32 v16, v14, v13
	v_sub_f32_e32 v17, v14, v16
	v_sub_f32_e32 v13, v13, v17
	v_sub_f32_e32 v2, v2, v16
	v_add_f32_e32 v3, v14, v3
	v_add_f32_e32 v2, v2, v13
	v_add_f32_e32 v13, v15, v3
	v_sub_f32_e32 v14, v13, v15
	v_sub_f32_e32 v3, v3, v14
	v_add_f32_e32 v2, v2, v3
	v_add_f32_e32 v2, v13, v2
	v_cmp_neq_f32_e32 vcc, s6, v6
	v_mul_f32_e64 v3, |v7|, s7
	v_max_f32_e64 v7, -v7, 0
	v_cndmask_b32_e32 v2, v238, v2, vcc
	v_cmp_ngt_f32_e32 vcc, -1.0, v6
	s_nop 1
	v_cndmask_b32_e32 v2, v239, v2, vcc
	v_cmp_neq_f32_e32 vcc, -1.0, v6
	s_nop 1
	v_cndmask_b32_e32 v2, v240, v2, vcc
	v_cmp_lt_f32_e64 vcc, |v6|, s10
	s_nop 1
	v_cndmask_b32_e32 v2, v2, v6, vcc
	v_add_f32_e32 v2, v8, v2
	v_sub_f32_e32 v2, -0.5, v2
	v_mul_f32_e32 v2, 0x3fb8aa3b, v2
	v_exp_f32_e32 v6, v3
	v_exp_f32_e32 v2, v2
	v_add_f32_e32 v8, v9, v5
	v_add_f32_e32 v9, 1.0, v6
	v_mul_f32_e32 v5, 0xbfb8aa3b, v2
	v_add_f32_e32 v2, -1.0, v9
	v_sub_f32_e32 v3, v2, v9
	v_add_f32_e32 v3, 1.0, v3
	v_sub_f32_e32 v2, v6, v2
	v_add_f32_e32 v13, v2, v3
	v_frexp_mant_f32_e32 v2, v9
	v_cmp_gt_f32_e32 vcc, s8, v2
	v_cvt_f64_f32_e32 v[2:3], v9
	v_frexp_exp_i32_f64_e32 v2, v[2:3]
	v_subbrev_co_u32_e32 v2, vcc, 0, v2, vcc
	v_sub_u32_e32 v3, 0, v2
	v_ldexp_f32 v9, v9, v3
	v_ldexp_f32 v3, v13, v3
	v_add_f32_e32 v13, -1.0, v9
	v_add_f32_e32 v16, 1.0, v9
	v_add_f32_e32 v14, 1.0, v13
	v_add_f32_e32 v17, -1.0, v16
	v_sub_f32_e32 v14, v9, v14
	v_sub_f32_e32 v9, v9, v17
	v_add_f32_e32 v14, v3, v14
	v_add_f32_e32 v3, v3, v9
	v_add_f32_e32 v9, v16, v3
	v_rcp_f32_e32 v17, v9
	v_add_f32_e32 v15, v13, v14
	v_sub_f32_e32 v13, v15, v13
	v_sub_f32_e32 v13, v14, v13
	v_sub_f32_e32 v14, v9, v16
	v_sub_f32_e32 v3, v3, v14
	v_mul_f32_e32 v14, v15, v17
	v_mul_f32_e32 v16, v9, v14
	v_fma_f32 v18, v14, v9, -v16
	v_fmac_f32_e32 v18, v14, v3
	v_add_f32_e32 v19, v16, v18
	v_sub_f32_e32 v20, v15, v19
	v_sub_f32_e32 v15, v15, v20
	v_sub_f32_e32 v16, v19, v16
	v_sub_f32_e32 v15, v15, v19
	v_add_f32_e32 v13, v13, v15
	v_sub_f32_e32 v15, v16, v18
	v_add_f32_e32 v13, v15, v13
	v_add_f32_e32 v15, v20, v13
	v_mul_f32_e32 v16, v17, v15
	v_mul_f32_e32 v18, v9, v16
	v_fma_f32 v9, v16, v9, -v18
	v_fmac_f32_e32 v9, v16, v3
	v_sub_f32_e32 v3, v20, v15
	v_add_f32_e32 v3, v13, v3
	v_add_f32_e32 v13, v18, v9
	v_sub_f32_e32 v19, v15, v13
	v_sub_f32_e32 v15, v15, v19
	v_sub_f32_e32 v18, v13, v18
	v_sub_f32_e32 v13, v15, v13
	v_add_f32_e32 v3, v3, v13
	v_sub_f32_e32 v9, v18, v9
	v_cvt_f32_i32_e32 v2, v2
	v_add_f32_e32 v3, v9, v3
	v_add_f32_e32 v9, v14, v16
	v_add_f32_e32 v3, v19, v3
	v_sub_f32_e32 v13, v9, v14
	v_mul_f32_e32 v3, v17, v3
	v_sub_f32_e32 v13, v16, v13
	v_add_f32_e32 v3, v13, v3
	v_mul_f32_e32 v16, 0x3f317218, v2
	v_add_f32_e32 v13, v9, v3
	v_fma_f32 v17, v2, s9, -v16
	v_mul_f32_e32 v14, v13, v13
	v_fmac_f32_e32 v17, 0xb102e308, v2
; template <int MODE, bool BIG = false> DI void gemm_tile(const Params& p, int tm, int tn, int kv, char* smem) {
;     ...
;     for (int c4 = 0; c4 < 16; ++c4) {
;       float4 v = crow4[c4], ww = w04[c4];
;       float u[4] = {v.x + ww.x, v.y + ww.y, v.z + ww.z, v.w + ww.w};
; #pragma unroll
;       for (int e = 0; e < 4; ++e) {
;         const float z = -u[e];
;         const float sp = fmaxf(z, 0.f) + log1pf(__expf(-fabsf(z)));
;         u[e] = __expf(-__expf(-sp - 0.5f));
;       }
;       W4[c4] = make_float4(u[0], u[1], u[2], u[3]);
	v_sub_f32_e32 v2, v13, v9
	v_fmamk_f32 v15, v14, 0x3e9b6dac, v231
	v_sub_f32_e32 v2, v3, v2
	v_add_f32_e32 v3, v16, v17
	v_fmaak_f32 v15, v14, v15, 0x3f2aaada
	v_sub_f32_e32 v9, v3, v16
	v_ldexp_f32 v16, v13, 1
	v_mul_f32_e32 v13, v13, v14
	v_mul_f32_e32 v13, v13, v15
	v_add_f32_e32 v14, v16, v13
	v_sub_f32_e32 v15, v14, v16
	v_ldexp_f32 v2, v2, 1
	v_sub_f32_e32 v13, v13, v15
	v_add_f32_e32 v2, v2, v13
	v_add_f32_e32 v13, v14, v2
	v_sub_f32_e32 v14, v13, v14
	v_sub_f32_e32 v2, v2, v14
	v_add_f32_e32 v14, v3, v13
	v_sub_f32_e32 v15, v14, v3
	v_sub_f32_e32 v16, v14, v15
	v_sub_f32_e32 v9, v17, v9
	v_sub_f32_e32 v3, v3, v16
	v_sub_f32_e32 v13, v13, v15
	v_add_f32_e32 v3, v13, v3
	v_add_f32_e32 v13, v9, v2
	v_sub_f32_e32 v15, v13, v9
	v_sub_f32_e32 v16, v13, v15
	v_sub_f32_e32 v9, v9, v16
	v_sub_f32_e32 v2, v2, v15
	v_add_f32_e32 v3, v13, v3
	v_add_f32_e32 v2, v2, v9
	v_add_f32_e32 v9, v14, v3
	v_sub_f32_e32 v13, v9, v14
	v_sub_f32_e32 v3, v3, v13
	v_add_f32_e32 v2, v2, v3
	v_add_f32_e32 v2, v9, v2
	v_cmp_neq_f32_e32 vcc, s6, v6
	s_nop 1
	v_cndmask_b32_e32 v2, v238, v2, vcc
	v_cmp_ngt_f32_e32 vcc, -1.0, v6
	s_nop 1
	v_cndmask_b32_e32 v2, v239, v2, vcc
	v_cmp_neq_f32_e32 vcc, -1.0, v6
	s_nop 1
	v_cndmask_b32_e32 v2, v240, v2, vcc
	v_cmp_lt_f32_e64 vcc, |v6|, s10
	s_nop 1
	v_cndmask_b32_e32 v2, v2, v6, vcc
	v_add_f32_e32 v2, v7, v2
	v_sub_f32_e32 v2, -0.5, v2
	v_mul_f32_e32 v2, 0x3fb8aa3b, v2
	v_exp_f32_e32 v3, v2
	v_mul_f32_e64 v2, |v4|, s7
	v_exp_f32_e32 v6, v2
	v_max_f32_e64 v7, -v4, 0
	v_exp_f32_e32 v2, v5
	v_mul_f32_e32 v3, 0xbfb8aa3b, v3
	v_add_f32_e32 v9, 1.0, v6
	v_add_f32_e32 v4, -1.0, v9
	v_sub_f32_e32 v5, v4, v9
	v_add_f32_e32 v5, 1.0, v5
	v_sub_f32_e32 v4, v6, v4
	v_add_f32_e32 v13, v4, v5
	v_frexp_mant_f32_e32 v4, v9
	v_cmp_gt_f32_e32 vcc, s8, v4
	v_cvt_f64_f32_e32 v[4:5], v9
	v_frexp_exp_i32_f64_e32 v4, v[4:5]
	v_subbrev_co_u32_e32 v4, vcc, 0, v4, vcc
	v_sub_u32_e32 v5, 0, v4
	v_ldexp_f32 v9, v9, v5
	v_ldexp_f32 v5, v13, v5
	v_add_f32_e32 v13, -1.0, v9
	v_add_f32_e32 v16, 1.0, v9
	v_add_f32_e32 v14, 1.0, v13
	v_add_f32_e32 v17, -1.0, v16
	v_sub_f32_e32 v14, v9, v14
	v_sub_f32_e32 v9, v9, v17
	v_add_f32_e32 v14, v5, v14
	v_add_f32_e32 v5, v5, v9
	v_add_f32_e32 v9, v16, v5
	v_rcp_f32_e32 v17, v9
	v_add_f32_e32 v15, v13, v14
	v_sub_f32_e32 v13, v15, v13
	v_sub_f32_e32 v13, v14, v13
	v_sub_f32_e32 v14, v9, v16
	v_sub_f32_e32 v5, v5, v14
	v_mul_f32_e32 v14, v15, v17
	v_mul_f32_e32 v16, v9, v14
	v_fma_f32 v18, v14, v9, -v16
	v_fmac_f32_e32 v18, v14, v5
	v_add_f32_e32 v19, v16, v18
	v_sub_f32_e32 v20, v15, v19
	v_sub_f32_e32 v15, v15, v20
	v_sub_f32_e32 v16, v19, v16
	v_sub_f32_e32 v15, v15, v19
	v_add_f32_e32 v13, v13, v15
	v_sub_f32_e32 v15, v16, v18
	v_add_f32_e32 v13, v15, v13
	v_add_f32_e32 v15, v20, v13
	v_mul_f32_e32 v16, v17, v15
	v_mul_f32_e32 v18, v9, v16
	v_fma_f32 v9, v16, v9, -v18
	v_fmac_f32_e32 v9, v16, v5
	v_sub_f32_e32 v5, v20, v15
	v_add_f32_e32 v5, v13, v5
	v_add_f32_e32 v13, v18, v9
	v_sub_f32_e32 v19, v15, v13
	v_sub_f32_e32 v15, v15, v19
	v_sub_f32_e32 v18, v13, v18
	v_sub_f32_e32 v13, v15, v13
	v_add_f32_e32 v5, v5, v13
	v_sub_f32_e32 v9, v18, v9
	v_cvt_f32_i32_e32 v4, v4
	v_add_f32_e32 v5, v9, v5
	v_add_f32_e32 v9, v14, v16
	v_add_f32_e32 v5, v19, v5
	v_sub_f32_e32 v13, v9, v14
	v_mul_f32_e32 v5, v17, v5
	v_sub_f32_e32 v13, v16, v13
	v_add_f32_e32 v5, v13, v5
	v_mul_f32_e32 v16, 0x3f317218, v4
	v_add_f32_e32 v13, v9, v5
	v_fma_f32 v17, v4, s9, -v16
	v_mul_f32_e32 v14, v13, v13
	v_fmac_f32_e32 v17, 0xb102e308, v4
	v_sub_f32_e32 v4, v13, v9
	v_fmamk_f32 v15, v14, 0x3e9b6dac, v231
	v_sub_f32_e32 v4, v5, v4
	v_add_f32_e32 v5, v16, v17
	v_fmaak_f32 v15, v14, v15, 0x3f2aaada
	v_sub_f32_e32 v9, v5, v16
	v_ldexp_f32 v16, v13, 1
	v_mul_f32_e32 v13, v13, v14
	v_mul_f32_e32 v13, v13, v15
	v_add_f32_e32 v14, v16, v13
	v_sub_f32_e32 v15, v14, v16
	v_ldexp_f32 v4, v4, 1
	v_sub_f32_e32 v13, v13, v15
	v_add_f32_e32 v4, v4, v13
	v_add_f32_e32 v13, v14, v4
	v_sub_f32_e32 v14, v13, v14
	v_sub_f32_e32 v4, v4, v14
	v_add_f32_e32 v14, v5, v13
	v_sub_f32_e32 v15, v14, v5
	v_sub_f32_e32 v16, v14, v15
	v_sub_f32_e32 v9, v17, v9
	v_sub_f32_e32 v5, v5, v16
	v_sub_f32_e32 v13, v13, v15
	v_add_f32_e32 v5, v13, v5
	v_add_f32_e32 v13, v9, v4
	v_sub_f32_e32 v15, v13, v9
	v_sub_f32_e32 v16, v13, v15
	v_sub_f32_e32 v9, v9, v16
	v_sub_f32_e32 v4, v4, v15
	v_add_f32_e32 v5, v13, v5
	v_add_f32_e32 v4, v4, v9
	v_add_f32_e32 v9, v14, v5
	v_sub_f32_e32 v13, v9, v14
	v_sub_f32_e32 v5, v5, v13
	v_add_f32_e32 v4, v4, v5
	v_add_f32_e32 v4, v9, v4
	v_cmp_neq_f32_e32 vcc, s6, v6
	v_mul_f32_e64 v5, |v8|, s7
	v_max_f32_e64 v8, -v8, 0
	v_cndmask_b32_e32 v4, v238, v4, vcc
	v_cmp_ngt_f32_e32 vcc, -1.0, v6
	v_exp_f32_e32 v3, v3
	s_nop 0
	v_cndmask_b32_e32 v4, v239, v4, vcc
	v_cmp_neq_f32_e32 vcc, -1.0, v6
	s_nop 1
	v_cndmask_b32_e32 v4, v240, v4, vcc
	v_cmp_lt_f32_e64 vcc, |v6|, s10
	s_nop 1
	v_cndmask_b32_e32 v4, v4, v6, vcc
	v_exp_f32_e32 v6, v5
	v_add_f32_e32 v4, v7, v4
	v_sub_f32_e32 v4, -0.5, v4
	v_mul_f32_e32 v4, 0x3fb8aa3b, v4
	v_add_f32_e32 v9, 1.0, v6
	v_exp_f32_e32 v7, v4
	v_add_f32_e32 v4, -1.0, v9
	v_sub_f32_e32 v5, v4, v9
	v_add_f32_e32 v5, 1.0, v5
	v_sub_f32_e32 v4, v6, v4
	v_add_f32_e32 v13, v4, v5
	v_frexp_mant_f32_e32 v4, v9
	v_cmp_gt_f32_e32 vcc, s8, v4
	v_cvt_f64_f32_e32 v[4:5], v9
	v_frexp_exp_i32_f64_e32 v4, v[4:5]
	v_subbrev_co_u32_e32 v4, vcc, 0, v4, vcc
	v_sub_u32_e32 v5, 0, v4
	v_ldexp_f32 v9, v9, v5
	v_ldexp_f32 v5, v13, v5
	v_add_f32_e32 v13, -1.0, v9
	v_add_f32_e32 v16, 1.0, v9
	v_add_f32_e32 v14, 1.0, v13
	v_add_f32_e32 v17, -1.0, v16
	v_sub_f32_e32 v14, v9, v14
	v_sub_f32_e32 v9, v9, v17
	v_add_f32_e32 v14, v5, v14
	v_add_f32_e32 v5, v5, v9
; template <int MODE, bool BIG = false> DI void gemm_tile(const Params& p, int tm, int tn, int kv, char* smem) {
;     ...
;     for (int c4 = 0; c4 < 16; ++c4) {
;       float4 v = crow4[c4], ww = w04[c4];
;       float u[4] = {v.x + ww.x, v.y + ww.y, v.z + ww.z, v.w + ww.w};
; #pragma unroll
;       for (int e = 0; e < 4; ++e) {
;         const float z = -u[e];
;         const float sp = fmaxf(z, 0.f) + log1pf(__expf(-fabsf(z)));
;         u[e] = __expf(-__expf(-sp - 0.5f));
;       }
;       W4[c4] = make_float4(u[0], u[1], u[2], u[3]);
	v_add_f32_e32 v9, v16, v5
	v_rcp_f32_e32 v17, v9
	v_add_f32_e32 v15, v13, v14
	v_sub_f32_e32 v13, v15, v13
	v_sub_f32_e32 v13, v14, v13
	v_sub_f32_e32 v14, v9, v16
	v_sub_f32_e32 v5, v5, v14
	v_mul_f32_e32 v14, v15, v17
	v_mul_f32_e32 v16, v9, v14
	v_fma_f32 v18, v14, v9, -v16
	v_fmac_f32_e32 v18, v14, v5
	v_add_f32_e32 v19, v16, v18
	v_sub_f32_e32 v20, v15, v19
	v_sub_f32_e32 v15, v15, v20
	v_sub_f32_e32 v16, v19, v16
	v_sub_f32_e32 v15, v15, v19
	v_add_f32_e32 v13, v13, v15
	v_sub_f32_e32 v15, v16, v18
	v_add_f32_e32 v13, v15, v13
	v_add_f32_e32 v15, v20, v13
	v_mul_f32_e32 v16, v17, v15
	v_mul_f32_e32 v18, v9, v16
	v_fma_f32 v9, v16, v9, -v18
	v_fmac_f32_e32 v9, v16, v5
	v_sub_f32_e32 v5, v20, v15
	v_add_f32_e32 v5, v13, v5
	v_add_f32_e32 v13, v18, v9
	v_sub_f32_e32 v19, v15, v13
	v_sub_f32_e32 v15, v15, v19
	v_sub_f32_e32 v18, v13, v18
	v_sub_f32_e32 v13, v15, v13
	v_add_f32_e32 v5, v5, v13
	v_sub_f32_e32 v9, v18, v9
	v_cvt_f32_i32_e32 v4, v4
	v_add_f32_e32 v5, v9, v5
	v_add_f32_e32 v9, v14, v16
	v_add_f32_e32 v5, v19, v5
	v_sub_f32_e32 v13, v9, v14
	v_mul_f32_e32 v5, v17, v5
	v_sub_f32_e32 v13, v16, v13
	v_add_f32_e32 v5, v13, v5
	v_mul_f32_e32 v16, 0x3f317218, v4
	v_add_f32_e32 v13, v9, v5
	v_fma_f32 v17, v4, s9, -v16
	v_mul_f32_e32 v14, v13, v13
	v_fmac_f32_e32 v17, 0xb102e308, v4
	v_sub_f32_e32 v4, v13, v9
	v_fmamk_f32 v15, v14, 0x3e9b6dac, v231
	v_sub_f32_e32 v4, v5, v4
	v_add_f32_e32 v5, v16, v17
	v_fmaak_f32 v15, v14, v15, 0x3f2aaada
	v_sub_f32_e32 v9, v5, v16
	v_ldexp_f32 v16, v13, 1
	v_mul_f32_e32 v13, v13, v14
	v_mul_f32_e32 v13, v13, v15
	v_add_f32_e32 v14, v16, v13
	v_sub_f32_e32 v15, v14, v16
	v_ldexp_f32 v4, v4, 1
	v_sub_f32_e32 v13, v13, v15
	v_add_f32_e32 v4, v4, v13
	v_add_f32_e32 v13, v14, v4
	v_sub_f32_e32 v14, v13, v14
	v_sub_f32_e32 v4, v4, v14
	v_add_f32_e32 v14, v5, v13
	v_sub_f32_e32 v15, v14, v5
	v_sub_f32_e32 v16, v14, v15
	v_sub_f32_e32 v9, v17, v9
	v_sub_f32_e32 v5, v5, v16
	v_sub_f32_e32 v13, v13, v15
	v_add_f32_e32 v5, v13, v5
	v_add_f32_e32 v13, v9, v4
	v_sub_f32_e32 v15, v13, v9
	v_sub_f32_e32 v16, v13, v15
	v_sub_f32_e32 v9, v9, v16
	v_sub_f32_e32 v4, v4, v15
	v_add_f32_e32 v5, v13, v5
	v_add_f32_e32 v4, v4, v9
	v_add_f32_e32 v9, v14, v5
	v_sub_f32_e32 v13, v9, v14
	v_sub_f32_e32 v5, v5, v13
	v_add_f32_e32 v4, v4, v5
	v_add_f32_e32 v4, v9, v4
	v_cmp_neq_f32_e32 vcc, s6, v6
	s_nop 1
	v_cndmask_b32_e32 v4, v238, v4, vcc
	v_cmp_ngt_f32_e32 vcc, -1.0, v6
	s_nop 1
	v_cndmask_b32_e32 v4, v239, v4, vcc
	v_cmp_neq_f32_e32 vcc, -1.0, v6
	s_nop 1
	v_cndmask_b32_e32 v4, v240, v4, vcc
	v_cmp_lt_f32_e64 vcc, |v6|, s10
	s_nop 1
	v_cndmask_b32_e32 v4, v4, v6, vcc
	v_add_f32_e32 v4, v8, v4
	v_sub_f32_e32 v4, -0.5, v4
	v_mul_f32_e32 v4, 0x3fb8aa3b, v4
	v_exp_f32_e32 v5, v4
	v_mul_f32_e32 v4, 0xbfb8aa3b, v7
	v_exp_f32_e32 v4, v4
	ds_read_b128 v[6:9], v12 offset:192
	v_mul_f32_e32 v5, 0xbfb8aa3b, v5
	v_exp_f32_e32 v5, v5
	ds_write_b128 v75, v[2:5] offset:176
	ds_read_b128 v[2:5], v74 offset:192
	s_waitcnt lgkmcnt(0)
	v_add_f32_e32 v2, v6, v2
	v_mul_f32_e64 v6, |v2|, s7
	v_exp_f32_e32 v6, v6
	v_add_f32_e32 v4, v8, v4
	v_max_f32_e64 v8, -v2, 0
	v_add_f32_e32 v7, v7, v3
	v_add_f32_e32 v13, 1.0, v6
	v_add_f32_e32 v2, -1.0, v13
	v_sub_f32_e32 v3, v2, v13
	v_add_f32_e32 v3, 1.0, v3
	v_sub_f32_e32 v2, v6, v2
	v_add_f32_e32 v14, v2, v3
	v_frexp_mant_f32_e32 v2, v13
	v_cmp_gt_f32_e32 vcc, s8, v2
	v_cvt_f64_f32_e32 v[2:3], v13
	v_frexp_exp_i32_f64_e32 v2, v[2:3]
	v_subbrev_co_u32_e32 v2, vcc, 0, v2, vcc
	v_sub_u32_e32 v3, 0, v2
	v_ldexp_f32 v13, v13, v3
	v_ldexp_f32 v3, v14, v3
	v_add_f32_e32 v14, -1.0, v13
	v_add_f32_e32 v17, 1.0, v13
	v_add_f32_e32 v15, 1.0, v14
	v_add_f32_e32 v18, -1.0, v17
	v_sub_f32_e32 v15, v13, v15
	v_sub_f32_e32 v13, v13, v18
	v_add_f32_e32 v15, v3, v15
	v_add_f32_e32 v3, v3, v13
	v_add_f32_e32 v13, v17, v3
	v_rcp_f32_e32 v18, v13
	v_add_f32_e32 v16, v14, v15
	v_sub_f32_e32 v14, v16, v14
	v_sub_f32_e32 v14, v15, v14
	v_sub_f32_e32 v15, v13, v17
	v_sub_f32_e32 v3, v3, v15
	v_mul_f32_e32 v15, v16, v18
	v_mul_f32_e32 v17, v13, v15
	v_fma_f32 v19, v15, v13, -v17
	v_fmac_f32_e32 v19, v15, v3
	v_add_f32_e32 v20, v17, v19
	v_sub_f32_e32 v21, v16, v20
	v_sub_f32_e32 v16, v16, v21
	v_sub_f32_e32 v17, v20, v17
	v_sub_f32_e32 v16, v16, v20
	v_add_f32_e32 v14, v14, v16
	v_sub_f32_e32 v16, v17, v19
	v_add_f32_e32 v14, v16, v14
	v_add_f32_e32 v16, v21, v14
	v_mul_f32_e32 v17, v18, v16
	v_mul_f32_e32 v19, v13, v17
	v_fma_f32 v13, v17, v13, -v19
	v_fmac_f32_e32 v13, v17, v3
	v_sub_f32_e32 v3, v21, v16
	v_add_f32_e32 v3, v14, v3
	v_add_f32_e32 v14, v19, v13
	v_sub_f32_e32 v20, v16, v14
	v_sub_f32_e32 v16, v16, v20
	v_sub_f32_e32 v19, v14, v19
	v_sub_f32_e32 v14, v16, v14
	v_add_f32_e32 v3, v3, v14
	v_sub_f32_e32 v13, v19, v13
	v_cvt_f32_i32_e32 v2, v2
	v_add_f32_e32 v3, v13, v3
	v_add_f32_e32 v13, v15, v17
	v_add_f32_e32 v3, v20, v3
	v_sub_f32_e32 v14, v13, v15
	v_mul_f32_e32 v3, v18, v3
	v_sub_f32_e32 v14, v17, v14
	v_add_f32_e32 v3, v14, v3
	v_mul_f32_e32 v17, 0x3f317218, v2
	v_add_f32_e32 v14, v13, v3
	v_fma_f32 v18, v2, s9, -v17
	v_mul_f32_e32 v15, v14, v14
	v_fmac_f32_e32 v18, 0xb102e308, v2
	v_sub_f32_e32 v2, v14, v13
	v_fmamk_f32 v16, v15, 0x3e9b6dac, v231
	v_sub_f32_e32 v2, v3, v2
	v_add_f32_e32 v3, v17, v18
	v_fmaak_f32 v16, v15, v16, 0x3f2aaada
	v_sub_f32_e32 v13, v3, v17
	v_ldexp_f32 v17, v14, 1
	v_mul_f32_e32 v14, v14, v15
	v_mul_f32_e32 v14, v14, v16
	v_add_f32_e32 v15, v17, v14
	v_sub_f32_e32 v16, v15, v17
	v_ldexp_f32 v2, v2, 1
	v_sub_f32_e32 v14, v14, v16
	v_add_f32_e32 v2, v2, v14
	v_add_f32_e32 v14, v15, v2
	v_sub_f32_e32 v15, v14, v15
	v_sub_f32_e32 v2, v2, v15
	v_add_f32_e32 v15, v3, v14
; template <int MODE, bool BIG = false> DI void gemm_tile(const Params& p, int tm, int tn, int kv, char* smem) {
;     ...
;     for (int c4 = 0; c4 < 16; ++c4) {
;       float4 v = crow4[c4], ww = w04[c4];
;       float u[4] = {v.x + ww.x, v.y + ww.y, v.z + ww.z, v.w + ww.w};
; #pragma unroll
;       for (int e = 0; e < 4; ++e) {
;         const float z = -u[e];
;         const float sp = fmaxf(z, 0.f) + log1pf(__expf(-fabsf(z)));
;         u[e] = __expf(-__expf(-sp - 0.5f));
;       }
;       W4[c4] = make_float4(u[0], u[1], u[2], u[3]);
	v_sub_f32_e32 v16, v15, v3
	v_sub_f32_e32 v17, v15, v16
	v_sub_f32_e32 v13, v18, v13
	v_sub_f32_e32 v3, v3, v17
	v_sub_f32_e32 v14, v14, v16
	v_add_f32_e32 v3, v14, v3
	v_add_f32_e32 v14, v13, v2
	v_sub_f32_e32 v16, v14, v13
	v_sub_f32_e32 v17, v14, v16
	v_sub_f32_e32 v13, v13, v17
	v_sub_f32_e32 v2, v2, v16
	v_add_f32_e32 v3, v14, v3
	v_add_f32_e32 v2, v2, v13
	v_add_f32_e32 v13, v15, v3
	v_sub_f32_e32 v14, v13, v15
	v_sub_f32_e32 v3, v3, v14
	v_add_f32_e32 v2, v2, v3
	v_add_f32_e32 v2, v13, v2
	v_cmp_neq_f32_e32 vcc, s6, v6
	v_mul_f32_e64 v3, |v7|, s7
	v_max_f32_e64 v7, -v7, 0
	v_cndmask_b32_e32 v2, v238, v2, vcc
	v_cmp_ngt_f32_e32 vcc, -1.0, v6
	s_nop 1
	v_cndmask_b32_e32 v2, v239, v2, vcc
	v_cmp_neq_f32_e32 vcc, -1.0, v6
	s_nop 1
	v_cndmask_b32_e32 v2, v240, v2, vcc
	v_cmp_lt_f32_e64 vcc, |v6|, s10
	s_nop 1
	v_cndmask_b32_e32 v2, v2, v6, vcc
	v_add_f32_e32 v2, v8, v2
	v_sub_f32_e32 v2, -0.5, v2
	v_mul_f32_e32 v2, 0x3fb8aa3b, v2
	v_exp_f32_e32 v6, v3
	v_exp_f32_e32 v2, v2
	v_add_f32_e32 v8, v9, v5
	v_add_f32_e32 v9, 1.0, v6
	v_mul_f32_e32 v5, 0xbfb8aa3b, v2
	v_add_f32_e32 v2, -1.0, v9
	v_sub_f32_e32 v3, v2, v9
	v_add_f32_e32 v3, 1.0, v3
	v_sub_f32_e32 v2, v6, v2
	v_add_f32_e32 v13, v2, v3
	v_frexp_mant_f32_e32 v2, v9
	v_cmp_gt_f32_e32 vcc, s8, v2
	v_cvt_f64_f32_e32 v[2:3], v9
	v_frexp_exp_i32_f64_e32 v2, v[2:3]
	v_subbrev_co_u32_e32 v2, vcc, 0, v2, vcc
	v_sub_u32_e32 v3, 0, v2
	v_ldexp_f32 v9, v9, v3
	v_ldexp_f32 v3, v13, v3
	v_add_f32_e32 v13, -1.0, v9
	v_add_f32_e32 v16, 1.0, v9
	v_add_f32_e32 v14, 1.0, v13
	v_add_f32_e32 v17, -1.0, v16
	v_sub_f32_e32 v14, v9, v14
	v_sub_f32_e32 v9, v9, v17
	v_add_f32_e32 v14, v3, v14
	v_add_f32_e32 v3, v3, v9
	v_add_f32_e32 v9, v16, v3
	v_rcp_f32_e32 v17, v9
	v_add_f32_e32 v15, v13, v14
	v_sub_f32_e32 v13, v15, v13
	v_sub_f32_e32 v13, v14, v13
	v_sub_f32_e32 v14, v9, v16
	v_sub_f32_e32 v3, v3, v14
	v_mul_f32_e32 v14, v15, v17
	v_mul_f32_e32 v16, v9, v14
	v_fma_f32 v18, v14, v9, -v16
	v_fmac_f32_e32 v18, v14, v3
	v_add_f32_e32 v19, v16, v18
	v_sub_f32_e32 v20, v15, v19
	v_sub_f32_e32 v15, v15, v20
	v_sub_f32_e32 v16, v19, v16
	v_sub_f32_e32 v15, v15, v19
	v_add_f32_e32 v13, v13, v15
	v_sub_f32_e32 v15, v16, v18
	v_add_f32_e32 v13, v15, v13
	v_add_f32_e32 v15, v20, v13
	v_mul_f32_e32 v16, v17, v15
	v_mul_f32_e32 v18, v9, v16
	v_fma_f32 v9, v16, v9, -v18
	v_fmac_f32_e32 v9, v16, v3
	v_sub_f32_e32 v3, v20, v15
	v_add_f32_e32 v3, v13, v3
	v_add_f32_e32 v13, v18, v9
	v_sub_f32_e32 v19, v15, v13
	v_sub_f32_e32 v15, v15, v19
	v_sub_f32_e32 v18, v13, v18
	v_sub_f32_e32 v13, v15, v13
	v_add_f32_e32 v3, v3, v13
	v_sub_f32_e32 v9, v18, v9
	v_cvt_f32_i32_e32 v2, v2
	v_add_f32_e32 v3, v9, v3
	v_add_f32_e32 v9, v14, v16
	v_add_f32_e32 v3, v19, v3
	v_sub_f32_e32 v13, v9, v14
	v_mul_f32_e32 v3, v17, v3
	v_sub_f32_e32 v13, v16, v13
	v_add_f32_e32 v3, v13, v3
	v_mul_f32_e32 v16, 0x3f317218, v2
	v_add_f32_e32 v13, v9, v3
	v_fma_f32 v17, v2, s9, -v16
	v_mul_f32_e32 v14, v13, v13
	v_fmac_f32_e32 v17, 0xb102e308, v2
	v_sub_f32_e32 v2, v13, v9
	v_fmamk_f32 v15, v14, 0x3e9b6dac, v231
	v_sub_f32_e32 v2, v3, v2
	v_add_f32_e32 v3, v16, v17
	v_fmaak_f32 v15, v14, v15, 0x3f2aaada
	v_sub_f32_e32 v9, v3, v16
	v_ldexp_f32 v16, v13, 1
	v_mul_f32_e32 v13, v13, v14
	v_mul_f32_e32 v13, v13, v15
	v_add_f32_e32 v14, v16, v13
	v_sub_f32_e32 v15, v14, v16
	v_ldexp_f32 v2, v2, 1
	v_sub_f32_e32 v13, v13, v15
	v_add_f32_e32 v2, v2, v13
	v_add_f32_e32 v13, v14, v2
	v_sub_f32_e32 v14, v13, v14
	v_sub_f32_e32 v2, v2, v14
	v_add_f32_e32 v14, v3, v13
	v_sub_f32_e32 v15, v14, v3
	v_sub_f32_e32 v16, v14, v15
	v_sub_f32_e32 v9, v17, v9
	v_sub_f32_e32 v3, v3, v16
	v_sub_f32_e32 v13, v13, v15
	v_add_f32_e32 v3, v13, v3
	v_add_f32_e32 v13, v9, v2
	v_sub_f32_e32 v15, v13, v9
	v_sub_f32_e32 v16, v13, v15
	v_sub_f32_e32 v9, v9, v16
	v_sub_f32_e32 v2, v2, v15
	v_add_f32_e32 v3, v13, v3
	v_add_f32_e32 v2, v2, v9
	v_add_f32_e32 v9, v14, v3
	v_sub_f32_e32 v13, v9, v14
	v_sub_f32_e32 v3, v3, v13
	v_add_f32_e32 v2, v2, v3
	v_add_f32_e32 v2, v9, v2
	v_cmp_neq_f32_e32 vcc, s6, v6
	s_nop 1
	v_cndmask_b32_e32 v2, v238, v2, vcc
	v_cmp_ngt_f32_e32 vcc, -1.0, v6
	s_nop 1
	v_cndmask_b32_e32 v2, v239, v2, vcc
	v_cmp_neq_f32_e32 vcc, -1.0, v6
	s_nop 1
	v_cndmask_b32_e32 v2, v240, v2, vcc
	v_cmp_lt_f32_e64 vcc, |v6|, s10
	s_nop 1
	v_cndmask_b32_e32 v2, v2, v6, vcc
	v_add_f32_e32 v2, v7, v2
	v_sub_f32_e32 v2, -0.5, v2
	v_mul_f32_e32 v2, 0x3fb8aa3b, v2
	v_exp_f32_e32 v3, v2
	v_mul_f32_e64 v2, |v4|, s7
	v_exp_f32_e32 v6, v2
	v_max_f32_e64 v7, -v4, 0
	v_exp_f32_e32 v2, v5
	v_mul_f32_e32 v3, 0xbfb8aa3b, v3
	v_add_f32_e32 v9, 1.0, v6
	v_add_f32_e32 v4, -1.0, v9
	v_sub_f32_e32 v5, v4, v9
	v_add_f32_e32 v5, 1.0, v5
	v_sub_f32_e32 v4, v6, v4
	v_add_f32_e32 v13, v4, v5
	v_frexp_mant_f32_e32 v4, v9
	v_cmp_gt_f32_e32 vcc, s8, v4
	v_cvt_f64_f32_e32 v[4:5], v9
	v_frexp_exp_i32_f64_e32 v4, v[4:5]
	v_subbrev_co_u32_e32 v4, vcc, 0, v4, vcc
	v_sub_u32_e32 v5, 0, v4
	v_ldexp_f32 v9, v9, v5
	v_ldexp_f32 v5, v13, v5
	v_add_f32_e32 v13, -1.0, v9
	v_add_f32_e32 v16, 1.0, v9
	v_add_f32_e32 v14, 1.0, v13
	v_add_f32_e32 v17, -1.0, v16
	v_sub_f32_e32 v14, v9, v14
	v_sub_f32_e32 v9, v9, v17
	v_add_f32_e32 v14, v5, v14
	v_add_f32_e32 v5, v5, v9
	v_add_f32_e32 v9, v16, v5
	v_rcp_f32_e32 v17, v9
	v_add_f32_e32 v15, v13, v14
	v_sub_f32_e32 v13, v15, v13
	v_sub_f32_e32 v13, v14, v13
	v_sub_f32_e32 v14, v9, v16
	v_sub_f32_e32 v5, v5, v14
	v_mul_f32_e32 v14, v15, v17
	v_mul_f32_e32 v16, v9, v14
	v_fma_f32 v18, v14, v9, -v16
	v_fmac_f32_e32 v18, v14, v5
	v_add_f32_e32 v19, v16, v18
	v_sub_f32_e32 v20, v15, v19
	v_sub_f32_e32 v15, v15, v20
	v_sub_f32_e32 v16, v19, v16
	v_sub_f32_e32 v15, v15, v19
; template <int MODE, bool BIG = false> DI void gemm_tile(const Params& p, int tm, int tn, int kv, char* smem) {
;     ...
;     for (int c4 = 0; c4 < 16; ++c4) {
;       float4 v = crow4[c4], ww = w04[c4];
;       float u[4] = {v.x + ww.x, v.y + ww.y, v.z + ww.z, v.w + ww.w};
; #pragma unroll
;       for (int e = 0; e < 4; ++e) {
;         const float z = -u[e];
;         const float sp = fmaxf(z, 0.f) + log1pf(__expf(-fabsf(z)));
;         u[e] = __expf(-__expf(-sp - 0.5f));
;       }
;       W4[c4] = make_float4(u[0], u[1], u[2], u[3]);
	v_add_f32_e32 v13, v13, v15
	v_sub_f32_e32 v15, v16, v18
	v_add_f32_e32 v13, v15, v13
	v_add_f32_e32 v15, v20, v13
	v_mul_f32_e32 v16, v17, v15
	v_mul_f32_e32 v18, v9, v16
	v_fma_f32 v9, v16, v9, -v18
	v_fmac_f32_e32 v9, v16, v5
	v_sub_f32_e32 v5, v20, v15
	v_add_f32_e32 v5, v13, v5
	v_add_f32_e32 v13, v18, v9
	v_sub_f32_e32 v19, v15, v13
	v_sub_f32_e32 v15, v15, v19
	v_sub_f32_e32 v18, v13, v18
	v_sub_f32_e32 v13, v15, v13
	v_add_f32_e32 v5, v5, v13
	v_sub_f32_e32 v9, v18, v9
	v_cvt_f32_i32_e32 v4, v4
	v_add_f32_e32 v5, v9, v5
	v_add_f32_e32 v9, v14, v16
	v_add_f32_e32 v5, v19, v5
	v_sub_f32_e32 v13, v9, v14
	v_mul_f32_e32 v5, v17, v5
	v_sub_f32_e32 v13, v16, v13
	v_add_f32_e32 v5, v13, v5
	v_mul_f32_e32 v16, 0x3f317218, v4
	v_add_f32_e32 v13, v9, v5
	v_fma_f32 v17, v4, s9, -v16
	v_mul_f32_e32 v14, v13, v13
	v_fmac_f32_e32 v17, 0xb102e308, v4
	v_sub_f32_e32 v4, v13, v9
	v_fmamk_f32 v15, v14, 0x3e9b6dac, v231
	v_sub_f32_e32 v4, v5, v4
	v_add_f32_e32 v5, v16, v17
	v_fmaak_f32 v15, v14, v15, 0x3f2aaada
	v_sub_f32_e32 v9, v5, v16
	v_ldexp_f32 v16, v13, 1
	v_mul_f32_e32 v13, v13, v14
	v_mul_f32_e32 v13, v13, v15
	v_add_f32_e32 v14, v16, v13
	v_sub_f32_e32 v15, v14, v16
	v_ldexp_f32 v4, v4, 1
	v_sub_f32_e32 v13, v13, v15
	v_add_f32_e32 v4, v4, v13
	v_add_f32_e32 v13, v14, v4
	v_sub_f32_e32 v14, v13, v14
	v_sub_f32_e32 v4, v4, v14
	v_add_f32_e32 v14, v5, v13
	v_sub_f32_e32 v15, v14, v5
	v_sub_f32_e32 v16, v14, v15
	v_sub_f32_e32 v9, v17, v9
	v_sub_f32_e32 v5, v5, v16
	v_sub_f32_e32 v13, v13, v15
	v_add_f32_e32 v5, v13, v5
	v_add_f32_e32 v13, v9, v4
	v_sub_f32_e32 v15, v13, v9
	v_sub_f32_e32 v16, v13, v15
	v_sub_f32_e32 v9, v9, v16
	v_sub_f32_e32 v4, v4, v15
	v_add_f32_e32 v5, v13, v5
	v_add_f32_e32 v4, v4, v9
	v_add_f32_e32 v9, v14, v5
	v_sub_f32_e32 v13, v9, v14
	v_sub_f32_e32 v5, v5, v13
	v_add_f32_e32 v4, v4, v5
	v_add_f32_e32 v4, v9, v4
	v_cmp_neq_f32_e32 vcc, s6, v6
	v_mul_f32_e64 v5, |v8|, s7
	v_max_f32_e64 v8, -v8, 0
	v_cndmask_b32_e32 v4, v238, v4, vcc
	v_cmp_ngt_f32_e32 vcc, -1.0, v6
	v_exp_f32_e32 v3, v3
	s_nop 0
	v_cndmask_b32_e32 v4, v239, v4, vcc
	v_cmp_neq_f32_e32 vcc, -1.0, v6
	s_nop 1
	v_cndmask_b32_e32 v4, v240, v4, vcc
	v_cmp_lt_f32_e64 vcc, |v6|, s10
	s_nop 1
	v_cndmask_b32_e32 v4, v4, v6, vcc
	v_exp_f32_e32 v6, v5
	v_add_f32_e32 v4, v7, v4
	v_sub_f32_e32 v4, -0.5, v4
	v_mul_f32_e32 v4, 0x3fb8aa3b, v4
	v_add_f32_e32 v9, 1.0, v6
	v_exp_f32_e32 v7, v4
	v_add_f32_e32 v4, -1.0, v9
	v_sub_f32_e32 v5, v4, v9
	v_add_f32_e32 v5, 1.0, v5
	v_sub_f32_e32 v4, v6, v4
	v_add_f32_e32 v13, v4, v5
	v_frexp_mant_f32_e32 v4, v9
	v_cmp_gt_f32_e32 vcc, s8, v4
	v_cvt_f64_f32_e32 v[4:5], v9
	v_frexp_exp_i32_f64_e32 v4, v[4:5]
	v_subbrev_co_u32_e32 v4, vcc, 0, v4, vcc
	v_sub_u32_e32 v5, 0, v4
	v_ldexp_f32 v9, v9, v5
	v_ldexp_f32 v5, v13, v5
	v_add_f32_e32 v13, -1.0, v9
	v_add_f32_e32 v16, 1.0, v9
	v_add_f32_e32 v14, 1.0, v13
	v_add_f32_e32 v17, -1.0, v16
	v_sub_f32_e32 v14, v9, v14
	v_sub_f32_e32 v9, v9, v17
	v_add_f32_e32 v14, v5, v14
	v_add_f32_e32 v5, v5, v9
	v_add_f32_e32 v9, v16, v5
	v_rcp_f32_e32 v17, v9
	v_add_f32_e32 v15, v13, v14
	v_sub_f32_e32 v13, v15, v13
	v_sub_f32_e32 v13, v14, v13
	v_sub_f32_e32 v14, v9, v16
	v_sub_f32_e32 v5, v5, v14
	v_mul_f32_e32 v14, v15, v17
	v_mul_f32_e32 v16, v9, v14
	v_fma_f32 v18, v14, v9, -v16
	v_fmac_f32_e32 v18, v14, v5
	v_add_f32_e32 v19, v16, v18
	v_sub_f32_e32 v20, v15, v19
	v_sub_f32_e32 v15, v15, v20
	v_sub_f32_e32 v16, v19, v16
	v_sub_f32_e32 v15, v15, v19
	v_add_f32_e32 v13, v13, v15
	v_sub_f32_e32 v15, v16, v18
	v_add_f32_e32 v13, v15, v13
	v_add_f32_e32 v15, v20, v13
	v_mul_f32_e32 v16, v17, v15
	v_mul_f32_e32 v18, v9, v16
	v_fma_f32 v9, v16, v9, -v18
	v_fmac_f32_e32 v9, v16, v5
	v_sub_f32_e32 v5, v20, v15
	v_add_f32_e32 v5, v13, v5
	v_add_f32_e32 v13, v18, v9
	v_sub_f32_e32 v19, v15, v13
	v_sub_f32_e32 v15, v15, v19
	v_sub_f32_e32 v18, v13, v18
	v_sub_f32_e32 v13, v15, v13
	v_add_f32_e32 v5, v5, v13
	v_sub_f32_e32 v9, v18, v9
	v_cvt_f32_i32_e32 v4, v4
	v_add_f32_e32 v5, v9, v5
	v_add_f32_e32 v9, v14, v16
	v_add_f32_e32 v5, v19, v5
	v_sub_f32_e32 v13, v9, v14
	v_mul_f32_e32 v5, v17, v5
	v_sub_f32_e32 v13, v16, v13
	v_add_f32_e32 v5, v13, v5
	v_mul_f32_e32 v16, 0x3f317218, v4
	v_add_f32_e32 v13, v9, v5
	v_fma_f32 v17, v4, s9, -v16
	v_mul_f32_e32 v14, v13, v13
	v_fmac_f32_e32 v17, 0xb102e308, v4
	v_sub_f32_e32 v4, v13, v9
	v_fmamk_f32 v15, v14, 0x3e9b6dac, v231
	v_sub_f32_e32 v4, v5, v4
	v_add_f32_e32 v5, v16, v17
	v_fmaak_f32 v15, v14, v15, 0x3f2aaada
	v_sub_f32_e32 v9, v5, v16
	v_ldexp_f32 v16, v13, 1
	v_mul_f32_e32 v13, v13, v14
	v_mul_f32_e32 v13, v13, v15
	v_add_f32_e32 v14, v16, v13
	v_sub_f32_e32 v15, v14, v16
	v_ldexp_f32 v4, v4, 1
	v_sub_f32_e32 v13, v13, v15
	v_add_f32_e32 v4, v4, v13
	v_add_f32_e32 v13, v14, v4
	v_sub_f32_e32 v14, v13, v14
	v_sub_f32_e32 v4, v4, v14
	v_add_f32_e32 v14, v5, v13
	v_sub_f32_e32 v15, v14, v5
	v_sub_f32_e32 v16, v14, v15
	v_sub_f32_e32 v9, v17, v9
	v_sub_f32_e32 v5, v5, v16
	v_sub_f32_e32 v13, v13, v15
	v_add_f32_e32 v5, v13, v5
	v_add_f32_e32 v13, v9, v4
	v_sub_f32_e32 v15, v13, v9
	v_sub_f32_e32 v16, v13, v15
	v_sub_f32_e32 v9, v9, v16
	v_sub_f32_e32 v4, v4, v15
	v_add_f32_e32 v5, v13, v5
	v_add_f32_e32 v4, v4, v9
	v_add_f32_e32 v9, v14, v5
	v_sub_f32_e32 v13, v9, v14
	v_sub_f32_e32 v5, v5, v13
	v_add_f32_e32 v4, v4, v5
	v_add_f32_e32 v4, v9, v4
	v_cmp_neq_f32_e32 vcc, s6, v6
	s_nop 1
	v_cndmask_b32_e32 v4, v238, v4, vcc
	v_cmp_ngt_f32_e32 vcc, -1.0, v6
	s_nop 1
	v_cndmask_b32_e32 v4, v239, v4, vcc
	v_cmp_neq_f32_e32 vcc, -1.0, v6
	s_nop 1
	v_cndmask_b32_e32 v4, v240, v4, vcc
	v_cmp_lt_f32_e64 vcc, |v6|, s10
	s_nop 1
	v_cndmask_b32_e32 v4, v4, v6, vcc
	v_add_f32_e32 v4, v8, v4
	v_sub_f32_e32 v4, -0.5, v4
	v_mul_f32_e32 v4, 0x3fb8aa3b, v4
	v_exp_f32_e32 v5, v4
	v_mul_f32_e32 v4, 0xbfb8aa3b, v7
	v_exp_f32_e32 v4, v4
	ds_read_b128 v[6:9], v12 offset:208
	v_mul_f32_e32 v5, 0xbfb8aa3b, v5
	v_exp_f32_e32 v5, v5
	ds_write_b128 v75, v[2:5] offset:192
	ds_read_b128 v[2:5], v74 offset:208
	s_waitcnt lgkmcnt(0)
; template <int MODE, bool BIG = false> DI void gemm_tile(const Params& p, int tm, int tn, int kv, char* smem) {
;     ...
;     for (int c4 = 0; c4 < 16; ++c4) {
;       float4 v = crow4[c4], ww = w04[c4];
;       float u[4] = {v.x + ww.x, v.y + ww.y, v.z + ww.z, v.w + ww.w};
; #pragma unroll
;       for (int e = 0; e < 4; ++e) {
;         const float z = -u[e];
;         const float sp = fmaxf(z, 0.f) + log1pf(__expf(-fabsf(z)));
;         u[e] = __expf(-__expf(-sp - 0.5f));
;       }
;       W4[c4] = make_float4(u[0], u[1], u[2], u[3]);
	v_add_f32_e32 v2, v6, v2
	v_mul_f32_e64 v6, |v2|, s7
	v_exp_f32_e32 v6, v6
	v_add_f32_e32 v4, v8, v4
	v_max_f32_e64 v8, -v2, 0
	v_add_f32_e32 v7, v7, v3
	v_add_f32_e32 v13, 1.0, v6
	v_add_f32_e32 v2, -1.0, v13
	v_sub_f32_e32 v3, v2, v13
	v_add_f32_e32 v3, 1.0, v3
	v_sub_f32_e32 v2, v6, v2
	v_add_f32_e32 v14, v2, v3
	v_frexp_mant_f32_e32 v2, v13
	v_cmp_gt_f32_e32 vcc, s8, v2
	v_cvt_f64_f32_e32 v[2:3], v13
	v_frexp_exp_i32_f64_e32 v2, v[2:3]
	v_subbrev_co_u32_e32 v2, vcc, 0, v2, vcc
	v_sub_u32_e32 v3, 0, v2
	v_ldexp_f32 v13, v13, v3
	v_ldexp_f32 v3, v14, v3
	v_add_f32_e32 v14, -1.0, v13
	v_add_f32_e32 v17, 1.0, v13
	v_add_f32_e32 v15, 1.0, v14
	v_add_f32_e32 v18, -1.0, v17
	v_sub_f32_e32 v15, v13, v15
	v_sub_f32_e32 v13, v13, v18
	v_add_f32_e32 v15, v3, v15
	v_add_f32_e32 v3, v3, v13
	v_add_f32_e32 v13, v17, v3
	v_rcp_f32_e32 v18, v13
	v_add_f32_e32 v16, v14, v15
	v_sub_f32_e32 v14, v16, v14
	v_sub_f32_e32 v14, v15, v14
	v_sub_f32_e32 v15, v13, v17
	v_sub_f32_e32 v3, v3, v15
	v_mul_f32_e32 v15, v16, v18
	v_mul_f32_e32 v17, v13, v15
	v_fma_f32 v19, v15, v13, -v17
	v_fmac_f32_e32 v19, v15, v3
	v_add_f32_e32 v20, v17, v19
	v_sub_f32_e32 v21, v16, v20
	v_sub_f32_e32 v16, v16, v21
	v_sub_f32_e32 v17, v20, v17
	v_sub_f32_e32 v16, v16, v20
	v_add_f32_e32 v14, v14, v16
	v_sub_f32_e32 v16, v17, v19
	v_add_f32_e32 v14, v16, v14
	v_add_f32_e32 v16, v21, v14
	v_mul_f32_e32 v17, v18, v16
	v_mul_f32_e32 v19, v13, v17
	v_fma_f32 v13, v17, v13, -v19
	v_fmac_f32_e32 v13, v17, v3
	v_sub_f32_e32 v3, v21, v16
	v_add_f32_e32 v3, v14, v3
	v_add_f32_e32 v14, v19, v13
	v_sub_f32_e32 v20, v16, v14
	v_sub_f32_e32 v16, v16, v20
	v_sub_f32_e32 v19, v14, v19
	v_sub_f32_e32 v14, v16, v14
	v_add_f32_e32 v3, v3, v14
	v_sub_f32_e32 v13, v19, v13
	v_cvt_f32_i32_e32 v2, v2
	v_add_f32_e32 v3, v13, v3
	v_add_f32_e32 v13, v15, v17
	v_add_f32_e32 v3, v20, v3
	v_sub_f32_e32 v14, v13, v15
	v_mul_f32_e32 v3, v18, v3
	v_sub_f32_e32 v14, v17, v14
	v_add_f32_e32 v3, v14, v3
	v_mul_f32_e32 v17, 0x3f317218, v2
	v_add_f32_e32 v14, v13, v3
	v_fma_f32 v18, v2, s9, -v17
	v_mul_f32_e32 v15, v14, v14
	v_fmac_f32_e32 v18, 0xb102e308, v2
	v_sub_f32_e32 v2, v14, v13
	v_fmamk_f32 v16, v15, 0x3e9b6dac, v231
	v_sub_f32_e32 v2, v3, v2
	v_add_f32_e32 v3, v17, v18
	v_fmaak_f32 v16, v15, v16, 0x3f2aaada
	v_sub_f32_e32 v13, v3, v17
	v_ldexp_f32 v17, v14, 1
	v_mul_f32_e32 v14, v14, v15
	v_mul_f32_e32 v14, v14, v16
	v_add_f32_e32 v15, v17, v14
	v_sub_f32_e32 v16, v15, v17
	v_ldexp_f32 v2, v2, 1
	v_sub_f32_e32 v14, v14, v16
	v_add_f32_e32 v2, v2, v14
	v_add_f32_e32 v14, v15, v2
	v_sub_f32_e32 v15, v14, v15
	v_sub_f32_e32 v2, v2, v15
	v_add_f32_e32 v15, v3, v14
	v_sub_f32_e32 v16, v15, v3
	v_sub_f32_e32 v17, v15, v16
	v_sub_f32_e32 v13, v18, v13
	v_sub_f32_e32 v3, v3, v17
	v_sub_f32_e32 v14, v14, v16
	v_add_f32_e32 v3, v14, v3
	v_add_f32_e32 v14, v13, v2
	v_sub_f32_e32 v16, v14, v13
	v_sub_f32_e32 v17, v14, v16
	v_sub_f32_e32 v13, v13, v17
	v_sub_f32_e32 v2, v2, v16
	v_add_f32_e32 v3, v14, v3
	v_add_f32_e32 v2, v2, v13
	v_add_f32_e32 v13, v15, v3
	v_sub_f32_e32 v14, v13, v15
	v_sub_f32_e32 v3, v3, v14
	v_add_f32_e32 v2, v2, v3
	v_add_f32_e32 v2, v13, v2
	v_cmp_neq_f32_e32 vcc, s6, v6
	v_mul_f32_e64 v3, |v7|, s7
	v_max_f32_e64 v7, -v7, 0
	v_cndmask_b32_e32 v2, v238, v2, vcc
	v_cmp_ngt_f32_e32 vcc, -1.0, v6
	s_nop 1
	v_cndmask_b32_e32 v2, v239, v2, vcc
	v_cmp_neq_f32_e32 vcc, -1.0, v6
	s_nop 1
	v_cndmask_b32_e32 v2, v240, v2, vcc
	v_cmp_lt_f32_e64 vcc, |v6|, s10
	s_nop 1
	v_cndmask_b32_e32 v2, v2, v6, vcc
	v_add_f32_e32 v2, v8, v2
	v_sub_f32_e32 v2, -0.5, v2
	v_mul_f32_e32 v2, 0x3fb8aa3b, v2
	v_exp_f32_e32 v6, v3
	v_exp_f32_e32 v2, v2
	v_add_f32_e32 v8, v9, v5
	v_add_f32_e32 v9, 1.0, v6
	v_mul_f32_e32 v5, 0xbfb8aa3b, v2
	v_add_f32_e32 v2, -1.0, v9
	v_sub_f32_e32 v3, v2, v9
	v_add_f32_e32 v3, 1.0, v3
	v_sub_f32_e32 v2, v6, v2
	v_add_f32_e32 v13, v2, v3
	v_frexp_mant_f32_e32 v2, v9
	v_cmp_gt_f32_e32 vcc, s8, v2
	v_cvt_f64_f32_e32 v[2:3], v9
	v_frexp_exp_i32_f64_e32 v2, v[2:3]
	v_subbrev_co_u32_e32 v2, vcc, 0, v2, vcc
	v_sub_u32_e32 v3, 0, v2
	v_ldexp_f32 v9, v9, v3
	v_ldexp_f32 v3, v13, v3
	v_add_f32_e32 v13, -1.0, v9
	v_add_f32_e32 v16, 1.0, v9
	v_add_f32_e32 v14, 1.0, v13
	v_add_f32_e32 v17, -1.0, v16
	v_sub_f32_e32 v14, v9, v14
	v_sub_f32_e32 v9, v9, v17
	v_add_f32_e32 v14, v3, v14
	v_add_f32_e32 v3, v3, v9
	v_add_f32_e32 v9, v16, v3
	v_rcp_f32_e32 v17, v9
	v_add_f32_e32 v15, v13, v14
	v_sub_f32_e32 v13, v15, v13
	v_sub_f32_e32 v13, v14, v13
	v_sub_f32_e32 v14, v9, v16
	v_sub_f32_e32 v3, v3, v14
	v_mul_f32_e32 v14, v15, v17
	v_mul_f32_e32 v16, v9, v14
	v_fma_f32 v18, v14, v9, -v16
	v_fmac_f32_e32 v18, v14, v3
	v_add_f32_e32 v19, v16, v18
	v_sub_f32_e32 v20, v15, v19
	v_sub_f32_e32 v15, v15, v20
	v_sub_f32_e32 v16, v19, v16
	v_sub_f32_e32 v15, v15, v19
	v_add_f32_e32 v13, v13, v15
	v_sub_f32_e32 v15, v16, v18
	v_add_f32_e32 v13, v15, v13
	v_add_f32_e32 v15, v20, v13
	v_mul_f32_e32 v16, v17, v15
	v_mul_f32_e32 v18, v9, v16
	v_fma_f32 v9, v16, v9, -v18
	v_fmac_f32_e32 v9, v16, v3
	v_sub_f32_e32 v3, v20, v15
	v_add_f32_e32 v3, v13, v3
	v_add_f32_e32 v13, v18, v9
	v_sub_f32_e32 v19, v15, v13
	v_sub_f32_e32 v15, v15, v19
	v_sub_f32_e32 v18, v13, v18
	v_sub_f32_e32 v13, v15, v13
	v_add_f32_e32 v3, v3, v13
	v_sub_f32_e32 v9, v18, v9
	v_cvt_f32_i32_e32 v2, v2
	v_add_f32_e32 v3, v9, v3
	v_add_f32_e32 v9, v14, v16
	v_add_f32_e32 v3, v19, v3
	v_sub_f32_e32 v13, v9, v14
	v_mul_f32_e32 v3, v17, v3
	v_sub_f32_e32 v13, v16, v13
	v_add_f32_e32 v3, v13, v3
	v_mul_f32_e32 v16, 0x3f317218, v2
	v_add_f32_e32 v13, v9, v3
	v_fma_f32 v17, v2, s9, -v16
	v_mul_f32_e32 v14, v13, v13
	v_fmac_f32_e32 v17, 0xb102e308, v2
; template <int MODE, bool BIG = false> DI void gemm_tile(const Params& p, int tm, int tn, int kv, char* smem) {
;     ...
;     for (int c4 = 0; c4 < 16; ++c4) {
;       float4 v = crow4[c4], ww = w04[c4];
;       float u[4] = {v.x + ww.x, v.y + ww.y, v.z + ww.z, v.w + ww.w};
; #pragma unroll
;       for (int e = 0; e < 4; ++e) {
;         const float z = -u[e];
;         const float sp = fmaxf(z, 0.f) + log1pf(__expf(-fabsf(z)));
;         u[e] = __expf(-__expf(-sp - 0.5f));
;       }
;       W4[c4] = make_float4(u[0], u[1], u[2], u[3]);
	v_sub_f32_e32 v2, v13, v9
	v_fmamk_f32 v15, v14, 0x3e9b6dac, v231
	v_sub_f32_e32 v2, v3, v2
	v_add_f32_e32 v3, v16, v17
	v_fmaak_f32 v15, v14, v15, 0x3f2aaada
	v_sub_f32_e32 v9, v3, v16
	v_ldexp_f32 v16, v13, 1
	v_mul_f32_e32 v13, v13, v14
	v_mul_f32_e32 v13, v13, v15
	v_add_f32_e32 v14, v16, v13
	v_sub_f32_e32 v15, v14, v16
	v_ldexp_f32 v2, v2, 1
	v_sub_f32_e32 v13, v13, v15
	v_add_f32_e32 v2, v2, v13
	v_add_f32_e32 v13, v14, v2
	v_sub_f32_e32 v14, v13, v14
	v_sub_f32_e32 v2, v2, v14
	v_add_f32_e32 v14, v3, v13
	v_sub_f32_e32 v15, v14, v3
	v_sub_f32_e32 v16, v14, v15
	v_sub_f32_e32 v9, v17, v9
	v_sub_f32_e32 v3, v3, v16
	v_sub_f32_e32 v13, v13, v15
	v_add_f32_e32 v3, v13, v3
	v_add_f32_e32 v13, v9, v2
	v_sub_f32_e32 v15, v13, v9
	v_sub_f32_e32 v16, v13, v15
	v_sub_f32_e32 v9, v9, v16
	v_sub_f32_e32 v2, v2, v15
	v_add_f32_e32 v3, v13, v3
	v_add_f32_e32 v2, v2, v9
	v_add_f32_e32 v9, v14, v3
	v_sub_f32_e32 v13, v9, v14
	v_sub_f32_e32 v3, v3, v13
	v_add_f32_e32 v2, v2, v3
	v_add_f32_e32 v2, v9, v2
	v_cmp_neq_f32_e32 vcc, s6, v6
	s_nop 1
	v_cndmask_b32_e32 v2, v238, v2, vcc
	v_cmp_ngt_f32_e32 vcc, -1.0, v6
	s_nop 1
	v_cndmask_b32_e32 v2, v239, v2, vcc
	v_cmp_neq_f32_e32 vcc, -1.0, v6
	s_nop 1
	v_cndmask_b32_e32 v2, v240, v2, vcc
	v_cmp_lt_f32_e64 vcc, |v6|, s10
	s_nop 1
	v_cndmask_b32_e32 v2, v2, v6, vcc
	v_add_f32_e32 v2, v7, v2
	v_sub_f32_e32 v2, -0.5, v2
	v_mul_f32_e32 v2, 0x3fb8aa3b, v2
	v_exp_f32_e32 v3, v2
	v_mul_f32_e64 v2, |v4|, s7
	v_exp_f32_e32 v6, v2
	v_max_f32_e64 v7, -v4, 0
	v_exp_f32_e32 v2, v5
	v_mul_f32_e32 v3, 0xbfb8aa3b, v3
	v_add_f32_e32 v9, 1.0, v6
	v_add_f32_e32 v4, -1.0, v9
	v_sub_f32_e32 v5, v4, v9
	v_add_f32_e32 v5, 1.0, v5
	v_sub_f32_e32 v4, v6, v4
	v_add_f32_e32 v13, v4, v5
	v_frexp_mant_f32_e32 v4, v9
	v_cmp_gt_f32_e32 vcc, s8, v4
	v_cvt_f64_f32_e32 v[4:5], v9
	v_frexp_exp_i32_f64_e32 v4, v[4:5]
	v_subbrev_co_u32_e32 v4, vcc, 0, v4, vcc
	v_sub_u32_e32 v5, 0, v4
	v_ldexp_f32 v9, v9, v5
	v_ldexp_f32 v5, v13, v5
	v_add_f32_e32 v13, -1.0, v9
	v_add_f32_e32 v16, 1.0, v9
	v_add_f32_e32 v14, 1.0, v13
	v_add_f32_e32 v17, -1.0, v16
	v_sub_f32_e32 v14, v9, v14
	v_sub_f32_e32 v9, v9, v17
	v_add_f32_e32 v14, v5, v14
	v_add_f32_e32 v5, v5, v9
	v_add_f32_e32 v9, v16, v5
	v_rcp_f32_e32 v17, v9
	v_add_f32_e32 v15, v13, v14
	v_sub_f32_e32 v13, v15, v13
	v_sub_f32_e32 v13, v14, v13
	v_sub_f32_e32 v14, v9, v16
	v_sub_f32_e32 v5, v5, v14
	v_mul_f32_e32 v14, v15, v17
	v_mul_f32_e32 v16, v9, v14
	v_fma_f32 v18, v14, v9, -v16
	v_fmac_f32_e32 v18, v14, v5
	v_add_f32_e32 v19, v16, v18
	v_sub_f32_e32 v20, v15, v19
	v_sub_f32_e32 v15, v15, v20
	v_sub_f32_e32 v16, v19, v16
	v_sub_f32_e32 v15, v15, v19
	v_add_f32_e32 v13, v13, v15
	v_sub_f32_e32 v15, v16, v18
	v_add_f32_e32 v13, v15, v13
	v_add_f32_e32 v15, v20, v13
	v_mul_f32_e32 v16, v17, v15
	v_mul_f32_e32 v18, v9, v16
	v_fma_f32 v9, v16, v9, -v18
	v_fmac_f32_e32 v9, v16, v5
	v_sub_f32_e32 v5, v20, v15
	v_add_f32_e32 v5, v13, v5
	v_add_f32_e32 v13, v18, v9
	v_sub_f32_e32 v19, v15, v13
	v_sub_f32_e32 v15, v15, v19
	v_sub_f32_e32 v18, v13, v18
	v_sub_f32_e32 v13, v15, v13
	v_add_f32_e32 v5, v5, v13
	v_sub_f32_e32 v9, v18, v9
	v_cvt_f32_i32_e32 v4, v4
	v_add_f32_e32 v5, v9, v5
	v_add_f32_e32 v9, v14, v16
	v_add_f32_e32 v5, v19, v5
	v_sub_f32_e32 v13, v9, v14
	v_mul_f32_e32 v5, v17, v5
	v_sub_f32_e32 v13, v16, v13
	v_add_f32_e32 v5, v13, v5
	v_mul_f32_e32 v16, 0x3f317218, v4
	v_add_f32_e32 v13, v9, v5
	v_fma_f32 v17, v4, s9, -v16
	v_mul_f32_e32 v14, v13, v13
	v_fmac_f32_e32 v17, 0xb102e308, v4
	v_sub_f32_e32 v4, v13, v9
	v_fmamk_f32 v15, v14, 0x3e9b6dac, v231
	v_sub_f32_e32 v4, v5, v4
	v_add_f32_e32 v5, v16, v17
	v_fmaak_f32 v15, v14, v15, 0x3f2aaada
	v_sub_f32_e32 v9, v5, v16
	v_ldexp_f32 v16, v13, 1
	v_mul_f32_e32 v13, v13, v14
	v_mul_f32_e32 v13, v13, v15
	v_add_f32_e32 v14, v16, v13
	v_sub_f32_e32 v15, v14, v16
	v_ldexp_f32 v4, v4, 1
	v_sub_f32_e32 v13, v13, v15
	v_add_f32_e32 v4, v4, v13
	v_add_f32_e32 v13, v14, v4
	v_sub_f32_e32 v14, v13, v14
	v_sub_f32_e32 v4, v4, v14
	v_add_f32_e32 v14, v5, v13
	v_sub_f32_e32 v15, v14, v5
	v_sub_f32_e32 v16, v14, v15
	v_sub_f32_e32 v9, v17, v9
	v_sub_f32_e32 v5, v5, v16
	v_sub_f32_e32 v13, v13, v15
	v_add_f32_e32 v5, v13, v5
	v_add_f32_e32 v13, v9, v4
	v_sub_f32_e32 v15, v13, v9
	v_sub_f32_e32 v16, v13, v15
	v_sub_f32_e32 v9, v9, v16
	v_sub_f32_e32 v4, v4, v15
	v_add_f32_e32 v5, v13, v5
	v_add_f32_e32 v4, v4, v9
	v_add_f32_e32 v9, v14, v5
	v_sub_f32_e32 v13, v9, v14
	v_sub_f32_e32 v5, v5, v13
	v_add_f32_e32 v4, v4, v5
	v_add_f32_e32 v4, v9, v4
	v_cmp_neq_f32_e32 vcc, s6, v6
	v_mul_f32_e64 v5, |v8|, s7
	v_max_f32_e64 v8, -v8, 0
	v_cndmask_b32_e32 v4, v238, v4, vcc
	v_cmp_ngt_f32_e32 vcc, -1.0, v6
	v_exp_f32_e32 v3, v3
	s_nop 0
	v_cndmask_b32_e32 v4, v239, v4, vcc
	v_cmp_neq_f32_e32 vcc, -1.0, v6
	s_nop 1
	v_cndmask_b32_e32 v4, v240, v4, vcc
	v_cmp_lt_f32_e64 vcc, |v6|, s10
	s_nop 1
	v_cndmask_b32_e32 v4, v4, v6, vcc
	v_exp_f32_e32 v6, v5
	v_add_f32_e32 v4, v7, v4
	v_sub_f32_e32 v4, -0.5, v4
	v_mul_f32_e32 v4, 0x3fb8aa3b, v4
	v_add_f32_e32 v9, 1.0, v6
	v_exp_f32_e32 v7, v4
	v_add_f32_e32 v4, -1.0, v9
	v_sub_f32_e32 v5, v4, v9
	v_add_f32_e32 v5, 1.0, v5
	v_sub_f32_e32 v4, v6, v4
	v_add_f32_e32 v13, v4, v5
	v_frexp_mant_f32_e32 v4, v9
	v_cmp_gt_f32_e32 vcc, s8, v4
	v_cvt_f64_f32_e32 v[4:5], v9
	v_frexp_exp_i32_f64_e32 v4, v[4:5]
	v_subbrev_co_u32_e32 v4, vcc, 0, v4, vcc
	v_sub_u32_e32 v5, 0, v4
	v_ldexp_f32 v9, v9, v5
	v_ldexp_f32 v5, v13, v5
	v_add_f32_e32 v13, -1.0, v9
	v_add_f32_e32 v16, 1.0, v9
	v_add_f32_e32 v14, 1.0, v13
	v_add_f32_e32 v17, -1.0, v16
	v_sub_f32_e32 v14, v9, v14
	v_sub_f32_e32 v9, v9, v17
	v_add_f32_e32 v14, v5, v14
	v_add_f32_e32 v5, v5, v9
; template <int MODE, bool BIG = false> DI void gemm_tile(const Params& p, int tm, int tn, int kv, char* smem) {
;     ...
;     for (int c4 = 0; c4 < 16; ++c4) {
;       float4 v = crow4[c4], ww = w04[c4];
;       float u[4] = {v.x + ww.x, v.y + ww.y, v.z + ww.z, v.w + ww.w};
; #pragma unroll
;       for (int e = 0; e < 4; ++e) {
;         const float z = -u[e];
;         const float sp = fmaxf(z, 0.f) + log1pf(__expf(-fabsf(z)));
;         u[e] = __expf(-__expf(-sp - 0.5f));
;       }
;       W4[c4] = make_float4(u[0], u[1], u[2], u[3]);
	v_add_f32_e32 v9, v16, v5
	v_rcp_f32_e32 v17, v9
	v_add_f32_e32 v15, v13, v14
	v_sub_f32_e32 v13, v15, v13
	v_sub_f32_e32 v13, v14, v13
	v_sub_f32_e32 v14, v9, v16
	v_sub_f32_e32 v5, v5, v14
	v_mul_f32_e32 v14, v15, v17
	v_mul_f32_e32 v16, v9, v14
	v_fma_f32 v18, v14, v9, -v16
	v_fmac_f32_e32 v18, v14, v5
	v_add_f32_e32 v19, v16, v18
	v_sub_f32_e32 v20, v15, v19
	v_sub_f32_e32 v15, v15, v20
	v_sub_f32_e32 v16, v19, v16
	v_sub_f32_e32 v15, v15, v19
	v_add_f32_e32 v13, v13, v15
	v_sub_f32_e32 v15, v16, v18
	v_add_f32_e32 v13, v15, v13
	v_add_f32_e32 v15, v20, v13
	v_mul_f32_e32 v16, v17, v15
	v_mul_f32_e32 v18, v9, v16
	v_fma_f32 v9, v16, v9, -v18
	v_fmac_f32_e32 v9, v16, v5
	v_sub_f32_e32 v5, v20, v15
	v_add_f32_e32 v5, v13, v5
	v_add_f32_e32 v13, v18, v9
	v_sub_f32_e32 v19, v15, v13
	v_sub_f32_e32 v15, v15, v19
	v_sub_f32_e32 v18, v13, v18
	v_sub_f32_e32 v13, v15, v13
	v_add_f32_e32 v5, v5, v13
	v_sub_f32_e32 v9, v18, v9
	v_cvt_f32_i32_e32 v4, v4
	v_add_f32_e32 v5, v9, v5
	v_add_f32_e32 v9, v14, v16
	v_add_f32_e32 v5, v19, v5
	v_sub_f32_e32 v13, v9, v14
	v_mul_f32_e32 v5, v17, v5
	v_sub_f32_e32 v13, v16, v13
	v_add_f32_e32 v5, v13, v5
	v_mul_f32_e32 v16, 0x3f317218, v4
	v_add_f32_e32 v13, v9, v5
	v_fma_f32 v17, v4, s9, -v16
	v_mul_f32_e32 v14, v13, v13
	v_fmac_f32_e32 v17, 0xb102e308, v4
	v_sub_f32_e32 v4, v13, v9
	v_fmamk_f32 v15, v14, 0x3e9b6dac, v231
	v_sub_f32_e32 v4, v5, v4
	v_add_f32_e32 v5, v16, v17
	v_fmaak_f32 v15, v14, v15, 0x3f2aaada
	v_sub_f32_e32 v9, v5, v16
	v_ldexp_f32 v16, v13, 1
	v_mul_f32_e32 v13, v13, v14
	v_mul_f32_e32 v13, v13, v15
	v_add_f32_e32 v14, v16, v13
	v_sub_f32_e32 v15, v14, v16
	v_ldexp_f32 v4, v4, 1
	v_sub_f32_e32 v13, v13, v15
	v_add_f32_e32 v4, v4, v13
	v_add_f32_e32 v13, v14, v4
	v_sub_f32_e32 v14, v13, v14
	v_sub_f32_e32 v4, v4, v14
	v_add_f32_e32 v14, v5, v13
	v_sub_f32_e32 v15, v14, v5
	v_sub_f32_e32 v16, v14, v15
	v_sub_f32_e32 v9, v17, v9
	v_sub_f32_e32 v5, v5, v16
	v_sub_f32_e32 v13, v13, v15
	v_add_f32_e32 v5, v13, v5
	v_add_f32_e32 v13, v9, v4
	v_sub_f32_e32 v15, v13, v9
	v_sub_f32_e32 v16, v13, v15
	v_sub_f32_e32 v9, v9, v16
	v_sub_f32_e32 v4, v4, v15
	v_add_f32_e32 v5, v13, v5
	v_add_f32_e32 v4, v4, v9
	v_add_f32_e32 v9, v14, v5
	v_sub_f32_e32 v13, v9, v14
	v_sub_f32_e32 v5, v5, v13
	v_add_f32_e32 v4, v4, v5
	v_add_f32_e32 v4, v9, v4
	v_cmp_neq_f32_e32 vcc, s6, v6
	s_nop 1
	v_cndmask_b32_e32 v4, v238, v4, vcc
	v_cmp_ngt_f32_e32 vcc, -1.0, v6
	s_nop 1
	v_cndmask_b32_e32 v4, v239, v4, vcc
	v_cmp_neq_f32_e32 vcc, -1.0, v6
	s_nop 1
	v_cndmask_b32_e32 v4, v240, v4, vcc
	v_cmp_lt_f32_e64 vcc, |v6|, s10
	s_nop 1
	v_cndmask_b32_e32 v4, v4, v6, vcc
	v_add_f32_e32 v4, v8, v4
	v_sub_f32_e32 v4, -0.5, v4
	v_mul_f32_e32 v4, 0x3fb8aa3b, v4
	v_exp_f32_e32 v5, v4
	v_mul_f32_e32 v4, 0xbfb8aa3b, v7
	v_exp_f32_e32 v4, v4
	ds_read_b128 v[6:9], v12 offset:224
	v_mul_f32_e32 v5, 0xbfb8aa3b, v5
	v_exp_f32_e32 v5, v5
	ds_write_b128 v75, v[2:5] offset:208
	ds_read_b128 v[2:5], v74 offset:224
	s_waitcnt lgkmcnt(0)
	v_add_f32_e32 v2, v6, v2
	v_mul_f32_e64 v6, |v2|, s7
	v_exp_f32_e32 v6, v6
	v_add_f32_e32 v4, v8, v4
	v_max_f32_e64 v8, -v2, 0
	v_add_f32_e32 v7, v7, v3
	v_add_f32_e32 v13, 1.0, v6
	v_add_f32_e32 v2, -1.0, v13
	v_sub_f32_e32 v3, v2, v13
	v_add_f32_e32 v3, 1.0, v3
	v_sub_f32_e32 v2, v6, v2
	v_add_f32_e32 v14, v2, v3
	v_frexp_mant_f32_e32 v2, v13
	v_cmp_gt_f32_e32 vcc, s8, v2
	v_cvt_f64_f32_e32 v[2:3], v13
	v_frexp_exp_i32_f64_e32 v2, v[2:3]
	v_subbrev_co_u32_e32 v2, vcc, 0, v2, vcc
	v_sub_u32_e32 v3, 0, v2
	v_ldexp_f32 v13, v13, v3
	v_ldexp_f32 v3, v14, v3
	v_add_f32_e32 v14, -1.0, v13
	v_add_f32_e32 v17, 1.0, v13
	v_add_f32_e32 v15, 1.0, v14
	v_add_f32_e32 v18, -1.0, v17
	v_sub_f32_e32 v15, v13, v15
	v_sub_f32_e32 v13, v13, v18
	v_add_f32_e32 v15, v3, v15
	v_add_f32_e32 v3, v3, v13
	v_add_f32_e32 v13, v17, v3
	v_rcp_f32_e32 v18, v13
	v_add_f32_e32 v16, v14, v15
	v_sub_f32_e32 v14, v16, v14
	v_sub_f32_e32 v14, v15, v14
	v_sub_f32_e32 v15, v13, v17
	v_sub_f32_e32 v3, v3, v15
	v_mul_f32_e32 v15, v16, v18
	v_mul_f32_e32 v17, v13, v15
	v_fma_f32 v19, v15, v13, -v17
	v_fmac_f32_e32 v19, v15, v3
	v_add_f32_e32 v20, v17, v19
	v_sub_f32_e32 v21, v16, v20
	v_sub_f32_e32 v16, v16, v21
	v_sub_f32_e32 v17, v20, v17
	v_sub_f32_e32 v16, v16, v20
	v_add_f32_e32 v14, v14, v16
	v_sub_f32_e32 v16, v17, v19
	v_add_f32_e32 v14, v16, v14
	v_add_f32_e32 v16, v21, v14
	v_mul_f32_e32 v17, v18, v16
	v_mul_f32_e32 v19, v13, v17
	v_fma_f32 v13, v17, v13, -v19
	v_fmac_f32_e32 v13, v17, v3
	v_sub_f32_e32 v3, v21, v16
	v_add_f32_e32 v3, v14, v3
	v_add_f32_e32 v14, v19, v13
	v_sub_f32_e32 v20, v16, v14
	v_sub_f32_e32 v16, v16, v20
	v_sub_f32_e32 v19, v14, v19
	v_sub_f32_e32 v14, v16, v14
	v_add_f32_e32 v3, v3, v14
	v_sub_f32_e32 v13, v19, v13
	v_cvt_f32_i32_e32 v2, v2
	v_add_f32_e32 v3, v13, v3
	v_add_f32_e32 v13, v15, v17
	v_add_f32_e32 v3, v20, v3
	v_sub_f32_e32 v14, v13, v15
	v_mul_f32_e32 v3, v18, v3
	v_sub_f32_e32 v14, v17, v14
	v_add_f32_e32 v3, v14, v3
	v_mul_f32_e32 v17, 0x3f317218, v2
	v_add_f32_e32 v14, v13, v3
	v_fma_f32 v18, v2, s9, -v17
	v_mul_f32_e32 v15, v14, v14
	v_fmac_f32_e32 v18, 0xb102e308, v2
	v_sub_f32_e32 v2, v14, v13
	v_fmamk_f32 v16, v15, 0x3e9b6dac, v231
	v_sub_f32_e32 v2, v3, v2
	v_add_f32_e32 v3, v17, v18
	v_fmaak_f32 v16, v15, v16, 0x3f2aaada
	v_sub_f32_e32 v13, v3, v17
	v_ldexp_f32 v17, v14, 1
	v_mul_f32_e32 v14, v14, v15
	v_mul_f32_e32 v14, v14, v16
	v_add_f32_e32 v15, v17, v14
	v_sub_f32_e32 v16, v15, v17
	v_ldexp_f32 v2, v2, 1
	v_sub_f32_e32 v14, v14, v16
	v_add_f32_e32 v2, v2, v14
	v_add_f32_e32 v14, v15, v2
	v_sub_f32_e32 v15, v14, v15
	v_sub_f32_e32 v2, v2, v15
	v_add_f32_e32 v15, v3, v14
; template <int MODE, bool BIG = false> DI void gemm_tile(const Params& p, int tm, int tn, int kv, char* smem) {
;     ...
;     for (int c4 = 0; c4 < 16; ++c4) {
;       float4 v = crow4[c4], ww = w04[c4];
;       float u[4] = {v.x + ww.x, v.y + ww.y, v.z + ww.z, v.w + ww.w};
; #pragma unroll
;       for (int e = 0; e < 4; ++e) {
;         const float z = -u[e];
;         const float sp = fmaxf(z, 0.f) + log1pf(__expf(-fabsf(z)));
;         u[e] = __expf(-__expf(-sp - 0.5f));
;       }
;       W4[c4] = make_float4(u[0], u[1], u[2], u[3]);
	v_sub_f32_e32 v16, v15, v3
	v_sub_f32_e32 v17, v15, v16
	v_sub_f32_e32 v13, v18, v13
	v_sub_f32_e32 v3, v3, v17
	v_sub_f32_e32 v14, v14, v16
	v_add_f32_e32 v3, v14, v3
	v_add_f32_e32 v14, v13, v2
	v_sub_f32_e32 v16, v14, v13
	v_sub_f32_e32 v17, v14, v16
	v_sub_f32_e32 v13, v13, v17
	v_sub_f32_e32 v2, v2, v16
	v_add_f32_e32 v3, v14, v3
	v_add_f32_e32 v2, v2, v13
	v_add_f32_e32 v13, v15, v3
	v_sub_f32_e32 v14, v13, v15
	v_sub_f32_e32 v3, v3, v14
	v_add_f32_e32 v2, v2, v3
	v_add_f32_e32 v2, v13, v2
	v_cmp_neq_f32_e32 vcc, s6, v6
	v_mul_f32_e64 v3, |v7|, s7
	v_max_f32_e64 v7, -v7, 0
	v_cndmask_b32_e32 v2, v238, v2, vcc
	v_cmp_ngt_f32_e32 vcc, -1.0, v6
	s_nop 1
	v_cndmask_b32_e32 v2, v239, v2, vcc
	v_cmp_neq_f32_e32 vcc, -1.0, v6
	s_nop 1
	v_cndmask_b32_e32 v2, v240, v2, vcc
	v_cmp_lt_f32_e64 vcc, |v6|, s10
	s_nop 1
	v_cndmask_b32_e32 v2, v2, v6, vcc
	v_add_f32_e32 v2, v8, v2
	v_sub_f32_e32 v2, -0.5, v2
	v_mul_f32_e32 v2, 0x3fb8aa3b, v2
	v_exp_f32_e32 v6, v3
	v_exp_f32_e32 v2, v2
	v_add_f32_e32 v8, v9, v5
	v_add_f32_e32 v9, 1.0, v6
	v_mul_f32_e32 v5, 0xbfb8aa3b, v2
	v_add_f32_e32 v2, -1.0, v9
	v_sub_f32_e32 v3, v2, v9
	v_add_f32_e32 v3, 1.0, v3
	v_sub_f32_e32 v2, v6, v2
	v_add_f32_e32 v13, v2, v3
	v_frexp_mant_f32_e32 v2, v9
	v_cmp_gt_f32_e32 vcc, s8, v2
	v_cvt_f64_f32_e32 v[2:3], v9
	v_frexp_exp_i32_f64_e32 v2, v[2:3]
	v_subbrev_co_u32_e32 v2, vcc, 0, v2, vcc
	v_sub_u32_e32 v3, 0, v2
	v_ldexp_f32 v9, v9, v3
	v_ldexp_f32 v3, v13, v3
	v_add_f32_e32 v13, -1.0, v9
	v_add_f32_e32 v16, 1.0, v9
	v_add_f32_e32 v14, 1.0, v13
	v_add_f32_e32 v17, -1.0, v16
	v_sub_f32_e32 v14, v9, v14
	v_sub_f32_e32 v9, v9, v17
	v_add_f32_e32 v14, v3, v14
	v_add_f32_e32 v3, v3, v9
	v_add_f32_e32 v9, v16, v3
	v_rcp_f32_e32 v17, v9
	v_add_f32_e32 v15, v13, v14
	v_sub_f32_e32 v13, v15, v13
	v_sub_f32_e32 v13, v14, v13
	v_sub_f32_e32 v14, v9, v16
	v_sub_f32_e32 v3, v3, v14
	v_mul_f32_e32 v14, v15, v17
	v_mul_f32_e32 v16, v9, v14
	v_fma_f32 v18, v14, v9, -v16
	v_fmac_f32_e32 v18, v14, v3
	v_add_f32_e32 v19, v16, v18
	v_sub_f32_e32 v20, v15, v19
	v_sub_f32_e32 v15, v15, v20
	v_sub_f32_e32 v16, v19, v16
	v_sub_f32_e32 v15, v15, v19
	v_add_f32_e32 v13, v13, v15
	v_sub_f32_e32 v15, v16, v18
	v_add_f32_e32 v13, v15, v13
	v_add_f32_e32 v15, v20, v13
	v_mul_f32_e32 v16, v17, v15
	v_mul_f32_e32 v18, v9, v16
	v_fma_f32 v9, v16, v9, -v18
	v_fmac_f32_e32 v9, v16, v3
	v_sub_f32_e32 v3, v20, v15
	v_add_f32_e32 v3, v13, v3
	v_add_f32_e32 v13, v18, v9
	v_sub_f32_e32 v19, v15, v13
	v_sub_f32_e32 v15, v15, v19
	v_sub_f32_e32 v18, v13, v18
	v_sub_f32_e32 v13, v15, v13
	v_add_f32_e32 v3, v3, v13
	v_sub_f32_e32 v9, v18, v9
	v_cvt_f32_i32_e32 v2, v2
	v_add_f32_e32 v3, v9, v3
	v_add_f32_e32 v9, v14, v16
	v_add_f32_e32 v3, v19, v3
	v_sub_f32_e32 v13, v9, v14
	v_mul_f32_e32 v3, v17, v3
	v_sub_f32_e32 v13, v16, v13
	v_add_f32_e32 v3, v13, v3
	v_mul_f32_e32 v16, 0x3f317218, v2
	v_add_f32_e32 v13, v9, v3
	v_fma_f32 v17, v2, s9, -v16
	v_mul_f32_e32 v14, v13, v13
	v_fmac_f32_e32 v17, 0xb102e308, v2
	v_sub_f32_e32 v2, v13, v9
	v_fmamk_f32 v15, v14, 0x3e9b6dac, v231
	v_sub_f32_e32 v2, v3, v2
	v_add_f32_e32 v3, v16, v17
	v_fmaak_f32 v15, v14, v15, 0x3f2aaada
	v_sub_f32_e32 v9, v3, v16
	v_ldexp_f32 v16, v13, 1
	v_mul_f32_e32 v13, v13, v14
	v_mul_f32_e32 v13, v13, v15
	v_add_f32_e32 v14, v16, v13
	v_sub_f32_e32 v15, v14, v16
	v_ldexp_f32 v2, v2, 1
	v_sub_f32_e32 v13, v13, v15
	v_add_f32_e32 v2, v2, v13
	v_add_f32_e32 v13, v14, v2
	v_sub_f32_e32 v14, v13, v14
	v_sub_f32_e32 v2, v2, v14
	v_add_f32_e32 v14, v3, v13
	v_sub_f32_e32 v15, v14, v3
	v_sub_f32_e32 v16, v14, v15
	v_sub_f32_e32 v9, v17, v9
	v_sub_f32_e32 v3, v3, v16
	v_sub_f32_e32 v13, v13, v15
	v_add_f32_e32 v3, v13, v3
	v_add_f32_e32 v13, v9, v2
	v_sub_f32_e32 v15, v13, v9
	v_sub_f32_e32 v16, v13, v15
	v_sub_f32_e32 v9, v9, v16
	v_sub_f32_e32 v2, v2, v15
	v_add_f32_e32 v3, v13, v3
	v_add_f32_e32 v2, v2, v9
	v_add_f32_e32 v9, v14, v3
	v_sub_f32_e32 v13, v9, v14
	v_sub_f32_e32 v3, v3, v13
	v_add_f32_e32 v2, v2, v3
	v_add_f32_e32 v2, v9, v2
	v_cmp_neq_f32_e32 vcc, s6, v6
	s_nop 1
	v_cndmask_b32_e32 v2, v238, v2, vcc
	v_cmp_ngt_f32_e32 vcc, -1.0, v6
	s_nop 1
	v_cndmask_b32_e32 v2, v239, v2, vcc
	v_cmp_neq_f32_e32 vcc, -1.0, v6
	s_nop 1
	v_cndmask_b32_e32 v2, v240, v2, vcc
	v_cmp_lt_f32_e64 vcc, |v6|, s10
	s_nop 1
	v_cndmask_b32_e32 v2, v2, v6, vcc
	v_add_f32_e32 v2, v7, v2
	v_sub_f32_e32 v2, -0.5, v2
	v_mul_f32_e32 v2, 0x3fb8aa3b, v2
	v_exp_f32_e32 v3, v2
	v_mul_f32_e64 v2, |v4|, s7
	v_exp_f32_e32 v6, v2
	v_max_f32_e64 v7, -v4, 0
	v_exp_f32_e32 v2, v5
	v_mul_f32_e32 v3, 0xbfb8aa3b, v3
	v_add_f32_e32 v9, 1.0, v6
	v_add_f32_e32 v4, -1.0, v9
	v_sub_f32_e32 v5, v4, v9
	v_add_f32_e32 v5, 1.0, v5
	v_sub_f32_e32 v4, v6, v4
	v_add_f32_e32 v13, v4, v5
	v_frexp_mant_f32_e32 v4, v9
	v_cmp_gt_f32_e32 vcc, s8, v4
	v_cvt_f64_f32_e32 v[4:5], v9
	v_frexp_exp_i32_f64_e32 v4, v[4:5]
	v_subbrev_co_u32_e32 v4, vcc, 0, v4, vcc
	v_sub_u32_e32 v5, 0, v4
	v_ldexp_f32 v9, v9, v5
	v_ldexp_f32 v5, v13, v5
	v_add_f32_e32 v13, -1.0, v9
	v_add_f32_e32 v16, 1.0, v9
	v_add_f32_e32 v14, 1.0, v13
	v_add_f32_e32 v17, -1.0, v16
	v_sub_f32_e32 v14, v9, v14
	v_sub_f32_e32 v9, v9, v17
	v_add_f32_e32 v14, v5, v14
	v_add_f32_e32 v5, v5, v9
	v_add_f32_e32 v9, v16, v5
	v_rcp_f32_e32 v17, v9
	v_add_f32_e32 v15, v13, v14
	v_sub_f32_e32 v13, v15, v13
	v_sub_f32_e32 v13, v14, v13
	v_sub_f32_e32 v14, v9, v16
	v_sub_f32_e32 v5, v5, v14
	v_mul_f32_e32 v14, v15, v17
	v_mul_f32_e32 v16, v9, v14
	v_fma_f32 v18, v14, v9, -v16
	v_fmac_f32_e32 v18, v14, v5
	v_add_f32_e32 v19, v16, v18
	v_sub_f32_e32 v20, v15, v19
	v_sub_f32_e32 v15, v15, v20
	v_sub_f32_e32 v16, v19, v16
	v_sub_f32_e32 v15, v15, v19
; template <int MODE, bool BIG = false> DI void gemm_tile(const Params& p, int tm, int tn, int kv, char* smem) {
;     ...
;     for (int c4 = 0; c4 < 16; ++c4) {
;       float4 v = crow4[c4], ww = w04[c4];
;       float u[4] = {v.x + ww.x, v.y + ww.y, v.z + ww.z, v.w + ww.w};
; #pragma unroll
;       for (int e = 0; e < 4; ++e) {
;         const float z = -u[e];
;         const float sp = fmaxf(z, 0.f) + log1pf(__expf(-fabsf(z)));
;         u[e] = __expf(-__expf(-sp - 0.5f));
;       }
;       W4[c4] = make_float4(u[0], u[1], u[2], u[3]);
	v_add_f32_e32 v13, v13, v15
	v_sub_f32_e32 v15, v16, v18
	v_add_f32_e32 v13, v15, v13
	v_add_f32_e32 v15, v20, v13
	v_mul_f32_e32 v16, v17, v15
	v_mul_f32_e32 v18, v9, v16
	v_fma_f32 v9, v16, v9, -v18
	v_fmac_f32_e32 v9, v16, v5
	v_sub_f32_e32 v5, v20, v15
	v_add_f32_e32 v5, v13, v5
	v_add_f32_e32 v13, v18, v9
	v_sub_f32_e32 v19, v15, v13
	v_sub_f32_e32 v15, v15, v19
	v_sub_f32_e32 v18, v13, v18
	v_sub_f32_e32 v13, v15, v13
	v_add_f32_e32 v5, v5, v13
	v_sub_f32_e32 v9, v18, v9
	v_cvt_f32_i32_e32 v4, v4
	v_add_f32_e32 v5, v9, v5
	v_add_f32_e32 v9, v14, v16
	v_add_f32_e32 v5, v19, v5
	v_sub_f32_e32 v13, v9, v14
	v_mul_f32_e32 v5, v17, v5
	v_sub_f32_e32 v13, v16, v13
	v_add_f32_e32 v5, v13, v5
	v_mul_f32_e32 v16, 0x3f317218, v4
	v_add_f32_e32 v13, v9, v5
	v_fma_f32 v17, v4, s9, -v16
	v_mul_f32_e32 v14, v13, v13
	v_fmac_f32_e32 v17, 0xb102e308, v4
	v_sub_f32_e32 v4, v13, v9
	v_fmamk_f32 v15, v14, 0x3e9b6dac, v231
	v_sub_f32_e32 v4, v5, v4
	v_add_f32_e32 v5, v16, v17
	v_fmaak_f32 v15, v14, v15, 0x3f2aaada
	v_sub_f32_e32 v9, v5, v16
	v_ldexp_f32 v16, v13, 1
	v_mul_f32_e32 v13, v13, v14
	v_mul_f32_e32 v13, v13, v15
	v_add_f32_e32 v14, v16, v13
	v_sub_f32_e32 v15, v14, v16
	v_ldexp_f32 v4, v4, 1
	v_sub_f32_e32 v13, v13, v15
	v_add_f32_e32 v4, v4, v13
	v_add_f32_e32 v13, v14, v4
	v_sub_f32_e32 v14, v13, v14
	v_sub_f32_e32 v4, v4, v14
	v_add_f32_e32 v14, v5, v13
	v_sub_f32_e32 v15, v14, v5
	v_sub_f32_e32 v16, v14, v15
	v_sub_f32_e32 v9, v17, v9
	v_sub_f32_e32 v5, v5, v16
	v_sub_f32_e32 v13, v13, v15
	v_add_f32_e32 v5, v13, v5
	v_add_f32_e32 v13, v9, v4
	v_sub_f32_e32 v15, v13, v9
	v_sub_f32_e32 v16, v13, v15
	v_sub_f32_e32 v9, v9, v16
	v_sub_f32_e32 v4, v4, v15
	v_add_f32_e32 v5, v13, v5
	v_add_f32_e32 v4, v4, v9
	v_add_f32_e32 v9, v14, v5
	v_sub_f32_e32 v13, v9, v14
	v_sub_f32_e32 v5, v5, v13
	v_add_f32_e32 v4, v4, v5
	v_add_f32_e32 v4, v9, v4
	v_cmp_neq_f32_e32 vcc, s6, v6
	v_mul_f32_e64 v5, |v8|, s7
	v_max_f32_e64 v8, -v8, 0
	v_cndmask_b32_e32 v4, v238, v4, vcc
	v_cmp_ngt_f32_e32 vcc, -1.0, v6
	v_exp_f32_e32 v3, v3
	s_nop 0
	v_cndmask_b32_e32 v4, v239, v4, vcc
	v_cmp_neq_f32_e32 vcc, -1.0, v6
	s_nop 1
	v_cndmask_b32_e32 v4, v240, v4, vcc
	v_cmp_lt_f32_e64 vcc, |v6|, s10
	s_nop 1
	v_cndmask_b32_e32 v4, v4, v6, vcc
	v_exp_f32_e32 v6, v5
	v_add_f32_e32 v4, v7, v4
	v_sub_f32_e32 v4, -0.5, v4
	v_mul_f32_e32 v4, 0x3fb8aa3b, v4
	v_add_f32_e32 v9, 1.0, v6
	v_exp_f32_e32 v7, v4
	v_add_f32_e32 v4, -1.0, v9
	v_sub_f32_e32 v5, v4, v9
	v_add_f32_e32 v5, 1.0, v5
	v_sub_f32_e32 v4, v6, v4
	v_add_f32_e32 v13, v4, v5
	v_frexp_mant_f32_e32 v4, v9
	v_cmp_gt_f32_e32 vcc, s8, v4
	v_cvt_f64_f32_e32 v[4:5], v9
	v_frexp_exp_i32_f64_e32 v4, v[4:5]
	v_subbrev_co_u32_e32 v4, vcc, 0, v4, vcc
	v_sub_u32_e32 v5, 0, v4
	v_ldexp_f32 v9, v9, v5
	v_ldexp_f32 v5, v13, v5
	v_add_f32_e32 v13, -1.0, v9
	v_add_f32_e32 v16, 1.0, v9
	v_add_f32_e32 v14, 1.0, v13
	v_add_f32_e32 v17, -1.0, v16
	v_sub_f32_e32 v14, v9, v14
	v_sub_f32_e32 v9, v9, v17
	v_add_f32_e32 v14, v5, v14
	v_add_f32_e32 v5, v5, v9
	v_add_f32_e32 v9, v16, v5
	v_rcp_f32_e32 v17, v9
	v_add_f32_e32 v15, v13, v14
	v_sub_f32_e32 v13, v15, v13
	v_sub_f32_e32 v13, v14, v13
	v_sub_f32_e32 v14, v9, v16
	v_sub_f32_e32 v5, v5, v14
	v_mul_f32_e32 v14, v15, v17
	v_mul_f32_e32 v16, v9, v14
	v_fma_f32 v18, v14, v9, -v16
	v_fmac_f32_e32 v18, v14, v5
	v_add_f32_e32 v19, v16, v18
	v_sub_f32_e32 v20, v15, v19
	v_sub_f32_e32 v15, v15, v20
	v_sub_f32_e32 v16, v19, v16
	v_sub_f32_e32 v15, v15, v19
	v_add_f32_e32 v13, v13, v15
	v_sub_f32_e32 v15, v16, v18
	v_add_f32_e32 v13, v15, v13
	v_add_f32_e32 v15, v20, v13
	v_mul_f32_e32 v16, v17, v15
	v_mul_f32_e32 v18, v9, v16
	v_fma_f32 v9, v16, v9, -v18
	v_fmac_f32_e32 v9, v16, v5
	v_sub_f32_e32 v5, v20, v15
	v_add_f32_e32 v5, v13, v5
	v_add_f32_e32 v13, v18, v9
	v_sub_f32_e32 v19, v15, v13
	v_sub_f32_e32 v15, v15, v19
	v_sub_f32_e32 v18, v13, v18
	v_sub_f32_e32 v13, v15, v13
	v_add_f32_e32 v5, v5, v13
	v_sub_f32_e32 v9, v18, v9
	v_cvt_f32_i32_e32 v4, v4
	v_add_f32_e32 v5, v9, v5
	v_add_f32_e32 v9, v14, v16
	v_add_f32_e32 v5, v19, v5
	v_sub_f32_e32 v13, v9, v14
	v_mul_f32_e32 v5, v17, v5
	v_sub_f32_e32 v13, v16, v13
	v_add_f32_e32 v5, v13, v5
	v_mul_f32_e32 v16, 0x3f317218, v4
	v_add_f32_e32 v13, v9, v5
	v_fma_f32 v17, v4, s9, -v16
	v_mul_f32_e32 v14, v13, v13
	v_fmac_f32_e32 v17, 0xb102e308, v4
	v_sub_f32_e32 v4, v13, v9
	v_fmamk_f32 v15, v14, 0x3e9b6dac, v231
	v_sub_f32_e32 v4, v5, v4
	v_add_f32_e32 v5, v16, v17
	v_fmaak_f32 v15, v14, v15, 0x3f2aaada
	v_sub_f32_e32 v9, v5, v16
	v_ldexp_f32 v16, v13, 1
	v_mul_f32_e32 v13, v13, v14
	v_mul_f32_e32 v13, v13, v15
	v_add_f32_e32 v14, v16, v13
	v_sub_f32_e32 v15, v14, v16
	v_ldexp_f32 v4, v4, 1
	v_sub_f32_e32 v13, v13, v15
	v_add_f32_e32 v4, v4, v13
	v_add_f32_e32 v13, v14, v4
	v_sub_f32_e32 v14, v13, v14
	v_sub_f32_e32 v4, v4, v14
	v_add_f32_e32 v14, v5, v13
	v_sub_f32_e32 v15, v14, v5
	v_sub_f32_e32 v16, v14, v15
	v_sub_f32_e32 v9, v17, v9
	v_sub_f32_e32 v5, v5, v16
	v_sub_f32_e32 v13, v13, v15
	v_add_f32_e32 v5, v13, v5
	v_add_f32_e32 v13, v9, v4
	v_sub_f32_e32 v15, v13, v9
	v_sub_f32_e32 v16, v13, v15
	v_sub_f32_e32 v9, v9, v16
	v_sub_f32_e32 v4, v4, v15
	v_add_f32_e32 v5, v13, v5
	v_add_f32_e32 v4, v4, v9
	v_add_f32_e32 v9, v14, v5
	v_sub_f32_e32 v13, v9, v14
	v_sub_f32_e32 v5, v5, v13
	v_add_f32_e32 v4, v4, v5
	v_add_f32_e32 v4, v9, v4
	v_cmp_neq_f32_e32 vcc, s6, v6
	s_nop 1
	v_cndmask_b32_e32 v4, v238, v4, vcc
	v_cmp_ngt_f32_e32 vcc, -1.0, v6
	s_nop 1
	v_cndmask_b32_e32 v4, v239, v4, vcc
	v_cmp_neq_f32_e32 vcc, -1.0, v6
	s_nop 1
	v_cndmask_b32_e32 v4, v240, v4, vcc
	v_cmp_lt_f32_e64 vcc, |v6|, s10
	s_nop 1
	v_cndmask_b32_e32 v4, v4, v6, vcc
	v_add_f32_e32 v4, v8, v4
	v_sub_f32_e32 v4, -0.5, v4
	v_mul_f32_e32 v4, 0x3fb8aa3b, v4
	v_exp_f32_e32 v5, v4
	v_mul_f32_e32 v4, 0xbfb8aa3b, v7
	v_exp_f32_e32 v4, v4
	ds_read_b128 v[6:9], v12 offset:240
	v_mul_f32_e32 v5, 0xbfb8aa3b, v5
	v_exp_f32_e32 v5, v5
	ds_write_b128 v75, v[2:5] offset:224
	ds_read_b128 v[2:5], v74 offset:240
	s_waitcnt lgkmcnt(0)
; template <int MODE, bool BIG = false> DI void gemm_tile(const Params& p, int tm, int tn, int kv, char* smem) {
;     ...
;     for (int c4 = 0; c4 < 16; ++c4) {
;       float4 v = crow4[c4], ww = w04[c4];
;       float u[4] = {v.x + ww.x, v.y + ww.y, v.z + ww.z, v.w + ww.w};
; #pragma unroll
;       for (int e = 0; e < 4; ++e) {
;         const float z = -u[e];
;         const float sp = fmaxf(z, 0.f) + log1pf(__expf(-fabsf(z)));
;         u[e] = __expf(-__expf(-sp - 0.5f));
;       }
;       W4[c4] = make_float4(u[0], u[1], u[2], u[3]);
	v_add_f32_e32 v0, v6, v2
	v_mul_f32_e64 v2, |v0|, s7
	v_exp_f32_e32 v6, v2
	v_add_f32_e32 v4, v8, v4
	v_add_f32_e32 v7, v7, v3
	v_max_f32_e64 v0, -v0, 0
	v_add_f32_e32 v8, 1.0, v6
	v_add_f32_e32 v2, -1.0, v8
	v_sub_f32_e32 v3, v2, v8
	v_add_f32_e32 v3, 1.0, v3
	v_sub_f32_e32 v2, v6, v2
	v_add_f32_e32 v12, v2, v3
	v_frexp_mant_f32_e32 v2, v8
	v_cmp_gt_f32_e32 vcc, s8, v2
	v_cvt_f64_f32_e32 v[2:3], v8
	v_frexp_exp_i32_f64_e32 v2, v[2:3]
	v_subbrev_co_u32_e32 v2, vcc, 0, v2, vcc
	v_sub_u32_e32 v3, 0, v2
	v_ldexp_f32 v8, v8, v3
	v_ldexp_f32 v3, v12, v3
	v_add_f32_e32 v12, -1.0, v8
	v_add_f32_e32 v15, 1.0, v8
	v_add_f32_e32 v13, 1.0, v12
	v_add_f32_e32 v16, -1.0, v15
	v_sub_f32_e32 v13, v8, v13
	v_sub_f32_e32 v8, v8, v16
	v_add_f32_e32 v13, v3, v13
	v_add_f32_e32 v3, v3, v8
	v_add_f32_e32 v8, v15, v3
	v_rcp_f32_e32 v16, v8
	v_add_f32_e32 v14, v12, v13
	v_sub_f32_e32 v12, v14, v12
	v_sub_f32_e32 v12, v13, v12
	v_sub_f32_e32 v13, v8, v15
	v_sub_f32_e32 v3, v3, v13
	v_mul_f32_e32 v13, v14, v16
	v_mul_f32_e32 v15, v8, v13
	v_fma_f32 v17, v13, v8, -v15
	v_fmac_f32_e32 v17, v13, v3
	v_add_f32_e32 v18, v15, v17
	v_sub_f32_e32 v19, v14, v18
	v_sub_f32_e32 v14, v14, v19
	v_sub_f32_e32 v15, v18, v15
	v_sub_f32_e32 v14, v14, v18
	v_add_f32_e32 v12, v12, v14
	v_sub_f32_e32 v14, v15, v17
	v_add_f32_e32 v12, v14, v12
	v_add_f32_e32 v14, v19, v12
	v_mul_f32_e32 v15, v16, v14
	v_mul_f32_e32 v17, v8, v15
	v_fma_f32 v8, v15, v8, -v17
	v_fmac_f32_e32 v8, v15, v3
	v_sub_f32_e32 v3, v19, v14
	v_add_f32_e32 v3, v12, v3
	v_add_f32_e32 v12, v17, v8
	v_sub_f32_e32 v18, v14, v12
	v_sub_f32_e32 v14, v14, v18
	v_sub_f32_e32 v17, v12, v17
	v_sub_f32_e32 v12, v14, v12
	v_add_f32_e32 v3, v3, v12
	v_sub_f32_e32 v8, v17, v8
	v_cvt_f32_i32_e32 v2, v2
	v_add_f32_e32 v3, v8, v3
	v_add_f32_e32 v8, v13, v15
	v_add_f32_e32 v3, v18, v3
	v_sub_f32_e32 v12, v8, v13
	v_mul_f32_e32 v3, v16, v3
	v_sub_f32_e32 v12, v15, v12
	v_add_f32_e32 v3, v12, v3
	v_mul_f32_e32 v15, 0x3f317218, v2
	v_add_f32_e32 v12, v8, v3
	v_fma_f32 v16, v2, s9, -v15
	v_mul_f32_e32 v13, v12, v12
	v_fmac_f32_e32 v16, 0xb102e308, v2
	v_sub_f32_e32 v2, v12, v8
	v_fmamk_f32 v14, v13, 0x3e9b6dac, v231
	v_sub_f32_e32 v2, v3, v2
	v_add_f32_e32 v3, v15, v16
	v_fmaak_f32 v14, v13, v14, 0x3f2aaada
	v_sub_f32_e32 v8, v3, v15
	v_ldexp_f32 v15, v12, 1
	v_mul_f32_e32 v12, v12, v13
	v_mul_f32_e32 v12, v12, v14
	v_add_f32_e32 v13, v15, v12
	v_sub_f32_e32 v14, v13, v15
	v_ldexp_f32 v2, v2, 1
	v_sub_f32_e32 v12, v12, v14
	v_add_f32_e32 v2, v2, v12
	v_add_f32_e32 v12, v13, v2
	v_sub_f32_e32 v13, v12, v13
	v_sub_f32_e32 v2, v2, v13
	v_add_f32_e32 v13, v3, v12
	v_sub_f32_e32 v14, v13, v3
	v_sub_f32_e32 v15, v13, v14
	v_sub_f32_e32 v8, v16, v8
	v_sub_f32_e32 v3, v3, v15
	v_sub_f32_e32 v12, v12, v14
	v_add_f32_e32 v3, v12, v3
	v_add_f32_e32 v12, v8, v2
	v_sub_f32_e32 v14, v12, v8
	v_sub_f32_e32 v15, v12, v14
	v_sub_f32_e32 v8, v8, v15
	v_sub_f32_e32 v2, v2, v14
	v_add_f32_e32 v3, v12, v3
	v_add_f32_e32 v2, v2, v8
	v_add_f32_e32 v8, v13, v3
	v_sub_f32_e32 v12, v8, v13
	v_sub_f32_e32 v3, v3, v12
	v_add_f32_e32 v2, v2, v3
	v_add_f32_e32 v2, v8, v2
	v_cmp_neq_f32_e32 vcc, s6, v6
	v_add_f32_e32 v8, v9, v5
	v_max_f32_e64 v5, -v7, 0
	v_cndmask_b32_e32 v2, v238, v2, vcc
	v_cmp_ngt_f32_e32 vcc, -1.0, v6
	s_nop 1
	v_cndmask_b32_e32 v2, v239, v2, vcc
	v_cmp_neq_f32_e32 vcc, -1.0, v6
	s_nop 1
	v_cndmask_b32_e32 v2, v240, v2, vcc
	v_cmp_lt_f32_e64 vcc, |v6|, s10
	s_nop 1
	v_cndmask_b32_e32 v2, v2, v6, vcc
	v_add_f32_e32 v0, v0, v2
	v_mul_f32_e64 v2, |v7|, s7
	v_exp_f32_e32 v6, v2
	v_sub_f32_e32 v0, -0.5, v0
	v_mul_f32_e32 v0, 0x3fb8aa3b, v0
	v_exp_f32_e32 v0, v0
	v_add_f32_e32 v7, 1.0, v6
	v_add_f32_e32 v2, -1.0, v7
	v_sub_f32_e32 v3, v2, v7
	v_add_f32_e32 v3, 1.0, v3
	v_sub_f32_e32 v2, v6, v2
	v_add_f32_e32 v9, v2, v3
	v_frexp_mant_f32_e32 v2, v7
	v_cmp_gt_f32_e32 vcc, s8, v2
	v_cvt_f64_f32_e32 v[2:3], v7
	v_frexp_exp_i32_f64_e32 v2, v[2:3]
	v_subbrev_co_u32_e32 v2, vcc, 0, v2, vcc
	v_sub_u32_e32 v3, 0, v2
	v_ldexp_f32 v7, v7, v3
	v_ldexp_f32 v3, v9, v3
	v_add_f32_e32 v9, -1.0, v7
	v_add_f32_e32 v14, 1.0, v7
	v_add_f32_e32 v12, 1.0, v9
	v_add_f32_e32 v15, -1.0, v14
	v_sub_f32_e32 v12, v7, v12
	v_sub_f32_e32 v7, v7, v15
	v_add_f32_e32 v12, v3, v12
	v_add_f32_e32 v3, v3, v7
	v_add_f32_e32 v7, v14, v3
	v_rcp_f32_e32 v15, v7
	v_add_f32_e32 v13, v9, v12
	v_sub_f32_e32 v9, v13, v9
	v_sub_f32_e32 v9, v12, v9
	v_sub_f32_e32 v12, v7, v14
	v_sub_f32_e32 v3, v3, v12
	v_mul_f32_e32 v12, v13, v15
	v_mul_f32_e32 v14, v7, v12
	v_fma_f32 v16, v12, v7, -v14
	v_fmac_f32_e32 v16, v12, v3
	v_add_f32_e32 v17, v14, v16
	v_sub_f32_e32 v18, v13, v17
	v_sub_f32_e32 v13, v13, v18
	v_sub_f32_e32 v14, v17, v14
	v_sub_f32_e32 v13, v13, v17
	v_add_f32_e32 v9, v9, v13
	v_sub_f32_e32 v13, v14, v16
	v_add_f32_e32 v9, v13, v9
	v_add_f32_e32 v13, v18, v9
	v_mul_f32_e32 v14, v15, v13
	v_mul_f32_e32 v16, v7, v14
	v_fma_f32 v7, v14, v7, -v16
	v_fmac_f32_e32 v7, v14, v3
	v_sub_f32_e32 v3, v18, v13
	v_add_f32_e32 v3, v9, v3
	v_add_f32_e32 v9, v16, v7
	v_sub_f32_e32 v17, v13, v9
	v_sub_f32_e32 v13, v13, v17
	v_sub_f32_e32 v16, v9, v16
	v_sub_f32_e32 v9, v13, v9
	v_add_f32_e32 v3, v3, v9
	v_sub_f32_e32 v7, v16, v7
	v_cvt_f32_i32_e32 v2, v2
	v_add_f32_e32 v3, v7, v3
	v_add_f32_e32 v7, v12, v14
	v_add_f32_e32 v3, v17, v3
	v_sub_f32_e32 v9, v7, v12
	v_mul_f32_e32 v3, v15, v3
	v_sub_f32_e32 v9, v14, v9
	v_add_f32_e32 v3, v9, v3
	v_mul_f32_e32 v14, 0x3f317218, v2
	v_add_f32_e32 v9, v7, v3
	v_fma_f32 v15, v2, s9, -v14
	v_mul_f32_e32 v12, v9, v9
	v_fmac_f32_e32 v15, 0xb102e308, v2
	v_sub_f32_e32 v2, v9, v7
	v_fmamk_f32 v13, v12, 0x3e9b6dac, v231
	v_sub_f32_e32 v2, v3, v2
	v_add_f32_e32 v3, v14, v15
; template <int MODE, bool BIG = false> DI void gemm_tile(const Params& p, int tm, int tn, int kv, char* smem) {
;     ...
;     for (int c4 = 0; c4 < 16; ++c4) {
;       float4 v = crow4[c4], ww = w04[c4];
;       float u[4] = {v.x + ww.x, v.y + ww.y, v.z + ww.z, v.w + ww.w};
; #pragma unroll
;       for (int e = 0; e < 4; ++e) {
;         const float z = -u[e];
;         const float sp = fmaxf(z, 0.f) + log1pf(__expf(-fabsf(z)));
;         u[e] = __expf(-__expf(-sp - 0.5f));
;       }
;       W4[c4] = make_float4(u[0], u[1], u[2], u[3]);
	v_fmaak_f32 v13, v12, v13, 0x3f2aaada
	v_sub_f32_e32 v7, v3, v14
	v_ldexp_f32 v14, v9, 1
	v_mul_f32_e32 v9, v9, v12
	v_mul_f32_e32 v9, v9, v13
	v_add_f32_e32 v12, v14, v9
	v_sub_f32_e32 v13, v12, v14
	v_ldexp_f32 v2, v2, 1
	v_sub_f32_e32 v9, v9, v13
	v_add_f32_e32 v2, v2, v9
	v_add_f32_e32 v9, v12, v2
	v_sub_f32_e32 v12, v9, v12
	v_sub_f32_e32 v2, v2, v12
	v_add_f32_e32 v12, v3, v9
	v_sub_f32_e32 v13, v12, v3
	v_sub_f32_e32 v14, v12, v13
	v_sub_f32_e32 v7, v15, v7
	v_sub_f32_e32 v3, v3, v14
	v_sub_f32_e32 v9, v9, v13
	v_add_f32_e32 v3, v9, v3
	v_add_f32_e32 v9, v7, v2
	v_sub_f32_e32 v13, v9, v7
	v_sub_f32_e32 v14, v9, v13
	v_sub_f32_e32 v7, v7, v14
	v_sub_f32_e32 v2, v2, v13
	v_add_f32_e32 v3, v9, v3
	v_add_f32_e32 v2, v2, v7
	v_add_f32_e32 v7, v12, v3
	v_sub_f32_e32 v9, v7, v12
	v_sub_f32_e32 v3, v3, v9
	v_add_f32_e32 v2, v2, v3
	v_add_f32_e32 v2, v7, v2
	v_cmp_neq_f32_e32 vcc, s6, v6
	v_mul_f32_e32 v0, 0xbfb8aa3b, v0
	s_nop 0
	v_cndmask_b32_e32 v2, v238, v2, vcc
	v_cmp_ngt_f32_e32 vcc, -1.0, v6
	s_nop 1
	v_cndmask_b32_e32 v2, v239, v2, vcc
	v_cmp_neq_f32_e32 vcc, -1.0, v6
	s_nop 1
	v_cndmask_b32_e32 v2, v240, v2, vcc
	v_cmp_lt_f32_e64 vcc, |v6|, s10
	s_nop 1
	v_cndmask_b32_e32 v2, v2, v6, vcc
	v_add_f32_e32 v2, v5, v2
	v_sub_f32_e32 v2, -0.5, v2
	v_mul_f32_e32 v2, 0x3fb8aa3b, v2
	v_exp_f32_e32 v3, v2
	v_mul_f32_e64 v2, |v4|, s7
	v_exp_f32_e32 v6, v2
	v_exp_f32_e32 v2, v0
	v_mul_f32_e32 v0, 0xbfb8aa3b, v3
	v_max_f32_e64 v3, -v4, 0
	v_add_f32_e32 v7, 1.0, v6
	v_add_f32_e32 v4, -1.0, v7
	v_sub_f32_e32 v5, v4, v7
	v_add_f32_e32 v5, 1.0, v5
	v_sub_f32_e32 v4, v6, v4
	v_add_f32_e32 v9, v4, v5
	v_frexp_mant_f32_e32 v4, v7
	v_cmp_gt_f32_e32 vcc, s8, v4
	v_cvt_f64_f32_e32 v[4:5], v7
	v_frexp_exp_i32_f64_e32 v4, v[4:5]
	v_subbrev_co_u32_e32 v4, vcc, 0, v4, vcc
	v_sub_u32_e32 v5, 0, v4
	v_ldexp_f32 v7, v7, v5
	v_ldexp_f32 v5, v9, v5
	v_add_f32_e32 v9, -1.0, v7
	v_add_f32_e32 v14, 1.0, v7
	v_add_f32_e32 v12, 1.0, v9
	v_add_f32_e32 v15, -1.0, v14
	v_sub_f32_e32 v12, v7, v12
	v_sub_f32_e32 v7, v7, v15
	v_add_f32_e32 v12, v5, v12
	v_add_f32_e32 v5, v5, v7
	v_add_f32_e32 v7, v14, v5
	v_rcp_f32_e32 v15, v7
	v_add_f32_e32 v13, v9, v12
	v_sub_f32_e32 v9, v13, v9
	v_sub_f32_e32 v9, v12, v9
	v_sub_f32_e32 v12, v7, v14
	v_sub_f32_e32 v5, v5, v12
	v_mul_f32_e32 v12, v13, v15
	v_mul_f32_e32 v14, v7, v12
	v_fma_f32 v16, v12, v7, -v14
	v_fmac_f32_e32 v16, v12, v5
	v_add_f32_e32 v17, v14, v16
	v_sub_f32_e32 v18, v13, v17
	v_sub_f32_e32 v13, v13, v18
	v_sub_f32_e32 v14, v17, v14
	v_sub_f32_e32 v13, v13, v17
	v_add_f32_e32 v9, v9, v13
	v_sub_f32_e32 v13, v14, v16
	v_add_f32_e32 v9, v13, v9
	v_add_f32_e32 v13, v18, v9
	v_mul_f32_e32 v14, v15, v13
	v_mul_f32_e32 v16, v7, v14
	v_fma_f32 v7, v14, v7, -v16
	v_fmac_f32_e32 v7, v14, v5
	v_sub_f32_e32 v5, v18, v13
	v_add_f32_e32 v5, v9, v5
	v_add_f32_e32 v9, v16, v7
	v_sub_f32_e32 v17, v13, v9
	v_sub_f32_e32 v13, v13, v17
	v_sub_f32_e32 v16, v9, v16
	v_sub_f32_e32 v9, v13, v9
	v_add_f32_e32 v5, v5, v9
	v_sub_f32_e32 v7, v16, v7
	v_cvt_f32_i32_e32 v4, v4
	v_add_f32_e32 v5, v7, v5
	v_add_f32_e32 v7, v12, v14
	v_add_f32_e32 v5, v17, v5
	v_sub_f32_e32 v9, v7, v12
	v_mul_f32_e32 v5, v15, v5
	v_sub_f32_e32 v9, v14, v9
	v_add_f32_e32 v5, v9, v5
	v_mul_f32_e32 v14, 0x3f317218, v4
	v_add_f32_e32 v9, v7, v5
	v_fma_f32 v15, v4, s9, -v14
	v_mul_f32_e32 v12, v9, v9
	v_fmac_f32_e32 v15, 0xb102e308, v4
	v_sub_f32_e32 v4, v9, v7
	v_fmamk_f32 v13, v12, 0x3e9b6dac, v231
	v_sub_f32_e32 v4, v5, v4
	v_add_f32_e32 v5, v14, v15
	v_fmaak_f32 v13, v12, v13, 0x3f2aaada
	v_sub_f32_e32 v7, v5, v14
	v_ldexp_f32 v14, v9, 1
	v_mul_f32_e32 v9, v9, v12
	v_mul_f32_e32 v9, v9, v13
	v_add_f32_e32 v12, v14, v9
	v_sub_f32_e32 v13, v12, v14
	v_ldexp_f32 v4, v4, 1
	v_sub_f32_e32 v9, v9, v13
	v_add_f32_e32 v4, v4, v9
	v_add_f32_e32 v9, v12, v4
	v_sub_f32_e32 v12, v9, v12
	v_sub_f32_e32 v4, v4, v12
	v_add_f32_e32 v12, v5, v9
	v_sub_f32_e32 v13, v12, v5
	v_sub_f32_e32 v14, v12, v13
	v_sub_f32_e32 v7, v15, v7
	v_sub_f32_e32 v5, v5, v14
	v_sub_f32_e32 v9, v9, v13
	v_add_f32_e32 v5, v9, v5
	v_add_f32_e32 v9, v7, v4
	v_sub_f32_e32 v13, v9, v7
	v_sub_f32_e32 v14, v9, v13
	v_sub_f32_e32 v7, v7, v14
	v_sub_f32_e32 v4, v4, v13
	v_add_f32_e32 v5, v9, v5
	v_add_f32_e32 v4, v4, v7
	v_add_f32_e32 v7, v12, v5
	v_sub_f32_e32 v9, v7, v12
	v_sub_f32_e32 v5, v5, v9
	v_add_f32_e32 v4, v4, v5
	v_add_f32_e32 v4, v7, v4
	v_cmp_neq_f32_e32 vcc, s6, v6
	s_nop 1
	v_cndmask_b32_e32 v4, v238, v4, vcc
	v_cmp_ngt_f32_e32 vcc, -1.0, v6
	s_nop 1
	v_cndmask_b32_e32 v4, v239, v4, vcc
	v_cmp_neq_f32_e32 vcc, -1.0, v6
	s_nop 1
	v_cndmask_b32_e32 v4, v240, v4, vcc
	v_cmp_lt_f32_e64 vcc, |v6|, s10
	s_nop 1
	v_cndmask_b32_e32 v4, v4, v6, vcc
	v_add_f32_e32 v3, v3, v4
	v_mul_f32_e64 v4, |v8|, s7
	v_exp_f32_e32 v6, v4
	v_sub_f32_e32 v3, -0.5, v3
	v_mul_f32_e32 v3, 0x3fb8aa3b, v3
	v_exp_f32_e32 v7, v3
	v_max_f32_e64 v3, -v8, 0
	v_add_f32_e32 v8, 1.0, v6
	v_add_f32_e32 v4, -1.0, v8
	v_sub_f32_e32 v5, v4, v8
	v_add_f32_e32 v5, 1.0, v5
	v_sub_f32_e32 v4, v6, v4
	v_add_f32_e32 v9, v4, v5
	v_frexp_mant_f32_e32 v4, v8
	v_cmp_gt_f32_e32 vcc, s8, v4
	v_cvt_f64_f32_e32 v[4:5], v8
	v_frexp_exp_i32_f64_e32 v4, v[4:5]
	v_subbrev_co_u32_e32 v4, vcc, 0, v4, vcc
	v_sub_u32_e32 v5, 0, v4
	v_ldexp_f32 v8, v8, v5
	v_ldexp_f32 v5, v9, v5
	v_add_f32_e32 v9, -1.0, v8
	v_add_f32_e32 v14, 1.0, v8
	v_add_f32_e32 v12, 1.0, v9
	v_add_f32_e32 v15, -1.0, v14
	v_sub_f32_e32 v12, v8, v12
	v_sub_f32_e32 v8, v8, v15
	v_add_f32_e32 v12, v5, v12
	v_add_f32_e32 v5, v5, v8
	v_add_f32_e32 v8, v14, v5
	v_rcp_f32_e32 v15, v8
	v_add_f32_e32 v13, v9, v12
	v_sub_f32_e32 v9, v13, v9
	v_sub_f32_e32 v9, v12, v9
	v_sub_f32_e32 v12, v8, v14
; template <int MODE, bool BIG = false> DI void gemm_tile(const Params& p, int tm, int tn, int kv, char* smem) {
;     ...
;     for (int c4 = 0; c4 < 16; ++c4) {
;       float4 v = crow4[c4], ww = w04[c4];
;       float u[4] = {v.x + ww.x, v.y + ww.y, v.z + ww.z, v.w + ww.w};
; #pragma unroll
;       for (int e = 0; e < 4; ++e) {
;         const float z = -u[e];
;         const float sp = fmaxf(z, 0.f) + log1pf(__expf(-fabsf(z)));
;         u[e] = __expf(-__expf(-sp - 0.5f));
;       }
;       W4[c4] = make_float4(u[0], u[1], u[2], u[3]);
; __global__ void __launch_bounds__(256, 2) fwd_megakernel(Params p) {
;     ...
;           for (int i = lo + start; i < hi; i += stride) gemm_tile<G_RWW>(p, b * 32 + (i >> 2), i & 3, 0, smem);
;           for (int i = lo + start; i < hi; i += stride) gemm_tile<G_RWA>(p, b * 32 + (i >> 2), i & 3, 0, smem);
;         }
;         if (stage == 0) {
;           for (int i = (X.rank + (X.cnt >> 1)) % X.cnt; i < 17; i += X.cnt) t0_item(p, b * 17 + i, smem);
	v_sub_f32_e32 v5, v5, v12
	v_mul_f32_e32 v12, v13, v15
	v_mul_f32_e32 v14, v8, v12
	v_fma_f32 v16, v12, v8, -v14
	v_fmac_f32_e32 v16, v12, v5
	v_add_f32_e32 v17, v14, v16
	v_sub_f32_e32 v18, v13, v17
	v_sub_f32_e32 v13, v13, v18
	v_sub_f32_e32 v14, v17, v14
	v_sub_f32_e32 v13, v13, v17
	v_add_f32_e32 v9, v9, v13
	v_sub_f32_e32 v13, v14, v16
	v_add_f32_e32 v9, v13, v9
	v_add_f32_e32 v13, v18, v9
	v_mul_f32_e32 v14, v15, v13
	v_mul_f32_e32 v16, v8, v14
	v_fma_f32 v8, v14, v8, -v16
	v_fmac_f32_e32 v8, v14, v5
	v_sub_f32_e32 v5, v18, v13
	v_add_f32_e32 v5, v9, v5
	v_add_f32_e32 v9, v16, v8
	v_sub_f32_e32 v17, v13, v9
	v_sub_f32_e32 v13, v13, v17
	v_sub_f32_e32 v16, v9, v16
	v_sub_f32_e32 v9, v13, v9
	v_add_f32_e32 v5, v5, v9
	v_sub_f32_e32 v8, v16, v8
	v_cvt_f32_i32_e32 v4, v4
	v_add_f32_e32 v5, v8, v5
	v_add_f32_e32 v8, v12, v14
	v_add_f32_e32 v5, v17, v5
	v_sub_f32_e32 v9, v8, v12
	v_mul_f32_e32 v5, v15, v5
	v_sub_f32_e32 v9, v14, v9
	v_add_f32_e32 v5, v9, v5
	v_mul_f32_e32 v14, 0x3f317218, v4
	v_add_f32_e32 v9, v8, v5
	v_fma_f32 v15, v4, s9, -v14
	v_mul_f32_e32 v12, v9, v9
	v_fmac_f32_e32 v15, 0xb102e308, v4
	v_sub_f32_e32 v4, v9, v8
	v_fmamk_f32 v13, v12, 0x3e9b6dac, v231
	v_sub_f32_e32 v4, v5, v4
	v_add_f32_e32 v5, v14, v15
	v_fmaak_f32 v13, v12, v13, 0x3f2aaada
	v_sub_f32_e32 v8, v5, v14
	v_ldexp_f32 v14, v9, 1
	v_mul_f32_e32 v9, v9, v12
	v_mul_f32_e32 v9, v9, v13
	v_add_f32_e32 v12, v14, v9
	v_sub_f32_e32 v13, v12, v14
	v_ldexp_f32 v4, v4, 1
	v_sub_f32_e32 v9, v9, v13
	v_add_f32_e32 v4, v4, v9
	v_add_f32_e32 v9, v12, v4
	v_sub_f32_e32 v12, v9, v12
	v_sub_f32_e32 v4, v4, v12
	v_add_f32_e32 v12, v5, v9
	v_sub_f32_e32 v13, v12, v5
	v_sub_f32_e32 v14, v12, v13
	v_sub_f32_e32 v8, v15, v8
	v_sub_f32_e32 v5, v5, v14
	v_sub_f32_e32 v9, v9, v13
	v_add_f32_e32 v5, v9, v5
	v_add_f32_e32 v9, v8, v4
	v_sub_f32_e32 v13, v9, v8
	v_sub_f32_e32 v14, v9, v13
	v_sub_f32_e32 v8, v8, v14
	v_sub_f32_e32 v4, v4, v13
	v_add_f32_e32 v5, v9, v5
	v_add_f32_e32 v4, v4, v8
	v_add_f32_e32 v8, v12, v5
	v_sub_f32_e32 v9, v8, v12
	v_sub_f32_e32 v5, v5, v9
	v_add_f32_e32 v4, v4, v5
	v_add_f32_e32 v4, v8, v4
	v_cmp_neq_f32_e32 vcc, s6, v6
	s_mov_b32 s6, s88
	s_mov_b32 s7, s86
	v_cndmask_b32_e32 v4, v238, v4, vcc
	v_cmp_ngt_f32_e32 vcc, -1.0, v6
	s_mov_b32 s8, s85
	s_nop 0
	v_cndmask_b32_e32 v4, v239, v4, vcc
	v_cmp_neq_f32_e32 vcc, -1.0, v6
	s_nop 1
	v_cndmask_b32_e32 v4, v240, v4, vcc
	v_cmp_lt_f32_e64 vcc, |v6|, s10
	s_nop 1
	v_cndmask_b32_e32 v4, v4, v6, vcc
	v_add_f32_e32 v3, v3, v4
	v_sub_f32_e32 v3, -0.5, v3
	v_mul_f32_e32 v3, 0x3fb8aa3b, v3
	v_exp_f32_e32 v5, v3
	v_exp_f32_e32 v3, v0
	v_mul_f32_e32 v0, 0xbfb8aa3b, v7
	v_exp_f32_e32 v4, v0
	v_mul_f32_e32 v0, 0xbfb8aa3b, v5
	v_exp_f32_e32 v5, v0
	ds_write_b128 v75, v[2:5] offset:240
	s_waitcnt lgkmcnt(0)
	s_barrier
	v_lshrrev_b32_e32 v66, 5, v173
	v_lshrrev_b32_e32 v69, 1, v173
	v_sub_u32_e32 v68, v66, v69
	v_lshlrev_b32_e32 v68, 11, v68
	v_and_b32_e32 v69, 1, v173
	v_lshlrev_b32_e32 v69, 8, v69
	v_sub_u32_e32 v68, v68, v69
	v_and_b32_e32 v69, 31, v173
	v_lshl_add_u32 v68, v69, 4, v68
	v_mul_u32_u24_e32 v66, 0x210, v66
	v_lshl_add_u32 v66, v69, 4, v66
	v_ashrrev_i32_e32 v69, 31, v68
	v_lshl_add_u64 v[68:69], v[10:11], 0, v[68:69]
	v_mov_b32_e32 v70, 0x4000
	v_mov_b32_e32 v71, 0
	ds_read_b128 v[2:5], v66
	ds_read_b128 v[6:9], v66 offset:4224
	ds_read_b128 v[10:13], v66 offset:8448
	ds_read_b128 v[14:17], v66 offset:12672
	ds_read_b128 v[18:21], v66 offset:16896
	ds_read_b128 v[22:25], v66 offset:21120
	ds_read_b128 v[26:29], v66 offset:25344
	ds_read_b128 v[30:33], v66 offset:29568
	s_waitcnt lgkmcnt(7)
	global_store_dwordx4 v[68:69], v[2:5], off
	v_lshl_add_u64 v[68:69], v[70:71], 0, v[68:69]
	ds_read_b128 v[34:37], v66 offset:33792
	s_waitcnt lgkmcnt(7)
	global_store_dwordx4 v[68:69], v[6:9], off
	v_lshl_add_u64 v[68:69], v[70:71], 0, v[68:69]
	ds_read_b128 v[38:41], v66 offset:38016
	s_waitcnt lgkmcnt(7)
	global_store_dwordx4 v[68:69], v[10:13], off
	v_lshl_add_u64 v[68:69], v[70:71], 0, v[68:69]
	ds_read_b128 v[42:45], v66 offset:42240
	s_waitcnt lgkmcnt(7)
	global_store_dwordx4 v[68:69], v[14:17], off
	v_lshl_add_u64 v[68:69], v[70:71], 0, v[68:69]
	ds_read_b128 v[46:49], v66 offset:46464
	s_waitcnt lgkmcnt(7)
	global_store_dwordx4 v[68:69], v[18:21], off
	v_lshl_add_u64 v[68:69], v[70:71], 0, v[68:69]
	ds_read_b128 v[50:53], v66 offset:50688
	s_waitcnt lgkmcnt(7)
	global_store_dwordx4 v[68:69], v[22:25], off
	v_lshl_add_u64 v[68:69], v[70:71], 0, v[68:69]
	ds_read_b128 v[54:57], v66 offset:54912
	s_waitcnt lgkmcnt(7)
	global_store_dwordx4 v[68:69], v[26:29], off
	v_lshl_add_u64 v[68:69], v[70:71], 0, v[68:69]
	ds_read_b128 v[58:61], v66 offset:59136
	s_waitcnt lgkmcnt(7)
	global_store_dwordx4 v[68:69], v[30:33], off
	v_lshl_add_u64 v[68:69], v[70:71], 0, v[68:69]
	ds_read_b128 v[62:65], v66 offset:63360
	s_waitcnt lgkmcnt(7)
	global_store_dwordx4 v[68:69], v[34:37], off
	v_lshl_add_u64 v[68:69], v[70:71], 0, v[68:69]
	s_waitcnt lgkmcnt(6)
	global_store_dwordx4 v[68:69], v[38:41], off
	v_lshl_add_u64 v[68:69], v[70:71], 0, v[68:69]
	s_waitcnt lgkmcnt(5)
	global_store_dwordx4 v[68:69], v[42:45], off
	v_lshl_add_u64 v[68:69], v[70:71], 0, v[68:69]
	s_waitcnt lgkmcnt(4)
	global_store_dwordx4 v[68:69], v[46:49], off
	v_lshl_add_u64 v[68:69], v[70:71], 0, v[68:69]
	s_waitcnt lgkmcnt(3)
	global_store_dwordx4 v[68:69], v[50:53], off
	v_lshl_add_u64 v[68:69], v[70:71], 0, v[68:69]
	s_waitcnt lgkmcnt(2)
	global_store_dwordx4 v[68:69], v[54:57], off
	v_lshl_add_u64 v[68:69], v[70:71], 0, v[68:69]
	s_waitcnt lgkmcnt(1)
	global_store_dwordx4 v[68:69], v[58:61], off
	v_lshl_add_u64 v[68:69], v[70:71], 0, v[68:69]
	s_waitcnt lgkmcnt(0)
	global_store_dwordx4 v[68:69], v[62:65], off
	v_lshl_add_u64 v[68:69], v[70:71], 0, v[68:69]
	s_cbranch_scc0 .LBB0_206
	s_cmp_eq_u32 s84, 32
	s_cbranch_scc0 .LBB0_343
	s_cmp_eq_u32 s77, 64
	s_cbranch_scc0 .LBB0_343
	s_branch .LBB0_365

; DI void t0_item(const Params& p, int item, char* smem) {
;     ...
;   const float* xr = p.x + (size_t)b * T * 1024;
;   float ss = 0.f;
;   for (int i = tid; i < 1024; i += 256) { const float v = xr[i]; ss += v * v; }
;   ss = wave_sum(ss);
; __global__ void __launch_bounds__(256, 2) fwd_megakernel(Params p) {
;     ...
;         if (stage == 0) {
;           for (int i = (X.rank + (X.cnt >> 1)) % X.cnt; i < 17; i += X.cnt) t0_item(p, b * 17 + i, smem);
.LBB0_365:
	v_readlane_b32 s0, v254, 48
	v_readlane_b32 s1, v254, 49
	s_andn2_b64 vcc, exec, s[0:1]
	s_mov_b64 s[0:1], -1
	s_cbranch_vccnz .LBB0_386
	s_cmp_eq_u32 s77, 64
	s_cbranch_scc0 .Lt0_orig
	s_cmp_ge_i32 s85, 17
	s_cbranch_scc1 .LBB0_385
	s_branch .Lt0_go
.Lt0_orig:
	v_readlane_b32 s0, v253, 47
	v_readlane_b32 s1, v253, 48
	s_andn2_b64 vcc, exec, s[0:1]
	s_cbranch_vccnz .LBB0_385
.Lt0_go:
	v_and_b32_e32 v2, 64, v169
	v_xor_b32_e32 v0, 32, v169
	v_add_u32_e32 v2, 64, v2
	v_cmp_lt_i32_e32 vcc, v0, v2
	v_xor_b32_e32 v3, 16, v169
	v_readlane_b32 s6, v253, 46
	s_cmp_eq_u32 s77, 64
	s_cselect_b32 s6, s85, s6
	v_cndmask_b32_e32 v0, v169, v0, vcc
	v_cmp_lt_i32_e32 vcc, v3, v2
	v_lshlrev_b32_e32 v0, 2, v0
	s_nop 0
	v_cndmask_b32_e32 v3, v169, v3, vcc
	v_lshlrev_b32_e32 v6, 2, v3
	v_xor_b32_e32 v3, 8, v169
	v_cmp_lt_i32_e32 vcc, v3, v2
	s_nop 1
	v_cndmask_b32_e32 v3, v169, v3, vcc
	v_lshlrev_b32_e32 v7, 2, v3
	v_xor_b32_e32 v3, 4, v169
	v_cmp_lt_i32_e32 vcc, v3, v2
	s_nop 1
	v_cndmask_b32_e32 v3, v169, v3, vcc
	v_lshlrev_b32_e32 v8, 2, v3
	v_xor_b32_e32 v3, 2, v169
	v_cmp_lt_i32_e32 vcc, v3, v2
	s_nop 1
	v_cndmask_b32_e32 v3, v169, v3, vcc
	v_lshlrev_b32_e32 v9, 2, v3
	v_xor_b32_e32 v3, 1, v169
	v_cmp_lt_i32_e32 vcc, v3, v2
	s_nop 1
	v_cndmask_b32_e32 v2, v169, v3, vcc
	v_lshlrev_b32_e32 v10, 2, v2
	s_branch .LBB0_369
